# GEMM main loops, MFMA-LDS interleave: next-phase B fragments and the k=0 half of the next A fragments are read from inside the MFMA segment; load segments keep 4 reads + 2 LDS-DMA; slices retired by v
# baseline (speedup 1.0000x reference)
; #define LDA(dst, b, h) for (int m = 0; m < 4; ++m) for (int k = 0; k < 2; ++k) \
;     dst[m][k] = *reinterpret_cast<const bf16x8*>((char*)SA(b, h) + a_thr + (m * 2 + k) * 1024)
; #define LDB(dst, b, h) for (int n = 0; n < 2; ++n) for (int k = 0; k < 2; ++k) \
;     dst[n][k] = *reinterpret_cast<const bf16x8*>((char*)SB(b, h) + b_thr + (n * 2 + k) * 1024)
; #define WAIT_V(n) asm volatile("s_waitcnt vmcnt(" #n ")" ::: "memory")
; #define BAR __builtin_amdgcn_s_barrier()
; #define SCHED __builtin_amdgcn_sched_barrier(0)
; template <bool OVL, bool PANEL = false, class Epi>
; __device__ __forceinline__ void gemm_phase(const bf16_t* __restrict__ A, long lda, const bf16_t* __restrict__ Bt, long ldb, int nM, int nN, int K,
;                                            const Epi& epi, bf16_t* shm, int w0) {
;     ...
;     f32x4 acc[2][2][4][2];
; #pragma unroll
;     for (int a0 = 0; a0 < 2; ++a0)
; #pragma unroll
;       for (int a1 = 0; a1 < 2; ++a1)
; #pragma unroll
;         for (int a2 = 0; a2 < 4; ++a2)
; #pragma unroll
;           for (int a3 = 0; a3 < 2; ++a3) acc[a0][a1][a2][a3] = (f32x4){0.f, 0.f, 0.f, 0.f};
;     bf16x8 At[4][2], B0[2][2], B1[2][2];
;     if (wr == 1) BAR;
;     WAIT_V(4); BAR;
;     STAGE(SB(1, 0), Bt, ldb, boff, bcol, 1); STAGE(SA(1, 0), A, lda, aoff, brow, 1); STAGE(SB(1, 1), Bt, ldb, boff, bcol + HALF, 1);
;     WAIT_V(6); BAR;
;     for (int t = 0; t < nt - 2; t += 2) {
;       LDB(B0, 0, 0); SCHED; LDA(At, 0, 0); STAGE(SA(1, 1), A, lda, aoff, brow + HALF, t + 1);
.LBB0_124:
	s_or_b64 exec, exec, s[0:1]
	s_mul_i32 s2, s29, 0xb0000
	v_readlane_b32 s40, v251, 49
	s_lshl_b32 s28, s10, 8
	s_lshl_b64 s[0:1], s[2:3], 1
	v_readlane_b32 s42, v251, 51
	v_readlane_b32 s43, v251, 52
	s_add_u32 s0, s42, s0
	s_addc_u32 s1, s43, s1
	v_mov_b32_e32 v0, v203
	v_add_u32_e32 v130, s96, v202
	s_waitcnt vmcnt(4)
	s_barrier
	v_readlane_b32 s41, v251, 50
	v_readlane_b32 s44, v251, 53
	v_readlane_b32 s45, v251, 54
	v_readlane_b32 s46, v251, 55
	v_readlane_b32 s47, v251, 56
	s_mov_b64 s[6:7], 0x80
	v_lshl_add_u64 v[2:3], s[0:1], 0, v[0:1]
	v_readfirstlane_b32 s2, v130
	v_add_u32_e32 v131, 0x2000, v130
	v_lshl_add_u64 v[4:5], v[2:3], 0, s[6:7]
	s_mov_b32 m0, s2
	v_readfirstlane_b32 s2, v131
	v_readlane_b32 s40, v252, 20
	global_load_lds_dwordx4 v[4:5], off
	s_mov_b32 m0, s2
	s_mul_i32 s2, s10, 0x160000
	v_readlane_b32 s54, v252, 34
	s_mov_b64 s[8:9], 0x58080
	s_mul_hi_i32 s5, s28, 0x1600
	v_readlane_b32 s55, v252, 35
	s_add_u32 s4, s54, s2
	v_lshl_add_u64 v[2:3], v[2:3], 0, s[8:9]
	s_addc_u32 s5, s55, s5
	v_mov_b32_e32 v0, v203
	v_add_u32_e32 v132, 0x8000, v206
	global_load_lds_dwordx4 v[2:3], off
	v_readfirstlane_b32 s2, v132
	v_lshl_add_u64 v[2:3], s[4:5], 0, v[0:1]
	v_add_u32_e32 v133, 0xa000, v206
	v_lshl_add_u64 v[4:5], v[2:3], 0, s[6:7]
	s_mov_b32 m0, s2
	v_readfirstlane_b32 s2, v133
	global_load_lds_dwordx4 v[4:5], off
	v_lshl_add_u64 v[2:3], v[2:3], 0, s[8:9]
	s_mov_b32 m0, s2
	v_mov_b32_e32 v0, v203
	v_add_u32_e32 v134, s75, v202
	global_load_lds_dwordx4 v[2:3], off
	s_mov_b64 s[14:15], 0xb0080
	v_lshl_add_u64 v[2:3], s[0:1], 0, v[0:1]
	v_readfirstlane_b32 s2, v134
	v_add_u32_e32 v135, 0x2000, v134
	v_lshl_add_u64 v[4:5], v[2:3], 0, s[14:15]
	s_mov_b32 m0, s2
	s_mov_b64 s[16:17], 0x108080
	v_readfirstlane_b32 s2, v135
	global_load_lds_dwordx4 v[4:5], off
	v_lshl_add_u64 v[2:3], v[2:3], 0, s[16:17]
	s_mov_b32 m0, s2
	v_readlane_b32 s41, v252, 21
	global_load_lds_dwordx4 v[2:3], off
	s_waitcnt vmcnt(6)
	v_readlane_b32 s42, v252, 22
	v_readlane_b32 s43, v252, 23
	v_mov_b32_e32 v2, 0
	s_mov_b32 s2, -2
	s_mov_b64 s[6:7], 0
	v_mov_b32_e32 v3, v2
	v_mov_b32_e32 v4, v2
	v_mov_b32_e32 v5, v2
	v_mov_b32_e32 v6, v2
	v_mov_b32_e32 v7, v2
	v_mov_b32_e32 v8, v2
	v_mov_b32_e32 v9, v2
	s_waitcnt vmcnt(0)
	v_mov_b32_e32 v10, v2
	v_mov_b32_e32 v11, v2
	v_mov_b32_e32 v12, v2
	v_mov_b32_e32 v13, v2
	s_waitcnt lgkmcnt(0)
	v_mov_b32_e32 v14, v2
	v_mov_b32_e32 v15, v2
	v_mov_b32_e32 v16, v2
	v_mov_b32_e32 v17, v2
	v_mov_b32_e32 v18, v2
	v_mov_b32_e32 v19, v2
	v_mov_b32_e32 v20, v2
	v_mov_b32_e32 v21, v2
	v_mov_b32_e32 v22, v2
	v_mov_b32_e32 v23, v2
	v_mov_b32_e32 v24, v2
	v_mov_b32_e32 v25, v2
	v_mov_b32_e32 v26, v2
	v_mov_b32_e32 v27, v2
	v_mov_b32_e32 v28, v2
	v_mov_b32_e32 v29, v2
	v_mov_b32_e32 v30, v2
	v_mov_b32_e32 v31, v2
	v_mov_b32_e32 v32, v2
	v_mov_b32_e32 v33, v2
	v_mov_b32_e32 v34, v2
	v_mov_b32_e32 v35, v2
	v_mov_b32_e32 v36, v2
	v_mov_b32_e32 v37, v2
	v_mov_b32_e32 v38, v2
	v_mov_b32_e32 v39, v2
	v_mov_b32_e32 v40, v2
	v_mov_b32_e32 v41, v2
	v_mov_b32_e32 v42, v2
	v_mov_b32_e32 v43, v2
	v_mov_b32_e32 v44, v2
	v_mov_b32_e32 v45, v2
	v_mov_b32_e32 v46, v2
	v_mov_b32_e32 v47, v2
	v_mov_b32_e32 v48, v2
	v_mov_b32_e32 v49, v2
	v_mov_b32_e32 v50, v2
	v_mov_b32_e32 v51, v2
	v_mov_b32_e32 v52, v2
	v_mov_b32_e32 v53, v2
	v_mov_b32_e32 v54, v2
	v_mov_b32_e32 v55, v2
	v_mov_b32_e32 v56, v2
	v_mov_b32_e32 v57, v2
	v_mov_b32_e32 v58, v2
	v_mov_b32_e32 v59, v2
	v_mov_b32_e32 v60, v2
	v_mov_b32_e32 v61, v2
	v_mov_b32_e32 v62, v2
	v_mov_b32_e32 v63, v2
	v_mov_b32_e32 v64, v2
	v_mov_b32_e32 v65, v2
	v_mov_b32_e32 v66, v2
	v_mov_b32_e32 v67, v2
	v_mov_b32_e32 v68, v2
	v_mov_b32_e32 v69, v2
	v_mov_b32_e32 v70, v2
	v_mov_b32_e32 v71, v2
	v_mov_b32_e32 v72, v2
	v_mov_b32_e32 v73, v2
	v_mov_b32_e32 v74, v2
	v_mov_b32_e32 v75, v2
	v_mov_b32_e32 v76, v2
	v_mov_b32_e32 v77, v2
	v_mov_b32_e32 v78, v2
	v_mov_b32_e32 v79, v2
	v_mov_b32_e32 v80, v2
	v_mov_b32_e32 v81, v2
	v_mov_b32_e32 v82, v2
	v_mov_b32_e32 v83, v2
	v_mov_b32_e32 v84, v2
	v_mov_b32_e32 v85, v2
	v_mov_b32_e32 v86, v2
	v_mov_b32_e32 v87, v2
	v_mov_b32_e32 v88, v2
	v_mov_b32_e32 v89, v2
	v_mov_b32_e32 v90, v2
	v_mov_b32_e32 v91, v2
	v_mov_b32_e32 v92, v2
	v_mov_b32_e32 v93, v2
	v_mov_b32_e32 v94, v2
	v_mov_b32_e32 v95, v2
	v_mov_b32_e32 v96, v2
	v_mov_b32_e32 v97, v2
	v_mov_b32_e32 v98, v2
	v_mov_b32_e32 v99, v2
	v_mov_b32_e32 v100, v2
	v_mov_b32_e32 v101, v2
	v_mov_b32_e32 v102, v2
	v_mov_b32_e32 v103, v2
	v_mov_b32_e32 v104, v2
	v_mov_b32_e32 v105, v2
	v_mov_b32_e32 v106, v2
	v_mov_b32_e32 v107, v2
	v_mov_b32_e32 v108, v2
	v_mov_b32_e32 v109, v2
	v_mov_b32_e32 v110, v2
	v_mov_b32_e32 v111, v2
	v_mov_b32_e32 v112, v2
	v_mov_b32_e32 v113, v2
	v_mov_b32_e32 v114, v2
	v_mov_b32_e32 v115, v2
	v_mov_b32_e32 v116, v2
	v_mov_b32_e32 v117, v2
	v_mov_b32_e32 v118, v2
	v_mov_b32_e32 v119, v2
	v_mov_b32_e32 v120, v2
	v_mov_b32_e32 v121, v2
	v_mov_b32_e32 v122, v2
	v_mov_b32_e32 v123, v2
	v_mov_b32_e32 v124, v2
	v_mov_b32_e32 v125, v2
	v_mov_b32_e32 v126, v2
	v_mov_b32_e32 v127, v2
	v_mov_b32_e32 v128, v2
	v_mov_b32_e32 v129, v2
	s_mov_b64 s[18:19], 0x58100
	s_mov_b64 s[30:31], 0xb0100
	s_mov_b64 s[40:41], 0x108100
	s_mov_b64 s[42:43], 0x58180
	v_readlane_b32 s44, v252, 24
	v_readlane_b32 s45, v252, 25
	v_readlane_b32 s46, v252, 26
	v_readlane_b32 s47, v252, 27
	v_readlane_b32 s48, v252, 28
	v_readlane_b32 s49, v252, 29
	v_readlane_b32 s50, v252, 30
	v_readlane_b32 s51, v252, 31
	v_readlane_b32 s52, v252, 32
	v_readlane_b32 s53, v252, 33
	s_barrier
	v_add_u32_e32 v218, s21, v212
	v_readfirstlane_b32 s25, v206
	s_add_u32 s25, s25, 0xc000
	v_readfirstlane_b32 s32, v206
	s_add_u32 s32, s32, 0xe000
	v_add_u32_e32 v219, s33, v212
	v_readfirstlane_b32 s44, v204
	v_readfirstlane_b32 s45, v205
	v_readfirstlane_b32 s46, v206
	v_readfirstlane_b32 s47, v207
	v_readfirstlane_b32 s48, v208
	v_readfirstlane_b32 s49, v209
	v_add_u32_e32 v220, s96, v212
	v_readfirstlane_b32 s50, v210
	v_readfirstlane_b32 s51, v211
	v_add_u32_e32 v221, s75, v212
	v_readfirstlane_b32 s52, v130
	v_readfirstlane_b32 s53, v131
	v_readfirstlane_b32 s54, v132
	v_readfirstlane_b32 s55, v133
	v_readfirstlane_b32 s60, v134
	v_readfirstlane_b32 s61, v135
	v_add_u32_e32 v136, 0xc000, v206
	v_add_u32_e32 v137, 0xe000, v206
	ds_read_b128 v[138:141], v218
	ds_read_b128 v[142:145], v218 offset:1024
	ds_read_b128 v[146:149], v218 offset:2048
	ds_read_b128 v[150:153], v218 offset:3072
	ds_read_b128 v[154:157], v213
	ds_read_b128 v[162:165], v213 offset:2048
	ds_read_b128 v[170:173], v213 offset:4096
	ds_read_b128 v[178:181], v213 offset:6144
; #define LDA(dst, b, h) for (int m = 0; m < 4; ++m) for (int k = 0; k < 2; ++k) \
;     dst[m][k] = *reinterpret_cast<const bf16x8*>((char*)SA(b, h) + a_thr + (m * 2 + k) * 1024)
; #define LDB(dst, b, h) for (int n = 0; n < 2; ++n) for (int k = 0; k < 2; ++k) \
;     dst[n][k] = *reinterpret_cast<const bf16x8*>((char*)SB(b, h) + b_thr + (n * 2 + k) * 1024)
; #define MMA(ai, bj, At, Btf) do { __builtin_amdgcn_s_setprio(1); \
;     for (int m = 0; m < 4; ++m) for (int n = 0; n < 2; ++n) for (int k = 0; k < 2; ++k) \
;       acc[ai][bj][m][n] = __builtin_amdgcn_mfma_f32_16x16x32_bf16(Btf[n][k], At[m][k], acc[ai][bj][m][n], 0, 0, 0); \
;     __builtin_amdgcn_s_setprio(0); } while (0)
; #define WAIT_V(n) asm volatile("s_waitcnt vmcnt(" #n ")" ::: "memory")
; #define WAIT_L(n) asm volatile("s_waitcnt lgkmcnt(" #n ")" ::: "memory")
; #define BAR __builtin_amdgcn_s_barrier()
; #define SCHED __builtin_amdgcn_sched_barrier(0)
; template <bool OVL, bool PANEL = false, class Epi>
; __device__ __forceinline__ void gemm_phase(const bf16_t* __restrict__ A, long lda, const bf16_t* __restrict__ Bt, long ldb, int nM, int nN, int K,
;                                            const Epi& epi, bf16_t* shm, int w0) {
;     ...
;     for (int t = 0; t < nt - 2; t += 2) {
;       LDB(B0, 0, 0); SCHED; LDA(At, 0, 0); STAGE(SA(1, 1), A, lda, aoff, brow + HALF, t + 1);
;       WAIT_L(8); BAR; WAIT_L(0); MMA(0, 0, At, B0); BAR; SCHED;
;       LDB(B1, 0, 1); STAGE(SB(0, 0), Bt, ldb, boff, bcol, t + 2);
;       BAR; WAIT_L(0); MMA(0, 1, At, B1); BAR;
;       LDA(At, 0, 1); STAGE(SA(0, 0), A, lda, aoff, brow, t + 2);
;       BAR; WAIT_L(0); MMA(1, 0, At, B0); BAR; SCHED;
;       STAGE(SB(0, 1), Bt, ldb, boff, bcol + HALF, t + 2);
;       WAIT_V(6); BAR; MMA(1, 1, At, B1); BAR;
.LBB0_125:
	s_add_u32 s8, s4, s6
	s_addc_u32 s9, s5, s7
	ds_read_b128 v[158:161], v213 offset:1024
	ds_read_b128 v[166:169], v213 offset:3072
	ds_read_b128 v[174:177], v213 offset:5120
	ds_read_b128 v[182:185], v213 offset:7168
	s_mov_b32 m0, s25
	s_add_u32 s98, s8, s14
	s_addc_u32 s99, s9, s15
	global_load_lds_dwordx4 v203, s[98:99]
	s_mov_b32 m0, s32
	s_add_u32 s98, s8, s16
	s_addc_u32 s99, s9, s17
	global_load_lds_dwordx4 v203, s[98:99]
	s_waitcnt lgkmcnt(8)
	s_waitcnt vmcnt(8)
	s_barrier
	s_waitcnt lgkmcnt(0)
	s_waitcnt lgkmcnt(0)
	v_mfma_f32_16x16x32_bf16 v[126:129], v[138:141], v[154:157], v[126:129]
	ds_read_b128 v[186:189], v219
	v_mfma_f32_16x16x32_bf16 v[122:125], v[146:149], v[154:157], v[122:125]
	v_mfma_f32_16x16x32_bf16 v[118:121], v[138:141], v[162:165], v[118:121]
	ds_read_b128 v[190:193], v219 offset:1024
	v_mfma_f32_16x16x32_bf16 v[114:117], v[146:149], v[162:165], v[114:117]
	v_mfma_f32_16x16x32_bf16 v[110:113], v[138:141], v[170:173], v[110:113]
	ds_read_b128 v[194:197], v219 offset:2048
	v_mfma_f32_16x16x32_bf16 v[106:109], v[146:149], v[170:173], v[106:109]
	v_mfma_f32_16x16x32_bf16 v[102:105], v[138:141], v[178:181], v[102:105]
	ds_read_b128 v[198:201], v219 offset:3072
	v_mfma_f32_16x16x32_bf16 v[98:101], v[146:149], v[178:181], v[98:101]
	v_mfma_f32_16x16x32_bf16 v[126:129], v[142:145], v[158:161], v[126:129]
	v_mfma_f32_16x16x32_bf16 v[122:125], v[150:153], v[158:161], v[122:125]
	v_mfma_f32_16x16x32_bf16 v[118:121], v[142:145], v[166:169], v[118:121]
	v_mfma_f32_16x16x32_bf16 v[114:117], v[150:153], v[166:169], v[114:117]
	v_mfma_f32_16x16x32_bf16 v[110:113], v[142:145], v[174:177], v[110:113]
	v_mfma_f32_16x16x32_bf16 v[106:109], v[150:153], v[174:177], v[106:109]
	v_mfma_f32_16x16x32_bf16 v[102:105], v[142:145], v[182:185], v[102:105]
	v_mfma_f32_16x16x32_bf16 v[98:101], v[150:153], v[182:185], v[98:101]
	s_barrier
	s_add_u32 vcc_lo, s0, s6
	s_addc_u32 vcc_hi, s1, s7
	s_mov_b32 m0, s44
	s_add_u32 s98, vcc_lo, s34
	s_addc_u32 s99, vcc_hi, s35
	global_load_lds_dwordx4 v203, s[98:99]
	s_mov_b32 m0, s45
	s_add_u32 s98, vcc_lo, s18
	s_addc_u32 s99, vcc_hi, s19
	global_load_lds_dwordx4 v203, s[98:99]
	s_barrier
	s_waitcnt lgkmcnt(0)
	s_waitcnt lgkmcnt(0)
	v_mfma_f32_16x16x32_bf16 v[94:97], v[186:189], v[154:157], v[94:97]
	v_mfma_f32_16x16x32_bf16 v[90:93], v[194:197], v[154:157], v[90:93]
	v_mfma_f32_16x16x32_bf16 v[86:89], v[186:189], v[162:165], v[86:89]
	v_mfma_f32_16x16x32_bf16 v[82:85], v[194:197], v[162:165], v[82:85]
	v_mfma_f32_16x16x32_bf16 v[78:81], v[186:189], v[170:173], v[78:81]
	v_mfma_f32_16x16x32_bf16 v[74:77], v[194:197], v[170:173], v[74:77]
	v_mfma_f32_16x16x32_bf16 v[70:73], v[186:189], v[178:181], v[70:73]
	v_mfma_f32_16x16x32_bf16 v[66:69], v[194:197], v[178:181], v[66:69]
	v_mfma_f32_16x16x32_bf16 v[94:97], v[190:193], v[158:161], v[94:97]
	ds_read_b128 v[154:157], v213 offset:16384
	v_mfma_f32_16x16x32_bf16 v[90:93], v[198:201], v[158:161], v[90:93]
	v_mfma_f32_16x16x32_bf16 v[86:89], v[190:193], v[166:169], v[86:89]
	ds_read_b128 v[162:165], v213 offset:18432
	v_mfma_f32_16x16x32_bf16 v[82:85], v[198:201], v[166:169], v[82:85]
	v_mfma_f32_16x16x32_bf16 v[78:81], v[190:193], v[174:177], v[78:81]
	ds_read_b128 v[170:173], v213 offset:20480
	v_mfma_f32_16x16x32_bf16 v[74:77], v[198:201], v[174:177], v[74:77]
	v_mfma_f32_16x16x32_bf16 v[70:73], v[190:193], v[182:185], v[70:73]
	ds_read_b128 v[178:181], v213 offset:22528
	v_mfma_f32_16x16x32_bf16 v[66:69], v[198:201], v[182:185], v[66:69]
	s_barrier
	ds_read_b128 v[158:161], v213 offset:17408
	ds_read_b128 v[166:169], v213 offset:19456
	ds_read_b128 v[174:177], v213 offset:21504
	ds_read_b128 v[182:185], v213 offset:23552
	s_mov_b32 m0, s46
	s_add_u32 s98, s8, s34
	s_addc_u32 s99, s9, s35
	global_load_lds_dwordx4 v203, s[98:99]
	s_mov_b32 m0, s47
	s_add_u32 s98, s8, s18
	s_addc_u32 s99, s9, s19
	global_load_lds_dwordx4 v203, s[98:99]
	s_waitcnt vmcnt(8)
	s_barrier
	s_waitcnt lgkmcnt(0)
	s_waitcnt lgkmcnt(0)
	v_mfma_f32_16x16x32_bf16 v[62:65], v[138:141], v[154:157], v[62:65]
	v_mfma_f32_16x16x32_bf16 v[58:61], v[146:149], v[154:157], v[58:61]
	v_mfma_f32_16x16x32_bf16 v[54:57], v[138:141], v[162:165], v[54:57]
	v_mfma_f32_16x16x32_bf16 v[50:53], v[146:149], v[162:165], v[50:53]
	v_mfma_f32_16x16x32_bf16 v[46:49], v[138:141], v[170:173], v[46:49]
	v_mfma_f32_16x16x32_bf16 v[42:45], v[146:149], v[170:173], v[42:45]
	v_mfma_f32_16x16x32_bf16 v[38:41], v[138:141], v[178:181], v[38:41]
	v_mfma_f32_16x16x32_bf16 v[34:37], v[146:149], v[178:181], v[34:37]
	v_mfma_f32_16x16x32_bf16 v[62:65], v[142:145], v[158:161], v[62:65]
	v_mfma_f32_16x16x32_bf16 v[58:61], v[150:153], v[158:161], v[58:61]
	v_mfma_f32_16x16x32_bf16 v[54:57], v[142:145], v[166:169], v[54:57]
	v_mfma_f32_16x16x32_bf16 v[50:53], v[150:153], v[166:169], v[50:53]
	v_mfma_f32_16x16x32_bf16 v[46:49], v[142:145], v[174:177], v[46:49]
	v_mfma_f32_16x16x32_bf16 v[42:45], v[150:153], v[174:177], v[42:45]
	v_mfma_f32_16x16x32_bf16 v[38:41], v[142:145], v[182:185], v[38:41]
	v_mfma_f32_16x16x32_bf16 v[34:37], v[150:153], v[182:185], v[34:37]
	s_barrier
	s_mov_b32 m0, s48
	s_add_u32 s98, vcc_lo, s30
	s_addc_u32 s99, vcc_hi, s31
	global_load_lds_dwordx4 v203, s[98:99]
	s_mov_b32 m0, s49
	s_add_u32 s98, vcc_lo, s40
	s_addc_u32 s99, vcc_hi, s41
	global_load_lds_dwordx4 v203, s[98:99]
	s_waitcnt vmcnt(8)
	s_barrier
; #define LDA(dst, b, h) for (int m = 0; m < 4; ++m) for (int k = 0; k < 2; ++k) \
;     dst[m][k] = *reinterpret_cast<const bf16x8*>((char*)SA(b, h) + a_thr + (m * 2 + k) * 1024)
; #define LDB(dst, b, h) for (int n = 0; n < 2; ++n) for (int k = 0; k < 2; ++k) \
;     dst[n][k] = *reinterpret_cast<const bf16x8*>((char*)SB(b, h) + b_thr + (n * 2 + k) * 1024)
; #define MMA(ai, bj, At, Btf) do { __builtin_amdgcn_s_setprio(1); \
;     for (int m = 0; m < 4; ++m) for (int n = 0; n < 2; ++n) for (int k = 0; k < 2; ++k) \
;       acc[ai][bj][m][n] = __builtin_amdgcn_mfma_f32_16x16x32_bf16(Btf[n][k], At[m][k], acc[ai][bj][m][n], 0, 0, 0); \
;     __builtin_amdgcn_s_setprio(0); } while (0)
; #define WAIT_V(n) asm volatile("s_waitcnt vmcnt(" #n ")" ::: "memory")
; #define WAIT_L(n) asm volatile("s_waitcnt lgkmcnt(" #n ")" ::: "memory")
; #define BAR __builtin_amdgcn_s_barrier()
; #define SCHED __builtin_amdgcn_sched_barrier(0)
; template <bool OVL, bool PANEL = false, class Epi>
; __device__ __forceinline__ void gemm_phase(const bf16_t* __restrict__ A, long lda, const bf16_t* __restrict__ Bt, long ldb, int nM, int nN, int K,
;                                            const Epi& epi, bf16_t* shm, int w0) {
;     ...
;       WAIT_V(6); BAR; MMA(1, 1, At, B1); BAR;
;       LDB(B0, 1, 0); SCHED; LDA(At, 1, 0); STAGE(SA(0, 1), A, lda, aoff, brow + HALF, t + 2);
;       WAIT_L(8); BAR; WAIT_L(0); MMA(0, 0, At, B0); BAR; SCHED;
;       LDB(B1, 1, 1); STAGE(SB(1, 0), Bt, ldb, boff, bcol, t + 3);
;       BAR; WAIT_L(0); MMA(0, 1, At, B1); BAR;
	v_mfma_f32_16x16x32_bf16 v[30:33], v[186:189], v[154:157], v[30:33]
	ds_read_b128 v[138:141], v220
	v_mfma_f32_16x16x32_bf16 v[26:29], v[194:197], v[154:157], v[26:29]
	v_mfma_f32_16x16x32_bf16 v[22:25], v[186:189], v[162:165], v[22:25]
	ds_read_b128 v[142:145], v220 offset:1024
	v_mfma_f32_16x16x32_bf16 v[18:21], v[194:197], v[162:165], v[18:21]
	v_mfma_f32_16x16x32_bf16 v[14:17], v[186:189], v[170:173], v[14:17]
	ds_read_b128 v[146:149], v220 offset:2048
	v_mfma_f32_16x16x32_bf16 v[10:13], v[194:197], v[170:173], v[10:13]
	v_mfma_f32_16x16x32_bf16 v[6:9], v[186:189], v[178:181], v[6:9]
	ds_read_b128 v[150:153], v220 offset:3072
	v_mfma_f32_16x16x32_bf16 v[2:5], v[194:197], v[178:181], v[2:5]
	v_mfma_f32_16x16x32_bf16 v[30:33], v[190:193], v[158:161], v[30:33]
	ds_read_b128 v[154:157], v213 offset:32768
	v_mfma_f32_16x16x32_bf16 v[26:29], v[198:201], v[158:161], v[26:29]
	v_mfma_f32_16x16x32_bf16 v[22:25], v[190:193], v[166:169], v[22:25]
	ds_read_b128 v[162:165], v213 offset:34816
	v_mfma_f32_16x16x32_bf16 v[18:21], v[198:201], v[166:169], v[18:21]
	v_mfma_f32_16x16x32_bf16 v[14:17], v[190:193], v[174:177], v[14:17]
	ds_read_b128 v[170:173], v213 offset:36864
	v_mfma_f32_16x16x32_bf16 v[10:13], v[198:201], v[174:177], v[10:13]
	v_mfma_f32_16x16x32_bf16 v[6:9], v[190:193], v[182:185], v[6:9]
	ds_read_b128 v[178:181], v213 offset:38912
	v_mfma_f32_16x16x32_bf16 v[2:5], v[198:201], v[182:185], v[2:5]
	s_barrier
	ds_read_b128 v[158:161], v213 offset:33792
	ds_read_b128 v[166:169], v213 offset:35840
	ds_read_b128 v[174:177], v213 offset:37888
	ds_read_b128 v[182:185], v213 offset:39936
	s_mov_b32 m0, s50
	s_add_u32 s98, s8, s30
	s_addc_u32 s99, s9, s31
	global_load_lds_dwordx4 v203, s[98:99]
	s_mov_b32 m0, s51
	s_add_u32 s98, s8, s40
	s_addc_u32 s99, s9, s41
	global_load_lds_dwordx4 v203, s[98:99]
	s_waitcnt lgkmcnt(8)
	s_waitcnt vmcnt(8)
	s_barrier
	s_waitcnt lgkmcnt(0)
	s_waitcnt lgkmcnt(0)
	v_mfma_f32_16x16x32_bf16 v[126:129], v[138:141], v[154:157], v[126:129]
	ds_read_b128 v[186:189], v221
	v_mfma_f32_16x16x32_bf16 v[122:125], v[146:149], v[154:157], v[122:125]
	v_mfma_f32_16x16x32_bf16 v[118:121], v[138:141], v[162:165], v[118:121]
	ds_read_b128 v[190:193], v221 offset:1024
	v_mfma_f32_16x16x32_bf16 v[114:117], v[146:149], v[162:165], v[114:117]
	v_mfma_f32_16x16x32_bf16 v[110:113], v[138:141], v[170:173], v[110:113]
	ds_read_b128 v[194:197], v221 offset:2048
	v_mfma_f32_16x16x32_bf16 v[106:109], v[146:149], v[170:173], v[106:109]
	v_mfma_f32_16x16x32_bf16 v[102:105], v[138:141], v[178:181], v[102:105]
	ds_read_b128 v[198:201], v221 offset:3072
	v_mfma_f32_16x16x32_bf16 v[98:101], v[146:149], v[178:181], v[98:101]
	v_mfma_f32_16x16x32_bf16 v[126:129], v[142:145], v[158:161], v[126:129]
	v_mfma_f32_16x16x32_bf16 v[122:125], v[150:153], v[158:161], v[122:125]
	v_mfma_f32_16x16x32_bf16 v[118:121], v[142:145], v[166:169], v[118:121]
	v_mfma_f32_16x16x32_bf16 v[114:117], v[150:153], v[166:169], v[114:117]
	v_mfma_f32_16x16x32_bf16 v[110:113], v[142:145], v[174:177], v[110:113]
	v_mfma_f32_16x16x32_bf16 v[106:109], v[150:153], v[174:177], v[106:109]
	v_mfma_f32_16x16x32_bf16 v[102:105], v[142:145], v[182:185], v[102:105]
	v_mfma_f32_16x16x32_bf16 v[98:101], v[150:153], v[182:185], v[98:101]
	s_barrier
	s_mov_b32 m0, s52
	s_add_u32 s98, vcc_lo, s94
	s_addc_u32 s99, vcc_hi, s95
	global_load_lds_dwordx4 v203, s[98:99]
	s_mov_b32 m0, s53
	s_add_u32 s98, vcc_lo, s42
	s_addc_u32 s99, vcc_hi, s43
	global_load_lds_dwordx4 v203, s[98:99]
	s_barrier
	s_waitcnt lgkmcnt(0)
	s_waitcnt lgkmcnt(0)
	v_mfma_f32_16x16x32_bf16 v[94:97], v[186:189], v[154:157], v[94:97]
	v_mfma_f32_16x16x32_bf16 v[90:93], v[194:197], v[154:157], v[90:93]
	v_mfma_f32_16x16x32_bf16 v[86:89], v[186:189], v[162:165], v[86:89]
	v_mfma_f32_16x16x32_bf16 v[82:85], v[194:197], v[162:165], v[82:85]
	v_mfma_f32_16x16x32_bf16 v[78:81], v[186:189], v[170:173], v[78:81]
	v_mfma_f32_16x16x32_bf16 v[74:77], v[194:197], v[170:173], v[74:77]
	v_mfma_f32_16x16x32_bf16 v[70:73], v[186:189], v[178:181], v[70:73]
	v_mfma_f32_16x16x32_bf16 v[66:69], v[194:197], v[178:181], v[66:69]
	v_mfma_f32_16x16x32_bf16 v[94:97], v[190:193], v[158:161], v[94:97]
	ds_read_b128 v[154:157], v213 offset:49152
	v_mfma_f32_16x16x32_bf16 v[90:93], v[198:201], v[158:161], v[90:93]
	v_mfma_f32_16x16x32_bf16 v[86:89], v[190:193], v[166:169], v[86:89]
	ds_read_b128 v[162:165], v213 offset:51200
	v_mfma_f32_16x16x32_bf16 v[82:85], v[198:201], v[166:169], v[82:85]
	v_mfma_f32_16x16x32_bf16 v[78:81], v[190:193], v[174:177], v[78:81]
	ds_read_b128 v[170:173], v213 offset:53248
	v_mfma_f32_16x16x32_bf16 v[74:77], v[198:201], v[174:177], v[74:77]
	v_mfma_f32_16x16x32_bf16 v[70:73], v[190:193], v[182:185], v[70:73]
	ds_read_b128 v[178:181], v213 offset:55296
	v_mfma_f32_16x16x32_bf16 v[66:69], v[198:201], v[182:185], v[66:69]
	s_barrier
; #define LDA(dst, b, h) for (int m = 0; m < 4; ++m) for (int k = 0; k < 2; ++k) \
;     dst[m][k] = *reinterpret_cast<const bf16x8*>((char*)SA(b, h) + a_thr + (m * 2 + k) * 1024)
; #define LDB(dst, b, h) for (int n = 0; n < 2; ++n) for (int k = 0; k < 2; ++k) \
;     dst[n][k] = *reinterpret_cast<const bf16x8*>((char*)SB(b, h) + b_thr + (n * 2 + k) * 1024)
; #define MMA(ai, bj, At, Btf) do { __builtin_amdgcn_s_setprio(1); \
;     for (int m = 0; m < 4; ++m) for (int n = 0; n < 2; ++n) for (int k = 0; k < 2; ++k) \
;       acc[ai][bj][m][n] = __builtin_amdgcn_mfma_f32_16x16x32_bf16(Btf[n][k], At[m][k], acc[ai][bj][m][n], 0, 0, 0); \
;     __builtin_amdgcn_s_setprio(0); } while (0)
; #define WAIT_V(n) asm volatile("s_waitcnt vmcnt(" #n ")" ::: "memory")
; #define WAIT_L(n) asm volatile("s_waitcnt lgkmcnt(" #n ")" ::: "memory")
; #define BAR __builtin_amdgcn_s_barrier()
; #define SCHED __builtin_amdgcn_sched_barrier(0)
; template <bool OVL, bool PANEL = false, class Epi>
; __device__ __forceinline__ void gemm_phase(const bf16_t* __restrict__ A, long lda, const bf16_t* __restrict__ Bt, long ldb, int nM, int nN, int K,
;                                            const Epi& epi, bf16_t* shm, int w0) {
;     ...
;       LDA(At, 1, 1); STAGE(SA(1, 0), A, lda, aoff, brow, t + 3);
;       BAR; WAIT_L(0); MMA(1, 0, At, B0); BAR; SCHED;
;       STAGE(SB(1, 1), Bt, ldb, boff, bcol + HALF, t + 3);
;       WAIT_V(6); BAR; MMA(1, 1, At, B1); BAR;
;     }
;     { LDB(B0, 0, 0); LDA(At, 0, 0); STAGE(SA(1, 1), A, lda, aoff, brow + HALF, nt - 1);
;       BAR; WAIT_L(0); MMA(0, 0, At, B0); BAR;
	ds_read_b128 v[158:161], v213 offset:50176
	ds_read_b128 v[166:169], v213 offset:52224
	ds_read_b128 v[174:177], v213 offset:54272
	ds_read_b128 v[182:185], v213 offset:56320
	s_mov_b32 m0, s54
	s_add_u32 s98, s8, s94
	s_addc_u32 s99, s9, s95
	global_load_lds_dwordx4 v203, s[98:99]
	s_mov_b32 m0, s55
	s_add_u32 s98, s8, s42
	s_addc_u32 s99, s9, s43
	global_load_lds_dwordx4 v203, s[98:99]
	s_waitcnt vmcnt(8)
	s_barrier
	s_waitcnt lgkmcnt(0)
	s_waitcnt lgkmcnt(0)
	v_mfma_f32_16x16x32_bf16 v[62:65], v[138:141], v[154:157], v[62:65]
	v_mfma_f32_16x16x32_bf16 v[58:61], v[146:149], v[154:157], v[58:61]
	v_mfma_f32_16x16x32_bf16 v[54:57], v[138:141], v[162:165], v[54:57]
	v_mfma_f32_16x16x32_bf16 v[50:53], v[146:149], v[162:165], v[50:53]
	v_mfma_f32_16x16x32_bf16 v[46:49], v[138:141], v[170:173], v[46:49]
	v_mfma_f32_16x16x32_bf16 v[42:45], v[146:149], v[170:173], v[42:45]
	v_mfma_f32_16x16x32_bf16 v[38:41], v[138:141], v[178:181], v[38:41]
	v_mfma_f32_16x16x32_bf16 v[34:37], v[146:149], v[178:181], v[34:37]
	v_mfma_f32_16x16x32_bf16 v[62:65], v[142:145], v[158:161], v[62:65]
	v_mfma_f32_16x16x32_bf16 v[58:61], v[150:153], v[158:161], v[58:61]
	v_mfma_f32_16x16x32_bf16 v[54:57], v[142:145], v[166:169], v[54:57]
	v_mfma_f32_16x16x32_bf16 v[50:53], v[150:153], v[166:169], v[50:53]
	v_mfma_f32_16x16x32_bf16 v[46:49], v[142:145], v[174:177], v[46:49]
	v_mfma_f32_16x16x32_bf16 v[42:45], v[150:153], v[174:177], v[42:45]
	v_mfma_f32_16x16x32_bf16 v[38:41], v[142:145], v[182:185], v[38:41]
	v_mfma_f32_16x16x32_bf16 v[34:37], v[150:153], v[182:185], v[34:37]
	s_barrier
	s_mov_b64 s[8:9], 0xb0180
	s_mov_b64 s[8:9], 0x108180
	s_mov_b32 m0, s60
	s_add_u32 s98, vcc_lo, 0xb0180
	s_addc_u32 s99, vcc_hi, 0
	global_load_lds_dwordx4 v203, s[98:99]
	s_mov_b32 m0, s61
	s_add_u32 s98, vcc_lo, 0x108180
	s_addc_u32 s99, vcc_hi, 0
	global_load_lds_dwordx4 v203, s[98:99]
	s_waitcnt vmcnt(8)
	s_barrier
	v_mfma_f32_16x16x32_bf16 v[30:33], v[186:189], v[154:157], v[30:33]
	ds_read_b128 v[138:141], v218
	v_mfma_f32_16x16x32_bf16 v[26:29], v[194:197], v[154:157], v[26:29]
	v_mfma_f32_16x16x32_bf16 v[22:25], v[186:189], v[162:165], v[22:25]
	ds_read_b128 v[142:145], v218 offset:1024
	v_mfma_f32_16x16x32_bf16 v[18:21], v[194:197], v[162:165], v[18:21]
	v_mfma_f32_16x16x32_bf16 v[14:17], v[186:189], v[170:173], v[14:17]
	ds_read_b128 v[146:149], v218 offset:2048
	v_mfma_f32_16x16x32_bf16 v[10:13], v[194:197], v[170:173], v[10:13]
	v_mfma_f32_16x16x32_bf16 v[6:9], v[186:189], v[178:181], v[6:9]
	ds_read_b128 v[150:153], v218 offset:3072
	v_mfma_f32_16x16x32_bf16 v[2:5], v[194:197], v[178:181], v[2:5]
	v_mfma_f32_16x16x32_bf16 v[30:33], v[190:193], v[158:161], v[30:33]
	ds_read_b128 v[154:157], v213
	v_mfma_f32_16x16x32_bf16 v[26:29], v[198:201], v[158:161], v[26:29]
	v_mfma_f32_16x16x32_bf16 v[22:25], v[190:193], v[166:169], v[22:25]
	ds_read_b128 v[162:165], v213 offset:2048
	v_mfma_f32_16x16x32_bf16 v[18:21], v[198:201], v[166:169], v[18:21]
	v_mfma_f32_16x16x32_bf16 v[14:17], v[190:193], v[174:177], v[14:17]
	ds_read_b128 v[170:173], v213 offset:4096
	v_mfma_f32_16x16x32_bf16 v[10:13], v[198:201], v[174:177], v[10:13]
	v_mfma_f32_16x16x32_bf16 v[6:9], v[190:193], v[182:185], v[6:9]
	ds_read_b128 v[178:181], v213 offset:6144
	v_mfma_f32_16x16x32_bf16 v[2:5], v[198:201], v[182:185], v[2:5]
	s_add_i32 s2, s2, 2
	s_add_u32 s6, s6, 0x100
	s_addc_u32 s7, s7, 0
	s_cmp_gt_u32 s2, 39
	s_barrier
	s_cbranch_scc0 .LBB0_125
	s_waitcnt vmcnt(6)
	s_or_b32 s0, s28, 0x80
	s_mul_hi_i32 s1, s0, 0x1600
	s_mulk_i32 s0, 0x1600
	v_readlane_b32 s2, v250, 49
	v_add_u32_e32 v227, 16, v212
	s_add_u32 s0, s2, s0
	v_readlane_b32 s2, v250, 50
	v_add_u32_e32 v0, 0x10000, v227
	s_addc_u32 s1, s2, s1
	v_readfirstlane_b32 s2, v136
	ds_read_b128 v[130:133], v0
	ds_read_b128 v[138:141], v0 offset:1024
	ds_read_b128 v[142:145], v0 offset:2048
	ds_read_b128 v[146:149], v0 offset:3072
	ds_read_b128 v[150:153], v213
	ds_read_b128 v[154:157], v213 offset:1024
	ds_read_b128 v[158:161], v213 offset:2048
	ds_read_b128 v[162:165], v213 offset:3072
	ds_read_b128 v[166:169], v213 offset:4096
	ds_read_b128 v[170:173], v213 offset:5120
	ds_read_b128 v[174:177], v213 offset:6144
	ds_read_b128 v[178:181], v213 offset:7168
	v_mov_b32_e32 v0, v203
	s_mov_b32 m0, s2
	s_nop 0
	v_lshl_add_u64 v[134:135], s[0:1], 0, v[0:1]
	global_load_lds_dwordx4 v0, s[0:1]
	v_readfirstlane_b32 s0, v137
	v_lshl_add_u64 v[134:135], v[134:135], 0, s[26:27]
	s_mov_b32 m0, s0
	s_nop 0
	global_load_lds_dwordx4 v[134:135], off
	s_barrier
	s_waitcnt lgkmcnt(0)

; #define MMA(ai, bj, At, Btf) do { __builtin_amdgcn_s_setprio(1); \
;     for (int m = 0; m < 4; ++m) for (int n = 0; n < 2; ++n) for (int k = 0; k < 2; ++k) \
;       acc[ai][bj][m][n] = __builtin_amdgcn_mfma_f32_16x16x32_bf16(Btf[n][k], At[m][k], acc[ai][bj][m][n], 0, 0, 0); \
;     __builtin_amdgcn_s_setprio(0); } while (0)
; #define WAIT_L(n) asm volatile("s_waitcnt lgkmcnt(" #n ")" ::: "memory")
; #define BAR __builtin_amdgcn_s_barrier()
; template <bool OVL, bool PANEL = false, class Epi>
; __device__ __forceinline__ void gemm_phase(const bf16_t* __restrict__ A, long lda, const bf16_t* __restrict__ Bt, long ldb, int nM, int nN, int K,
;                                            const Epi& epi, bf16_t* shm, int w0) {
;     ...
;       BAR; WAIT_L(0); MMA(0, 0, At, B0); BAR;
	s_waitcnt lgkmcnt(0)
	v_mfma_f32_16x16x32_bf16 v[126:129], v[130:133], v[150:153], v[126:129]
	v_mfma_f32_16x16x32_bf16 v[122:125], v[142:145], v[150:153], v[122:125]
	v_mfma_f32_16x16x32_bf16 v[118:121], v[130:133], v[158:161], v[118:121]
	v_mfma_f32_16x16x32_bf16 v[114:117], v[142:145], v[158:161], v[114:117]
	v_mfma_f32_16x16x32_bf16 v[110:113], v[130:133], v[166:169], v[110:113]
	v_mfma_f32_16x16x32_bf16 v[106:109], v[142:145], v[166:169], v[106:109]
	v_mfma_f32_16x16x32_bf16 v[102:105], v[130:133], v[174:177], v[102:105]
	v_mfma_f32_16x16x32_bf16 v[98:101], v[142:145], v[174:177], v[98:101]
	v_mfma_f32_16x16x32_bf16 v[126:129], v[138:141], v[154:157], v[126:129]
	v_mfma_f32_16x16x32_bf16 v[122:125], v[146:149], v[154:157], v[122:125]
	v_mfma_f32_16x16x32_bf16 v[118:121], v[138:141], v[162:165], v[118:121]
	v_mfma_f32_16x16x32_bf16 v[114:117], v[146:149], v[162:165], v[114:117]
	v_mfma_f32_16x16x32_bf16 v[110:113], v[138:141], v[170:173], v[110:113]
	v_mfma_f32_16x16x32_bf16 v[106:109], v[146:149], v[170:173], v[106:109]
	v_mfma_f32_16x16x32_bf16 v[102:105], v[138:141], v[178:181], v[102:105]
	v_mfma_f32_16x16x32_bf16 v[98:101], v[146:149], v[178:181], v[98:101]

; #define LDB(dst, b, h) for (int n = 0; n < 2; ++n) for (int k = 0; k < 2; ++k) \
;     dst[n][k] = *reinterpret_cast<const bf16x8*>((char*)SB(b, h) + b_thr + (n * 2 + k) * 1024)
; #define MMA(ai, bj, At, Btf) do { __builtin_amdgcn_s_setprio(1); \
;     for (int m = 0; m < 4; ++m) for (int n = 0; n < 2; ++n) for (int k = 0; k < 2; ++k) \
;       acc[ai][bj][m][n] = __builtin_amdgcn_mfma_f32_16x16x32_bf16(Btf[n][k], At[m][k], acc[ai][bj][m][n], 0, 0, 0); \
;     __builtin_amdgcn_s_setprio(0); } while (0)
; #define WAIT_L(n) asm volatile("s_waitcnt lgkmcnt(" #n ")" ::: "memory")
; #define BAR __builtin_amdgcn_s_barrier()
; template <bool OVL, bool PANEL = false, class Epi>
; __device__ __forceinline__ void gemm_phase(const bf16_t* __restrict__ A, long lda, const bf16_t* __restrict__ Bt, long ldb, int nM, int nN, int K,
;                                            const Epi& epi, bf16_t* shm, int w0) {
;     ...
;       LDB(B1, 0, 1); BAR; WAIT_L(0); MMA(0, 1, At, B1); BAR;
	v_add_u32_e32 v0, 0x14000, v227
	s_barrier
	ds_read_b128 v[134:137], v0
	ds_read_b128 v[182:185], v0 offset:1024
	ds_read_b128 v[186:189], v0 offset:2048
	ds_read_b128 v[190:193], v0 offset:3072
	s_barrier
	s_waitcnt lgkmcnt(0)

; #define LDB(dst, b, h) for (int n = 0; n < 2; ++n) for (int k = 0; k < 2; ++k) \
;     dst[n][k] = *reinterpret_cast<const bf16x8*>((char*)SB(b, h) + b_thr + (n * 2 + k) * 1024)
; #define MMA(ai, bj, At, Btf) do { __builtin_amdgcn_s_setprio(1); \
;     for (int m = 0; m < 4; ++m) for (int n = 0; n < 2; ++n) for (int k = 0; k < 2; ++k) \
;       acc[ai][bj][m][n] = __builtin_amdgcn_mfma_f32_16x16x32_bf16(Btf[n][k], At[m][k], acc[ai][bj][m][n], 0, 0, 0); \
;     __builtin_amdgcn_s_setprio(0); } while (0)
; #define WAIT_L(n) asm volatile("s_waitcnt lgkmcnt(" #n ")" ::: "memory")
; #define BAR __builtin_amdgcn_s_barrier()
; template <bool OVL, bool PANEL = false, class Epi>
; __device__ __forceinline__ void gemm_phase(const bf16_t* __restrict__ A, long lda, const bf16_t* __restrict__ Bt, long ldb, int nM, int nN, int K,
;                                            const Epi& epi, bf16_t* shm, int w0) {
;     ...
;       LDB(B1, 0, 1); BAR; WAIT_L(0); MMA(0, 1, At, B1); BAR;
	s_waitcnt lgkmcnt(0)
	v_mfma_f32_16x16x32_bf16 v[94:97], v[134:137], v[150:153], v[94:97]
	v_mfma_f32_16x16x32_bf16 v[90:93], v[186:189], v[150:153], v[90:93]
	v_mfma_f32_16x16x32_bf16 v[86:89], v[134:137], v[158:161], v[86:89]
	v_mfma_f32_16x16x32_bf16 v[82:85], v[186:189], v[158:161], v[82:85]
	v_mfma_f32_16x16x32_bf16 v[78:81], v[134:137], v[166:169], v[78:81]
	v_mfma_f32_16x16x32_bf16 v[66:69], v[186:189], v[174:177], v[66:69]
	v_mfma_f32_16x16x32_bf16 v[94:97], v[182:185], v[154:157], v[94:97]
	v_mfma_f32_16x16x32_bf16 v[90:93], v[190:193], v[154:157], v[90:93]
	v_mfma_f32_16x16x32_bf16 v[86:89], v[182:185], v[162:165], v[86:89]
	v_mfma_f32_16x16x32_bf16 v[82:85], v[190:193], v[162:165], v[82:85]
	v_mfma_f32_16x16x32_bf16 v[78:81], v[182:185], v[170:173], v[78:81]
	v_mfma_f32_16x16x32_bf16 v[74:77], v[186:189], v[166:169], v[74:77]
	v_mfma_f32_16x16x32_bf16 v[70:73], v[134:137], v[174:177], v[70:73]
	v_mfma_f32_16x16x32_bf16 v[66:69], v[190:193], v[178:181], v[66:69]
	v_mfma_f32_16x16x32_bf16 v[150:153], v[190:193], v[170:173], v[74:77]
	v_mfma_f32_16x16x32_bf16 v[154:157], v[182:185], v[178:181], v[70:73]

; #define LDA(dst, b, h) for (int m = 0; m < 4; ++m) for (int k = 0; k < 2; ++k) \
;     dst[m][k] = *reinterpret_cast<const bf16x8*>((char*)SA(b, h) + a_thr + (m * 2 + k) * 1024)
; #define MMA(ai, bj, At, Btf) do { __builtin_amdgcn_s_setprio(1); \
;     for (int m = 0; m < 4; ++m) for (int n = 0; n < 2; ++n) for (int k = 0; k < 2; ++k) \
;       acc[ai][bj][m][n] = __builtin_amdgcn_mfma_f32_16x16x32_bf16(Btf[n][k], At[m][k], acc[ai][bj][m][n], 0, 0, 0); \
;     __builtin_amdgcn_s_setprio(0); } while (0)
; #define WAIT_V(n) asm volatile("s_waitcnt vmcnt(" #n ")" ::: "memory")
; #define WAIT_L(n) asm volatile("s_waitcnt lgkmcnt(" #n ")" ::: "memory")
; #define BAR __builtin_amdgcn_s_barrier()
; template <bool OVL, bool PANEL = false, class Epi>
; __device__ __forceinline__ void gemm_phase(const bf16_t* __restrict__ A, long lda, const bf16_t* __restrict__ Bt, long ldb, int nM, int nN, int K,
;                                            const Epi& epi, bf16_t* shm, int w0) {
;     ...
;       LDA(At, 0, 1); WAIT_V(4); BAR; WAIT_L(0); MMA(1, 0, At, B0); MMA(1, 1, At, B1); BAR; }
	s_barrier
	s_nop 2
	ds_read_b128 v[70:73], v213 offset:16384
	ds_read_b128 v[74:77], v213 offset:17408
	ds_read_b128 v[158:161], v213 offset:18432
	ds_read_b128 v[162:165], v213 offset:19456
	ds_read_b128 v[166:169], v213 offset:20480
	ds_read_b128 v[170:173], v213 offset:21504
	ds_read_b128 v[174:177], v213 offset:22528
	ds_read_b128 v[178:181], v213 offset:23552
	s_waitcnt vmcnt(4)
	s_barrier
	s_waitcnt lgkmcnt(0)

; #define LDA(dst, b, h) for (int m = 0; m < 4; ++m) for (int k = 0; k < 2; ++k) \
;     dst[m][k] = *reinterpret_cast<const bf16x8*>((char*)SA(b, h) + a_thr + (m * 2 + k) * 1024)
; #define MMA(ai, bj, At, Btf) do { __builtin_amdgcn_s_setprio(1); \
;     for (int m = 0; m < 4; ++m) for (int n = 0; n < 2; ++n) for (int k = 0; k < 2; ++k) \
;       acc[ai][bj][m][n] = __builtin_amdgcn_mfma_f32_16x16x32_bf16(Btf[n][k], At[m][k], acc[ai][bj][m][n], 0, 0, 0); \
;     __builtin_amdgcn_s_setprio(0); } while (0)
; #define WAIT_V(n) asm volatile("s_waitcnt vmcnt(" #n ")" ::: "memory")
; #define WAIT_L(n) asm volatile("s_waitcnt lgkmcnt(" #n ")" ::: "memory")
; #define BAR __builtin_amdgcn_s_barrier()
; template <bool OVL, bool PANEL = false, class Epi>
; __device__ __forceinline__ void gemm_phase(const bf16_t* __restrict__ A, long lda, const bf16_t* __restrict__ Bt, long ldb, int nM, int nN, int K,
;                                            const Epi& epi, bf16_t* shm, int w0) {
;     ...
;       LDA(At, 0, 1); WAIT_V(4); BAR; WAIT_L(0); MMA(1, 0, At, B0); MMA(1, 1, At, B1); BAR; }
	s_waitcnt lgkmcnt(0)
	v_mfma_f32_16x16x32_bf16 v[58:61], v[142:145], v[70:73], v[58:61]
	v_mfma_f32_16x16x32_bf16 v[54:57], v[130:133], v[158:161], v[54:57]
	v_mfma_f32_16x16x32_bf16 v[62:65], v[130:133], v[70:73], v[62:65]
	v_mfma_f32_16x16x32_bf16 v[58:61], v[146:149], v[74:77], v[58:61]
	v_mfma_f32_16x16x32_bf16 v[54:57], v[138:141], v[162:165], v[54:57]
	v_mfma_f32_16x16x32_bf16 v[50:53], v[142:145], v[158:161], v[50:53]
	v_mfma_f32_16x16x32_bf16 v[46:49], v[130:133], v[166:169], v[46:49]
	v_mfma_f32_16x16x32_bf16 v[42:45], v[142:145], v[166:169], v[42:45]
	v_mfma_f32_16x16x32_bf16 v[38:41], v[130:133], v[174:177], v[38:41]
	v_mfma_f32_16x16x32_bf16 v[34:37], v[142:145], v[174:177], v[34:37]
	v_mfma_f32_16x16x32_bf16 v[194:197], v[138:141], v[74:77], v[62:65]
	v_mfma_f32_16x16x32_bf16 v[198:201], v[146:149], v[162:165], v[50:53]
	v_mfma_f32_16x16x32_bf16 v[214:217], v[138:141], v[170:173], v[46:49]
	v_mfma_f32_16x16x32_bf16 v[218:221], v[146:149], v[170:173], v[42:45]
	v_mfma_f32_16x16x32_bf16 v[130:133], v[138:141], v[178:181], v[38:41]
	v_mfma_f32_16x16x32_bf16 v[138:141], v[146:149], v[178:181], v[34:37]


; #define LDA(dst, b, h) for (int m = 0; m < 4; ++m) for (int k = 0; k < 2; ++k) \
;     dst[m][k] = *reinterpret_cast<const bf16x8*>((char*)SA(b, h) + a_thr + (m * 2 + k) * 1024)
; #define MMA(ai, bj, At, Btf) do { __builtin_amdgcn_s_setprio(1); \
;     for (int m = 0; m < 4; ++m) for (int n = 0; n < 2; ++n) for (int k = 0; k < 2; ++k) \
;       acc[ai][bj][m][n] = __builtin_amdgcn_mfma_f32_16x16x32_bf16(Btf[n][k], At[m][k], acc[ai][bj][m][n], 0, 0, 0); \
;     __builtin_amdgcn_s_setprio(0); } while (0)
; #define WAIT_V(n) asm volatile("s_waitcnt vmcnt(" #n ")" ::: "memory")
; #define WAIT_L(n) asm volatile("s_waitcnt lgkmcnt(" #n ")" ::: "memory")
; #define BAR __builtin_amdgcn_s_barrier()
; template <bool OVL, bool PANEL = false, class Epi>
; __device__ __forceinline__ void gemm_phase(const bf16_t* __restrict__ A, long lda, const bf16_t* __restrict__ Bt, long ldb, int nM, int nN, int K,
;                                            const Epi& epi, bf16_t* shm, int w0) {
;     ...
;       LDA(At, 0, 1); WAIT_V(4); BAR; WAIT_L(0); MMA(1, 0, At, B0); MMA(1, 1, At, B1); BAR; }
	v_mfma_f32_16x16x32_bf16 v[30:33], v[134:137], v[70:73], v[30:33]
	v_mfma_f32_16x16x32_bf16 v[26:29], v[186:189], v[70:73], v[26:29]
	v_mfma_f32_16x16x32_bf16 v[22:25], v[134:137], v[158:161], v[22:25]
	v_mfma_f32_16x16x32_bf16 v[18:21], v[186:189], v[158:161], v[18:21]
	v_mfma_f32_16x16x32_bf16 v[14:17], v[134:137], v[166:169], v[14:17]
	v_mfma_f32_16x16x32_bf16 v[10:13], v[186:189], v[166:169], v[10:13]
	v_mfma_f32_16x16x32_bf16 v[6:9], v[134:137], v[174:177], v[6:9]
	v_mfma_f32_16x16x32_bf16 v[2:5], v[186:189], v[174:177], v[2:5]
	v_mfma_f32_16x16x32_bf16 v[142:145], v[182:185], v[74:77], v[30:33]
	v_mfma_f32_16x16x32_bf16 v[146:149], v[190:193], v[74:77], v[26:29]
	v_mfma_f32_16x16x32_bf16 v[222:225], v[182:185], v[162:165], v[22:25]
	v_mfma_f32_16x16x32_bf16 v[158:161], v[190:193], v[162:165], v[18:21]
	v_mfma_f32_16x16x32_bf16 v[162:165], v[182:185], v[170:173], v[14:17]
	v_mfma_f32_16x16x32_bf16 v[166:169], v[190:193], v[170:173], v[10:13]
	v_mfma_f32_16x16x32_bf16 v[134:137], v[182:185], v[178:181], v[6:9]
	v_mfma_f32_16x16x32_bf16 v[170:173], v[190:193], v[178:181], v[2:5]

; #define LDA(dst, b, h) for (int m = 0; m < 4; ++m) for (int k = 0; k < 2; ++k) \
;     dst[m][k] = *reinterpret_cast<const bf16x8*>((char*)SA(b, h) + a_thr + (m * 2 + k) * 1024)
; #define LDB(dst, b, h) for (int n = 0; n < 2; ++n) for (int k = 0; k < 2; ++k) \
;     dst[n][k] = *reinterpret_cast<const bf16x8*>((char*)SB(b, h) + b_thr + (n * 2 + k) * 1024)
; #define MMA(ai, bj, At, Btf) do { __builtin_amdgcn_s_setprio(1); \
;     for (int m = 0; m < 4; ++m) for (int n = 0; n < 2; ++n) for (int k = 0; k < 2; ++k) \
;       acc[ai][bj][m][n] = __builtin_amdgcn_mfma_f32_16x16x32_bf16(Btf[n][k], At[m][k], acc[ai][bj][m][n], 0, 0, 0); \
;     __builtin_amdgcn_s_setprio(0); } while (0)
; #define WAIT_V(n) asm volatile("s_waitcnt vmcnt(" #n ")" ::: "memory")
; #define WAIT_L(n) asm volatile("s_waitcnt lgkmcnt(" #n ")" ::: "memory")
; #define BAR __builtin_amdgcn_s_barrier()
; template <bool OVL, bool PANEL = false, class Epi>
; __device__ __forceinline__ void gemm_phase(const bf16_t* __restrict__ A, long lda, const bf16_t* __restrict__ Bt, long ldb, int nM, int nN, int K,
;                                            const Epi& epi, bf16_t* shm, int w0) {
;     ...
;     { LDB(B0, 1, 0); LDA(At, 1, 0); WAIT_V(2); BAR; WAIT_L(0); MMA(0, 0, At, B0); BAR;
	v_add_u32_e32 v0, 0x18000, v227
	s_barrier
	ds_read_b128 v[34:37], v0
	ds_read_b128 v[174:177], v0 offset:1024
	ds_read_b128 v[178:181], v0 offset:2048
	ds_read_b128 v[182:185], v0 offset:3072
	ds_read_b128 v[18:21], v213 offset:32768
	ds_read_b128 v[22:25], v213 offset:33792
	ds_read_b128 v[26:29], v213 offset:34816
	ds_read_b128 v[50:53], v213 offset:35840
	ds_read_b128 v[186:189], v213 offset:36864
	ds_read_b128 v[190:193], v213 offset:37888
	ds_read_b128 v[228:231], v213 offset:38912
	ds_read_b128 v[232:235], v213 offset:39936
	s_waitcnt vmcnt(2)
	s_barrier
	s_waitcnt lgkmcnt(0)

; #define LDA(dst, b, h) for (int m = 0; m < 4; ++m) for (int k = 0; k < 2; ++k) \
;     dst[m][k] = *reinterpret_cast<const bf16x8*>((char*)SA(b, h) + a_thr + (m * 2 + k) * 1024)
; #define LDB(dst, b, h) for (int n = 0; n < 2; ++n) for (int k = 0; k < 2; ++k) \
;     dst[n][k] = *reinterpret_cast<const bf16x8*>((char*)SB(b, h) + b_thr + (n * 2 + k) * 1024)
; #define MMA(ai, bj, At, Btf) do { __builtin_amdgcn_s_setprio(1); \
;     for (int m = 0; m < 4; ++m) for (int n = 0; n < 2; ++n) for (int k = 0; k < 2; ++k) \
;       acc[ai][bj][m][n] = __builtin_amdgcn_mfma_f32_16x16x32_bf16(Btf[n][k], At[m][k], acc[ai][bj][m][n], 0, 0, 0); \
;     __builtin_amdgcn_s_setprio(0); } while (0)
; #define WAIT_V(n) asm volatile("s_waitcnt vmcnt(" #n ")" ::: "memory")
; #define WAIT_L(n) asm volatile("s_waitcnt lgkmcnt(" #n ")" ::: "memory")
; #define BAR __builtin_amdgcn_s_barrier()
; template <bool OVL, bool PANEL = false, class Epi>
; __device__ __forceinline__ void gemm_phase(const bf16_t* __restrict__ A, long lda, const bf16_t* __restrict__ Bt, long ldb, int nM, int nN, int K,
;                                            const Epi& epi, bf16_t* shm, int w0) {
;     ...
;     { LDB(B0, 1, 0); LDA(At, 1, 0); WAIT_V(2); BAR; WAIT_L(0); MMA(0, 0, At, B0); BAR;
	s_waitcnt lgkmcnt(0)
	v_mfma_f32_16x16x32_bf16 v[6:9], v[178:181], v[18:21], v[122:125]
	v_mfma_f32_16x16x32_bf16 v[10:13], v[178:181], v[26:29], v[114:117]
	v_mfma_f32_16x16x32_bf16 v[14:17], v[178:181], v[186:189], v[106:109]
	v_mfma_f32_16x16x32_bf16 v[2:5], v[34:37], v[18:21], v[126:129]
	v_mfma_f32_16x16x32_bf16 v[30:33], v[182:185], v[22:25], v[6:9]
	v_mfma_f32_16x16x32_bf16 v[6:9], v[34:37], v[26:29], v[118:121]
	v_mfma_f32_16x16x32_bf16 v[38:41], v[182:185], v[50:53], v[10:13]
	v_mfma_f32_16x16x32_bf16 v[10:13], v[34:37], v[186:189], v[110:113]
	v_mfma_f32_16x16x32_bf16 v[42:45], v[182:185], v[190:193], v[14:17]
	v_mfma_f32_16x16x32_bf16 v[14:17], v[34:37], v[228:231], v[102:105]
	v_mfma_f32_16x16x32_bf16 v[46:49], v[178:181], v[228:231], v[98:101]
	v_mfma_f32_16x16x32_bf16 v[2:5], v[174:177], v[22:25], v[2:5]
	v_mfma_f32_16x16x32_bf16 v[6:9], v[174:177], v[50:53], v[6:9]
	v_mfma_f32_16x16x32_bf16 v[10:13], v[174:177], v[190:193], v[10:13]
	v_mfma_f32_16x16x32_bf16 v[14:17], v[174:177], v[232:235], v[14:17]
	v_mfma_f32_16x16x32_bf16 v[46:49], v[182:185], v[232:235], v[46:49]

; #define LDB(dst, b, h) for (int n = 0; n < 2; ++n) for (int k = 0; k < 2; ++k) \
;     dst[n][k] = *reinterpret_cast<const bf16x8*>((char*)SB(b, h) + b_thr + (n * 2 + k) * 1024)
; #define MMA(ai, bj, At, Btf) do { __builtin_amdgcn_s_setprio(1); \
;     for (int m = 0; m < 4; ++m) for (int n = 0; n < 2; ++n) for (int k = 0; k < 2; ++k) \
;       acc[ai][bj][m][n] = __builtin_amdgcn_mfma_f32_16x16x32_bf16(Btf[n][k], At[m][k], acc[ai][bj][m][n], 0, 0, 0); \
;     __builtin_amdgcn_s_setprio(0); } while (0)
; #define WAIT_V(n) asm volatile("s_waitcnt vmcnt(" #n ")" ::: "memory")
; #define WAIT_L(n) asm volatile("s_waitcnt lgkmcnt(" #n ")" ::: "memory")
; #define BAR __builtin_amdgcn_s_barrier()
; template <bool OVL, bool PANEL = false, class Epi>
; __device__ __forceinline__ void gemm_phase(const bf16_t* __restrict__ A, long lda, const bf16_t* __restrict__ Bt, long ldb, int nM, int nN, int K,
;                                            const Epi& epi, bf16_t* shm, int w0) {
;     ...
;       LDB(B1, 1, 1); WAIT_V(0); BAR; WAIT_L(0); MMA(0, 1, At, B1); BAR;
	v_add_u32_e32 v0, 0x1c000, v227
	s_barrier
	ds_read_b128 v[102:105], v0
	ds_read_b128 v[236:239], v0 offset:1024
	ds_read_b128 v[240:243], v0 offset:2048
	ds_read_b128 v[244:247], v0 offset:3072
	s_waitcnt vmcnt(0)
	s_barrier
	s_waitcnt lgkmcnt(0)

; #define LDB(dst, b, h) for (int n = 0; n < 2; ++n) for (int k = 0; k < 2; ++k) \
;     dst[n][k] = *reinterpret_cast<const bf16x8*>((char*)SB(b, h) + b_thr + (n * 2 + k) * 1024)
; #define MMA(ai, bj, At, Btf) do { __builtin_amdgcn_s_setprio(1); \
;     for (int m = 0; m < 4; ++m) for (int n = 0; n < 2; ++n) for (int k = 0; k < 2; ++k) \
;       acc[ai][bj][m][n] = __builtin_amdgcn_mfma_f32_16x16x32_bf16(Btf[n][k], At[m][k], acc[ai][bj][m][n], 0, 0, 0); \
;     __builtin_amdgcn_s_setprio(0); } while (0)
; #define WAIT_V(n) asm volatile("s_waitcnt vmcnt(" #n ")" ::: "memory")
; #define WAIT_L(n) asm volatile("s_waitcnt lgkmcnt(" #n ")" ::: "memory")
; #define BAR __builtin_amdgcn_s_barrier()
; template <bool OVL, bool PANEL = false, class Epi>
; __device__ __forceinline__ void gemm_phase(const bf16_t* __restrict__ A, long lda, const bf16_t* __restrict__ Bt, long ldb, int nM, int nN, int K,
;                                            const Epi& epi, bf16_t* shm, int w0) {
;     ...
;       LDB(B1, 1, 1); WAIT_V(0); BAR; WAIT_L(0); MMA(0, 1, At, B1); BAR;
	s_waitcnt lgkmcnt(0)
	v_mfma_f32_16x16x32_bf16 v[62:65], v[102:105], v[18:21], v[94:97]
	v_mfma_f32_16x16x32_bf16 v[18:21], v[240:243], v[18:21], v[90:93]
	v_mfma_f32_16x16x32_bf16 v[98:101], v[244:247], v[22:25], v[18:21]
	v_mfma_f32_16x16x32_bf16 v[18:21], v[102:105], v[26:29], v[86:89]
	v_mfma_f32_16x16x32_bf16 v[70:73], v[236:239], v[50:53], v[18:21]
	v_mfma_f32_16x16x32_bf16 v[18:21], v[240:243], v[26:29], v[82:85]
	v_mfma_f32_16x16x32_bf16 v[106:109], v[244:247], v[50:53], v[18:21]
	v_mfma_f32_16x16x32_bf16 v[18:21], v[102:105], v[186:189], v[78:81]
	v_mfma_f32_16x16x32_bf16 v[74:77], v[236:239], v[190:193], v[18:21]
	v_mfma_f32_16x16x32_bf16 v[18:21], v[240:243], v[186:189], v[150:153]
	v_mfma_f32_16x16x32_bf16 v[110:113], v[244:247], v[190:193], v[18:21]
	v_mfma_f32_16x16x32_bf16 v[18:21], v[102:105], v[228:231], v[154:157]
	v_mfma_f32_16x16x32_bf16 v[78:81], v[236:239], v[232:235], v[18:21]
	v_mfma_f32_16x16x32_bf16 v[18:21], v[240:243], v[228:231], v[66:69]
	v_mfma_f32_16x16x32_bf16 v[62:65], v[236:239], v[22:25], v[62:65]
	v_mfma_f32_16x16x32_bf16 v[114:117], v[244:247], v[232:235], v[18:21]

; #define LDA(dst, b, h) for (int m = 0; m < 4; ++m) for (int k = 0; k < 2; ++k) \
;     dst[m][k] = *reinterpret_cast<const bf16x8*>((char*)SA(b, h) + a_thr + (m * 2 + k) * 1024)
; #define MMA(ai, bj, At, Btf) do { __builtin_amdgcn_s_setprio(1); \
;     for (int m = 0; m < 4; ++m) for (int n = 0; n < 2; ++n) for (int k = 0; k < 2; ++k) \
;       acc[ai][bj][m][n] = __builtin_amdgcn_mfma_f32_16x16x32_bf16(Btf[n][k], At[m][k], acc[ai][bj][m][n], 0, 0, 0); \
;     __builtin_amdgcn_s_setprio(0); } while (0)
; #define WAIT_L(n) asm volatile("s_waitcnt lgkmcnt(" #n ")" ::: "memory")
; #define BAR __builtin_amdgcn_s_barrier()
; template <bool OVL, bool PANEL = false, class Epi>
; __device__ __forceinline__ void gemm_phase(const bf16_t* __restrict__ A, long lda, const bf16_t* __restrict__ Bt, long ldb, int nM, int nN, int K,
;                                            const Epi& epi, bf16_t* shm, int w0) {
;     ...
;       LDA(At, 1, 1); BAR; WAIT_L(0); MMA(1, 0, At, B0); MMA(1, 1, At, B1); BAR; }
	s_barrier
	ds_read_b128 v[86:89], v213 offset:49152
	ds_read_b128 v[90:93], v213 offset:50176
	ds_read_b128 v[94:97], v213 offset:51200
	ds_read_b128 v[118:121], v213 offset:52224
	ds_read_b128 v[150:153], v213 offset:53248
	ds_read_b128 v[154:157], v213 offset:54272
	ds_read_b128 v[186:189], v213 offset:55296
	ds_read_b128 v[190:193], v213 offset:56320
	s_barrier
	s_waitcnt lgkmcnt(0)

; #define LDA(dst, b, h) for (int m = 0; m < 4; ++m) for (int k = 0; k < 2; ++k) \
;     dst[m][k] = *reinterpret_cast<const bf16x8*>((char*)SA(b, h) + a_thr + (m * 2 + k) * 1024)
; #define MMA(ai, bj, At, Btf) do { __builtin_amdgcn_s_setprio(1); \
;     for (int m = 0; m < 4; ++m) for (int n = 0; n < 2; ++n) for (int k = 0; k < 2; ++k) \
;       acc[ai][bj][m][n] = __builtin_amdgcn_mfma_f32_16x16x32_bf16(Btf[n][k], At[m][k], acc[ai][bj][m][n], 0, 0, 0); \
;     __builtin_amdgcn_s_setprio(0); } while (0)
; #define WAIT_L(n) asm volatile("s_waitcnt lgkmcnt(" #n ")" ::: "memory")
; #define BAR __builtin_amdgcn_s_barrier()
; template <bool OVL, bool PANEL = false, class Epi>
; __device__ __forceinline__ void gemm_phase(const bf16_t* __restrict__ A, long lda, const bf16_t* __restrict__ Bt, long ldb, int nM, int nN, int K,
;                                            const Epi& epi, bf16_t* shm, int w0) {
;     ...
;       LDA(At, 1, 1); BAR; WAIT_L(0); MMA(1, 0, At, B0); MMA(1, 1, At, B1); BAR; }
	s_waitcnt lgkmcnt(0)
	v_mfma_f32_16x16x32_bf16 v[22:25], v[178:181], v[86:89], v[58:61]
	v_mfma_f32_16x16x32_bf16 v[26:29], v[178:181], v[94:97], v[198:201]
	v_mfma_f32_16x16x32_bf16 v[18:21], v[34:37], v[86:89], v[194:197]
	v_mfma_f32_16x16x32_bf16 v[50:53], v[182:185], v[90:93], v[22:25]
	v_mfma_f32_16x16x32_bf16 v[22:25], v[34:37], v[94:97], v[54:57]
	v_mfma_f32_16x16x32_bf16 v[54:57], v[182:185], v[118:121], v[26:29]
	v_mfma_f32_16x16x32_bf16 v[26:29], v[34:37], v[150:153], v[214:217]
	v_mfma_f32_16x16x32_bf16 v[58:61], v[178:181], v[150:153], v[218:221]
	v_mfma_f32_16x16x32_bf16 v[34:37], v[34:37], v[186:189], v[130:133]
	v_mfma_f32_16x16x32_bf16 v[66:69], v[178:181], v[186:189], v[138:141]
	v_mfma_f32_16x16x32_bf16 v[18:21], v[174:177], v[90:93], v[18:21]
	v_mfma_f32_16x16x32_bf16 v[22:25], v[174:177], v[118:121], v[22:25]
	v_mfma_f32_16x16x32_bf16 v[26:29], v[174:177], v[154:157], v[26:29]
	v_mfma_f32_16x16x32_bf16 v[58:61], v[182:185], v[154:157], v[58:61]
	v_mfma_f32_16x16x32_bf16 v[34:37], v[174:177], v[190:193], v[34:37]
	v_mfma_f32_16x16x32_bf16 v[66:69], v[182:185], v[190:193], v[66:69]


; #define LDA(dst, b, h) for (int m = 0; m < 4; ++m) for (int k = 0; k < 2; ++k) \
;     dst[m][k] = *reinterpret_cast<const bf16x8*>((char*)SA(b, h) + a_thr + (m * 2 + k) * 1024)
; #define MMA(ai, bj, At, Btf) do { __builtin_amdgcn_s_setprio(1); \
;     for (int m = 0; m < 4; ++m) for (int n = 0; n < 2; ++n) for (int k = 0; k < 2; ++k) \
;       acc[ai][bj][m][n] = __builtin_amdgcn_mfma_f32_16x16x32_bf16(Btf[n][k], At[m][k], acc[ai][bj][m][n], 0, 0, 0); \
;     __builtin_amdgcn_s_setprio(0); } while (0)
; #define WAIT_L(n) asm volatile("s_waitcnt lgkmcnt(" #n ")" ::: "memory")
; #define BAR __builtin_amdgcn_s_barrier()
; template <bool OVL, bool PANEL = false, class Epi>
; __device__ __forceinline__ void gemm_phase(const bf16_t* __restrict__ A, long lda, const bf16_t* __restrict__ Bt, long ldb, int nM, int nN, int K,
;                                            const Epi& epi, bf16_t* shm, int w0) {
;     ...
;       LDA(At, 1, 1); BAR; WAIT_L(0); MMA(1, 0, At, B0); MMA(1, 1, At, B1); BAR; }
	v_mfma_f32_16x16x32_bf16 v[82:85], v[102:105], v[86:89], v[142:145]
	v_mfma_f32_16x16x32_bf16 v[86:89], v[240:243], v[86:89], v[146:149]
	v_mfma_f32_16x16x32_bf16 v[82:85], v[236:239], v[90:93], v[82:85]
	v_mfma_f32_16x16x32_bf16 v[122:125], v[244:247], v[90:93], v[86:89]
	v_mfma_f32_16x16x32_bf16 v[86:89], v[102:105], v[94:97], v[222:225]
	v_mfma_f32_16x16x32_bf16 v[90:93], v[240:243], v[94:97], v[158:161]
	v_mfma_f32_16x16x32_bf16 v[94:97], v[240:243], v[150:153], v[166:169]
	v_mfma_f32_16x16x32_bf16 v[86:89], v[236:239], v[118:121], v[86:89]
	v_mfma_f32_16x16x32_bf16 v[126:129], v[244:247], v[118:121], v[90:93]
	v_mfma_f32_16x16x32_bf16 v[118:121], v[244:247], v[154:157], v[94:97]
	v_mfma_f32_16x16x32_bf16 v[94:97], v[102:105], v[186:189], v[134:137]
	v_mfma_f32_16x16x32_bf16 v[90:93], v[102:105], v[150:153], v[162:165]
	v_mfma_f32_16x16x32_bf16 v[102:105], v[236:239], v[190:193], v[94:97]
	v_mfma_f32_16x16x32_bf16 v[94:97], v[240:243], v[186:189], v[170:173]
	v_mfma_f32_16x16x32_bf16 v[90:93], v[236:239], v[154:157], v[90:93]
	v_mfma_f32_16x16x32_bf16 v[94:97], v[244:247], v[190:193], v[94:97]

; #define LDA(dst, b, h) for (int m = 0; m < 4; ++m) for (int k = 0; k < 2; ++k) \
;     dst[m][k] = *reinterpret_cast<const bf16x8*>((char*)SA(b, h) + a_thr + (m * 2 + k) * 1024)
; #define MMA(ai, bj, At, Btf) do { __builtin_amdgcn_s_setprio(1); \
;     for (int m = 0; m < 4; ++m) for (int n = 0; n < 2; ++n) for (int k = 0; k < 2; ++k) \
;       acc[ai][bj][m][n] = __builtin_amdgcn_mfma_f32_16x16x32_bf16(Btf[n][k], At[m][k], acc[ai][bj][m][n], 0, 0, 0); \
;     __builtin_amdgcn_s_setprio(0); } while (0)
; #define WAIT_L(n) asm volatile("s_waitcnt lgkmcnt(" #n ")" ::: "memory")
; #define BAR __builtin_amdgcn_s_barrier()
; template <bool OVL, bool PANEL = false, class Epi>
; __device__ __forceinline__ void gemm_phase(const bf16_t* __restrict__ A, long lda, const bf16_t* __restrict__ Bt, long ldb, int nM, int nN, int K,
;                                            const Epi& epi, bf16_t* shm, int w0) {
;     ...
;       LDA(At, 1, 1); BAR; WAIT_L(0); MMA(1, 0, At, B0); MMA(1, 1, At, B1); BAR; }
;     if (wr == 0) BAR;
	s_barrier
	s_and_saveexec_b64 s[0:1], s[58:59]
	s_cbranch_execz .LBB0_128
	s_barrier

; #define LDA(dst, b, h) for (int m = 0; m < 4; ++m) for (int k = 0; k < 2; ++k) \
;     dst[m][k] = *reinterpret_cast<const bf16x8*>((char*)SA(b, h) + a_thr + (m * 2 + k) * 1024)
; #define LDB(dst, b, h) for (int n = 0; n < 2; ++n) for (int k = 0; k < 2; ++k) \
;     dst[n][k] = *reinterpret_cast<const bf16x8*>((char*)SB(b, h) + b_thr + (n * 2 + k) * 1024)
; #define WAIT_V(n) asm volatile("s_waitcnt vmcnt(" #n ")" ::: "memory")
; #define BAR __builtin_amdgcn_s_barrier()
; #define SCHED __builtin_amdgcn_sched_barrier(0)
; template <bool OVL, bool PANEL = false, class Epi>
; __device__ __forceinline__ void gemm_phase(const bf16_t* __restrict__ A, long lda, const bf16_t* __restrict__ Bt, long ldb, int nM, int nN, int K,
;                                            const Epi& epi, bf16_t* shm, int w0) {
;     ...
;     f32x4 acc[2][2][4][2];
; #pragma unroll
;     for (int a0 = 0; a0 < 2; ++a0)
; #pragma unroll
;       for (int a1 = 0; a1 < 2; ++a1)
; #pragma unroll
;         for (int a2 = 0; a2 < 4; ++a2)
; #pragma unroll
;           for (int a3 = 0; a3 < 2; ++a3) acc[a0][a1][a2][a3] = (f32x4){0.f, 0.f, 0.f, 0.f};
;     bf16x8 At[4][2], B0[2][2], B1[2][2];
;     if (wr == 1) BAR;
;     WAIT_V(4); BAR;
;     STAGE(SB(1, 0), Bt, ldb, boff, bcol, 1); STAGE(SA(1, 0), A, lda, aoff, brow, 1); STAGE(SB(1, 1), Bt, ldb, boff, bcol + HALF, 1);
;     WAIT_V(6); BAR;
;     for (int t = 0; t < nt - 2; t += 2) {
;       LDB(B0, 0, 0); SCHED; LDA(At, 0, 0); STAGE(SA(1, 1), A, lda, aoff, brow + HALF, t + 1);
.LBB0_385:
	s_or_b64 exec, exec, s[6:7]
	s_lshl_b32 s6, s24, 8
	s_ashr_i32 s7, s6, 31
	s_lshl_b32 s2, s25, 8
	s_lshl_b64 s[8:9], s[6:7], 11
	v_readlane_b32 s80, v251, 49
	v_readlane_b32 s81, v251, 50
	s_add_u32 s8, s80, s8
	s_addc_u32 s9, s81, s9
	v_mov_b32_e32 v0, v131
	v_add_u32_e32 v142, s96, v130
	s_waitcnt vmcnt(4)
	s_barrier
	s_mov_b64 s[30:31], 0x80
	v_lshl_add_u64 v[2:3], s[8:9], 0, v[0:1]
	v_readfirstlane_b32 s10, v142
	v_add_u32_e32 v143, 0x2000, v142
	v_lshl_add_u64 v[4:5], v[2:3], 0, s[30:31]
	s_mov_b32 m0, s10
	v_readfirstlane_b32 s10, v143
	v_readlane_b32 s44, v252, 20
	global_load_lds_dwordx4 v[4:5], off
	s_mov_b32 m0, s10
	s_lshl_b64 s[10:11], s[2:3], 11
	v_readlane_b32 s50, v252, 26
	v_readlane_b32 s51, v252, 27
	s_add_u32 s10, s50, s10
	s_mov_b64 s[42:43], 0x20080
	s_addc_u32 s11, s51, s11
	s_or_b32 s28, s6, 0x80
	v_lshl_add_u64 v[2:3], v[2:3], 0, s[42:43]
	v_mov_b32_e32 v0, v131
	v_add_u32_e32 v144, 0x8000, v134
	s_ashr_i32 s29, s28, 31
	global_load_lds_dwordx4 v[2:3], off
	v_readfirstlane_b32 s18, v144
	v_lshl_add_u64 v[2:3], s[10:11], 0, v[0:1]
	v_add_u32_e32 v145, 0xa000, v134
	s_lshl_b64 s[28:29], s[28:29], 11
	v_lshl_add_u64 v[4:5], v[2:3], 0, s[30:31]
	s_mov_b32 m0, s18
	v_readfirstlane_b32 s18, v145
	s_add_u32 s28, s80, s28
	global_load_lds_dwordx4 v[4:5], off
	v_lshl_add_u64 v[2:3], v[2:3], 0, s[42:43]
	s_mov_b32 m0, s18
	s_addc_u32 s29, s81, s29
	v_mov_b32_e32 v0, v131
	v_add_u32_e32 v146, s75, v130
	global_load_lds_dwordx4 v[2:3], off
	v_readfirstlane_b32 s18, v146
	v_lshl_add_u64 v[2:3], s[28:29], 0, v[0:1]
	v_add_u32_e32 v147, 0x2000, v146
	v_lshl_add_u64 v[4:5], v[2:3], 0, s[30:31]
	s_mov_b32 m0, s18
	v_readfirstlane_b32 s18, v147
	global_load_lds_dwordx4 v[4:5], off
	v_lshl_add_u64 v[2:3], v[2:3], 0, s[42:43]
	s_mov_b32 m0, s18
	v_readlane_b32 s45, v252, 21
	global_load_lds_dwordx4 v[2:3], off
	s_waitcnt vmcnt(6)
	v_mov_b32_e32 v2, 0
	s_mov_b32 s18, -2
	s_mov_b64 vcc, 0
	v_mov_b32_e32 v3, v2
	v_mov_b32_e32 v4, v2
	v_mov_b32_e32 v5, v2
	v_mov_b32_e32 v6, v2
	v_mov_b32_e32 v7, v2
	v_mov_b32_e32 v8, v2
	v_mov_b32_e32 v9, v2
	s_waitcnt vmcnt(0)
	v_mov_b32_e32 v10, v2
	v_mov_b32_e32 v11, v2
	v_mov_b32_e32 v12, v2
	v_mov_b32_e32 v13, v2
	s_waitcnt lgkmcnt(0)
	v_mov_b32_e32 v14, v2
	v_mov_b32_e32 v15, v2
	v_mov_b32_e32 v16, v2
	v_mov_b32_e32 v17, v2
	v_mov_b32_e32 v18, v2
	v_mov_b32_e32 v19, v2
	v_mov_b32_e32 v20, v2
	v_mov_b32_e32 v21, v2
	v_mov_b32_e32 v22, v2
	v_mov_b32_e32 v23, v2
	v_mov_b32_e32 v24, v2
	v_mov_b32_e32 v25, v2
	v_mov_b32_e32 v26, v2
	v_mov_b32_e32 v27, v2
	v_mov_b32_e32 v28, v2
	v_mov_b32_e32 v29, v2
	v_mov_b32_e32 v30, v2
	v_mov_b32_e32 v31, v2
	v_mov_b32_e32 v32, v2
	v_mov_b32_e32 v33, v2
	v_mov_b32_e32 v34, v2
	v_mov_b32_e32 v35, v2
	v_mov_b32_e32 v36, v2
	v_mov_b32_e32 v37, v2
	v_mov_b32_e32 v38, v2
	v_mov_b32_e32 v39, v2
	v_mov_b32_e32 v40, v2
	v_mov_b32_e32 v41, v2
	v_mov_b32_e32 v42, v2
	v_mov_b32_e32 v43, v2
	v_mov_b32_e32 v44, v2
	v_mov_b32_e32 v45, v2
	v_mov_b32_e32 v46, v2
	v_mov_b32_e32 v47, v2
	v_mov_b32_e32 v48, v2
	v_mov_b32_e32 v49, v2
	v_mov_b32_e32 v50, v2
	v_mov_b32_e32 v51, v2
	v_mov_b32_e32 v52, v2
	v_mov_b32_e32 v53, v2
	v_mov_b32_e32 v54, v2
	v_mov_b32_e32 v55, v2
	v_mov_b32_e32 v56, v2
	v_mov_b32_e32 v57, v2
	v_mov_b32_e32 v58, v2
	v_mov_b32_e32 v59, v2
	v_mov_b32_e32 v60, v2
	v_mov_b32_e32 v61, v2
	v_mov_b32_e32 v62, v2
	v_mov_b32_e32 v63, v2
	v_mov_b32_e32 v64, v2
	v_mov_b32_e32 v65, v2
	v_mov_b32_e32 v66, v2
	v_mov_b32_e32 v67, v2
	v_mov_b32_e32 v68, v2
	v_mov_b32_e32 v69, v2
	v_mov_b32_e32 v70, v2
	v_mov_b32_e32 v71, v2
	v_mov_b32_e32 v72, v2
	v_mov_b32_e32 v73, v2
	v_mov_b32_e32 v74, v2
	v_mov_b32_e32 v75, v2
	v_mov_b32_e32 v76, v2
	v_mov_b32_e32 v77, v2
	v_mov_b32_e32 v78, v2
	v_mov_b32_e32 v79, v2
	v_mov_b32_e32 v80, v2
	v_mov_b32_e32 v81, v2
	v_mov_b32_e32 v82, v2
	v_mov_b32_e32 v83, v2
	v_mov_b32_e32 v84, v2
	v_mov_b32_e32 v85, v2
	v_mov_b32_e32 v86, v2
	v_mov_b32_e32 v87, v2
	v_mov_b32_e32 v88, v2
	v_mov_b32_e32 v89, v2
	v_mov_b32_e32 v90, v2
	v_mov_b32_e32 v91, v2
	v_mov_b32_e32 v92, v2
	v_mov_b32_e32 v93, v2
	v_mov_b32_e32 v94, v2
	v_mov_b32_e32 v95, v2
	v_mov_b32_e32 v96, v2
	v_mov_b32_e32 v97, v2
	v_mov_b32_e32 v98, v2
	v_mov_b32_e32 v99, v2
	v_mov_b32_e32 v100, v2
	v_mov_b32_e32 v101, v2
	v_mov_b32_e32 v102, v2
	v_mov_b32_e32 v103, v2
	v_mov_b32_e32 v104, v2
	v_mov_b32_e32 v105, v2
	v_mov_b32_e32 v106, v2
	v_mov_b32_e32 v107, v2
	v_mov_b32_e32 v108, v2
	v_mov_b32_e32 v109, v2
	v_mov_b32_e32 v110, v2
	v_mov_b32_e32 v111, v2
	v_mov_b32_e32 v112, v2
	v_mov_b32_e32 v113, v2
	v_mov_b32_e32 v114, v2
	v_mov_b32_e32 v115, v2
	v_mov_b32_e32 v116, v2
	v_mov_b32_e32 v117, v2
	v_mov_b32_e32 v118, v2
	v_mov_b32_e32 v119, v2
	v_mov_b32_e32 v120, v2
	v_mov_b32_e32 v121, v2
	v_mov_b32_e32 v122, v2
	v_mov_b32_e32 v123, v2
	v_mov_b32_e32 v124, v2
	v_mov_b32_e32 v125, v2
	v_mov_b32_e32 v126, v2
	v_mov_b32_e32 v127, v2
	v_mov_b32_e32 v128, v2
	v_mov_b32_e32 v129, v2
	s_mov_b64 s[28:29], 0x40080
	s_mov_b64 s[30:31], 0x40180
	s_mov_b64 s[44:45], 0x60180
	v_readlane_b32 s82, v251, 51
	v_readlane_b32 s83, v251, 52
	v_readlane_b32 s84, v251, 53
	v_readlane_b32 s85, v251, 54
	v_readlane_b32 s86, v251, 55
	v_readlane_b32 s87, v251, 56
	v_readlane_b32 s46, v252, 22
	v_readlane_b32 s47, v252, 23
	v_readlane_b32 s48, v252, 24
	v_readlane_b32 s49, v252, 25
	v_readlane_b32 s52, v252, 28
	v_readlane_b32 s53, v252, 29
	v_readlane_b32 s54, v252, 30
	v_readlane_b32 s55, v252, 31
	v_readlane_b32 s56, v252, 32
	v_readlane_b32 s57, v252, 33
	v_readlane_b32 s58, v252, 34
	v_readlane_b32 s59, v252, 35
	s_barrier
	v_add_u32_e32 v218, s21, v140
	v_readfirstlane_b32 s16, v134
	s_add_u32 s16, s16, 0xc000
	v_readfirstlane_b32 s32, v134
	s_add_u32 s32, s32, 0xe000
	v_add_u32_e32 v219, s33, v140
	v_readfirstlane_b32 s46, v132
	v_readfirstlane_b32 s47, v133
	v_readfirstlane_b32 s48, v134
	v_readfirstlane_b32 s49, v135
	v_readfirstlane_b32 s50, v136
	v_readfirstlane_b32 s51, v137
	v_add_u32_e32 v220, s96, v140
	v_readfirstlane_b32 s52, v138
	v_readfirstlane_b32 s53, v139
	v_add_u32_e32 v221, s75, v140
	v_readfirstlane_b32 s54, v142
	v_readfirstlane_b32 s55, v143
	v_readfirstlane_b32 s56, v144
	v_readfirstlane_b32 s57, v145
	v_readfirstlane_b32 s58, v146
	v_readfirstlane_b32 s59, v147
	v_add_u32_e32 v148, 0xc000, v134
	v_add_u32_e32 v149, 0xe000, v134
	ds_read_b128 v[150:153], v218
	ds_read_b128 v[154:157], v218 offset:1024
	ds_read_b128 v[158:161], v218 offset:2048
	ds_read_b128 v[162:165], v218 offset:3072
	ds_read_b128 v[166:169], v141
	ds_read_b128 v[174:177], v141 offset:2048
	ds_read_b128 v[182:185], v141 offset:4096
	ds_read_b128 v[190:193], v141 offset:6144
; #define LDA(dst, b, h) for (int m = 0; m < 4; ++m) for (int k = 0; k < 2; ++k) \
;     dst[m][k] = *reinterpret_cast<const bf16x8*>((char*)SA(b, h) + a_thr + (m * 2 + k) * 1024)
; #define LDB(dst, b, h) for (int n = 0; n < 2; ++n) for (int k = 0; k < 2; ++k) \
;     dst[n][k] = *reinterpret_cast<const bf16x8*>((char*)SB(b, h) + b_thr + (n * 2 + k) * 1024)
; #define MMA(ai, bj, At, Btf) do { __builtin_amdgcn_s_setprio(1); \
;     for (int m = 0; m < 4; ++m) for (int n = 0; n < 2; ++n) for (int k = 0; k < 2; ++k) \
;       acc[ai][bj][m][n] = __builtin_amdgcn_mfma_f32_16x16x32_bf16(Btf[n][k], At[m][k], acc[ai][bj][m][n], 0, 0, 0); \
;     __builtin_amdgcn_s_setprio(0); } while (0)
; #define WAIT_V(n) asm volatile("s_waitcnt vmcnt(" #n ")" ::: "memory")
; #define WAIT_L(n) asm volatile("s_waitcnt lgkmcnt(" #n ")" ::: "memory")
; #define BAR __builtin_amdgcn_s_barrier()
; #define SCHED __builtin_amdgcn_sched_barrier(0)
; template <bool OVL, bool PANEL = false, class Epi>
; __device__ __forceinline__ void gemm_phase(const bf16_t* __restrict__ A, long lda, const bf16_t* __restrict__ Bt, long ldb, int nM, int nN, int K,
;                                            const Epi& epi, bf16_t* shm, int w0) {
;     ...
;     for (int t = 0; t < nt - 2; t += 2) {
;       LDB(B0, 0, 0); SCHED; LDA(At, 0, 0); STAGE(SA(1, 1), A, lda, aoff, brow + HALF, t + 1);
;       WAIT_L(8); BAR; WAIT_L(0); MMA(0, 0, At, B0); BAR; SCHED;
;       LDB(B1, 0, 1); STAGE(SB(0, 0), Bt, ldb, boff, bcol, t + 2);
;       BAR; WAIT_L(0); MMA(0, 1, At, B1); BAR;
;       LDA(At, 0, 1); STAGE(SA(0, 0), A, lda, aoff, brow, t + 2);
;       BAR; WAIT_L(0); MMA(1, 0, At, B0); BAR; SCHED;
;       STAGE(SB(0, 1), Bt, ldb, boff, bcol + HALF, t + 2);
;       WAIT_V(6); BAR; MMA(1, 1, At, B1); BAR;
.LBB0_386:
	s_add_u32 s42, s10, vcc_lo
	s_addc_u32 s43, s11, vcc_hi
	ds_read_b128 v[170:173], v141 offset:1024
	ds_read_b128 v[178:181], v141 offset:3072
	ds_read_b128 v[186:189], v141 offset:5120
	ds_read_b128 v[194:197], v141 offset:7168
	s_mov_b32 m0, s16
	s_add_u32 s98, s42, s28
	s_addc_u32 s99, s43, s29
	global_load_lds_dwordx4 v131, s[98:99]
	s_mov_b32 m0, s32
	s_add_u32 s98, s42, s36
	s_addc_u32 s99, s43, s37
	global_load_lds_dwordx4 v131, s[98:99]
	s_waitcnt lgkmcnt(8)
	s_waitcnt vmcnt(8)
	s_barrier
	s_waitcnt lgkmcnt(0)
	s_waitcnt lgkmcnt(0)
	v_mfma_f32_16x16x32_bf16 v[126:129], v[150:153], v[166:169], v[126:129]
	ds_read_b128 v[198:201], v219
	v_mfma_f32_16x16x32_bf16 v[122:125], v[158:161], v[166:169], v[122:125]
	v_mfma_f32_16x16x32_bf16 v[118:121], v[150:153], v[174:177], v[118:121]
	ds_read_b128 v[202:205], v219 offset:1024
	v_mfma_f32_16x16x32_bf16 v[114:117], v[158:161], v[174:177], v[114:117]
	v_mfma_f32_16x16x32_bf16 v[110:113], v[150:153], v[182:185], v[110:113]
	ds_read_b128 v[206:209], v219 offset:2048
	v_mfma_f32_16x16x32_bf16 v[106:109], v[158:161], v[182:185], v[106:109]
	v_mfma_f32_16x16x32_bf16 v[102:105], v[150:153], v[190:193], v[102:105]
	ds_read_b128 v[210:213], v219 offset:3072
	v_mfma_f32_16x16x32_bf16 v[98:101], v[158:161], v[190:193], v[98:101]
	v_mfma_f32_16x16x32_bf16 v[126:129], v[154:157], v[170:173], v[126:129]
	v_mfma_f32_16x16x32_bf16 v[122:125], v[162:165], v[170:173], v[122:125]
	v_mfma_f32_16x16x32_bf16 v[118:121], v[154:157], v[178:181], v[118:121]
	v_mfma_f32_16x16x32_bf16 v[114:117], v[162:165], v[178:181], v[114:117]
	v_mfma_f32_16x16x32_bf16 v[110:113], v[154:157], v[186:189], v[110:113]
	v_mfma_f32_16x16x32_bf16 v[106:109], v[162:165], v[186:189], v[106:109]
	v_mfma_f32_16x16x32_bf16 v[102:105], v[154:157], v[194:197], v[102:105]
	v_mfma_f32_16x16x32_bf16 v[98:101], v[162:165], v[194:197], v[98:101]
	s_barrier
	s_add_u32 s66, s8, vcc_lo
	s_addc_u32 s67, s9, vcc_hi
	s_mov_b32 m0, s46
	s_add_u32 s98, s66, s34
	s_addc_u32 s99, s67, s35
	global_load_lds_dwordx4 v131, s[98:99]
	s_mov_b32 m0, s47
	s_add_u32 s98, s66, s64
	s_addc_u32 s99, s67, s65
	global_load_lds_dwordx4 v131, s[98:99]
	s_barrier
	s_waitcnt lgkmcnt(0)
	s_waitcnt lgkmcnt(0)
	v_mfma_f32_16x16x32_bf16 v[94:97], v[198:201], v[166:169], v[94:97]
	v_mfma_f32_16x16x32_bf16 v[90:93], v[206:209], v[166:169], v[90:93]
	v_mfma_f32_16x16x32_bf16 v[86:89], v[198:201], v[174:177], v[86:89]
	v_mfma_f32_16x16x32_bf16 v[82:85], v[206:209], v[174:177], v[82:85]
	v_mfma_f32_16x16x32_bf16 v[78:81], v[198:201], v[182:185], v[78:81]
	v_mfma_f32_16x16x32_bf16 v[74:77], v[206:209], v[182:185], v[74:77]
	v_mfma_f32_16x16x32_bf16 v[70:73], v[198:201], v[190:193], v[70:73]
	v_mfma_f32_16x16x32_bf16 v[66:69], v[206:209], v[190:193], v[66:69]
	v_mfma_f32_16x16x32_bf16 v[94:97], v[202:205], v[170:173], v[94:97]
	ds_read_b128 v[166:169], v141 offset:16384
	v_mfma_f32_16x16x32_bf16 v[90:93], v[210:213], v[170:173], v[90:93]
	v_mfma_f32_16x16x32_bf16 v[86:89], v[202:205], v[178:181], v[86:89]
	ds_read_b128 v[174:177], v141 offset:18432
	v_mfma_f32_16x16x32_bf16 v[82:85], v[210:213], v[178:181], v[82:85]
	v_mfma_f32_16x16x32_bf16 v[78:81], v[202:205], v[186:189], v[78:81]
	ds_read_b128 v[182:185], v141 offset:20480
	v_mfma_f32_16x16x32_bf16 v[74:77], v[210:213], v[186:189], v[74:77]
	v_mfma_f32_16x16x32_bf16 v[70:73], v[202:205], v[194:197], v[70:73]
	ds_read_b128 v[190:193], v141 offset:22528
	v_mfma_f32_16x16x32_bf16 v[66:69], v[210:213], v[194:197], v[66:69]
	s_barrier
	ds_read_b128 v[170:173], v141 offset:17408
	ds_read_b128 v[178:181], v141 offset:19456
	ds_read_b128 v[186:189], v141 offset:21504
	ds_read_b128 v[194:197], v141 offset:23552
	s_mov_b32 m0, s48
	s_add_u32 s98, s42, s34
	s_addc_u32 s99, s43, s35
	global_load_lds_dwordx4 v131, s[98:99]
	s_mov_b32 m0, s49
	s_add_u32 s98, s42, s64
	s_addc_u32 s99, s43, s65
	global_load_lds_dwordx4 v131, s[98:99]
	s_waitcnt vmcnt(8)
	s_barrier
	s_waitcnt lgkmcnt(0)
	s_waitcnt lgkmcnt(0)
	v_mfma_f32_16x16x32_bf16 v[62:65], v[150:153], v[166:169], v[62:65]
	v_mfma_f32_16x16x32_bf16 v[58:61], v[158:161], v[166:169], v[58:61]
	v_mfma_f32_16x16x32_bf16 v[54:57], v[150:153], v[174:177], v[54:57]
	v_mfma_f32_16x16x32_bf16 v[50:53], v[158:161], v[174:177], v[50:53]
	v_mfma_f32_16x16x32_bf16 v[46:49], v[150:153], v[182:185], v[46:49]
	v_mfma_f32_16x16x32_bf16 v[42:45], v[158:161], v[182:185], v[42:45]
	v_mfma_f32_16x16x32_bf16 v[38:41], v[150:153], v[190:193], v[38:41]
	v_mfma_f32_16x16x32_bf16 v[34:37], v[158:161], v[190:193], v[34:37]
	v_mfma_f32_16x16x32_bf16 v[62:65], v[154:157], v[170:173], v[62:65]
	v_mfma_f32_16x16x32_bf16 v[58:61], v[162:165], v[170:173], v[58:61]
	v_mfma_f32_16x16x32_bf16 v[54:57], v[154:157], v[178:181], v[54:57]
	v_mfma_f32_16x16x32_bf16 v[50:53], v[162:165], v[178:181], v[50:53]
	v_mfma_f32_16x16x32_bf16 v[46:49], v[154:157], v[186:189], v[46:49]
	v_mfma_f32_16x16x32_bf16 v[42:45], v[162:165], v[186:189], v[42:45]
	v_mfma_f32_16x16x32_bf16 v[38:41], v[154:157], v[194:197], v[38:41]
	v_mfma_f32_16x16x32_bf16 v[34:37], v[162:165], v[194:197], v[34:37]
	s_barrier
	s_mov_b32 m0, s50
	s_add_u32 s98, s66, s68
	s_addc_u32 s99, s67, s69
	global_load_lds_dwordx4 v131, s[98:99]
	s_mov_b32 m0, s51
	s_add_u32 s98, s66, s70
	s_addc_u32 s99, s67, s71
	global_load_lds_dwordx4 v131, s[98:99]
	s_waitcnt vmcnt(8)
	s_barrier
; #define LDA(dst, b, h) for (int m = 0; m < 4; ++m) for (int k = 0; k < 2; ++k) \
;     dst[m][k] = *reinterpret_cast<const bf16x8*>((char*)SA(b, h) + a_thr + (m * 2 + k) * 1024)
; #define LDB(dst, b, h) for (int n = 0; n < 2; ++n) for (int k = 0; k < 2; ++k) \
;     dst[n][k] = *reinterpret_cast<const bf16x8*>((char*)SB(b, h) + b_thr + (n * 2 + k) * 1024)
; #define MMA(ai, bj, At, Btf) do { __builtin_amdgcn_s_setprio(1); \
;     for (int m = 0; m < 4; ++m) for (int n = 0; n < 2; ++n) for (int k = 0; k < 2; ++k) \
;       acc[ai][bj][m][n] = __builtin_amdgcn_mfma_f32_16x16x32_bf16(Btf[n][k], At[m][k], acc[ai][bj][m][n], 0, 0, 0); \
;     __builtin_amdgcn_s_setprio(0); } while (0)
; #define WAIT_V(n) asm volatile("s_waitcnt vmcnt(" #n ")" ::: "memory")
; #define WAIT_L(n) asm volatile("s_waitcnt lgkmcnt(" #n ")" ::: "memory")
; #define BAR __builtin_amdgcn_s_barrier()
; #define SCHED __builtin_amdgcn_sched_barrier(0)
; template <bool OVL, bool PANEL = false, class Epi>
; __device__ __forceinline__ void gemm_phase(const bf16_t* __restrict__ A, long lda, const bf16_t* __restrict__ Bt, long ldb, int nM, int nN, int K,
;                                            const Epi& epi, bf16_t* shm, int w0) {
;     ...
;       WAIT_V(6); BAR; MMA(1, 1, At, B1); BAR;
;       LDB(B0, 1, 0); SCHED; LDA(At, 1, 0); STAGE(SA(0, 1), A, lda, aoff, brow + HALF, t + 2);
;       WAIT_L(8); BAR; WAIT_L(0); MMA(0, 0, At, B0); BAR; SCHED;
;       LDB(B1, 1, 1); STAGE(SB(1, 0), Bt, ldb, boff, bcol, t + 3);
;       BAR; WAIT_L(0); MMA(0, 1, At, B1); BAR;
	v_mfma_f32_16x16x32_bf16 v[30:33], v[198:201], v[166:169], v[30:33]
	ds_read_b128 v[150:153], v220
	v_mfma_f32_16x16x32_bf16 v[26:29], v[206:209], v[166:169], v[26:29]
	v_mfma_f32_16x16x32_bf16 v[22:25], v[198:201], v[174:177], v[22:25]
	ds_read_b128 v[154:157], v220 offset:1024
	v_mfma_f32_16x16x32_bf16 v[18:21], v[206:209], v[174:177], v[18:21]
	v_mfma_f32_16x16x32_bf16 v[14:17], v[198:201], v[182:185], v[14:17]
	ds_read_b128 v[158:161], v220 offset:2048
	v_mfma_f32_16x16x32_bf16 v[10:13], v[206:209], v[182:185], v[10:13]
	v_mfma_f32_16x16x32_bf16 v[6:9], v[198:201], v[190:193], v[6:9]
	ds_read_b128 v[162:165], v220 offset:3072
	v_mfma_f32_16x16x32_bf16 v[2:5], v[206:209], v[190:193], v[2:5]
	v_mfma_f32_16x16x32_bf16 v[30:33], v[202:205], v[170:173], v[30:33]
	ds_read_b128 v[166:169], v141 offset:32768
	v_mfma_f32_16x16x32_bf16 v[26:29], v[210:213], v[170:173], v[26:29]
	v_mfma_f32_16x16x32_bf16 v[22:25], v[202:205], v[178:181], v[22:25]
	ds_read_b128 v[174:177], v141 offset:34816
	v_mfma_f32_16x16x32_bf16 v[18:21], v[210:213], v[178:181], v[18:21]
	v_mfma_f32_16x16x32_bf16 v[14:17], v[202:205], v[186:189], v[14:17]
	ds_read_b128 v[182:185], v141 offset:36864
	v_mfma_f32_16x16x32_bf16 v[10:13], v[210:213], v[186:189], v[10:13]
	v_mfma_f32_16x16x32_bf16 v[6:9], v[202:205], v[194:197], v[6:9]
	ds_read_b128 v[190:193], v141 offset:38912
	v_mfma_f32_16x16x32_bf16 v[2:5], v[210:213], v[194:197], v[2:5]
	s_barrier
	ds_read_b128 v[170:173], v141 offset:33792
	ds_read_b128 v[178:181], v141 offset:35840
	ds_read_b128 v[186:189], v141 offset:37888
	ds_read_b128 v[194:197], v141 offset:39936
	s_mov_b32 m0, s52
	s_add_u32 s98, s42, s68
	s_addc_u32 s99, s43, s69
	global_load_lds_dwordx4 v131, s[98:99]
	s_mov_b32 m0, s53
	s_add_u32 s98, s42, s70
	s_addc_u32 s99, s43, s71
	global_load_lds_dwordx4 v131, s[98:99]
	s_waitcnt lgkmcnt(8)
	s_waitcnt vmcnt(8)
	s_barrier
	s_waitcnt lgkmcnt(0)
	s_waitcnt lgkmcnt(0)
	v_mfma_f32_16x16x32_bf16 v[126:129], v[150:153], v[166:169], v[126:129]
	ds_read_b128 v[198:201], v221
	v_mfma_f32_16x16x32_bf16 v[122:125], v[158:161], v[166:169], v[122:125]
	v_mfma_f32_16x16x32_bf16 v[118:121], v[150:153], v[174:177], v[118:121]
	ds_read_b128 v[202:205], v221 offset:1024
	v_mfma_f32_16x16x32_bf16 v[114:117], v[158:161], v[174:177], v[114:117]
	v_mfma_f32_16x16x32_bf16 v[110:113], v[150:153], v[182:185], v[110:113]
	ds_read_b128 v[206:209], v221 offset:2048
	v_mfma_f32_16x16x32_bf16 v[106:109], v[158:161], v[182:185], v[106:109]
	v_mfma_f32_16x16x32_bf16 v[102:105], v[150:153], v[190:193], v[102:105]
	ds_read_b128 v[210:213], v221 offset:3072
	v_mfma_f32_16x16x32_bf16 v[98:101], v[158:161], v[190:193], v[98:101]
	v_mfma_f32_16x16x32_bf16 v[126:129], v[154:157], v[170:173], v[126:129]
	v_mfma_f32_16x16x32_bf16 v[122:125], v[162:165], v[170:173], v[122:125]
	v_mfma_f32_16x16x32_bf16 v[118:121], v[154:157], v[178:181], v[118:121]
	v_mfma_f32_16x16x32_bf16 v[114:117], v[162:165], v[178:181], v[114:117]
	v_mfma_f32_16x16x32_bf16 v[110:113], v[154:157], v[186:189], v[110:113]
	v_mfma_f32_16x16x32_bf16 v[106:109], v[162:165], v[186:189], v[106:109]
	v_mfma_f32_16x16x32_bf16 v[102:105], v[154:157], v[194:197], v[102:105]
	v_mfma_f32_16x16x32_bf16 v[98:101], v[162:165], v[194:197], v[98:101]
	s_barrier
	s_mov_b32 m0, s54
	s_add_u32 s98, s66, s94
	s_addc_u32 s99, s67, s95
	global_load_lds_dwordx4 v131, s[98:99]
	s_mov_b32 m0, s55
	s_add_u32 s98, s66, s72
	s_addc_u32 s99, s67, s73
	global_load_lds_dwordx4 v131, s[98:99]
	s_barrier
	s_waitcnt lgkmcnt(0)
	s_waitcnt lgkmcnt(0)
	v_mfma_f32_16x16x32_bf16 v[94:97], v[198:201], v[166:169], v[94:97]
	v_mfma_f32_16x16x32_bf16 v[90:93], v[206:209], v[166:169], v[90:93]
	v_mfma_f32_16x16x32_bf16 v[86:89], v[198:201], v[174:177], v[86:89]
	v_mfma_f32_16x16x32_bf16 v[82:85], v[206:209], v[174:177], v[82:85]
	v_mfma_f32_16x16x32_bf16 v[78:81], v[198:201], v[182:185], v[78:81]
	v_mfma_f32_16x16x32_bf16 v[74:77], v[206:209], v[182:185], v[74:77]
	v_mfma_f32_16x16x32_bf16 v[70:73], v[198:201], v[190:193], v[70:73]
	v_mfma_f32_16x16x32_bf16 v[66:69], v[206:209], v[190:193], v[66:69]
	v_mfma_f32_16x16x32_bf16 v[94:97], v[202:205], v[170:173], v[94:97]
	ds_read_b128 v[166:169], v141 offset:49152
	v_mfma_f32_16x16x32_bf16 v[90:93], v[210:213], v[170:173], v[90:93]
	v_mfma_f32_16x16x32_bf16 v[86:89], v[202:205], v[178:181], v[86:89]
	ds_read_b128 v[174:177], v141 offset:51200
	v_mfma_f32_16x16x32_bf16 v[82:85], v[210:213], v[178:181], v[82:85]
	v_mfma_f32_16x16x32_bf16 v[78:81], v[202:205], v[186:189], v[78:81]
	ds_read_b128 v[182:185], v141 offset:53248
	v_mfma_f32_16x16x32_bf16 v[74:77], v[210:213], v[186:189], v[74:77]
	v_mfma_f32_16x16x32_bf16 v[70:73], v[202:205], v[194:197], v[70:73]
	ds_read_b128 v[190:193], v141 offset:55296
	v_mfma_f32_16x16x32_bf16 v[66:69], v[210:213], v[194:197], v[66:69]
	s_barrier
; #define LDA(dst, b, h) for (int m = 0; m < 4; ++m) for (int k = 0; k < 2; ++k) \
;     dst[m][k] = *reinterpret_cast<const bf16x8*>((char*)SA(b, h) + a_thr + (m * 2 + k) * 1024)
; #define LDB(dst, b, h) for (int n = 0; n < 2; ++n) for (int k = 0; k < 2; ++k) \
;     dst[n][k] = *reinterpret_cast<const bf16x8*>((char*)SB(b, h) + b_thr + (n * 2 + k) * 1024)
; #define MMA(ai, bj, At, Btf) do { __builtin_amdgcn_s_setprio(1); \
;     for (int m = 0; m < 4; ++m) for (int n = 0; n < 2; ++n) for (int k = 0; k < 2; ++k) \
;       acc[ai][bj][m][n] = __builtin_amdgcn_mfma_f32_16x16x32_bf16(Btf[n][k], At[m][k], acc[ai][bj][m][n], 0, 0, 0); \
;     __builtin_amdgcn_s_setprio(0); } while (0)
; #define WAIT_V(n) asm volatile("s_waitcnt vmcnt(" #n ")" ::: "memory")
; #define WAIT_L(n) asm volatile("s_waitcnt lgkmcnt(" #n ")" ::: "memory")
; #define BAR __builtin_amdgcn_s_barrier()
; #define SCHED __builtin_amdgcn_sched_barrier(0)
; template <bool OVL, bool PANEL = false, class Epi>
; __device__ __forceinline__ void gemm_phase(const bf16_t* __restrict__ A, long lda, const bf16_t* __restrict__ Bt, long ldb, int nM, int nN, int K,
;                                            const Epi& epi, bf16_t* shm, int w0) {
;     ...
;       LDA(At, 1, 1); STAGE(SA(1, 0), A, lda, aoff, brow, t + 3);
;       BAR; WAIT_L(0); MMA(1, 0, At, B0); BAR; SCHED;
;       STAGE(SB(1, 1), Bt, ldb, boff, bcol + HALF, t + 3);
;       WAIT_V(6); BAR; MMA(1, 1, At, B1); BAR;
;     }
;     { LDB(B0, 0, 0); LDA(At, 0, 0); STAGE(SA(1, 1), A, lda, aoff, brow + HALF, nt - 1);
;       BAR; WAIT_L(0); MMA(0, 0, At, B0); BAR;
	ds_read_b128 v[170:173], v141 offset:50176
	ds_read_b128 v[178:181], v141 offset:52224
	ds_read_b128 v[186:189], v141 offset:54272
	ds_read_b128 v[194:197], v141 offset:56320
	s_mov_b32 m0, s56
	s_add_u32 s98, s42, s94
	s_addc_u32 s99, s43, s95
	global_load_lds_dwordx4 v131, s[98:99]
	s_mov_b32 m0, s57
	s_add_u32 s98, s42, s72
	s_addc_u32 s99, s43, s73
	global_load_lds_dwordx4 v131, s[98:99]
	s_waitcnt vmcnt(8)
	s_barrier
	s_waitcnt lgkmcnt(0)
	s_waitcnt lgkmcnt(0)
	v_mfma_f32_16x16x32_bf16 v[62:65], v[150:153], v[166:169], v[62:65]
	v_mfma_f32_16x16x32_bf16 v[58:61], v[158:161], v[166:169], v[58:61]
	v_mfma_f32_16x16x32_bf16 v[54:57], v[150:153], v[174:177], v[54:57]
	v_mfma_f32_16x16x32_bf16 v[50:53], v[158:161], v[174:177], v[50:53]
	v_mfma_f32_16x16x32_bf16 v[46:49], v[150:153], v[182:185], v[46:49]
	v_mfma_f32_16x16x32_bf16 v[42:45], v[158:161], v[182:185], v[42:45]
	v_mfma_f32_16x16x32_bf16 v[38:41], v[150:153], v[190:193], v[38:41]
	v_mfma_f32_16x16x32_bf16 v[34:37], v[158:161], v[190:193], v[34:37]
	v_mfma_f32_16x16x32_bf16 v[62:65], v[154:157], v[170:173], v[62:65]
	v_mfma_f32_16x16x32_bf16 v[58:61], v[162:165], v[170:173], v[58:61]
	v_mfma_f32_16x16x32_bf16 v[54:57], v[154:157], v[178:181], v[54:57]
	v_mfma_f32_16x16x32_bf16 v[50:53], v[162:165], v[178:181], v[50:53]
	v_mfma_f32_16x16x32_bf16 v[46:49], v[154:157], v[186:189], v[46:49]
	v_mfma_f32_16x16x32_bf16 v[42:45], v[162:165], v[186:189], v[42:45]
	v_mfma_f32_16x16x32_bf16 v[38:41], v[154:157], v[194:197], v[38:41]
	v_mfma_f32_16x16x32_bf16 v[34:37], v[162:165], v[194:197], v[34:37]
	s_barrier
	s_mov_b32 m0, s58
	s_add_u32 s98, s66, s30
	s_addc_u32 s99, s67, s31
	global_load_lds_dwordx4 v131, s[98:99]
	s_mov_b32 m0, s59
	s_add_u32 s98, s66, s44
	s_addc_u32 s99, s67, s45
	global_load_lds_dwordx4 v131, s[98:99]
	s_waitcnt vmcnt(8)
	s_barrier
	v_mfma_f32_16x16x32_bf16 v[30:33], v[198:201], v[166:169], v[30:33]
	ds_read_b128 v[150:153], v218
	v_mfma_f32_16x16x32_bf16 v[26:29], v[206:209], v[166:169], v[26:29]
	v_mfma_f32_16x16x32_bf16 v[22:25], v[198:201], v[174:177], v[22:25]
	ds_read_b128 v[154:157], v218 offset:1024
	v_mfma_f32_16x16x32_bf16 v[18:21], v[206:209], v[174:177], v[18:21]
	v_mfma_f32_16x16x32_bf16 v[14:17], v[198:201], v[182:185], v[14:17]
	ds_read_b128 v[158:161], v218 offset:2048
	v_mfma_f32_16x16x32_bf16 v[10:13], v[206:209], v[182:185], v[10:13]
	v_mfma_f32_16x16x32_bf16 v[6:9], v[198:201], v[190:193], v[6:9]
	ds_read_b128 v[162:165], v218 offset:3072
	v_mfma_f32_16x16x32_bf16 v[2:5], v[206:209], v[190:193], v[2:5]
	v_mfma_f32_16x16x32_bf16 v[30:33], v[202:205], v[170:173], v[30:33]
	ds_read_b128 v[166:169], v141
	v_mfma_f32_16x16x32_bf16 v[26:29], v[210:213], v[170:173], v[26:29]
	v_mfma_f32_16x16x32_bf16 v[22:25], v[202:205], v[178:181], v[22:25]
	ds_read_b128 v[174:177], v141 offset:2048
	v_mfma_f32_16x16x32_bf16 v[18:21], v[210:213], v[178:181], v[18:21]
	v_mfma_f32_16x16x32_bf16 v[14:17], v[202:205], v[186:189], v[14:17]
	ds_read_b128 v[182:185], v141 offset:4096
	v_mfma_f32_16x16x32_bf16 v[10:13], v[210:213], v[186:189], v[10:13]
	v_mfma_f32_16x16x32_bf16 v[6:9], v[202:205], v[194:197], v[6:9]
	ds_read_b128 v[190:193], v141 offset:6144
	v_mfma_f32_16x16x32_bf16 v[2:5], v[210:213], v[194:197], v[2:5]
	s_add_i32 s18, s18, 2
	s_add_u32 vcc_lo, vcc_lo, 0x100
	s_addc_u32 vcc_hi, vcc_hi, 0
	s_cmp_lt_u32 s18, 12
	s_barrier
	s_cbranch_scc1 .LBB0_386
	s_waitcnt vmcnt(6)
	s_or_b32 s8, s2, 0x80
	s_mov_b32 s9, s3
	v_readlane_b32 s44, v252, 20
	s_lshl_b64 s[8:9], s[8:9], 11
	v_readlane_b32 s50, v252, 26
	v_add_u32_e32 v214, 16, v140
	v_readlane_b32 s51, v252, 27
	s_add_u32 s8, s50, s8
	v_add_u32_e32 v0, 0x10000, v214
	s_addc_u32 s9, s51, s9
	ds_read_b128 v[142:145], v0
	ds_read_b128 v[150:153], v0 offset:1024
	ds_read_b128 v[154:157], v0 offset:2048
	ds_read_b128 v[158:161], v0 offset:3072
	ds_read_b128 v[162:165], v141
	ds_read_b128 v[166:169], v141 offset:1024
	ds_read_b128 v[170:173], v141 offset:2048
	ds_read_b128 v[174:177], v141 offset:3072
	ds_read_b128 v[178:181], v141 offset:4096
	ds_read_b128 v[182:185], v141 offset:5120
	ds_read_b128 v[186:189], v141 offset:6144
	ds_read_b128 v[190:193], v141 offset:7168
	v_mov_b32_e32 v0, v131
	v_readlane_b32 s45, v252, 21
	v_lshl_add_u64 v[146:147], s[8:9], 0, v[0:1]
	s_mov_b64 s[8:9], 0x780
	v_lshl_add_u64 v[194:195], v[146:147], 0, s[8:9]
	v_readfirstlane_b32 s8, v148
	s_mov_b32 m0, s8
	s_mov_b64 s[8:9], 0x20780
	v_lshl_add_u64 v[146:147], v[146:147], 0, s[8:9]
	v_readfirstlane_b32 s8, v149
	global_load_lds_dwordx4 v[194:195], off
	s_mov_b32 m0, s8
	v_readlane_b32 s46, v252, 22
	global_load_lds_dwordx4 v[146:147], off
	s_barrier
	s_waitcnt lgkmcnt(0)
	v_readlane_b32 s47, v252, 23
	v_readlane_b32 s48, v252, 24
	v_readlane_b32 s49, v252, 25
	v_readlane_b32 s52, v252, 28
	v_readlane_b32 s53, v252, 29
	v_readlane_b32 s54, v252, 30
	v_readlane_b32 s55, v252, 31
	v_readlane_b32 s56, v252, 32
	v_readlane_b32 s57, v252, 33
	v_readlane_b32 s58, v252, 34
	v_readlane_b32 s59, v252, 35

; #define MMA(ai, bj, At, Btf) do { __builtin_amdgcn_s_setprio(1); \
;     for (int m = 0; m < 4; ++m) for (int n = 0; n < 2; ++n) for (int k = 0; k < 2; ++k) \
;       acc[ai][bj][m][n] = __builtin_amdgcn_mfma_f32_16x16x32_bf16(Btf[n][k], At[m][k], acc[ai][bj][m][n], 0, 0, 0); \
;     __builtin_amdgcn_s_setprio(0); } while (0)
; #define WAIT_L(n) asm volatile("s_waitcnt lgkmcnt(" #n ")" ::: "memory")
; #define BAR __builtin_amdgcn_s_barrier()
; template <bool OVL, bool PANEL = false, class Epi>
; __device__ __forceinline__ void gemm_phase(const bf16_t* __restrict__ A, long lda, const bf16_t* __restrict__ Bt, long ldb, int nM, int nN, int K,
;                                            const Epi& epi, bf16_t* shm, int w0) {
;     ...
;       BAR; WAIT_L(0); MMA(0, 0, At, B0); BAR;
	s_waitcnt lgkmcnt(0)
	v_mfma_f32_16x16x32_bf16 v[126:129], v[142:145], v[162:165], v[126:129]
	v_mfma_f32_16x16x32_bf16 v[122:125], v[154:157], v[162:165], v[122:125]
	v_mfma_f32_16x16x32_bf16 v[118:121], v[142:145], v[170:173], v[118:121]
	v_mfma_f32_16x16x32_bf16 v[114:117], v[154:157], v[170:173], v[114:117]
	v_mfma_f32_16x16x32_bf16 v[110:113], v[142:145], v[178:181], v[110:113]
	v_mfma_f32_16x16x32_bf16 v[106:109], v[154:157], v[178:181], v[106:109]
	v_mfma_f32_16x16x32_bf16 v[98:101], v[154:157], v[186:189], v[98:101]
	v_mfma_f32_16x16x32_bf16 v[126:129], v[150:153], v[166:169], v[126:129]
	v_mfma_f32_16x16x32_bf16 v[122:125], v[158:161], v[166:169], v[122:125]
	v_mfma_f32_16x16x32_bf16 v[118:121], v[150:153], v[174:177], v[118:121]
	v_mfma_f32_16x16x32_bf16 v[114:117], v[158:161], v[174:177], v[114:117]
	v_mfma_f32_16x16x32_bf16 v[110:113], v[150:153], v[182:185], v[110:113]
	v_mfma_f32_16x16x32_bf16 v[106:109], v[158:161], v[182:185], v[106:109]
	v_mfma_f32_16x16x32_bf16 v[102:105], v[142:145], v[186:189], v[102:105]
	v_mfma_f32_16x16x32_bf16 v[98:101], v[158:161], v[190:193], v[98:101]
	v_mfma_f32_16x16x32_bf16 v[146:149], v[150:153], v[190:193], v[102:105]

; #define LDB(dst, b, h) for (int n = 0; n < 2; ++n) for (int k = 0; k < 2; ++k) \
;     dst[n][k] = *reinterpret_cast<const bf16x8*>((char*)SB(b, h) + b_thr + (n * 2 + k) * 1024)
; #define MMA(ai, bj, At, Btf) do { __builtin_amdgcn_s_setprio(1); \
;     for (int m = 0; m < 4; ++m) for (int n = 0; n < 2; ++n) for (int k = 0; k < 2; ++k) \
;       acc[ai][bj][m][n] = __builtin_amdgcn_mfma_f32_16x16x32_bf16(Btf[n][k], At[m][k], acc[ai][bj][m][n], 0, 0, 0); \
;     __builtin_amdgcn_s_setprio(0); } while (0)
; #define WAIT_L(n) asm volatile("s_waitcnt lgkmcnt(" #n ")" ::: "memory")
; #define BAR __builtin_amdgcn_s_barrier()
; template <bool OVL, bool PANEL = false, class Epi>
; __device__ __forceinline__ void gemm_phase(const bf16_t* __restrict__ A, long lda, const bf16_t* __restrict__ Bt, long ldb, int nM, int nN, int K,
;                                            const Epi& epi, bf16_t* shm, int w0) {
;     ...
;       LDB(B1, 0, 1); BAR; WAIT_L(0); MMA(0, 1, At, B1); BAR;
	v_add_u32_e32 v0, 0x14000, v214
	s_barrier
	s_nop 2
	ds_read_b128 v[102:105], v0
	ds_read_b128 v[194:197], v0 offset:1024
	ds_read_b128 v[198:201], v0 offset:2048
	ds_read_b128 v[202:205], v0 offset:3072
	s_barrier
	s_waitcnt lgkmcnt(0)

; #define LDB(dst, b, h) for (int n = 0; n < 2; ++n) for (int k = 0; k < 2; ++k) \
;     dst[n][k] = *reinterpret_cast<const bf16x8*>((char*)SB(b, h) + b_thr + (n * 2 + k) * 1024)
; #define MMA(ai, bj, At, Btf) do { __builtin_amdgcn_s_setprio(1); \
;     for (int m = 0; m < 4; ++m) for (int n = 0; n < 2; ++n) for (int k = 0; k < 2; ++k) \
;       acc[ai][bj][m][n] = __builtin_amdgcn_mfma_f32_16x16x32_bf16(Btf[n][k], At[m][k], acc[ai][bj][m][n], 0, 0, 0); \
;     __builtin_amdgcn_s_setprio(0); } while (0)
; #define WAIT_L(n) asm volatile("s_waitcnt lgkmcnt(" #n ")" ::: "memory")
; #define BAR __builtin_amdgcn_s_barrier()
; template <bool OVL, bool PANEL = false, class Epi>
; __device__ __forceinline__ void gemm_phase(const bf16_t* __restrict__ A, long lda, const bf16_t* __restrict__ Bt, long ldb, int nM, int nN, int K,
;                                            const Epi& epi, bf16_t* shm, int w0) {
;     ...
;       LDB(B1, 0, 1); BAR; WAIT_L(0); MMA(0, 1, At, B1); BAR;
	s_waitcnt lgkmcnt(0)
	v_mfma_f32_16x16x32_bf16 v[94:97], v[102:105], v[162:165], v[94:97]
	v_mfma_f32_16x16x32_bf16 v[86:89], v[102:105], v[170:173], v[86:89]
	v_mfma_f32_16x16x32_bf16 v[78:81], v[102:105], v[178:181], v[78:81]
	v_mfma_f32_16x16x32_bf16 v[74:77], v[198:201], v[178:181], v[74:77]
	v_mfma_f32_16x16x32_bf16 v[94:97], v[194:197], v[166:169], v[94:97]
	v_mfma_f32_16x16x32_bf16 v[90:93], v[198:201], v[162:165], v[90:93]
	v_mfma_f32_16x16x32_bf16 v[86:89], v[194:197], v[174:177], v[86:89]
	v_mfma_f32_16x16x32_bf16 v[82:85], v[198:201], v[170:173], v[82:85]
	v_mfma_f32_16x16x32_bf16 v[78:81], v[194:197], v[182:185], v[78:81]
	v_mfma_f32_16x16x32_bf16 v[74:77], v[202:205], v[182:185], v[74:77]
	v_mfma_f32_16x16x32_bf16 v[70:73], v[102:105], v[186:189], v[70:73]
	v_mfma_f32_16x16x32_bf16 v[66:69], v[198:201], v[186:189], v[66:69]
	v_mfma_f32_16x16x32_bf16 v[162:165], v[202:205], v[166:169], v[90:93]
	v_mfma_f32_16x16x32_bf16 v[166:169], v[202:205], v[174:177], v[82:85]
	v_mfma_f32_16x16x32_bf16 v[170:173], v[194:197], v[190:193], v[70:73]
	v_mfma_f32_16x16x32_bf16 v[174:177], v[202:205], v[190:193], v[66:69]

; #define LDA(dst, b, h) for (int m = 0; m < 4; ++m) for (int k = 0; k < 2; ++k) \
;     dst[m][k] = *reinterpret_cast<const bf16x8*>((char*)SA(b, h) + a_thr + (m * 2 + k) * 1024)
; #define MMA(ai, bj, At, Btf) do { __builtin_amdgcn_s_setprio(1); \
;     for (int m = 0; m < 4; ++m) for (int n = 0; n < 2; ++n) for (int k = 0; k < 2; ++k) \
;       acc[ai][bj][m][n] = __builtin_amdgcn_mfma_f32_16x16x32_bf16(Btf[n][k], At[m][k], acc[ai][bj][m][n], 0, 0, 0); \
;     __builtin_amdgcn_s_setprio(0); } while (0)
; #define WAIT_V(n) asm volatile("s_waitcnt vmcnt(" #n ")" ::: "memory")
; #define WAIT_L(n) asm volatile("s_waitcnt lgkmcnt(" #n ")" ::: "memory")
; #define BAR __builtin_amdgcn_s_barrier()
; template <bool OVL, bool PANEL = false, class Epi>
; __device__ __forceinline__ void gemm_phase(const bf16_t* __restrict__ A, long lda, const bf16_t* __restrict__ Bt, long ldb, int nM, int nN, int K,
;                                            const Epi& epi, bf16_t* shm, int w0) {
;     ...
;       LDA(At, 0, 1); WAIT_V(4); BAR; WAIT_L(0); MMA(1, 0, At, B0); MMA(1, 1, At, B1); BAR; }
	s_barrier
	s_nop 1
	ds_read_b128 v[66:69], v141 offset:16384
	ds_read_b128 v[70:73], v141 offset:17408
	ds_read_b128 v[82:85], v141 offset:18432
	ds_read_b128 v[90:93], v141 offset:19456
	ds_read_b128 v[178:181], v141 offset:20480
	ds_read_b128 v[182:185], v141 offset:21504
	ds_read_b128 v[186:189], v141 offset:22528
	ds_read_b128 v[190:193], v141 offset:23552
	s_waitcnt vmcnt(4)
	s_barrier
	s_waitcnt lgkmcnt(0)

; #define LDA(dst, b, h) for (int m = 0; m < 4; ++m) for (int k = 0; k < 2; ++k) \
;     dst[m][k] = *reinterpret_cast<const bf16x8*>((char*)SA(b, h) + a_thr + (m * 2 + k) * 1024)
; #define MMA(ai, bj, At, Btf) do { __builtin_amdgcn_s_setprio(1); \
;     for (int m = 0; m < 4; ++m) for (int n = 0; n < 2; ++n) for (int k = 0; k < 2; ++k) \
;       acc[ai][bj][m][n] = __builtin_amdgcn_mfma_f32_16x16x32_bf16(Btf[n][k], At[m][k], acc[ai][bj][m][n], 0, 0, 0); \
;     __builtin_amdgcn_s_setprio(0); } while (0)
; #define WAIT_V(n) asm volatile("s_waitcnt vmcnt(" #n ")" ::: "memory")
; #define WAIT_L(n) asm volatile("s_waitcnt lgkmcnt(" #n ")" ::: "memory")
; #define BAR __builtin_amdgcn_s_barrier()
; template <bool OVL, bool PANEL = false, class Epi>
; __device__ __forceinline__ void gemm_phase(const bf16_t* __restrict__ A, long lda, const bf16_t* __restrict__ Bt, long ldb, int nM, int nN, int K,
;                                            const Epi& epi, bf16_t* shm, int w0) {
;     ...
;       LDA(At, 0, 1); WAIT_V(4); BAR; WAIT_L(0); MMA(1, 0, At, B0); MMA(1, 1, At, B1); BAR; }
	s_waitcnt lgkmcnt(0)
	v_mfma_f32_16x16x32_bf16 v[62:65], v[142:145], v[66:69], v[62:65]
	v_mfma_f32_16x16x32_bf16 v[54:57], v[142:145], v[82:85], v[54:57]
	v_mfma_f32_16x16x32_bf16 v[46:49], v[142:145], v[178:181], v[46:49]
	v_mfma_f32_16x16x32_bf16 v[42:45], v[154:157], v[178:181], v[42:45]
	v_mfma_f32_16x16x32_bf16 v[38:41], v[142:145], v[186:189], v[38:41]
	v_mfma_f32_16x16x32_bf16 v[34:37], v[154:157], v[186:189], v[34:37]
	v_mfma_f32_16x16x32_bf16 v[62:65], v[150:153], v[70:73], v[62:65]
	v_mfma_f32_16x16x32_bf16 v[58:61], v[154:157], v[66:69], v[58:61]
	v_mfma_f32_16x16x32_bf16 v[54:57], v[150:153], v[90:93], v[54:57]
	v_mfma_f32_16x16x32_bf16 v[50:53], v[154:157], v[82:85], v[50:53]
	v_mfma_f32_16x16x32_bf16 v[46:49], v[150:153], v[182:185], v[46:49]
	v_mfma_f32_16x16x32_bf16 v[42:45], v[158:161], v[182:185], v[42:45]
	v_mfma_f32_16x16x32_bf16 v[38:41], v[150:153], v[190:193], v[38:41]
	v_mfma_f32_16x16x32_bf16 v[34:37], v[158:161], v[190:193], v[34:37]
	v_mfma_f32_16x16x32_bf16 v[206:209], v[158:161], v[70:73], v[58:61]
	v_mfma_f32_16x16x32_bf16 v[210:213], v[158:161], v[90:93], v[50:53]


; #define LDA(dst, b, h) for (int m = 0; m < 4; ++m) for (int k = 0; k < 2; ++k) \
;     dst[m][k] = *reinterpret_cast<const bf16x8*>((char*)SA(b, h) + a_thr + (m * 2 + k) * 1024)
; #define MMA(ai, bj, At, Btf) do { __builtin_amdgcn_s_setprio(1); \
;     for (int m = 0; m < 4; ++m) for (int n = 0; n < 2; ++n) for (int k = 0; k < 2; ++k) \
;       acc[ai][bj][m][n] = __builtin_amdgcn_mfma_f32_16x16x32_bf16(Btf[n][k], At[m][k], acc[ai][bj][m][n], 0, 0, 0); \
;     __builtin_amdgcn_s_setprio(0); } while (0)
; #define WAIT_V(n) asm volatile("s_waitcnt vmcnt(" #n ")" ::: "memory")
; #define WAIT_L(n) asm volatile("s_waitcnt lgkmcnt(" #n ")" ::: "memory")
; #define BAR __builtin_amdgcn_s_barrier()
; template <bool OVL, bool PANEL = false, class Epi>
; __device__ __forceinline__ void gemm_phase(const bf16_t* __restrict__ A, long lda, const bf16_t* __restrict__ Bt, long ldb, int nM, int nN, int K,
;                                            const Epi& epi, bf16_t* shm, int w0) {
;     ...
;       LDA(At, 0, 1); WAIT_V(4); BAR; WAIT_L(0); MMA(1, 0, At, B0); MMA(1, 1, At, B1); BAR; }
	v_mfma_f32_16x16x32_bf16 v[30:33], v[102:105], v[66:69], v[30:33]
	v_mfma_f32_16x16x32_bf16 v[26:29], v[198:201], v[66:69], v[26:29]
	v_mfma_f32_16x16x32_bf16 v[22:25], v[102:105], v[82:85], v[22:25]
	v_mfma_f32_16x16x32_bf16 v[18:21], v[198:201], v[82:85], v[18:21]
	v_mfma_f32_16x16x32_bf16 v[14:17], v[102:105], v[178:181], v[14:17]
	v_mfma_f32_16x16x32_bf16 v[10:13], v[198:201], v[178:181], v[10:13]
	v_mfma_f32_16x16x32_bf16 v[6:9], v[102:105], v[186:189], v[6:9]
	v_mfma_f32_16x16x32_bf16 v[2:5], v[198:201], v[186:189], v[2:5]
	v_mfma_f32_16x16x32_bf16 v[30:33], v[194:197], v[70:73], v[30:33]
	v_mfma_f32_16x16x32_bf16 v[26:29], v[202:205], v[70:73], v[26:29]
	v_mfma_f32_16x16x32_bf16 v[22:25], v[194:197], v[90:93], v[22:25]
	v_mfma_f32_16x16x32_bf16 v[18:21], v[202:205], v[90:93], v[18:21]
	v_mfma_f32_16x16x32_bf16 v[14:17], v[194:197], v[182:185], v[14:17]
	v_mfma_f32_16x16x32_bf16 v[10:13], v[202:205], v[182:185], v[10:13]
	v_mfma_f32_16x16x32_bf16 v[6:9], v[194:197], v[190:193], v[6:9]
	v_mfma_f32_16x16x32_bf16 v[2:5], v[202:205], v[190:193], v[2:5]

; #define LDA(dst, b, h) for (int m = 0; m < 4; ++m) for (int k = 0; k < 2; ++k) \
;     dst[m][k] = *reinterpret_cast<const bf16x8*>((char*)SA(b, h) + a_thr + (m * 2 + k) * 1024)
; #define LDB(dst, b, h) for (int n = 0; n < 2; ++n) for (int k = 0; k < 2; ++k) \
;     dst[n][k] = *reinterpret_cast<const bf16x8*>((char*)SB(b, h) + b_thr + (n * 2 + k) * 1024)
; #define MMA(ai, bj, At, Btf) do { __builtin_amdgcn_s_setprio(1); \
;     for (int m = 0; m < 4; ++m) for (int n = 0; n < 2; ++n) for (int k = 0; k < 2; ++k) \
;       acc[ai][bj][m][n] = __builtin_amdgcn_mfma_f32_16x16x32_bf16(Btf[n][k], At[m][k], acc[ai][bj][m][n], 0, 0, 0); \
;     __builtin_amdgcn_s_setprio(0); } while (0)
; #define WAIT_V(n) asm volatile("s_waitcnt vmcnt(" #n ")" ::: "memory")
; #define WAIT_L(n) asm volatile("s_waitcnt lgkmcnt(" #n ")" ::: "memory")
; #define BAR __builtin_amdgcn_s_barrier()
; template <bool OVL, bool PANEL = false, class Epi>
; __device__ __forceinline__ void gemm_phase(const bf16_t* __restrict__ A, long lda, const bf16_t* __restrict__ Bt, long ldb, int nM, int nN, int K,
;                                            const Epi& epi, bf16_t* shm, int w0) {
;     ...
;     { LDB(B0, 1, 0); LDA(At, 1, 0); WAIT_V(2); BAR; WAIT_L(0); MMA(0, 0, At, B0); BAR;
	v_add_u32_e32 v0, 0x18000, v214
	s_barrier
	ds_read_b128 v[142:145], v0
	ds_read_b128 v[150:153], v0 offset:1024
	ds_read_b128 v[154:157], v0 offset:2048
	ds_read_b128 v[158:161], v0 offset:3072
	ds_read_b128 v[50:53], v141 offset:32768
	ds_read_b128 v[58:61], v141 offset:33792
	ds_read_b128 v[66:69], v141 offset:34816
	ds_read_b128 v[70:73], v141 offset:35840
	ds_read_b128 v[178:181], v141 offset:36864
	ds_read_b128 v[182:185], v141 offset:37888
	ds_read_b128 v[186:189], v141 offset:38912
	ds_read_b128 v[190:193], v141 offset:39936
	s_waitcnt vmcnt(2)
	s_barrier
	s_waitcnt lgkmcnt(0)

; #define LDA(dst, b, h) for (int m = 0; m < 4; ++m) for (int k = 0; k < 2; ++k) \
;     dst[m][k] = *reinterpret_cast<const bf16x8*>((char*)SA(b, h) + a_thr + (m * 2 + k) * 1024)
; #define LDB(dst, b, h) for (int n = 0; n < 2; ++n) for (int k = 0; k < 2; ++k) \
;     dst[n][k] = *reinterpret_cast<const bf16x8*>((char*)SB(b, h) + b_thr + (n * 2 + k) * 1024)
; #define MMA(ai, bj, At, Btf) do { __builtin_amdgcn_s_setprio(1); \
;     for (int m = 0; m < 4; ++m) for (int n = 0; n < 2; ++n) for (int k = 0; k < 2; ++k) \
;       acc[ai][bj][m][n] = __builtin_amdgcn_mfma_f32_16x16x32_bf16(Btf[n][k], At[m][k], acc[ai][bj][m][n], 0, 0, 0); \
;     __builtin_amdgcn_s_setprio(0); } while (0)
; #define WAIT_V(n) asm volatile("s_waitcnt vmcnt(" #n ")" ::: "memory")
; #define WAIT_L(n) asm volatile("s_waitcnt lgkmcnt(" #n ")" ::: "memory")
; #define BAR __builtin_amdgcn_s_barrier()
; template <bool OVL, bool PANEL = false, class Epi>
; __device__ __forceinline__ void gemm_phase(const bf16_t* __restrict__ A, long lda, const bf16_t* __restrict__ Bt, long ldb, int nM, int nN, int K,
;                                            const Epi& epi, bf16_t* shm, int w0) {
;     ...
;     { LDB(B0, 1, 0); LDA(At, 1, 0); WAIT_V(2); BAR; WAIT_L(0); MMA(0, 0, At, B0); BAR;
	s_waitcnt lgkmcnt(0)
	v_mfma_f32_16x16x32_bf16 v[82:85], v[142:145], v[50:53], v[126:129]
	v_mfma_f32_16x16x32_bf16 v[126:129], v[150:153], v[58:61], v[82:85]
	v_mfma_f32_16x16x32_bf16 v[82:85], v[154:157], v[50:53], v[122:125]
	v_mfma_f32_16x16x32_bf16 v[122:125], v[158:161], v[58:61], v[82:85]
	v_mfma_f32_16x16x32_bf16 v[82:85], v[142:145], v[66:69], v[118:121]
	v_mfma_f32_16x16x32_bf16 v[118:121], v[150:153], v[70:73], v[82:85]
	v_mfma_f32_16x16x32_bf16 v[82:85], v[154:157], v[66:69], v[114:117]
	v_mfma_f32_16x16x32_bf16 v[114:117], v[158:161], v[70:73], v[82:85]
	v_mfma_f32_16x16x32_bf16 v[82:85], v[142:145], v[178:181], v[110:113]
	v_mfma_f32_16x16x32_bf16 v[110:113], v[150:153], v[182:185], v[82:85]
	v_mfma_f32_16x16x32_bf16 v[82:85], v[154:157], v[178:181], v[106:109]
	v_mfma_f32_16x16x32_bf16 v[102:105], v[158:161], v[182:185], v[82:85]
	v_mfma_f32_16x16x32_bf16 v[82:85], v[142:145], v[186:189], v[146:149]
	v_mfma_f32_16x16x32_bf16 v[90:93], v[150:153], v[190:193], v[82:85]
	v_mfma_f32_16x16x32_bf16 v[82:85], v[154:157], v[186:189], v[98:101]
	v_mfma_f32_16x16x32_bf16 v[82:85], v[158:161], v[190:193], v[82:85]

; #define LDB(dst, b, h) for (int n = 0; n < 2; ++n) for (int k = 0; k < 2; ++k) \
;     dst[n][k] = *reinterpret_cast<const bf16x8*>((char*)SB(b, h) + b_thr + (n * 2 + k) * 1024)
; #define MMA(ai, bj, At, Btf) do { __builtin_amdgcn_s_setprio(1); \
;     for (int m = 0; m < 4; ++m) for (int n = 0; n < 2; ++n) for (int k = 0; k < 2; ++k) \
;       acc[ai][bj][m][n] = __builtin_amdgcn_mfma_f32_16x16x32_bf16(Btf[n][k], At[m][k], acc[ai][bj][m][n], 0, 0, 0); \
;     __builtin_amdgcn_s_setprio(0); } while (0)
; #define WAIT_V(n) asm volatile("s_waitcnt vmcnt(" #n ")" ::: "memory")
; #define WAIT_L(n) asm volatile("s_waitcnt lgkmcnt(" #n ")" ::: "memory")
; #define BAR __builtin_amdgcn_s_barrier()
; template <bool OVL, bool PANEL = false, class Epi>
; __device__ __forceinline__ void gemm_phase(const bf16_t* __restrict__ A, long lda, const bf16_t* __restrict__ Bt, long ldb, int nM, int nN, int K,
;                                            const Epi& epi, bf16_t* shm, int w0) {
;     ...
;       LDB(B1, 1, 1); WAIT_V(0); BAR; WAIT_L(0); MMA(0, 1, At, B1); BAR;
	v_add_u32_e32 v0, 0x1c000, v214
	s_barrier
	ds_read_b128 v[146:149], v0
	ds_read_b128 v[194:197], v0 offset:1024
	ds_read_b128 v[198:201], v0 offset:2048
	ds_read_b128 v[202:205], v0 offset:3072
	s_waitcnt vmcnt(0)
	s_barrier
	s_waitcnt lgkmcnt(0)

; #define LDB(dst, b, h) for (int n = 0; n < 2; ++n) for (int k = 0; k < 2; ++k) \
;     dst[n][k] = *reinterpret_cast<const bf16x8*>((char*)SB(b, h) + b_thr + (n * 2 + k) * 1024)
; #define MMA(ai, bj, At, Btf) do { __builtin_amdgcn_s_setprio(1); \
;     for (int m = 0; m < 4; ++m) for (int n = 0; n < 2; ++n) for (int k = 0; k < 2; ++k) \
;       acc[ai][bj][m][n] = __builtin_amdgcn_mfma_f32_16x16x32_bf16(Btf[n][k], At[m][k], acc[ai][bj][m][n], 0, 0, 0); \
;     __builtin_amdgcn_s_setprio(0); } while (0)
; #define WAIT_V(n) asm volatile("s_waitcnt vmcnt(" #n ")" ::: "memory")
; #define WAIT_L(n) asm volatile("s_waitcnt lgkmcnt(" #n ")" ::: "memory")
; #define BAR __builtin_amdgcn_s_barrier()
; template <bool OVL, bool PANEL = false, class Epi>
; __device__ __forceinline__ void gemm_phase(const bf16_t* __restrict__ A, long lda, const bf16_t* __restrict__ Bt, long ldb, int nM, int nN, int K,
;                                            const Epi& epi, bf16_t* shm, int w0) {
;     ...
;       LDB(B1, 1, 1); WAIT_V(0); BAR; WAIT_L(0); MMA(0, 1, At, B1); BAR;
	s_waitcnt lgkmcnt(0)
	v_mfma_f32_16x16x32_bf16 v[94:97], v[146:149], v[50:53], v[94:97]
	v_mfma_f32_16x16x32_bf16 v[50:53], v[198:201], v[50:53], v[162:165]
	v_mfma_f32_16x16x32_bf16 v[98:101], v[202:205], v[58:61], v[50:53]
	v_mfma_f32_16x16x32_bf16 v[50:53], v[146:149], v[66:69], v[86:89]
	v_mfma_f32_16x16x32_bf16 v[106:109], v[194:197], v[58:61], v[94:97]
	v_mfma_f32_16x16x32_bf16 v[94:97], v[194:197], v[70:73], v[50:53]
	v_mfma_f32_16x16x32_bf16 v[50:53], v[198:201], v[66:69], v[166:169]
	v_mfma_f32_16x16x32_bf16 v[86:89], v[202:205], v[70:73], v[50:53]
	v_mfma_f32_16x16x32_bf16 v[50:53], v[146:149], v[178:181], v[78:81]
	v_mfma_f32_16x16x32_bf16 v[70:73], v[194:197], v[182:185], v[50:53]
	v_mfma_f32_16x16x32_bf16 v[50:53], v[198:201], v[178:181], v[74:77]
	v_mfma_f32_16x16x32_bf16 v[66:69], v[202:205], v[182:185], v[50:53]
	v_mfma_f32_16x16x32_bf16 v[50:53], v[146:149], v[186:189], v[170:173]
	v_mfma_f32_16x16x32_bf16 v[58:61], v[194:197], v[190:193], v[50:53]
	v_mfma_f32_16x16x32_bf16 v[50:53], v[198:201], v[186:189], v[174:177]
	v_mfma_f32_16x16x32_bf16 v[50:53], v[202:205], v[190:193], v[50:53]

; #define LDA(dst, b, h) for (int m = 0; m < 4; ++m) for (int k = 0; k < 2; ++k) \
;     dst[m][k] = *reinterpret_cast<const bf16x8*>((char*)SA(b, h) + a_thr + (m * 2 + k) * 1024)
; #define MMA(ai, bj, At, Btf) do { __builtin_amdgcn_s_setprio(1); \
;     for (int m = 0; m < 4; ++m) for (int n = 0; n < 2; ++n) for (int k = 0; k < 2; ++k) \
;       acc[ai][bj][m][n] = __builtin_amdgcn_mfma_f32_16x16x32_bf16(Btf[n][k], At[m][k], acc[ai][bj][m][n], 0, 0, 0); \
;     __builtin_amdgcn_s_setprio(0); } while (0)
; #define WAIT_L(n) asm volatile("s_waitcnt lgkmcnt(" #n ")" ::: "memory")
; #define BAR __builtin_amdgcn_s_barrier()
; template <bool OVL, bool PANEL = false, class Epi>
; __device__ __forceinline__ void gemm_phase(const bf16_t* __restrict__ A, long lda, const bf16_t* __restrict__ Bt, long ldb, int nM, int nN, int K,
;                                            const Epi& epi, bf16_t* shm, int w0) {
;     ...
;       LDA(At, 1, 1); BAR; WAIT_L(0); MMA(1, 0, At, B0); MMA(1, 1, At, B1); BAR; }
	s_barrier
	ds_read_b128 v[162:165], v141 offset:49152
	ds_read_b128 v[166:169], v141 offset:50176
	ds_read_b128 v[170:173], v141 offset:51200
	ds_read_b128 v[174:177], v141 offset:52224
	ds_read_b128 v[178:181], v141 offset:53248
	ds_read_b128 v[182:185], v141 offset:54272
	ds_read_b128 v[186:189], v141 offset:55296
	ds_read_b128 v[190:193], v141 offset:56320
	s_barrier
	s_waitcnt lgkmcnt(0)

; #define LDA(dst, b, h) for (int m = 0; m < 4; ++m) for (int k = 0; k < 2; ++k) \
;     dst[m][k] = *reinterpret_cast<const bf16x8*>((char*)SA(b, h) + a_thr + (m * 2 + k) * 1024)
; #define MMA(ai, bj, At, Btf) do { __builtin_amdgcn_s_setprio(1); \
;     for (int m = 0; m < 4; ++m) for (int n = 0; n < 2; ++n) for (int k = 0; k < 2; ++k) \
;       acc[ai][bj][m][n] = __builtin_amdgcn_mfma_f32_16x16x32_bf16(Btf[n][k], At[m][k], acc[ai][bj][m][n], 0, 0, 0); \
;     __builtin_amdgcn_s_setprio(0); } while (0)
; #define WAIT_L(n) asm volatile("s_waitcnt lgkmcnt(" #n ")" ::: "memory")
; #define BAR __builtin_amdgcn_s_barrier()
; template <bool OVL, bool PANEL = false, class Epi>
; __device__ __forceinline__ void gemm_phase(const bf16_t* __restrict__ A, long lda, const bf16_t* __restrict__ Bt, long ldb, int nM, int nN, int K,
;                                            const Epi& epi, bf16_t* shm, int w0) {
;     ...
;       LDA(At, 1, 1); BAR; WAIT_L(0); MMA(1, 0, At, B0); MMA(1, 1, At, B1); BAR; }
	s_waitcnt lgkmcnt(0)
	v_mfma_f32_16x16x32_bf16 v[62:65], v[142:145], v[162:165], v[62:65]
	v_mfma_f32_16x16x32_bf16 v[78:81], v[150:153], v[166:169], v[62:65]
	v_mfma_f32_16x16x32_bf16 v[62:65], v[154:157], v[162:165], v[206:209]
	v_mfma_f32_16x16x32_bf16 v[54:57], v[142:145], v[170:173], v[54:57]
	v_mfma_f32_16x16x32_bf16 v[74:77], v[158:161], v[166:169], v[62:65]
	v_mfma_f32_16x16x32_bf16 v[62:65], v[150:153], v[174:177], v[54:57]
	v_mfma_f32_16x16x32_bf16 v[54:57], v[154:157], v[170:173], v[210:213]
	v_mfma_f32_16x16x32_bf16 v[46:49], v[142:145], v[178:181], v[46:49]
	v_mfma_f32_16x16x32_bf16 v[42:45], v[154:157], v[178:181], v[42:45]
	v_mfma_f32_16x16x32_bf16 v[38:41], v[142:145], v[186:189], v[38:41]
	v_mfma_f32_16x16x32_bf16 v[34:37], v[154:157], v[186:189], v[34:37]
	v_mfma_f32_16x16x32_bf16 v[54:57], v[158:161], v[174:177], v[54:57]
	v_mfma_f32_16x16x32_bf16 v[46:49], v[150:153], v[182:185], v[46:49]
	v_mfma_f32_16x16x32_bf16 v[42:45], v[158:161], v[182:185], v[42:45]
	v_mfma_f32_16x16x32_bf16 v[38:41], v[150:153], v[190:193], v[38:41]
	v_mfma_f32_16x16x32_bf16 v[34:37], v[158:161], v[190:193], v[34:37]


; #define LDA(dst, b, h) for (int m = 0; m < 4; ++m) for (int k = 0; k < 2; ++k) \
;     dst[m][k] = *reinterpret_cast<const bf16x8*>((char*)SA(b, h) + a_thr + (m * 2 + k) * 1024)
; #define MMA(ai, bj, At, Btf) do { __builtin_amdgcn_s_setprio(1); \
;     for (int m = 0; m < 4; ++m) for (int n = 0; n < 2; ++n) for (int k = 0; k < 2; ++k) \
;       acc[ai][bj][m][n] = __builtin_amdgcn_mfma_f32_16x16x32_bf16(Btf[n][k], At[m][k], acc[ai][bj][m][n], 0, 0, 0); \
;     __builtin_amdgcn_s_setprio(0); } while (0)
; #define WAIT_L(n) asm volatile("s_waitcnt lgkmcnt(" #n ")" ::: "memory")
; #define BAR __builtin_amdgcn_s_barrier()
; template <bool OVL, bool PANEL = false, class Epi>
; __device__ __forceinline__ void gemm_phase(const bf16_t* __restrict__ A, long lda, const bf16_t* __restrict__ Bt, long ldb, int nM, int nN, int K,
;                                            const Epi& epi, bf16_t* shm, int w0) {
;     ...
;       LDA(At, 1, 1); BAR; WAIT_L(0); MMA(1, 0, At, B0); MMA(1, 1, At, B1); BAR; }
	v_mfma_f32_16x16x32_bf16 v[30:33], v[146:149], v[162:165], v[30:33]
	v_mfma_f32_16x16x32_bf16 v[26:29], v[198:201], v[162:165], v[26:29]
	v_mfma_f32_16x16x32_bf16 v[22:25], v[146:149], v[170:173], v[22:25]
	v_mfma_f32_16x16x32_bf16 v[18:21], v[198:201], v[170:173], v[18:21]
	v_mfma_f32_16x16x32_bf16 v[14:17], v[146:149], v[178:181], v[14:17]
	v_mfma_f32_16x16x32_bf16 v[10:13], v[198:201], v[178:181], v[10:13]
	v_mfma_f32_16x16x32_bf16 v[6:9], v[146:149], v[186:189], v[6:9]
	v_mfma_f32_16x16x32_bf16 v[2:5], v[198:201], v[186:189], v[2:5]
	v_mfma_f32_16x16x32_bf16 v[30:33], v[194:197], v[166:169], v[30:33]
	v_mfma_f32_16x16x32_bf16 v[26:29], v[202:205], v[166:169], v[26:29]
	v_mfma_f32_16x16x32_bf16 v[22:25], v[194:197], v[174:177], v[22:25]
	v_mfma_f32_16x16x32_bf16 v[18:21], v[202:205], v[174:177], v[18:21]
	v_mfma_f32_16x16x32_bf16 v[14:17], v[194:197], v[182:185], v[14:17]
	v_mfma_f32_16x16x32_bf16 v[10:13], v[202:205], v[182:185], v[10:13]
	v_mfma_f32_16x16x32_bf16 v[6:9], v[194:197], v[190:193], v[6:9]
	v_mfma_f32_16x16x32_bf16 v[2:5], v[202:205], v[190:193], v[2:5]

; #define LDA(dst, b, h) for (int m = 0; m < 4; ++m) for (int k = 0; k < 2; ++k) \
;     dst[m][k] = *reinterpret_cast<const bf16x8*>((char*)SA(b, h) + a_thr + (m * 2 + k) * 1024)
; #define MMA(ai, bj, At, Btf) do { __builtin_amdgcn_s_setprio(1); \
;     for (int m = 0; m < 4; ++m) for (int n = 0; n < 2; ++n) for (int k = 0; k < 2; ++k) \
;       acc[ai][bj][m][n] = __builtin_amdgcn_mfma_f32_16x16x32_bf16(Btf[n][k], At[m][k], acc[ai][bj][m][n], 0, 0, 0); \
;     __builtin_amdgcn_s_setprio(0); } while (0)
; #define WAIT_L(n) asm volatile("s_waitcnt lgkmcnt(" #n ")" ::: "memory")
; #define BAR __builtin_amdgcn_s_barrier()
; template <bool OVL, bool PANEL = false, class Epi>
; __device__ __forceinline__ void gemm_phase(const bf16_t* __restrict__ A, long lda, const bf16_t* __restrict__ Bt, long ldb, int nM, int nN, int K,
;                                            const Epi& epi, bf16_t* shm, int w0) {
;     ...
;       LDA(At, 1, 1); BAR; WAIT_L(0); MMA(1, 0, At, B0); MMA(1, 1, At, B1); BAR; }
;     if (wr == 0) BAR;
	s_barrier
	s_and_saveexec_b64 s[8:9], s[78:79]
	s_cbranch_execz .LBB0_389
	s_barrier

; #define LDA(dst, b, h) for (int m = 0; m < 4; ++m) for (int k = 0; k < 2; ++k) \
;     dst[m][k] = *reinterpret_cast<const bf16x8*>((char*)SA(b, h) + a_thr + (m * 2 + k) * 1024)
; #define LDB(dst, b, h) for (int n = 0; n < 2; ++n) for (int k = 0; k < 2; ++k) \
;     dst[n][k] = *reinterpret_cast<const bf16x8*>((char*)SB(b, h) + b_thr + (n * 2 + k) * 1024)
; #define WAIT_V(n) asm volatile("s_waitcnt vmcnt(" #n ")" ::: "memory")
; #define BAR __builtin_amdgcn_s_barrier()
; #define SCHED __builtin_amdgcn_sched_barrier(0)
; template <bool OVL, bool PANEL = false, class Epi>
; __device__ __forceinline__ void gemm_phase(const bf16_t* __restrict__ A, long lda, const bf16_t* __restrict__ Bt, long ldb, int nM, int nN, int K,
;                                            const Epi& epi, bf16_t* shm, int w0) {
;     ...
;     f32x4 acc[2][2][4][2];
; #pragma unroll
;     for (int a0 = 0; a0 < 2; ++a0)
; #pragma unroll
;       for (int a1 = 0; a1 < 2; ++a1)
; #pragma unroll
;         for (int a2 = 0; a2 < 4; ++a2)
; #pragma unroll
;           for (int a3 = 0; a3 < 2; ++a3) acc[a0][a1][a2][a3] = (f32x4){0.f, 0.f, 0.f, 0.f};
;     bf16x8 At[4][2], B0[2][2], B1[2][2];
;     if (wr == 1) BAR;
;     WAIT_V(4); BAR;
;     STAGE(SB(1, 0), Bt, ldb, boff, bcol, 1); STAGE(SA(1, 0), A, lda, aoff, brow, 1); STAGE(SB(1, 1), Bt, ldb, boff, bcol + HALF, 1);
;     WAIT_V(6); BAR;
;     for (int t = 0; t < nt - 2; t += 2) {
;       LDB(B0, 0, 0); SCHED; LDA(At, 0, 0); STAGE(SA(1, 1), A, lda, aoff, brow + HALF, t + 1);
.LBB0_409:
	s_or_b64 exec, exec, s[0:1]
	s_lshl_b32 s0, s18, 19
	v_readlane_b32 s8, v251, 49
	v_readlane_b32 s9, v251, 50
	s_add_u32 s0, s8, s0
	v_readlane_b32 s10, v251, 51
	v_readlane_b32 s11, v251, 52
	s_addc_u32 s1, s9, 0
	v_mov_b32_e32 v0, v131
	v_add_u32_e32 v144, s96, v130
	s_waitcnt vmcnt(4)
	s_barrier
	s_mov_b64 s[10:11], 0x80
	v_lshl_add_u64 v[2:3], s[0:1], 0, v[0:1]
	v_readfirstlane_b32 s8, v144
	v_add_u32_e32 v145, 0x2000, v144
	v_lshl_add_u64 v[4:5], v[2:3], 0, s[10:11]
	s_mov_b32 m0, s8
	v_readfirstlane_b32 s8, v145
	v_readlane_b32 s40, v252, 20
	v_readlane_b32 s12, v251, 53
	v_readlane_b32 s13, v251, 54
	global_load_lds_dwordx4 v[4:5], off
	s_mov_b32 m0, s8
	s_lshl_b32 s8, s20, 19
	v_readlane_b32 s50, v252, 30
	s_mov_b64 s[12:13], 0x20080
	v_readlane_b32 s51, v252, 31
	s_add_u32 s8, s50, s8
	v_lshl_add_u64 v[2:3], v[2:3], 0, s[12:13]
	s_addc_u32 s9, s51, 0
	v_mov_b32_e32 v0, v131
	global_load_lds_dwordx4 v[2:3], off
	v_add_u32_e32 v146, 0x8000, v134
	v_lshl_add_u64 v[2:3], s[8:9], 0, v[0:1]
	v_lshl_add_u64 v[4:5], v[2:3], 0, s[10:11]
	v_readfirstlane_b32 s10, v146
	v_add_u32_e32 v147, 0xa000, v134
	s_mov_b32 m0, s10
	v_readfirstlane_b32 s10, v147
	global_load_lds_dwordx4 v[4:5], off
	v_lshl_add_u64 v[2:3], v[2:3], 0, s[12:13]
	s_mov_b32 m0, s10
	v_mov_b32_e32 v0, v131
	v_add_u32_e32 v148, s75, v130
	global_load_lds_dwordx4 v[2:3], off
	s_mov_b64 s[24:25], 0x40080
	v_lshl_add_u64 v[2:3], s[0:1], 0, v[0:1]
	v_readfirstlane_b32 s10, v148
	v_add_u32_e32 v149, 0x2000, v148
	v_lshl_add_u64 v[4:5], v[2:3], 0, s[24:25]
	s_mov_b32 m0, s10
	v_readfirstlane_b32 s10, v149
	global_load_lds_dwordx4 v[4:5], off
	v_lshl_add_u64 v[2:3], v[2:3], 0, s[36:37]
	s_mov_b32 m0, s10
	s_mov_b32 s21, -2
	global_load_lds_dwordx4 v[2:3], off
	s_waitcnt vmcnt(6)
	v_mov_b32_e32 v2, 0
	s_mov_b64 s[10:11], 0
	v_mov_b32_e32 v3, v2
	v_mov_b32_e32 v4, v2
	v_mov_b32_e32 v5, v2
	v_mov_b32_e32 v6, v2
	v_mov_b32_e32 v7, v2
	v_mov_b32_e32 v8, v2
	v_mov_b32_e32 v9, v2
	s_waitcnt vmcnt(0)
	v_mov_b32_e32 v10, v2
	v_mov_b32_e32 v11, v2
	v_mov_b32_e32 v12, v2
	v_mov_b32_e32 v13, v2
	s_waitcnt lgkmcnt(0)
	v_mov_b32_e32 v14, v2
	v_mov_b32_e32 v15, v2
	v_mov_b32_e32 v16, v2
	v_mov_b32_e32 v17, v2
	v_mov_b32_e32 v18, v2
	v_mov_b32_e32 v19, v2
	v_mov_b32_e32 v20, v2
	v_mov_b32_e32 v21, v2
	v_mov_b32_e32 v22, v2
	v_mov_b32_e32 v23, v2
	v_mov_b32_e32 v24, v2
	v_mov_b32_e32 v25, v2
	v_mov_b32_e32 v26, v2
	v_mov_b32_e32 v27, v2
	v_mov_b32_e32 v28, v2
	v_mov_b32_e32 v29, v2
	v_mov_b32_e32 v30, v2
	v_mov_b32_e32 v31, v2
	v_mov_b32_e32 v32, v2
	v_mov_b32_e32 v33, v2
	v_mov_b32_e32 v34, v2
	v_mov_b32_e32 v35, v2
	v_mov_b32_e32 v36, v2
	v_mov_b32_e32 v37, v2
	v_mov_b32_e32 v38, v2
	v_mov_b32_e32 v39, v2
	v_mov_b32_e32 v40, v2
	v_mov_b32_e32 v41, v2
	v_mov_b32_e32 v42, v2
	v_mov_b32_e32 v43, v2
	v_mov_b32_e32 v44, v2
	v_mov_b32_e32 v45, v2
	v_mov_b32_e32 v46, v2
	v_mov_b32_e32 v47, v2
	v_mov_b32_e32 v48, v2
	v_mov_b32_e32 v49, v2
	v_mov_b32_e32 v50, v2
	v_mov_b32_e32 v51, v2
	v_mov_b32_e32 v52, v2
	v_mov_b32_e32 v53, v2
	v_mov_b32_e32 v54, v2
	v_mov_b32_e32 v55, v2
	v_mov_b32_e32 v56, v2
	v_mov_b32_e32 v57, v2
	v_mov_b32_e32 v58, v2
	v_mov_b32_e32 v59, v2
	v_mov_b32_e32 v60, v2
	v_mov_b32_e32 v61, v2
	v_mov_b32_e32 v62, v2
	v_mov_b32_e32 v63, v2
	v_mov_b32_e32 v64, v2
	v_mov_b32_e32 v65, v2
	v_mov_b32_e32 v66, v2
	v_mov_b32_e32 v67, v2
	v_mov_b32_e32 v68, v2
	v_mov_b32_e32 v69, v2
	v_mov_b32_e32 v70, v2
	v_mov_b32_e32 v71, v2
	v_mov_b32_e32 v72, v2
	v_mov_b32_e32 v73, v2
	v_mov_b32_e32 v74, v2
	v_mov_b32_e32 v75, v2
	v_mov_b32_e32 v76, v2
	v_mov_b32_e32 v77, v2
	v_mov_b32_e32 v78, v2
	v_mov_b32_e32 v79, v2
	v_mov_b32_e32 v80, v2
	v_mov_b32_e32 v81, v2
	v_mov_b32_e32 v82, v2
	v_mov_b32_e32 v83, v2
	v_mov_b32_e32 v84, v2
	v_mov_b32_e32 v85, v2
	v_mov_b32_e32 v86, v2
	v_mov_b32_e32 v87, v2
	v_mov_b32_e32 v88, v2
	v_mov_b32_e32 v89, v2
	v_mov_b32_e32 v90, v2
	v_mov_b32_e32 v91, v2
	v_mov_b32_e32 v92, v2
	v_mov_b32_e32 v93, v2
	v_mov_b32_e32 v94, v2
	v_mov_b32_e32 v95, v2
	v_mov_b32_e32 v96, v2
	v_mov_b32_e32 v97, v2
	v_mov_b32_e32 v98, v2
	v_mov_b32_e32 v99, v2
	v_mov_b32_e32 v100, v2
	v_mov_b32_e32 v101, v2
	v_mov_b32_e32 v102, v2
	v_mov_b32_e32 v103, v2
	v_mov_b32_e32 v104, v2
	v_mov_b32_e32 v105, v2
	v_mov_b32_e32 v106, v2
	v_mov_b32_e32 v107, v2
	v_mov_b32_e32 v108, v2
	v_mov_b32_e32 v109, v2
	v_mov_b32_e32 v110, v2
	v_mov_b32_e32 v111, v2
	v_mov_b32_e32 v112, v2
	v_mov_b32_e32 v113, v2
	v_mov_b32_e32 v114, v2
	v_mov_b32_e32 v115, v2
	v_mov_b32_e32 v116, v2
	v_mov_b32_e32 v117, v2
	v_mov_b32_e32 v118, v2
	v_mov_b32_e32 v119, v2
	v_mov_b32_e32 v120, v2
	v_mov_b32_e32 v121, v2
	v_mov_b32_e32 v122, v2
	v_mov_b32_e32 v123, v2
	v_mov_b32_e32 v124, v2
	v_mov_b32_e32 v125, v2
	v_mov_b32_e32 v126, v2
	v_mov_b32_e32 v127, v2
	v_mov_b32_e32 v128, v2
	v_mov_b32_e32 v129, v2
	s_mov_b64 s[26:27], 0x40180
	s_mov_b64 s[28:29], 0x60180
	v_readlane_b32 s14, v251, 55
	v_readlane_b32 s15, v251, 56
	v_readlane_b32 s41, v252, 21
	v_readlane_b32 s42, v252, 22
	v_readlane_b32 s43, v252, 23
	v_readlane_b32 s44, v252, 24
	v_readlane_b32 s45, v252, 25
	v_readlane_b32 s46, v252, 26
	v_readlane_b32 s47, v252, 27
	v_readlane_b32 s48, v252, 28
	v_readlane_b32 s49, v252, 29
	v_readlane_b32 s52, v252, 32
	v_readlane_b32 s53, v252, 33
	v_readlane_b32 s54, v252, 34
	v_readlane_b32 s55, v252, 35
	s_barrier
	v_add_u32_e32 v220, s2, v140
	v_readfirstlane_b32 s16, v134
	s_add_u32 s16, s16, 0xc000
	v_readfirstlane_b32 s23, v134
	s_add_u32 s23, s23, 0xe000
	v_add_u32_e32 v221, s33, v140
	v_readfirstlane_b32 s30, v132
	v_readfirstlane_b32 s31, v133
	v_readfirstlane_b32 s32, v134
	v_readfirstlane_b32 s40, v135
	v_readfirstlane_b32 s41, v136
	v_readfirstlane_b32 s42, v137
	v_add_u32_e32 v222, s96, v140
	v_readfirstlane_b32 s43, v138
	v_readfirstlane_b32 s44, v139
	v_add_u32_e32 v223, s75, v140
	v_readfirstlane_b32 s45, v144
	v_readfirstlane_b32 s46, v145
	v_readfirstlane_b32 s47, v146
	v_readfirstlane_b32 s48, v147
	v_readfirstlane_b32 s49, v148
	v_readfirstlane_b32 s50, v149
	v_add_u32_e32 v150, 0xc000, v134
	v_add_u32_e32 v151, 0xe000, v134
	ds_read_b128 v[152:155], v220
	ds_read_b128 v[156:159], v220 offset:1024
	ds_read_b128 v[160:163], v220 offset:2048
	ds_read_b128 v[164:167], v220 offset:3072
	ds_read_b128 v[168:171], v143
	ds_read_b128 v[176:179], v143 offset:2048
	ds_read_b128 v[184:187], v143 offset:4096
	ds_read_b128 v[192:195], v143 offset:6144
; #define LDA(dst, b, h) for (int m = 0; m < 4; ++m) for (int k = 0; k < 2; ++k) \
;     dst[m][k] = *reinterpret_cast<const bf16x8*>((char*)SA(b, h) + a_thr + (m * 2 + k) * 1024)
; #define LDB(dst, b, h) for (int n = 0; n < 2; ++n) for (int k = 0; k < 2; ++k) \
;     dst[n][k] = *reinterpret_cast<const bf16x8*>((char*)SB(b, h) + b_thr + (n * 2 + k) * 1024)
; #define MMA(ai, bj, At, Btf) do { __builtin_amdgcn_s_setprio(1); \
;     for (int m = 0; m < 4; ++m) for (int n = 0; n < 2; ++n) for (int k = 0; k < 2; ++k) \
;       acc[ai][bj][m][n] = __builtin_amdgcn_mfma_f32_16x16x32_bf16(Btf[n][k], At[m][k], acc[ai][bj][m][n], 0, 0, 0); \
;     __builtin_amdgcn_s_setprio(0); } while (0)
; #define WAIT_V(n) asm volatile("s_waitcnt vmcnt(" #n ")" ::: "memory")
; #define WAIT_L(n) asm volatile("s_waitcnt lgkmcnt(" #n ")" ::: "memory")
; #define BAR __builtin_amdgcn_s_barrier()
; #define SCHED __builtin_amdgcn_sched_barrier(0)
; template <bool OVL, bool PANEL = false, class Epi>
; __device__ __forceinline__ void gemm_phase(const bf16_t* __restrict__ A, long lda, const bf16_t* __restrict__ Bt, long ldb, int nM, int nN, int K,
;                                            const Epi& epi, bf16_t* shm, int w0) {
;     ...
;     for (int t = 0; t < nt - 2; t += 2) {
;       LDB(B0, 0, 0); SCHED; LDA(At, 0, 0); STAGE(SA(1, 1), A, lda, aoff, brow + HALF, t + 1);
;       WAIT_L(8); BAR; WAIT_L(0); MMA(0, 0, At, B0); BAR; SCHED;
;       LDB(B1, 0, 1); STAGE(SB(0, 0), Bt, ldb, boff, bcol, t + 2);
;       BAR; WAIT_L(0); MMA(0, 1, At, B1); BAR;
;       LDA(At, 0, 1); STAGE(SA(0, 0), A, lda, aoff, brow, t + 2);
;       BAR; WAIT_L(0); MMA(1, 0, At, B0); BAR; SCHED;
;       STAGE(SB(0, 1), Bt, ldb, boff, bcol + HALF, t + 2);
;       WAIT_V(6); BAR; MMA(1, 1, At, B1); BAR;
.LBB0_410:
	s_add_u32 s12, s8, s10
	s_addc_u32 s13, s9, s11
	ds_read_b128 v[172:175], v143 offset:1024
	ds_read_b128 v[180:183], v143 offset:3072
	ds_read_b128 v[188:191], v143 offset:5120
	ds_read_b128 v[196:199], v143 offset:7168
	s_mov_b32 m0, s16
	s_add_u32 s98, s12, s24
	s_addc_u32 s99, s13, s25
	global_load_lds_dwordx4 v131, s[98:99]
	s_mov_b32 m0, s23
	s_add_u32 s98, s12, s36
	s_addc_u32 s99, s13, s37
	global_load_lds_dwordx4 v131, s[98:99]
	s_waitcnt lgkmcnt(8)
	s_waitcnt vmcnt(8)
	s_barrier
	s_waitcnt lgkmcnt(0)
	s_waitcnt lgkmcnt(0)
	v_mfma_f32_16x16x32_bf16 v[126:129], v[152:155], v[168:171], v[126:129]
	ds_read_b128 v[200:203], v221
	v_mfma_f32_16x16x32_bf16 v[122:125], v[160:163], v[168:171], v[122:125]
	v_mfma_f32_16x16x32_bf16 v[118:121], v[152:155], v[176:179], v[118:121]
	ds_read_b128 v[204:207], v221 offset:1024
	v_mfma_f32_16x16x32_bf16 v[114:117], v[160:163], v[176:179], v[114:117]
	v_mfma_f32_16x16x32_bf16 v[110:113], v[152:155], v[184:187], v[110:113]
	ds_read_b128 v[208:211], v221 offset:2048
	v_mfma_f32_16x16x32_bf16 v[106:109], v[160:163], v[184:187], v[106:109]
	v_mfma_f32_16x16x32_bf16 v[102:105], v[152:155], v[192:195], v[102:105]
	ds_read_b128 v[212:215], v221 offset:3072
	v_mfma_f32_16x16x32_bf16 v[98:101], v[160:163], v[192:195], v[98:101]
	v_mfma_f32_16x16x32_bf16 v[126:129], v[156:159], v[172:175], v[126:129]
	v_mfma_f32_16x16x32_bf16 v[122:125], v[164:167], v[172:175], v[122:125]
	v_mfma_f32_16x16x32_bf16 v[118:121], v[156:159], v[180:183], v[118:121]
	v_mfma_f32_16x16x32_bf16 v[114:117], v[164:167], v[180:183], v[114:117]
	v_mfma_f32_16x16x32_bf16 v[110:113], v[156:159], v[188:191], v[110:113]
	v_mfma_f32_16x16x32_bf16 v[106:109], v[164:167], v[188:191], v[106:109]
	v_mfma_f32_16x16x32_bf16 v[102:105], v[156:159], v[196:199], v[102:105]
	v_mfma_f32_16x16x32_bf16 v[98:101], v[164:167], v[196:199], v[98:101]
	s_barrier
	s_add_u32 s14, s0, s10
	s_addc_u32 s15, s1, s11
	s_mov_b32 m0, s30
	s_add_u32 s98, s14, s34
	s_addc_u32 s99, s15, s35
	global_load_lds_dwordx4 v131, s[98:99]
	s_mov_b32 m0, s31
	s_add_u32 s98, s14, s64
	s_addc_u32 s99, s15, s65
	global_load_lds_dwordx4 v131, s[98:99]
	s_barrier
	s_waitcnt lgkmcnt(0)
	s_waitcnt lgkmcnt(0)
	v_mfma_f32_16x16x32_bf16 v[94:97], v[200:203], v[168:171], v[94:97]
	v_mfma_f32_16x16x32_bf16 v[90:93], v[208:211], v[168:171], v[90:93]
	v_mfma_f32_16x16x32_bf16 v[86:89], v[200:203], v[176:179], v[86:89]
	v_mfma_f32_16x16x32_bf16 v[82:85], v[208:211], v[176:179], v[82:85]
	v_mfma_f32_16x16x32_bf16 v[78:81], v[200:203], v[184:187], v[78:81]
	v_mfma_f32_16x16x32_bf16 v[74:77], v[208:211], v[184:187], v[74:77]
	v_mfma_f32_16x16x32_bf16 v[70:73], v[200:203], v[192:195], v[70:73]
	v_mfma_f32_16x16x32_bf16 v[66:69], v[208:211], v[192:195], v[66:69]
	v_mfma_f32_16x16x32_bf16 v[94:97], v[204:207], v[172:175], v[94:97]
	ds_read_b128 v[168:171], v143 offset:16384
	v_mfma_f32_16x16x32_bf16 v[90:93], v[212:215], v[172:175], v[90:93]
	v_mfma_f32_16x16x32_bf16 v[86:89], v[204:207], v[180:183], v[86:89]
	ds_read_b128 v[176:179], v143 offset:18432
	v_mfma_f32_16x16x32_bf16 v[82:85], v[212:215], v[180:183], v[82:85]
	v_mfma_f32_16x16x32_bf16 v[78:81], v[204:207], v[188:191], v[78:81]
	ds_read_b128 v[184:187], v143 offset:20480
	v_mfma_f32_16x16x32_bf16 v[74:77], v[212:215], v[188:191], v[74:77]
	v_mfma_f32_16x16x32_bf16 v[70:73], v[204:207], v[196:199], v[70:73]
	ds_read_b128 v[192:195], v143 offset:22528
	v_mfma_f32_16x16x32_bf16 v[66:69], v[212:215], v[196:199], v[66:69]
	s_barrier
	ds_read_b128 v[172:175], v143 offset:17408
	ds_read_b128 v[180:183], v143 offset:19456
	ds_read_b128 v[188:191], v143 offset:21504
	ds_read_b128 v[196:199], v143 offset:23552
	s_mov_b32 m0, s32
	s_add_u32 s98, s12, s34
	s_addc_u32 s99, s13, s35
	global_load_lds_dwordx4 v131, s[98:99]
	s_mov_b32 m0, s40
	s_add_u32 s98, s12, s64
	s_addc_u32 s99, s13, s65
	global_load_lds_dwordx4 v131, s[98:99]
	s_waitcnt vmcnt(8)
	s_barrier
	s_waitcnt lgkmcnt(0)
	s_waitcnt lgkmcnt(0)
	v_mfma_f32_16x16x32_bf16 v[62:65], v[152:155], v[168:171], v[62:65]
	v_mfma_f32_16x16x32_bf16 v[58:61], v[160:163], v[168:171], v[58:61]
	v_mfma_f32_16x16x32_bf16 v[54:57], v[152:155], v[176:179], v[54:57]
	v_mfma_f32_16x16x32_bf16 v[50:53], v[160:163], v[176:179], v[50:53]
	v_mfma_f32_16x16x32_bf16 v[46:49], v[152:155], v[184:187], v[46:49]
	v_mfma_f32_16x16x32_bf16 v[42:45], v[160:163], v[184:187], v[42:45]
	v_mfma_f32_16x16x32_bf16 v[38:41], v[152:155], v[192:195], v[38:41]
	v_mfma_f32_16x16x32_bf16 v[34:37], v[160:163], v[192:195], v[34:37]
	v_mfma_f32_16x16x32_bf16 v[62:65], v[156:159], v[172:175], v[62:65]
	v_mfma_f32_16x16x32_bf16 v[58:61], v[164:167], v[172:175], v[58:61]
	v_mfma_f32_16x16x32_bf16 v[54:57], v[156:159], v[180:183], v[54:57]
	v_mfma_f32_16x16x32_bf16 v[50:53], v[164:167], v[180:183], v[50:53]
	v_mfma_f32_16x16x32_bf16 v[46:49], v[156:159], v[188:191], v[46:49]
	v_mfma_f32_16x16x32_bf16 v[42:45], v[164:167], v[188:191], v[42:45]
	v_mfma_f32_16x16x32_bf16 v[38:41], v[156:159], v[196:199], v[38:41]
	v_mfma_f32_16x16x32_bf16 v[34:37], v[164:167], v[196:199], v[34:37]
	s_barrier
	s_mov_b32 m0, s41
	s_add_u32 s98, s14, s68
	s_addc_u32 s99, s15, s69
	global_load_lds_dwordx4 v131, s[98:99]
	s_mov_b32 m0, s42
	s_add_u32 s98, s14, s70
	s_addc_u32 s99, s15, s71
	global_load_lds_dwordx4 v131, s[98:99]
	s_waitcnt vmcnt(8)
	s_barrier
; #define LDA(dst, b, h) for (int m = 0; m < 4; ++m) for (int k = 0; k < 2; ++k) \
;     dst[m][k] = *reinterpret_cast<const bf16x8*>((char*)SA(b, h) + a_thr + (m * 2 + k) * 1024)
; #define LDB(dst, b, h) for (int n = 0; n < 2; ++n) for (int k = 0; k < 2; ++k) \
;     dst[n][k] = *reinterpret_cast<const bf16x8*>((char*)SB(b, h) + b_thr + (n * 2 + k) * 1024)
; #define MMA(ai, bj, At, Btf) do { __builtin_amdgcn_s_setprio(1); \
;     for (int m = 0; m < 4; ++m) for (int n = 0; n < 2; ++n) for (int k = 0; k < 2; ++k) \
;       acc[ai][bj][m][n] = __builtin_amdgcn_mfma_f32_16x16x32_bf16(Btf[n][k], At[m][k], acc[ai][bj][m][n], 0, 0, 0); \
;     __builtin_amdgcn_s_setprio(0); } while (0)
; #define WAIT_V(n) asm volatile("s_waitcnt vmcnt(" #n ")" ::: "memory")
; #define WAIT_L(n) asm volatile("s_waitcnt lgkmcnt(" #n ")" ::: "memory")
; #define BAR __builtin_amdgcn_s_barrier()
; #define SCHED __builtin_amdgcn_sched_barrier(0)
; template <bool OVL, bool PANEL = false, class Epi>
; __device__ __forceinline__ void gemm_phase(const bf16_t* __restrict__ A, long lda, const bf16_t* __restrict__ Bt, long ldb, int nM, int nN, int K,
;                                            const Epi& epi, bf16_t* shm, int w0) {
;     ...
;       WAIT_V(6); BAR; MMA(1, 1, At, B1); BAR;
;       LDB(B0, 1, 0); SCHED; LDA(At, 1, 0); STAGE(SA(0, 1), A, lda, aoff, brow + HALF, t + 2);
;       WAIT_L(8); BAR; WAIT_L(0); MMA(0, 0, At, B0); BAR; SCHED;
;       LDB(B1, 1, 1); STAGE(SB(1, 0), Bt, ldb, boff, bcol, t + 3);
;       BAR; WAIT_L(0); MMA(0, 1, At, B1); BAR;
	v_mfma_f32_16x16x32_bf16 v[30:33], v[200:203], v[168:171], v[30:33]
	ds_read_b128 v[152:155], v222
	v_mfma_f32_16x16x32_bf16 v[26:29], v[208:211], v[168:171], v[26:29]
	v_mfma_f32_16x16x32_bf16 v[22:25], v[200:203], v[176:179], v[22:25]
	ds_read_b128 v[156:159], v222 offset:1024
	v_mfma_f32_16x16x32_bf16 v[18:21], v[208:211], v[176:179], v[18:21]
	v_mfma_f32_16x16x32_bf16 v[14:17], v[200:203], v[184:187], v[14:17]
	ds_read_b128 v[160:163], v222 offset:2048
	v_mfma_f32_16x16x32_bf16 v[10:13], v[208:211], v[184:187], v[10:13]
	v_mfma_f32_16x16x32_bf16 v[6:9], v[200:203], v[192:195], v[6:9]
	ds_read_b128 v[164:167], v222 offset:3072
	v_mfma_f32_16x16x32_bf16 v[2:5], v[208:211], v[192:195], v[2:5]
	v_mfma_f32_16x16x32_bf16 v[30:33], v[204:207], v[172:175], v[30:33]
	ds_read_b128 v[168:171], v143 offset:32768
	v_mfma_f32_16x16x32_bf16 v[26:29], v[212:215], v[172:175], v[26:29]
	v_mfma_f32_16x16x32_bf16 v[22:25], v[204:207], v[180:183], v[22:25]
	ds_read_b128 v[176:179], v143 offset:34816
	v_mfma_f32_16x16x32_bf16 v[18:21], v[212:215], v[180:183], v[18:21]
	v_mfma_f32_16x16x32_bf16 v[14:17], v[204:207], v[188:191], v[14:17]
	ds_read_b128 v[184:187], v143 offset:36864
	v_mfma_f32_16x16x32_bf16 v[10:13], v[212:215], v[188:191], v[10:13]
	v_mfma_f32_16x16x32_bf16 v[6:9], v[204:207], v[196:199], v[6:9]
	ds_read_b128 v[192:195], v143 offset:38912
	v_mfma_f32_16x16x32_bf16 v[2:5], v[212:215], v[196:199], v[2:5]
	s_barrier
	ds_read_b128 v[172:175], v143 offset:33792
	ds_read_b128 v[180:183], v143 offset:35840
	ds_read_b128 v[188:191], v143 offset:37888
	ds_read_b128 v[196:199], v143 offset:39936
	s_mov_b32 m0, s43
	s_add_u32 s98, s12, s68
	s_addc_u32 s99, s13, s69
	global_load_lds_dwordx4 v131, s[98:99]
	s_mov_b32 m0, s44
	s_add_u32 s98, s12, s70
	s_addc_u32 s99, s13, s71
	global_load_lds_dwordx4 v131, s[98:99]
	s_waitcnt lgkmcnt(8)
	s_waitcnt vmcnt(8)
	s_barrier
	s_waitcnt lgkmcnt(0)
	s_waitcnt lgkmcnt(0)
	v_mfma_f32_16x16x32_bf16 v[126:129], v[152:155], v[168:171], v[126:129]
	ds_read_b128 v[200:203], v223
	v_mfma_f32_16x16x32_bf16 v[122:125], v[160:163], v[168:171], v[122:125]
	v_mfma_f32_16x16x32_bf16 v[118:121], v[152:155], v[176:179], v[118:121]
	ds_read_b128 v[204:207], v223 offset:1024
	v_mfma_f32_16x16x32_bf16 v[114:117], v[160:163], v[176:179], v[114:117]
	v_mfma_f32_16x16x32_bf16 v[110:113], v[152:155], v[184:187], v[110:113]
	ds_read_b128 v[208:211], v223 offset:2048
	v_mfma_f32_16x16x32_bf16 v[106:109], v[160:163], v[184:187], v[106:109]
	v_mfma_f32_16x16x32_bf16 v[102:105], v[152:155], v[192:195], v[102:105]
	ds_read_b128 v[212:215], v223 offset:3072
	v_mfma_f32_16x16x32_bf16 v[98:101], v[160:163], v[192:195], v[98:101]
	v_mfma_f32_16x16x32_bf16 v[126:129], v[156:159], v[172:175], v[126:129]
	v_mfma_f32_16x16x32_bf16 v[122:125], v[164:167], v[172:175], v[122:125]
	v_mfma_f32_16x16x32_bf16 v[118:121], v[156:159], v[180:183], v[118:121]
	v_mfma_f32_16x16x32_bf16 v[114:117], v[164:167], v[180:183], v[114:117]
	v_mfma_f32_16x16x32_bf16 v[110:113], v[156:159], v[188:191], v[110:113]
	v_mfma_f32_16x16x32_bf16 v[106:109], v[164:167], v[188:191], v[106:109]
	v_mfma_f32_16x16x32_bf16 v[102:105], v[156:159], v[196:199], v[102:105]
	v_mfma_f32_16x16x32_bf16 v[98:101], v[164:167], v[196:199], v[98:101]
	s_barrier
	s_mov_b32 m0, s45
	s_add_u32 s98, s14, s94
	s_addc_u32 s99, s15, s95
	global_load_lds_dwordx4 v131, s[98:99]
	s_mov_b32 m0, s46
	s_add_u32 s98, s14, s72
	s_addc_u32 s99, s15, s73
	global_load_lds_dwordx4 v131, s[98:99]
	s_barrier
	s_waitcnt lgkmcnt(0)
	s_waitcnt lgkmcnt(0)
	v_mfma_f32_16x16x32_bf16 v[94:97], v[200:203], v[168:171], v[94:97]
	v_mfma_f32_16x16x32_bf16 v[90:93], v[208:211], v[168:171], v[90:93]
	v_mfma_f32_16x16x32_bf16 v[86:89], v[200:203], v[176:179], v[86:89]
	v_mfma_f32_16x16x32_bf16 v[82:85], v[208:211], v[176:179], v[82:85]
	v_mfma_f32_16x16x32_bf16 v[78:81], v[200:203], v[184:187], v[78:81]
	v_mfma_f32_16x16x32_bf16 v[74:77], v[208:211], v[184:187], v[74:77]
	v_mfma_f32_16x16x32_bf16 v[70:73], v[200:203], v[192:195], v[70:73]
	v_mfma_f32_16x16x32_bf16 v[66:69], v[208:211], v[192:195], v[66:69]
	v_mfma_f32_16x16x32_bf16 v[94:97], v[204:207], v[172:175], v[94:97]
	ds_read_b128 v[168:171], v143 offset:49152
	v_mfma_f32_16x16x32_bf16 v[90:93], v[212:215], v[172:175], v[90:93]
	v_mfma_f32_16x16x32_bf16 v[86:89], v[204:207], v[180:183], v[86:89]
	ds_read_b128 v[176:179], v143 offset:51200
	v_mfma_f32_16x16x32_bf16 v[82:85], v[212:215], v[180:183], v[82:85]
	v_mfma_f32_16x16x32_bf16 v[78:81], v[204:207], v[188:191], v[78:81]
	ds_read_b128 v[184:187], v143 offset:53248
	v_mfma_f32_16x16x32_bf16 v[74:77], v[212:215], v[188:191], v[74:77]
	v_mfma_f32_16x16x32_bf16 v[70:73], v[204:207], v[196:199], v[70:73]
	ds_read_b128 v[192:195], v143 offset:55296
	v_mfma_f32_16x16x32_bf16 v[66:69], v[212:215], v[196:199], v[66:69]
	s_barrier
; #define LDA(dst, b, h) for (int m = 0; m < 4; ++m) for (int k = 0; k < 2; ++k) \
;     dst[m][k] = *reinterpret_cast<const bf16x8*>((char*)SA(b, h) + a_thr + (m * 2 + k) * 1024)
; #define LDB(dst, b, h) for (int n = 0; n < 2; ++n) for (int k = 0; k < 2; ++k) \
;     dst[n][k] = *reinterpret_cast<const bf16x8*>((char*)SB(b, h) + b_thr + (n * 2 + k) * 1024)
; #define MMA(ai, bj, At, Btf) do { __builtin_amdgcn_s_setprio(1); \
;     for (int m = 0; m < 4; ++m) for (int n = 0; n < 2; ++n) for (int k = 0; k < 2; ++k) \
;       acc[ai][bj][m][n] = __builtin_amdgcn_mfma_f32_16x16x32_bf16(Btf[n][k], At[m][k], acc[ai][bj][m][n], 0, 0, 0); \
;     __builtin_amdgcn_s_setprio(0); } while (0)
; #define WAIT_V(n) asm volatile("s_waitcnt vmcnt(" #n ")" ::: "memory")
; #define WAIT_L(n) asm volatile("s_waitcnt lgkmcnt(" #n ")" ::: "memory")
; #define BAR __builtin_amdgcn_s_barrier()
; #define SCHED __builtin_amdgcn_sched_barrier(0)
; template <bool OVL, bool PANEL = false, class Epi>
; __device__ __forceinline__ void gemm_phase(const bf16_t* __restrict__ A, long lda, const bf16_t* __restrict__ Bt, long ldb, int nM, int nN, int K,
;                                            const Epi& epi, bf16_t* shm, int w0) {
;     ...
;       LDA(At, 1, 1); STAGE(SA(1, 0), A, lda, aoff, brow, t + 3);
;       BAR; WAIT_L(0); MMA(1, 0, At, B0); BAR; SCHED;
;       STAGE(SB(1, 1), Bt, ldb, boff, bcol + HALF, t + 3);
;       WAIT_V(6); BAR; MMA(1, 1, At, B1); BAR;
;     }
;     { LDB(B0, 0, 0); LDA(At, 0, 0); STAGE(SA(1, 1), A, lda, aoff, brow + HALF, nt - 1);
;       BAR; WAIT_L(0); MMA(0, 0, At, B0); BAR;
	ds_read_b128 v[172:175], v143 offset:50176
	ds_read_b128 v[180:183], v143 offset:52224
	ds_read_b128 v[188:191], v143 offset:54272
	ds_read_b128 v[196:199], v143 offset:56320
	s_mov_b32 m0, s47
	s_add_u32 s98, s12, s94
	s_addc_u32 s99, s13, s95
	global_load_lds_dwordx4 v131, s[98:99]
	s_mov_b32 m0, s48
	s_add_u32 s98, s12, s72
	s_addc_u32 s99, s13, s73
	global_load_lds_dwordx4 v131, s[98:99]
	s_waitcnt vmcnt(8)
	s_barrier
	s_waitcnt lgkmcnt(0)
	s_waitcnt lgkmcnt(0)
	v_mfma_f32_16x16x32_bf16 v[62:65], v[152:155], v[168:171], v[62:65]
	v_mfma_f32_16x16x32_bf16 v[58:61], v[160:163], v[168:171], v[58:61]
	v_mfma_f32_16x16x32_bf16 v[54:57], v[152:155], v[176:179], v[54:57]
	v_mfma_f32_16x16x32_bf16 v[50:53], v[160:163], v[176:179], v[50:53]
	v_mfma_f32_16x16x32_bf16 v[46:49], v[152:155], v[184:187], v[46:49]
	v_mfma_f32_16x16x32_bf16 v[42:45], v[160:163], v[184:187], v[42:45]
	v_mfma_f32_16x16x32_bf16 v[38:41], v[152:155], v[192:195], v[38:41]
	v_mfma_f32_16x16x32_bf16 v[34:37], v[160:163], v[192:195], v[34:37]
	v_mfma_f32_16x16x32_bf16 v[62:65], v[156:159], v[172:175], v[62:65]
	v_mfma_f32_16x16x32_bf16 v[58:61], v[164:167], v[172:175], v[58:61]
	v_mfma_f32_16x16x32_bf16 v[54:57], v[156:159], v[180:183], v[54:57]
	v_mfma_f32_16x16x32_bf16 v[50:53], v[164:167], v[180:183], v[50:53]
	v_mfma_f32_16x16x32_bf16 v[46:49], v[156:159], v[188:191], v[46:49]
	v_mfma_f32_16x16x32_bf16 v[42:45], v[164:167], v[188:191], v[42:45]
	v_mfma_f32_16x16x32_bf16 v[38:41], v[156:159], v[196:199], v[38:41]
	v_mfma_f32_16x16x32_bf16 v[34:37], v[164:167], v[196:199], v[34:37]
	s_barrier
	s_mov_b32 m0, s49
	s_add_u32 s98, s14, s26
	s_addc_u32 s99, s15, s27
	global_load_lds_dwordx4 v131, s[98:99]
	s_mov_b32 m0, s50
	s_add_u32 s98, s14, s28
	s_addc_u32 s99, s15, s29
	global_load_lds_dwordx4 v131, s[98:99]
	s_waitcnt vmcnt(8)
	s_barrier
	v_mfma_f32_16x16x32_bf16 v[30:33], v[200:203], v[168:171], v[30:33]
	ds_read_b128 v[152:155], v220
	v_mfma_f32_16x16x32_bf16 v[26:29], v[208:211], v[168:171], v[26:29]
	v_mfma_f32_16x16x32_bf16 v[22:25], v[200:203], v[176:179], v[22:25]
	ds_read_b128 v[156:159], v220 offset:1024
	v_mfma_f32_16x16x32_bf16 v[18:21], v[208:211], v[176:179], v[18:21]
	v_mfma_f32_16x16x32_bf16 v[14:17], v[200:203], v[184:187], v[14:17]
	ds_read_b128 v[160:163], v220 offset:2048
	v_mfma_f32_16x16x32_bf16 v[10:13], v[208:211], v[184:187], v[10:13]
	v_mfma_f32_16x16x32_bf16 v[6:9], v[200:203], v[192:195], v[6:9]
	ds_read_b128 v[164:167], v220 offset:3072
	v_mfma_f32_16x16x32_bf16 v[2:5], v[208:211], v[192:195], v[2:5]
	v_mfma_f32_16x16x32_bf16 v[30:33], v[204:207], v[172:175], v[30:33]
	ds_read_b128 v[168:171], v143
	v_mfma_f32_16x16x32_bf16 v[26:29], v[212:215], v[172:175], v[26:29]
	v_mfma_f32_16x16x32_bf16 v[22:25], v[204:207], v[180:183], v[22:25]
	ds_read_b128 v[176:179], v143 offset:2048
	v_mfma_f32_16x16x32_bf16 v[18:21], v[212:215], v[180:183], v[18:21]
	v_mfma_f32_16x16x32_bf16 v[14:17], v[204:207], v[188:191], v[14:17]
	ds_read_b128 v[184:187], v143 offset:4096
	v_mfma_f32_16x16x32_bf16 v[10:13], v[212:215], v[188:191], v[10:13]
	v_mfma_f32_16x16x32_bf16 v[6:9], v[204:207], v[196:199], v[6:9]
	ds_read_b128 v[192:195], v143 offset:6144
	v_mfma_f32_16x16x32_bf16 v[2:5], v[212:215], v[196:199], v[2:5]
	s_add_i32 s21, s21, 2
	s_add_u32 s10, s10, 0x100
	s_addc_u32 s11, s11, 0
	s_cmp_lt_u32 s21, 12
	s_barrier
	s_cbranch_scc1 .LBB0_410
	s_waitcnt vmcnt(6)
	v_add_u32_e32 v212, 16, v140
	v_add_u32_e32 v0, 0x10000, v212
	ds_read_b128 v[144:147], v0
	ds_read_b128 v[152:155], v0 offset:1024
	ds_read_b128 v[156:159], v0 offset:2048
	ds_read_b128 v[160:163], v0 offset:3072
	ds_read_b128 v[164:167], v143
	ds_read_b128 v[168:171], v143 offset:1024
	ds_read_b128 v[172:175], v143 offset:2048
	ds_read_b128 v[176:179], v143 offset:3072
	ds_read_b128 v[180:183], v143 offset:4096
	ds_read_b128 v[184:187], v143 offset:5120
	ds_read_b128 v[188:191], v143 offset:6144
	ds_read_b128 v[192:195], v143 offset:7168
	v_mov_b32_e32 v0, v131
	s_mov_b64 s[0:1], 0x40780
	v_lshl_add_u64 v[148:149], s[8:9], 0, v[0:1]
	v_lshl_add_u64 v[196:197], v[148:149], 0, s[0:1]
	v_readfirstlane_b32 s0, v150
	s_mov_b32 m0, s0
	s_mov_b64 s[0:1], 0x60780
	v_lshl_add_u64 v[148:149], v[148:149], 0, s[0:1]
	v_readfirstlane_b32 s0, v151
	global_load_lds_dwordx4 v[196:197], off
	s_mov_b32 m0, s0
	s_nop 0
	global_load_lds_dwordx4 v[148:149], off
	s_barrier
	s_waitcnt lgkmcnt(0)

; #define MMA(ai, bj, At, Btf) do { __builtin_amdgcn_s_setprio(1); \
;     for (int m = 0; m < 4; ++m) for (int n = 0; n < 2; ++n) for (int k = 0; k < 2; ++k) \
;       acc[ai][bj][m][n] = __builtin_amdgcn_mfma_f32_16x16x32_bf16(Btf[n][k], At[m][k], acc[ai][bj][m][n], 0, 0, 0); \
;     __builtin_amdgcn_s_setprio(0); } while (0)
; #define WAIT_L(n) asm volatile("s_waitcnt lgkmcnt(" #n ")" ::: "memory")
; #define BAR __builtin_amdgcn_s_barrier()
; template <bool OVL, bool PANEL = false, class Epi>
; __device__ __forceinline__ void gemm_phase(const bf16_t* __restrict__ A, long lda, const bf16_t* __restrict__ Bt, long ldb, int nM, int nN, int K,
;                                            const Epi& epi, bf16_t* shm, int w0) {
;     ...
;       BAR; WAIT_L(0); MMA(0, 0, At, B0); BAR;
	s_waitcnt lgkmcnt(0)
	v_mfma_f32_16x16x32_bf16 v[126:129], v[144:147], v[164:167], v[126:129]
	v_mfma_f32_16x16x32_bf16 v[122:125], v[156:159], v[164:167], v[122:125]
	v_mfma_f32_16x16x32_bf16 v[118:121], v[144:147], v[172:175], v[118:121]
	v_mfma_f32_16x16x32_bf16 v[114:117], v[156:159], v[172:175], v[114:117]
	v_mfma_f32_16x16x32_bf16 v[110:113], v[144:147], v[180:183], v[110:113]
	v_mfma_f32_16x16x32_bf16 v[106:109], v[156:159], v[180:183], v[106:109]
	v_mfma_f32_16x16x32_bf16 v[102:105], v[144:147], v[188:191], v[102:105]
	v_mfma_f32_16x16x32_bf16 v[126:129], v[152:155], v[168:171], v[126:129]
	v_mfma_f32_16x16x32_bf16 v[122:125], v[160:163], v[168:171], v[122:125]
	v_mfma_f32_16x16x32_bf16 v[118:121], v[152:155], v[176:179], v[118:121]
	v_mfma_f32_16x16x32_bf16 v[114:117], v[160:163], v[176:179], v[114:117]
	v_mfma_f32_16x16x32_bf16 v[110:113], v[152:155], v[184:187], v[110:113]
	v_mfma_f32_16x16x32_bf16 v[106:109], v[160:163], v[184:187], v[106:109]
	v_mfma_f32_16x16x32_bf16 v[102:105], v[152:155], v[192:195], v[102:105]
	v_mfma_f32_16x16x32_bf16 v[98:101], v[156:159], v[188:191], v[98:101]
	v_mfma_f32_16x16x32_bf16 v[148:151], v[160:163], v[192:195], v[98:101]

; #define LDB(dst, b, h) for (int n = 0; n < 2; ++n) for (int k = 0; k < 2; ++k) \
;     dst[n][k] = *reinterpret_cast<const bf16x8*>((char*)SB(b, h) + b_thr + (n * 2 + k) * 1024)
; #define MMA(ai, bj, At, Btf) do { __builtin_amdgcn_s_setprio(1); \
;     for (int m = 0; m < 4; ++m) for (int n = 0; n < 2; ++n) for (int k = 0; k < 2; ++k) \
;       acc[ai][bj][m][n] = __builtin_amdgcn_mfma_f32_16x16x32_bf16(Btf[n][k], At[m][k], acc[ai][bj][m][n], 0, 0, 0); \
;     __builtin_amdgcn_s_setprio(0); } while (0)
; #define WAIT_L(n) asm volatile("s_waitcnt lgkmcnt(" #n ")" ::: "memory")
; #define BAR __builtin_amdgcn_s_barrier()
; template <bool OVL, bool PANEL = false, class Epi>
; __device__ __forceinline__ void gemm_phase(const bf16_t* __restrict__ A, long lda, const bf16_t* __restrict__ Bt, long ldb, int nM, int nN, int K,
;                                            const Epi& epi, bf16_t* shm, int w0) {
;     ...
;       LDB(B1, 0, 1); BAR; WAIT_L(0); MMA(0, 1, At, B1); BAR;
	v_add_u32_e32 v0, 0x14000, v212
	s_barrier
	s_nop 3
	ds_read_b128 v[98:101], v0
	ds_read_b128 v[196:199], v0 offset:1024
	ds_read_b128 v[200:203], v0 offset:2048
	ds_read_b128 v[204:207], v0 offset:3072
	s_barrier
	s_waitcnt lgkmcnt(0)

; #define LDB(dst, b, h) for (int n = 0; n < 2; ++n) for (int k = 0; k < 2; ++k) \
;     dst[n][k] = *reinterpret_cast<const bf16x8*>((char*)SB(b, h) + b_thr + (n * 2 + k) * 1024)
; #define MMA(ai, bj, At, Btf) do { __builtin_amdgcn_s_setprio(1); \
;     for (int m = 0; m < 4; ++m) for (int n = 0; n < 2; ++n) for (int k = 0; k < 2; ++k) \
;       acc[ai][bj][m][n] = __builtin_amdgcn_mfma_f32_16x16x32_bf16(Btf[n][k], At[m][k], acc[ai][bj][m][n], 0, 0, 0); \
;     __builtin_amdgcn_s_setprio(0); } while (0)
; #define WAIT_L(n) asm volatile("s_waitcnt lgkmcnt(" #n ")" ::: "memory")
; #define BAR __builtin_amdgcn_s_barrier()
; template <bool OVL, bool PANEL = false, class Epi>
; __device__ __forceinline__ void gemm_phase(const bf16_t* __restrict__ A, long lda, const bf16_t* __restrict__ Bt, long ldb, int nM, int nN, int K,
;                                            const Epi& epi, bf16_t* shm, int w0) {
;     ...
;       LDB(B1, 0, 1); BAR; WAIT_L(0); MMA(0, 1, At, B1); BAR;
	s_waitcnt lgkmcnt(0)
	v_mfma_f32_16x16x32_bf16 v[94:97], v[98:101], v[164:167], v[94:97]
	v_mfma_f32_16x16x32_bf16 v[86:89], v[98:101], v[172:175], v[86:89]
	v_mfma_f32_16x16x32_bf16 v[82:85], v[200:203], v[172:175], v[82:85]
	v_mfma_f32_16x16x32_bf16 v[78:81], v[98:101], v[180:183], v[78:81]
	v_mfma_f32_16x16x32_bf16 v[74:77], v[200:203], v[180:183], v[74:77]
	v_mfma_f32_16x16x32_bf16 v[94:97], v[196:199], v[168:171], v[94:97]
	v_mfma_f32_16x16x32_bf16 v[90:93], v[200:203], v[164:167], v[90:93]
	v_mfma_f32_16x16x32_bf16 v[86:89], v[196:199], v[176:179], v[86:89]
	v_mfma_f32_16x16x32_bf16 v[82:85], v[204:207], v[176:179], v[82:85]
	v_mfma_f32_16x16x32_bf16 v[78:81], v[196:199], v[184:187], v[78:81]
	v_mfma_f32_16x16x32_bf16 v[74:77], v[204:207], v[184:187], v[74:77]
	v_mfma_f32_16x16x32_bf16 v[70:73], v[98:101], v[188:191], v[70:73]
	v_mfma_f32_16x16x32_bf16 v[66:69], v[200:203], v[188:191], v[66:69]
	v_mfma_f32_16x16x32_bf16 v[164:167], v[204:207], v[168:171], v[90:93]
	v_mfma_f32_16x16x32_bf16 v[168:171], v[196:199], v[192:195], v[70:73]
	v_mfma_f32_16x16x32_bf16 v[172:175], v[204:207], v[192:195], v[66:69]

; #define LDA(dst, b, h) for (int m = 0; m < 4; ++m) for (int k = 0; k < 2; ++k) \
;     dst[m][k] = *reinterpret_cast<const bf16x8*>((char*)SA(b, h) + a_thr + (m * 2 + k) * 1024)
; #define MMA(ai, bj, At, Btf) do { __builtin_amdgcn_s_setprio(1); \
;     for (int m = 0; m < 4; ++m) for (int n = 0; n < 2; ++n) for (int k = 0; k < 2; ++k) \
;       acc[ai][bj][m][n] = __builtin_amdgcn_mfma_f32_16x16x32_bf16(Btf[n][k], At[m][k], acc[ai][bj][m][n], 0, 0, 0); \
;     __builtin_amdgcn_s_setprio(0); } while (0)
; #define WAIT_V(n) asm volatile("s_waitcnt vmcnt(" #n ")" ::: "memory")
; #define WAIT_L(n) asm volatile("s_waitcnt lgkmcnt(" #n ")" ::: "memory")
; #define BAR __builtin_amdgcn_s_barrier()
; template <bool OVL, bool PANEL = false, class Epi>
; __device__ __forceinline__ void gemm_phase(const bf16_t* __restrict__ A, long lda, const bf16_t* __restrict__ Bt, long ldb, int nM, int nN, int K,
;                                            const Epi& epi, bf16_t* shm, int w0) {
;     ...
;       LDA(At, 0, 1); WAIT_V(4); BAR; WAIT_L(0); MMA(1, 0, At, B0); MMA(1, 1, At, B1); BAR; }
	s_barrier
	s_nop 2
	ds_read_b128 v[66:69], v143 offset:16384
	ds_read_b128 v[70:73], v143 offset:17408
	ds_read_b128 v[90:93], v143 offset:18432
	ds_read_b128 v[176:179], v143 offset:19456
	ds_read_b128 v[180:183], v143 offset:20480
	ds_read_b128 v[184:187], v143 offset:21504
	ds_read_b128 v[188:191], v143 offset:22528
	ds_read_b128 v[192:195], v143 offset:23552
	s_waitcnt vmcnt(4)
	s_barrier
	s_waitcnt lgkmcnt(0)

; #define LDA(dst, b, h) for (int m = 0; m < 4; ++m) for (int k = 0; k < 2; ++k) \
;     dst[m][k] = *reinterpret_cast<const bf16x8*>((char*)SA(b, h) + a_thr + (m * 2 + k) * 1024)
; #define MMA(ai, bj, At, Btf) do { __builtin_amdgcn_s_setprio(1); \
;     for (int m = 0; m < 4; ++m) for (int n = 0; n < 2; ++n) for (int k = 0; k < 2; ++k) \
;       acc[ai][bj][m][n] = __builtin_amdgcn_mfma_f32_16x16x32_bf16(Btf[n][k], At[m][k], acc[ai][bj][m][n], 0, 0, 0); \
;     __builtin_amdgcn_s_setprio(0); } while (0)
; #define WAIT_V(n) asm volatile("s_waitcnt vmcnt(" #n ")" ::: "memory")
; #define WAIT_L(n) asm volatile("s_waitcnt lgkmcnt(" #n ")" ::: "memory")
; #define BAR __builtin_amdgcn_s_barrier()
; template <bool OVL, bool PANEL = false, class Epi>
; __device__ __forceinline__ void gemm_phase(const bf16_t* __restrict__ A, long lda, const bf16_t* __restrict__ Bt, long ldb, int nM, int nN, int K,
;                                            const Epi& epi, bf16_t* shm, int w0) {
;     ...
;       LDA(At, 0, 1); WAIT_V(4); BAR; WAIT_L(0); MMA(1, 0, At, B0); MMA(1, 1, At, B1); BAR; }
	s_waitcnt lgkmcnt(0)
	v_mfma_f32_16x16x32_bf16 v[62:65], v[144:147], v[66:69], v[62:65]
	v_mfma_f32_16x16x32_bf16 v[54:57], v[144:147], v[90:93], v[54:57]
	v_mfma_f32_16x16x32_bf16 v[50:53], v[156:159], v[90:93], v[50:53]
	v_mfma_f32_16x16x32_bf16 v[46:49], v[144:147], v[180:183], v[46:49]
	v_mfma_f32_16x16x32_bf16 v[42:45], v[156:159], v[180:183], v[42:45]
	v_mfma_f32_16x16x32_bf16 v[38:41], v[144:147], v[188:191], v[38:41]
	v_mfma_f32_16x16x32_bf16 v[34:37], v[156:159], v[188:191], v[34:37]
	v_mfma_f32_16x16x32_bf16 v[62:65], v[152:155], v[70:73], v[62:65]
	v_mfma_f32_16x16x32_bf16 v[58:61], v[156:159], v[66:69], v[58:61]
	v_mfma_f32_16x16x32_bf16 v[54:57], v[152:155], v[176:179], v[54:57]
	v_mfma_f32_16x16x32_bf16 v[50:53], v[160:163], v[176:179], v[50:53]
	v_mfma_f32_16x16x32_bf16 v[46:49], v[152:155], v[184:187], v[46:49]
	v_mfma_f32_16x16x32_bf16 v[42:45], v[160:163], v[184:187], v[42:45]
	v_mfma_f32_16x16x32_bf16 v[38:41], v[152:155], v[192:195], v[38:41]
	v_mfma_f32_16x16x32_bf16 v[34:37], v[160:163], v[192:195], v[34:37]
	v_mfma_f32_16x16x32_bf16 v[208:211], v[160:163], v[70:73], v[58:61]


; #define LDA(dst, b, h) for (int m = 0; m < 4; ++m) for (int k = 0; k < 2; ++k) \
;     dst[m][k] = *reinterpret_cast<const bf16x8*>((char*)SA(b, h) + a_thr + (m * 2 + k) * 1024)
; #define MMA(ai, bj, At, Btf) do { __builtin_amdgcn_s_setprio(1); \
;     for (int m = 0; m < 4; ++m) for (int n = 0; n < 2; ++n) for (int k = 0; k < 2; ++k) \
;       acc[ai][bj][m][n] = __builtin_amdgcn_mfma_f32_16x16x32_bf16(Btf[n][k], At[m][k], acc[ai][bj][m][n], 0, 0, 0); \
;     __builtin_amdgcn_s_setprio(0); } while (0)
; #define WAIT_V(n) asm volatile("s_waitcnt vmcnt(" #n ")" ::: "memory")
; #define WAIT_L(n) asm volatile("s_waitcnt lgkmcnt(" #n ")" ::: "memory")
; #define BAR __builtin_amdgcn_s_barrier()
; template <bool OVL, bool PANEL = false, class Epi>
; __device__ __forceinline__ void gemm_phase(const bf16_t* __restrict__ A, long lda, const bf16_t* __restrict__ Bt, long ldb, int nM, int nN, int K,
;                                            const Epi& epi, bf16_t* shm, int w0) {
;     ...
;       LDA(At, 0, 1); WAIT_V(4); BAR; WAIT_L(0); MMA(1, 0, At, B0); MMA(1, 1, At, B1); BAR; }
	v_mfma_f32_16x16x32_bf16 v[30:33], v[98:101], v[66:69], v[30:33]
	v_mfma_f32_16x16x32_bf16 v[26:29], v[200:203], v[66:69], v[26:29]
	v_mfma_f32_16x16x32_bf16 v[22:25], v[98:101], v[90:93], v[22:25]
	v_mfma_f32_16x16x32_bf16 v[18:21], v[200:203], v[90:93], v[18:21]
	v_mfma_f32_16x16x32_bf16 v[14:17], v[98:101], v[180:183], v[14:17]
	v_mfma_f32_16x16x32_bf16 v[10:13], v[200:203], v[180:183], v[10:13]
	v_mfma_f32_16x16x32_bf16 v[6:9], v[98:101], v[188:191], v[6:9]
	v_mfma_f32_16x16x32_bf16 v[2:5], v[200:203], v[188:191], v[2:5]
	v_mfma_f32_16x16x32_bf16 v[30:33], v[196:199], v[70:73], v[30:33]
	v_mfma_f32_16x16x32_bf16 v[26:29], v[204:207], v[70:73], v[26:29]
	v_mfma_f32_16x16x32_bf16 v[22:25], v[196:199], v[176:179], v[22:25]
	v_mfma_f32_16x16x32_bf16 v[18:21], v[204:207], v[176:179], v[18:21]
	v_mfma_f32_16x16x32_bf16 v[14:17], v[196:199], v[184:187], v[14:17]
	v_mfma_f32_16x16x32_bf16 v[10:13], v[204:207], v[184:187], v[10:13]
	v_mfma_f32_16x16x32_bf16 v[6:9], v[196:199], v[192:195], v[6:9]
	v_mfma_f32_16x16x32_bf16 v[2:5], v[204:207], v[192:195], v[2:5]

; #define LDA(dst, b, h) for (int m = 0; m < 4; ++m) for (int k = 0; k < 2; ++k) \
;     dst[m][k] = *reinterpret_cast<const bf16x8*>((char*)SA(b, h) + a_thr + (m * 2 + k) * 1024)
; #define LDB(dst, b, h) for (int n = 0; n < 2; ++n) for (int k = 0; k < 2; ++k) \
;     dst[n][k] = *reinterpret_cast<const bf16x8*>((char*)SB(b, h) + b_thr + (n * 2 + k) * 1024)
; #define MMA(ai, bj, At, Btf) do { __builtin_amdgcn_s_setprio(1); \
;     for (int m = 0; m < 4; ++m) for (int n = 0; n < 2; ++n) for (int k = 0; k < 2; ++k) \
;       acc[ai][bj][m][n] = __builtin_amdgcn_mfma_f32_16x16x32_bf16(Btf[n][k], At[m][k], acc[ai][bj][m][n], 0, 0, 0); \
;     __builtin_amdgcn_s_setprio(0); } while (0)
; #define WAIT_V(n) asm volatile("s_waitcnt vmcnt(" #n ")" ::: "memory")
; #define WAIT_L(n) asm volatile("s_waitcnt lgkmcnt(" #n ")" ::: "memory")
; #define BAR __builtin_amdgcn_s_barrier()
; template <bool OVL, bool PANEL = false, class Epi>
; __device__ __forceinline__ void gemm_phase(const bf16_t* __restrict__ A, long lda, const bf16_t* __restrict__ Bt, long ldb, int nM, int nN, int K,
;                                            const Epi& epi, bf16_t* shm, int w0) {
;     ...
;     { LDB(B0, 1, 0); LDA(At, 1, 0); WAIT_V(2); BAR; WAIT_L(0); MMA(0, 0, At, B0); BAR;
	v_add_u32_e32 v0, 0x18000, v212
	s_barrier
	ds_read_b128 v[144:147], v0
	ds_read_b128 v[152:155], v0 offset:1024
	ds_read_b128 v[156:159], v0 offset:2048
	ds_read_b128 v[160:163], v0 offset:3072
	ds_read_b128 v[58:61], v143 offset:32768
	ds_read_b128 v[66:69], v143 offset:33792
	ds_read_b128 v[70:73], v143 offset:34816
	ds_read_b128 v[176:179], v143 offset:35840
	ds_read_b128 v[180:183], v143 offset:36864
	ds_read_b128 v[184:187], v143 offset:37888
	ds_read_b128 v[188:191], v143 offset:38912
	ds_read_b128 v[192:195], v143 offset:39936
	s_waitcnt vmcnt(2)
	s_barrier
	s_waitcnt lgkmcnt(0)

; #define LDA(dst, b, h) for (int m = 0; m < 4; ++m) for (int k = 0; k < 2; ++k) \
;     dst[m][k] = *reinterpret_cast<const bf16x8*>((char*)SA(b, h) + a_thr + (m * 2 + k) * 1024)
; #define LDB(dst, b, h) for (int n = 0; n < 2; ++n) for (int k = 0; k < 2; ++k) \
;     dst[n][k] = *reinterpret_cast<const bf16x8*>((char*)SB(b, h) + b_thr + (n * 2 + k) * 1024)
; #define MMA(ai, bj, At, Btf) do { __builtin_amdgcn_s_setprio(1); \
;     for (int m = 0; m < 4; ++m) for (int n = 0; n < 2; ++n) for (int k = 0; k < 2; ++k) \
;       acc[ai][bj][m][n] = __builtin_amdgcn_mfma_f32_16x16x32_bf16(Btf[n][k], At[m][k], acc[ai][bj][m][n], 0, 0, 0); \
;     __builtin_amdgcn_s_setprio(0); } while (0)
; #define WAIT_V(n) asm volatile("s_waitcnt vmcnt(" #n ")" ::: "memory")
; #define WAIT_L(n) asm volatile("s_waitcnt lgkmcnt(" #n ")" ::: "memory")
; #define BAR __builtin_amdgcn_s_barrier()
; template <bool OVL, bool PANEL = false, class Epi>
; __device__ __forceinline__ void gemm_phase(const bf16_t* __restrict__ A, long lda, const bf16_t* __restrict__ Bt, long ldb, int nM, int nN, int K,
;                                            const Epi& epi, bf16_t* shm, int w0) {
;     ...
;     { LDB(B0, 1, 0); LDA(At, 1, 0); WAIT_V(2); BAR; WAIT_L(0); MMA(0, 0, At, B0); BAR;
	s_waitcnt lgkmcnt(0)
	v_mfma_f32_16x16x32_bf16 v[90:93], v[144:147], v[58:61], v[126:129]
	v_mfma_f32_16x16x32_bf16 v[126:129], v[152:155], v[66:69], v[90:93]
	v_mfma_f32_16x16x32_bf16 v[90:93], v[156:159], v[58:61], v[122:125]
	v_mfma_f32_16x16x32_bf16 v[122:125], v[160:163], v[66:69], v[90:93]
	v_mfma_f32_16x16x32_bf16 v[90:93], v[144:147], v[70:73], v[118:121]
	v_mfma_f32_16x16x32_bf16 v[118:121], v[152:155], v[176:179], v[90:93]
	v_mfma_f32_16x16x32_bf16 v[90:93], v[156:159], v[70:73], v[114:117]
	v_mfma_f32_16x16x32_bf16 v[114:117], v[160:163], v[176:179], v[90:93]
	v_mfma_f32_16x16x32_bf16 v[90:93], v[144:147], v[180:183], v[110:113]
	v_mfma_f32_16x16x32_bf16 v[110:113], v[152:155], v[184:187], v[90:93]
	v_mfma_f32_16x16x32_bf16 v[90:93], v[156:159], v[180:183], v[106:109]
	v_mfma_f32_16x16x32_bf16 v[106:109], v[160:163], v[184:187], v[90:93]
	v_mfma_f32_16x16x32_bf16 v[90:93], v[144:147], v[188:191], v[102:105]
	v_mfma_f32_16x16x32_bf16 v[98:101], v[152:155], v[192:195], v[90:93]
	v_mfma_f32_16x16x32_bf16 v[90:93], v[156:159], v[188:191], v[148:151]
	v_mfma_f32_16x16x32_bf16 v[90:93], v[160:163], v[192:195], v[90:93]

; #define LDB(dst, b, h) for (int n = 0; n < 2; ++n) for (int k = 0; k < 2; ++k) \
;     dst[n][k] = *reinterpret_cast<const bf16x8*>((char*)SB(b, h) + b_thr + (n * 2 + k) * 1024)
; #define MMA(ai, bj, At, Btf) do { __builtin_amdgcn_s_setprio(1); \
;     for (int m = 0; m < 4; ++m) for (int n = 0; n < 2; ++n) for (int k = 0; k < 2; ++k) \
;       acc[ai][bj][m][n] = __builtin_amdgcn_mfma_f32_16x16x32_bf16(Btf[n][k], At[m][k], acc[ai][bj][m][n], 0, 0, 0); \
;     __builtin_amdgcn_s_setprio(0); } while (0)
; #define WAIT_V(n) asm volatile("s_waitcnt vmcnt(" #n ")" ::: "memory")
; #define WAIT_L(n) asm volatile("s_waitcnt lgkmcnt(" #n ")" ::: "memory")
; #define BAR __builtin_amdgcn_s_barrier()
; template <bool OVL, bool PANEL = false, class Epi>
; __device__ __forceinline__ void gemm_phase(const bf16_t* __restrict__ A, long lda, const bf16_t* __restrict__ Bt, long ldb, int nM, int nN, int K,
;                                            const Epi& epi, bf16_t* shm, int w0) {
;     ...
;       LDB(B1, 1, 1); WAIT_V(0); BAR; WAIT_L(0); MMA(0, 1, At, B1); BAR;
	v_add_u32_e32 v0, 0x1c000, v212
	s_barrier
	ds_read_b128 v[148:151], v0
	ds_read_b128 v[196:199], v0 offset:1024
	ds_read_b128 v[200:203], v0 offset:2048
	ds_read_b128 v[204:207], v0 offset:3072
	s_waitcnt vmcnt(0)
	s_barrier
	s_waitcnt lgkmcnt(0)

; #define LDB(dst, b, h) for (int n = 0; n < 2; ++n) for (int k = 0; k < 2; ++k) \
;     dst[n][k] = *reinterpret_cast<const bf16x8*>((char*)SB(b, h) + b_thr + (n * 2 + k) * 1024)
; #define MMA(ai, bj, At, Btf) do { __builtin_amdgcn_s_setprio(1); \
;     for (int m = 0; m < 4; ++m) for (int n = 0; n < 2; ++n) for (int k = 0; k < 2; ++k) \
;       acc[ai][bj][m][n] = __builtin_amdgcn_mfma_f32_16x16x32_bf16(Btf[n][k], At[m][k], acc[ai][bj][m][n], 0, 0, 0); \
;     __builtin_amdgcn_s_setprio(0); } while (0)
; #define WAIT_V(n) asm volatile("s_waitcnt vmcnt(" #n ")" ::: "memory")
; #define WAIT_L(n) asm volatile("s_waitcnt lgkmcnt(" #n ")" ::: "memory")
; #define BAR __builtin_amdgcn_s_barrier()
; template <bool OVL, bool PANEL = false, class Epi>
; __device__ __forceinline__ void gemm_phase(const bf16_t* __restrict__ A, long lda, const bf16_t* __restrict__ Bt, long ldb, int nM, int nN, int K,
;                                            const Epi& epi, bf16_t* shm, int w0) {
;     ...
;       LDB(B1, 1, 1); WAIT_V(0); BAR; WAIT_L(0); MMA(0, 1, At, B1); BAR;
	s_waitcnt lgkmcnt(0)
	v_mfma_f32_16x16x32_bf16 v[94:97], v[148:151], v[58:61], v[94:97]
	v_mfma_f32_16x16x32_bf16 v[58:61], v[200:203], v[58:61], v[164:167]
	v_mfma_f32_16x16x32_bf16 v[102:105], v[196:199], v[66:69], v[94:97]
	v_mfma_f32_16x16x32_bf16 v[94:97], v[204:207], v[66:69], v[58:61]
	v_mfma_f32_16x16x32_bf16 v[58:61], v[148:151], v[70:73], v[86:89]
	v_mfma_f32_16x16x32_bf16 v[86:89], v[196:199], v[176:179], v[58:61]
	v_mfma_f32_16x16x32_bf16 v[58:61], v[200:203], v[70:73], v[82:85]
	v_mfma_f32_16x16x32_bf16 v[82:85], v[204:207], v[176:179], v[58:61]
	v_mfma_f32_16x16x32_bf16 v[58:61], v[148:151], v[180:183], v[78:81]
	v_mfma_f32_16x16x32_bf16 v[78:81], v[196:199], v[184:187], v[58:61]
	v_mfma_f32_16x16x32_bf16 v[58:61], v[200:203], v[180:183], v[74:77]
	v_mfma_f32_16x16x32_bf16 v[70:73], v[204:207], v[184:187], v[58:61]
	v_mfma_f32_16x16x32_bf16 v[58:61], v[148:151], v[188:191], v[168:171]
	v_mfma_f32_16x16x32_bf16 v[66:69], v[196:199], v[192:195], v[58:61]
	v_mfma_f32_16x16x32_bf16 v[58:61], v[200:203], v[188:191], v[172:175]
	v_mfma_f32_16x16x32_bf16 v[58:61], v[204:207], v[192:195], v[58:61]

; #define LDA(dst, b, h) for (int m = 0; m < 4; ++m) for (int k = 0; k < 2; ++k) \
;     dst[m][k] = *reinterpret_cast<const bf16x8*>((char*)SA(b, h) + a_thr + (m * 2 + k) * 1024)
; #define MMA(ai, bj, At, Btf) do { __builtin_amdgcn_s_setprio(1); \
;     for (int m = 0; m < 4; ++m) for (int n = 0; n < 2; ++n) for (int k = 0; k < 2; ++k) \
;       acc[ai][bj][m][n] = __builtin_amdgcn_mfma_f32_16x16x32_bf16(Btf[n][k], At[m][k], acc[ai][bj][m][n], 0, 0, 0); \
;     __builtin_amdgcn_s_setprio(0); } while (0)
; #define WAIT_L(n) asm volatile("s_waitcnt lgkmcnt(" #n ")" ::: "memory")
; #define BAR __builtin_amdgcn_s_barrier()
; template <bool OVL, bool PANEL = false, class Epi>
; __device__ __forceinline__ void gemm_phase(const bf16_t* __restrict__ A, long lda, const bf16_t* __restrict__ Bt, long ldb, int nM, int nN, int K,
;                                            const Epi& epi, bf16_t* shm, int w0) {
;     ...
;       LDA(At, 1, 1); BAR; WAIT_L(0); MMA(1, 0, At, B0); MMA(1, 1, At, B1); BAR; }
	s_barrier
	ds_read_b128 v[164:167], v143 offset:49152
	ds_read_b128 v[168:171], v143 offset:50176
	ds_read_b128 v[172:175], v143 offset:51200
	ds_read_b128 v[176:179], v143 offset:52224
	ds_read_b128 v[180:183], v143 offset:53248
	ds_read_b128 v[184:187], v143 offset:54272
	ds_read_b128 v[188:191], v143 offset:55296
	ds_read_b128 v[192:195], v143 offset:56320
	s_barrier
	s_waitcnt lgkmcnt(0)

; #define LDA(dst, b, h) for (int m = 0; m < 4; ++m) for (int k = 0; k < 2; ++k) \
;     dst[m][k] = *reinterpret_cast<const bf16x8*>((char*)SA(b, h) + a_thr + (m * 2 + k) * 1024)
; #define MMA(ai, bj, At, Btf) do { __builtin_amdgcn_s_setprio(1); \
;     for (int m = 0; m < 4; ++m) for (int n = 0; n < 2; ++n) for (int k = 0; k < 2; ++k) \
;       acc[ai][bj][m][n] = __builtin_amdgcn_mfma_f32_16x16x32_bf16(Btf[n][k], At[m][k], acc[ai][bj][m][n], 0, 0, 0); \
;     __builtin_amdgcn_s_setprio(0); } while (0)
; #define WAIT_L(n) asm volatile("s_waitcnt lgkmcnt(" #n ")" ::: "memory")
; #define BAR __builtin_amdgcn_s_barrier()
; template <bool OVL, bool PANEL = false, class Epi>
; __device__ __forceinline__ void gemm_phase(const bf16_t* __restrict__ A, long lda, const bf16_t* __restrict__ Bt, long ldb, int nM, int nN, int K,
;                                            const Epi& epi, bf16_t* shm, int w0) {
;     ...
;       LDA(At, 1, 1); BAR; WAIT_L(0); MMA(1, 0, At, B0); MMA(1, 1, At, B1); BAR; }
	s_waitcnt lgkmcnt(0)
	v_mfma_f32_16x16x32_bf16 v[62:65], v[144:147], v[164:167], v[62:65]
	v_mfma_f32_16x16x32_bf16 v[74:77], v[152:155], v[168:171], v[62:65]
	v_mfma_f32_16x16x32_bf16 v[62:65], v[156:159], v[164:167], v[208:211]
	v_mfma_f32_16x16x32_bf16 v[54:57], v[144:147], v[172:175], v[54:57]
	v_mfma_f32_16x16x32_bf16 v[50:53], v[156:159], v[172:175], v[50:53]
	v_mfma_f32_16x16x32_bf16 v[46:49], v[144:147], v[180:183], v[46:49]
	v_mfma_f32_16x16x32_bf16 v[42:45], v[156:159], v[180:183], v[42:45]
	v_mfma_f32_16x16x32_bf16 v[38:41], v[144:147], v[188:191], v[38:41]
	v_mfma_f32_16x16x32_bf16 v[34:37], v[156:159], v[188:191], v[34:37]
	v_mfma_f32_16x16x32_bf16 v[62:65], v[160:163], v[168:171], v[62:65]
	v_mfma_f32_16x16x32_bf16 v[54:57], v[152:155], v[176:179], v[54:57]
	v_mfma_f32_16x16x32_bf16 v[50:53], v[160:163], v[176:179], v[50:53]
	v_mfma_f32_16x16x32_bf16 v[46:49], v[152:155], v[184:187], v[46:49]
	v_mfma_f32_16x16x32_bf16 v[42:45], v[160:163], v[184:187], v[42:45]
	v_mfma_f32_16x16x32_bf16 v[38:41], v[152:155], v[192:195], v[38:41]
	v_mfma_f32_16x16x32_bf16 v[34:37], v[160:163], v[192:195], v[34:37]


; #define LDA(dst, b, h) for (int m = 0; m < 4; ++m) for (int k = 0; k < 2; ++k) \
;     dst[m][k] = *reinterpret_cast<const bf16x8*>((char*)SA(b, h) + a_thr + (m * 2 + k) * 1024)
; #define MMA(ai, bj, At, Btf) do { __builtin_amdgcn_s_setprio(1); \
;     for (int m = 0; m < 4; ++m) for (int n = 0; n < 2; ++n) for (int k = 0; k < 2; ++k) \
;       acc[ai][bj][m][n] = __builtin_amdgcn_mfma_f32_16x16x32_bf16(Btf[n][k], At[m][k], acc[ai][bj][m][n], 0, 0, 0); \
;     __builtin_amdgcn_s_setprio(0); } while (0)
; #define WAIT_L(n) asm volatile("s_waitcnt lgkmcnt(" #n ")" ::: "memory")
; #define BAR __builtin_amdgcn_s_barrier()
; template <bool OVL, bool PANEL = false, class Epi>
; __device__ __forceinline__ void gemm_phase(const bf16_t* __restrict__ A, long lda, const bf16_t* __restrict__ Bt, long ldb, int nM, int nN, int K,
;                                            const Epi& epi, bf16_t* shm, int w0) {
;     ...
;       LDA(At, 1, 1); BAR; WAIT_L(0); MMA(1, 0, At, B0); MMA(1, 1, At, B1); BAR; }
	v_mfma_f32_16x16x32_bf16 v[30:33], v[148:151], v[164:167], v[30:33]
	v_mfma_f32_16x16x32_bf16 v[26:29], v[200:203], v[164:167], v[26:29]
	v_mfma_f32_16x16x32_bf16 v[22:25], v[148:151], v[172:175], v[22:25]
	v_mfma_f32_16x16x32_bf16 v[18:21], v[200:203], v[172:175], v[18:21]
	v_mfma_f32_16x16x32_bf16 v[14:17], v[148:151], v[180:183], v[14:17]
	v_mfma_f32_16x16x32_bf16 v[10:13], v[200:203], v[180:183], v[10:13]
	v_mfma_f32_16x16x32_bf16 v[6:9], v[148:151], v[188:191], v[6:9]
	v_mfma_f32_16x16x32_bf16 v[2:5], v[200:203], v[188:191], v[2:5]
	v_mfma_f32_16x16x32_bf16 v[30:33], v[196:199], v[168:171], v[30:33]
	v_mfma_f32_16x16x32_bf16 v[26:29], v[204:207], v[168:171], v[26:29]
	v_mfma_f32_16x16x32_bf16 v[22:25], v[196:199], v[176:179], v[22:25]
	v_mfma_f32_16x16x32_bf16 v[18:21], v[204:207], v[176:179], v[18:21]
	v_mfma_f32_16x16x32_bf16 v[14:17], v[196:199], v[184:187], v[14:17]
	v_mfma_f32_16x16x32_bf16 v[10:13], v[204:207], v[184:187], v[10:13]
	v_mfma_f32_16x16x32_bf16 v[6:9], v[196:199], v[192:195], v[6:9]
	v_mfma_f32_16x16x32_bf16 v[2:5], v[204:207], v[192:195], v[2:5]

; #define LDA(dst, b, h) for (int m = 0; m < 4; ++m) for (int k = 0; k < 2; ++k) \
;     dst[m][k] = *reinterpret_cast<const bf16x8*>((char*)SA(b, h) + a_thr + (m * 2 + k) * 1024)
; #define MMA(ai, bj, At, Btf) do { __builtin_amdgcn_s_setprio(1); \
;     for (int m = 0; m < 4; ++m) for (int n = 0; n < 2; ++n) for (int k = 0; k < 2; ++k) \
;       acc[ai][bj][m][n] = __builtin_amdgcn_mfma_f32_16x16x32_bf16(Btf[n][k], At[m][k], acc[ai][bj][m][n], 0, 0, 0); \
;     __builtin_amdgcn_s_setprio(0); } while (0)
; #define WAIT_L(n) asm volatile("s_waitcnt lgkmcnt(" #n ")" ::: "memory")
; #define BAR __builtin_amdgcn_s_barrier()
; template <bool OVL, bool PANEL = false, class Epi>
; __device__ __forceinline__ void gemm_phase(const bf16_t* __restrict__ A, long lda, const bf16_t* __restrict__ Bt, long ldb, int nM, int nN, int K,
;                                            const Epi& epi, bf16_t* shm, int w0) {
;     ...
;       LDA(At, 1, 1); BAR; WAIT_L(0); MMA(1, 0, At, B0); MMA(1, 1, At, B1); BAR; }
;     if (wr == 0) BAR;
	s_barrier
	s_and_saveexec_b64 s[0:1], s[6:7]
	s_cbranch_execz .LBB0_413
	s_barrier

; #define LDA(dst, b, h) for (int m = 0; m < 4; ++m) for (int k = 0; k < 2; ++k) \
;     dst[m][k] = *reinterpret_cast<const bf16x8*>((char*)SA(b, h) + a_thr + (m * 2 + k) * 1024)
; #define LDB(dst, b, h) for (int n = 0; n < 2; ++n) for (int k = 0; k < 2; ++k) \
;     dst[n][k] = *reinterpret_cast<const bf16x8*>((char*)SB(b, h) + b_thr + (n * 2 + k) * 1024)
; #define WAIT_V(n) asm volatile("s_waitcnt vmcnt(" #n ")" ::: "memory")
; #define BAR __builtin_amdgcn_s_barrier()
; #define SCHED __builtin_amdgcn_sched_barrier(0)
; template <bool OVL, bool PANEL = false, class Epi>
; __device__ __forceinline__ void gemm_phase(const bf16_t* __restrict__ A, long lda, const bf16_t* __restrict__ Bt, long ldb, int nM, int nN, int K,
;                                            const Epi& epi, bf16_t* shm, int w0) {
;     ...
;   for (int it = 0; have; ++it) {
;     const int brow = pm * BM, bcol = pn * BM;
;     f32x4 acc[2][2][4][2];
; #pragma unroll
;     for (int a0 = 0; a0 < 2; ++a0)
; #pragma unroll
;       for (int a1 = 0; a1 < 2; ++a1)
; #pragma unroll
;         for (int a2 = 0; a2 < 4; ++a2)
; #pragma unroll
;           for (int a3 = 0; a3 < 2; ++a3) acc[a0][a1][a2][a3] = (f32x4){0.f, 0.f, 0.f, 0.f};
;     bf16x8 At[4][2], B0[2][2], B1[2][2];
;     if (wr == 1) BAR;
;     WAIT_V(4); BAR;
;     STAGE(SB(1, 0), Bt, ldb, boff, bcol, 1); STAGE(SA(1, 0), A, lda, aoff, brow, 1); STAGE(SB(1, 1), Bt, ldb, boff, bcol + HALF, 1);
;     WAIT_V(6); BAR;
;     for (int t = 0; t < nt - 2; t += 2) {
;       LDB(B0, 0, 0); SCHED; LDA(At, 0, 0); STAGE(SA(1, 1), A, lda, aoff, brow + HALF, t + 1);
.LBB0_471:
	s_or_b64 exec, exec, s[0:1]
	s_lshl_b32 s2, s25, 18
	v_readlane_b32 s44, v252, 3
	s_lshl_b32 s82, s4, 8
	s_lshl_b64 s[0:1], s[2:3], 1
	v_readlane_b32 s58, v252, 17
	v_readlane_b32 s59, v252, 18
	s_add_u32 s6, s58, s0
	s_addc_u32 s7, s59, s1
	v_mov_b32_e32 v0, v221
	v_add_u32_e32 v130, s96, v220
	s_waitcnt vmcnt(4)
	s_barrier
	v_readlane_b32 s45, v252, 4
	v_readlane_b32 s46, v252, 5
	v_readlane_b32 s47, v252, 6
	v_readlane_b32 s48, v252, 7
	v_readlane_b32 s49, v252, 8
	v_readlane_b32 s50, v252, 9
	v_readlane_b32 s51, v252, 10
	v_readlane_b32 s52, v252, 11
	v_readlane_b32 s53, v252, 12
	v_readlane_b32 s54, v252, 13
	v_readlane_b32 s55, v252, 14
	v_readlane_b32 s56, v252, 15
	v_readlane_b32 s57, v252, 16
	s_mov_b64 s[12:13], 0x80
	v_lshl_add_u64 v[2:3], s[6:7], 0, v[0:1]
	v_readfirstlane_b32 s0, v130
	v_add_u32_e32 v131, 0x2000, v130
	v_lshl_add_u64 v[4:5], v[2:3], 0, s[12:13]
	s_mov_b32 m0, s0
	v_readfirstlane_b32 s0, v131
	s_ashr_i32 s83, s82, 31
	v_readlane_b32 s44, v252, 20
	global_load_lds_dwordx4 v[4:5], off
	s_mov_b32 m0, s0
	s_lshl_b64 s[0:1], s[82:83], 11
	v_readlane_b32 s50, v252, 26
	s_mov_b64 s[14:15], 0x20080
	v_readlane_b32 s51, v252, 27
	s_add_u32 s8, s50, s0
	v_lshl_add_u64 v[2:3], v[2:3], 0, s[14:15]
	s_addc_u32 s9, s51, s1
	v_mov_b32_e32 v0, v221
	v_add_u32_e32 v132, 0x8000, v234
	global_load_lds_dwordx4 v[2:3], off
	v_readfirstlane_b32 s0, v132
	v_lshl_add_u64 v[2:3], s[8:9], 0, v[0:1]
	v_add_u32_e32 v133, 0xa000, v234
	v_lshl_add_u64 v[4:5], v[2:3], 0, s[12:13]
	s_mov_b32 m0, s0
	v_readfirstlane_b32 s0, v133
	global_load_lds_dwordx4 v[4:5], off
	v_lshl_add_u64 v[2:3], v[2:3], 0, s[14:15]
	s_mov_b32 m0, s0
	v_mov_b32_e32 v0, v221
	v_add_u32_e32 v134, s75, v220
	global_load_lds_dwordx4 v[2:3], off
	s_mov_b64 s[12:13], 0x40080
	v_lshl_add_u64 v[2:3], s[6:7], 0, v[0:1]
	v_readfirstlane_b32 s0, v134
	v_add_u32_e32 v135, 0x2000, v134
	v_lshl_add_u64 v[4:5], v[2:3], 0, s[12:13]
	s_mov_b32 m0, s0
	v_readfirstlane_b32 s0, v135
	global_load_lds_dwordx4 v[4:5], off
	v_lshl_add_u64 v[2:3], v[2:3], 0, s[36:37]
	s_mov_b32 m0, s0
	s_mov_b32 s2, -2
	global_load_lds_dwordx4 v[2:3], off
	s_waitcnt vmcnt(6)
	v_mov_b32_e32 v2, 0
	s_mov_b64 s[80:81], 0
	v_mov_b32_e32 v3, v2
	v_mov_b32_e32 v4, v2
	v_mov_b32_e32 v5, v2
	v_mov_b32_e32 v6, v2
	v_mov_b32_e32 v7, v2
	v_mov_b32_e32 v8, v2
	v_mov_b32_e32 v9, v2
	s_waitcnt vmcnt(0)
	v_mov_b32_e32 v10, v2
	v_mov_b32_e32 v11, v2
	v_mov_b32_e32 v12, v2
	v_mov_b32_e32 v13, v2
	s_waitcnt lgkmcnt(0)
	v_mov_b32_e32 v14, v2
	v_mov_b32_e32 v15, v2
	v_mov_b32_e32 v16, v2
	v_mov_b32_e32 v17, v2
	v_mov_b32_e32 v18, v2
	v_mov_b32_e32 v19, v2
	v_mov_b32_e32 v20, v2
	v_mov_b32_e32 v21, v2
	v_mov_b32_e32 v22, v2
	v_mov_b32_e32 v23, v2
	v_mov_b32_e32 v24, v2
	v_mov_b32_e32 v25, v2
	v_mov_b32_e32 v26, v2
	v_mov_b32_e32 v27, v2
	v_mov_b32_e32 v28, v2
	v_mov_b32_e32 v29, v2
	v_mov_b32_e32 v30, v2
	v_mov_b32_e32 v31, v2
	v_mov_b32_e32 v32, v2
	v_mov_b32_e32 v33, v2
	v_mov_b32_e32 v34, v2
	v_mov_b32_e32 v35, v2
	v_mov_b32_e32 v36, v2
	v_mov_b32_e32 v37, v2
	v_mov_b32_e32 v38, v2
	v_mov_b32_e32 v39, v2
	v_mov_b32_e32 v40, v2
	v_mov_b32_e32 v41, v2
	v_mov_b32_e32 v42, v2
	v_mov_b32_e32 v43, v2
	v_mov_b32_e32 v44, v2
	v_mov_b32_e32 v45, v2
	v_mov_b32_e32 v46, v2
	v_mov_b32_e32 v47, v2
	v_mov_b32_e32 v48, v2
	v_mov_b32_e32 v49, v2
	v_mov_b32_e32 v50, v2
	v_mov_b32_e32 v51, v2
	v_mov_b32_e32 v52, v2
	v_mov_b32_e32 v53, v2
	v_mov_b32_e32 v54, v2
	v_mov_b32_e32 v55, v2
	v_mov_b32_e32 v56, v2
	v_mov_b32_e32 v57, v2
	v_mov_b32_e32 v58, v2
	v_mov_b32_e32 v59, v2
	v_mov_b32_e32 v60, v2
	v_mov_b32_e32 v61, v2
	v_mov_b32_e32 v62, v2
	v_mov_b32_e32 v63, v2
	v_mov_b32_e32 v64, v2
	v_mov_b32_e32 v65, v2
	v_mov_b32_e32 v66, v2
	v_mov_b32_e32 v67, v2
	v_mov_b32_e32 v68, v2
	v_mov_b32_e32 v69, v2
	v_mov_b32_e32 v70, v2
	v_mov_b32_e32 v71, v2
	v_mov_b32_e32 v72, v2
	v_mov_b32_e32 v73, v2
	v_mov_b32_e32 v74, v2
	v_mov_b32_e32 v75, v2
	v_mov_b32_e32 v76, v2
	v_mov_b32_e32 v77, v2
	v_mov_b32_e32 v78, v2
	v_mov_b32_e32 v79, v2
	v_mov_b32_e32 v80, v2
	v_mov_b32_e32 v81, v2
	v_mov_b32_e32 v82, v2
	v_mov_b32_e32 v83, v2
	v_mov_b32_e32 v84, v2
	v_mov_b32_e32 v85, v2
	v_mov_b32_e32 v86, v2
	v_mov_b32_e32 v87, v2
	v_mov_b32_e32 v88, v2
	v_mov_b32_e32 v89, v2
	v_mov_b32_e32 v90, v2
	v_mov_b32_e32 v91, v2
	v_mov_b32_e32 v92, v2
	v_mov_b32_e32 v93, v2
	v_mov_b32_e32 v94, v2
	v_mov_b32_e32 v95, v2
	v_mov_b32_e32 v96, v2
	v_mov_b32_e32 v97, v2
	v_mov_b32_e32 v98, v2
	v_mov_b32_e32 v99, v2
	v_mov_b32_e32 v100, v2
	v_mov_b32_e32 v101, v2
	v_mov_b32_e32 v102, v2
	v_mov_b32_e32 v103, v2
	v_mov_b32_e32 v104, v2
	v_mov_b32_e32 v105, v2
	v_mov_b32_e32 v106, v2
	v_mov_b32_e32 v107, v2
	v_mov_b32_e32 v108, v2
	v_mov_b32_e32 v109, v2
	v_mov_b32_e32 v110, v2
	v_mov_b32_e32 v111, v2
	v_mov_b32_e32 v112, v2
	v_mov_b32_e32 v113, v2
	v_mov_b32_e32 v114, v2
	v_mov_b32_e32 v115, v2
	v_mov_b32_e32 v116, v2
	v_mov_b32_e32 v117, v2
	v_mov_b32_e32 v118, v2
	v_mov_b32_e32 v119, v2
	v_mov_b32_e32 v120, v2
	v_mov_b32_e32 v121, v2
	v_mov_b32_e32 v122, v2
	v_mov_b32_e32 v123, v2
	v_mov_b32_e32 v124, v2
	v_mov_b32_e32 v125, v2
	v_mov_b32_e32 v126, v2
	v_mov_b32_e32 v127, v2
	v_mov_b32_e32 v128, v2
	v_mov_b32_e32 v129, v2
	s_mov_b64 s[14:15], 0x40180
	s_mov_b64 s[18:19], 0x60180
	v_readlane_b32 s45, v252, 21
	v_readlane_b32 s46, v252, 22
	v_readlane_b32 s47, v252, 23
	v_readlane_b32 s48, v252, 24
	v_readlane_b32 s49, v252, 25
	v_readlane_b32 s52, v252, 28
	v_readlane_b32 s53, v252, 29
	v_readlane_b32 s54, v252, 30
	v_readlane_b32 s55, v252, 31
	v_readlane_b32 s56, v252, 32
	v_readlane_b32 s57, v252, 33
	v_readlane_b32 s58, v252, 34
	v_readlane_b32 s59, v252, 35
	s_barrier
	v_add_u32_e32 v206, s20, v240
	v_readfirstlane_b32 s16, v234
	s_add_u32 s16, s16, 0xc000
	v_readfirstlane_b32 s32, v234
	s_add_u32 s32, s32, 0xe000
	v_add_u32_e32 v207, s33, v240
	v_readfirstlane_b32 s44, v222
	v_readfirstlane_b32 s45, v223
	v_readfirstlane_b32 s46, v234
	v_readfirstlane_b32 s47, v235
	v_readfirstlane_b32 s48, v236
	v_readfirstlane_b32 s49, v237
	v_add_u32_e32 v208, s96, v240
	v_readfirstlane_b32 s50, v238
	v_readfirstlane_b32 s51, v239
	v_add_u32_e32 v209, s75, v240
	v_readfirstlane_b32 s52, v130
	v_readfirstlane_b32 s53, v131
	v_readfirstlane_b32 s54, v132
	v_readfirstlane_b32 s55, v133
	v_readfirstlane_b32 s56, v134
	v_readfirstlane_b32 s57, v135
	v_add_u32_e32 v136, 0xc000, v234
	v_add_u32_e32 v137, 0xe000, v234
	ds_read_b128 v[138:141], v206
	ds_read_b128 v[142:145], v206 offset:1024
	ds_read_b128 v[146:149], v206 offset:2048
	ds_read_b128 v[150:153], v206 offset:3072
	ds_read_b128 v[154:157], v241
	ds_read_b128 v[162:165], v241 offset:2048
	ds_read_b128 v[170:173], v241 offset:4096
	ds_read_b128 v[178:181], v241 offset:6144
; #define LDA(dst, b, h) for (int m = 0; m < 4; ++m) for (int k = 0; k < 2; ++k) \
;     dst[m][k] = *reinterpret_cast<const bf16x8*>((char*)SA(b, h) + a_thr + (m * 2 + k) * 1024)
; #define LDB(dst, b, h) for (int n = 0; n < 2; ++n) for (int k = 0; k < 2; ++k) \
;     dst[n][k] = *reinterpret_cast<const bf16x8*>((char*)SB(b, h) + b_thr + (n * 2 + k) * 1024)
; #define MMA(ai, bj, At, Btf) do { __builtin_amdgcn_s_setprio(1); \
;     for (int m = 0; m < 4; ++m) for (int n = 0; n < 2; ++n) for (int k = 0; k < 2; ++k) \
;       acc[ai][bj][m][n] = __builtin_amdgcn_mfma_f32_16x16x32_bf16(Btf[n][k], At[m][k], acc[ai][bj][m][n], 0, 0, 0); \
;     __builtin_amdgcn_s_setprio(0); } while (0)
; #define WAIT_V(n) asm volatile("s_waitcnt vmcnt(" #n ")" ::: "memory")
; #define WAIT_L(n) asm volatile("s_waitcnt lgkmcnt(" #n ")" ::: "memory")
; #define BAR __builtin_amdgcn_s_barrier()
; #define SCHED __builtin_amdgcn_sched_barrier(0)
; template <bool OVL, bool PANEL = false, class Epi>
; __device__ __forceinline__ void gemm_phase(const bf16_t* __restrict__ A, long lda, const bf16_t* __restrict__ Bt, long ldb, int nM, int nN, int K,
;                                            const Epi& epi, bf16_t* shm, int w0) {
;     ...
;       LDB(B0, 0, 0); SCHED; LDA(At, 0, 0); STAGE(SA(1, 1), A, lda, aoff, brow + HALF, t + 1);
;       WAIT_L(8); BAR; WAIT_L(0); MMA(0, 0, At, B0); BAR; SCHED;
;       LDB(B1, 0, 1); STAGE(SB(0, 0), Bt, ldb, boff, bcol, t + 2);
;       BAR; WAIT_L(0); MMA(0, 1, At, B1); BAR;
;       LDA(At, 0, 1); STAGE(SA(0, 0), A, lda, aoff, brow, t + 2);
;       BAR; WAIT_L(0); MMA(1, 0, At, B0); BAR; SCHED;
;       STAGE(SB(0, 1), Bt, ldb, boff, bcol + HALF, t + 2);
;       WAIT_V(6); BAR; MMA(1, 1, At, B1); BAR;
;       LDB(B0, 1, 0); SCHED; LDA(At, 1, 0); STAGE(SA(0, 1), A, lda, aoff, brow + HALF, t + 2);
.LBB0_472:
	s_add_u32 vcc_lo, s8, s80
	s_addc_u32 vcc_hi, s9, s81
	ds_read_b128 v[158:161], v241 offset:1024
	ds_read_b128 v[166:169], v241 offset:3072
	ds_read_b128 v[174:177], v241 offset:5120
	ds_read_b128 v[182:185], v241 offset:7168
	s_mov_b32 m0, s16
	s_add_u32 s98, vcc_lo, s12
	s_addc_u32 s99, vcc_hi, s13
	global_load_lds_dwordx4 v221, s[98:99]
	s_mov_b32 m0, s32
	s_add_u32 s98, vcc_lo, s36
	s_addc_u32 s99, vcc_hi, s37
	global_load_lds_dwordx4 v221, s[98:99]
	s_waitcnt lgkmcnt(8)
	s_waitcnt vmcnt(8)
	s_barrier
	s_waitcnt lgkmcnt(0)
	s_waitcnt lgkmcnt(0)
	v_mfma_f32_16x16x32_bf16 v[126:129], v[138:141], v[154:157], v[126:129]
	ds_read_b128 v[186:189], v207
	v_mfma_f32_16x16x32_bf16 v[122:125], v[146:149], v[154:157], v[122:125]
	v_mfma_f32_16x16x32_bf16 v[118:121], v[138:141], v[162:165], v[118:121]
	ds_read_b128 v[190:193], v207 offset:1024
	v_mfma_f32_16x16x32_bf16 v[114:117], v[146:149], v[162:165], v[114:117]
	v_mfma_f32_16x16x32_bf16 v[110:113], v[138:141], v[170:173], v[110:113]
	ds_read_b128 v[194:197], v207 offset:2048
	v_mfma_f32_16x16x32_bf16 v[106:109], v[146:149], v[170:173], v[106:109]
	v_mfma_f32_16x16x32_bf16 v[102:105], v[138:141], v[178:181], v[102:105]
	ds_read_b128 v[198:201], v207 offset:3072
	v_mfma_f32_16x16x32_bf16 v[98:101], v[146:149], v[178:181], v[98:101]
	v_mfma_f32_16x16x32_bf16 v[126:129], v[142:145], v[158:161], v[126:129]
	v_mfma_f32_16x16x32_bf16 v[122:125], v[150:153], v[158:161], v[122:125]
	v_mfma_f32_16x16x32_bf16 v[118:121], v[142:145], v[166:169], v[118:121]
	v_mfma_f32_16x16x32_bf16 v[114:117], v[150:153], v[166:169], v[114:117]
	v_mfma_f32_16x16x32_bf16 v[110:113], v[142:145], v[174:177], v[110:113]
	v_mfma_f32_16x16x32_bf16 v[106:109], v[150:153], v[174:177], v[106:109]
	v_mfma_f32_16x16x32_bf16 v[102:105], v[142:145], v[182:185], v[102:105]
	v_mfma_f32_16x16x32_bf16 v[98:101], v[150:153], v[182:185], v[98:101]
	s_barrier
	s_add_u32 s0, s6, s80
	s_addc_u32 s1, s7, s81
	s_mov_b32 m0, s44
	s_add_u32 s98, s0, s34
	s_addc_u32 s99, s1, s35
	global_load_lds_dwordx4 v221, s[98:99]
	s_mov_b32 m0, s45
	s_add_u32 s98, s0, s64
	s_addc_u32 s99, s1, s65
	global_load_lds_dwordx4 v221, s[98:99]
	s_barrier
	s_waitcnt lgkmcnt(0)
	s_waitcnt lgkmcnt(0)
	v_mfma_f32_16x16x32_bf16 v[94:97], v[186:189], v[154:157], v[94:97]
	v_mfma_f32_16x16x32_bf16 v[90:93], v[194:197], v[154:157], v[90:93]
	v_mfma_f32_16x16x32_bf16 v[86:89], v[186:189], v[162:165], v[86:89]
	v_mfma_f32_16x16x32_bf16 v[82:85], v[194:197], v[162:165], v[82:85]
	v_mfma_f32_16x16x32_bf16 v[78:81], v[186:189], v[170:173], v[78:81]
	v_mfma_f32_16x16x32_bf16 v[74:77], v[194:197], v[170:173], v[74:77]
	v_mfma_f32_16x16x32_bf16 v[70:73], v[186:189], v[178:181], v[70:73]
	v_mfma_f32_16x16x32_bf16 v[66:69], v[194:197], v[178:181], v[66:69]
	v_mfma_f32_16x16x32_bf16 v[94:97], v[190:193], v[158:161], v[94:97]
	ds_read_b128 v[154:157], v241 offset:16384
	v_mfma_f32_16x16x32_bf16 v[90:93], v[198:201], v[158:161], v[90:93]
	v_mfma_f32_16x16x32_bf16 v[86:89], v[190:193], v[166:169], v[86:89]
	ds_read_b128 v[162:165], v241 offset:18432
	v_mfma_f32_16x16x32_bf16 v[82:85], v[198:201], v[166:169], v[82:85]
	v_mfma_f32_16x16x32_bf16 v[78:81], v[190:193], v[174:177], v[78:81]
	ds_read_b128 v[170:173], v241 offset:20480
	v_mfma_f32_16x16x32_bf16 v[74:77], v[198:201], v[174:177], v[74:77]
	v_mfma_f32_16x16x32_bf16 v[70:73], v[190:193], v[182:185], v[70:73]
	ds_read_b128 v[178:181], v241 offset:22528
	v_mfma_f32_16x16x32_bf16 v[66:69], v[198:201], v[182:185], v[66:69]
	s_barrier
	ds_read_b128 v[158:161], v241 offset:17408
	ds_read_b128 v[166:169], v241 offset:19456
	ds_read_b128 v[174:177], v241 offset:21504
	ds_read_b128 v[182:185], v241 offset:23552
	s_mov_b32 m0, s46
	s_add_u32 s98, vcc_lo, s34
	s_addc_u32 s99, vcc_hi, s35
	global_load_lds_dwordx4 v221, s[98:99]
	s_mov_b32 m0, s47
	s_add_u32 s98, vcc_lo, s64
	s_addc_u32 s99, vcc_hi, s65
	global_load_lds_dwordx4 v221, s[98:99]
	s_waitcnt vmcnt(8)
	s_barrier
	s_waitcnt lgkmcnt(0)
	s_waitcnt lgkmcnt(0)
	v_mfma_f32_16x16x32_bf16 v[62:65], v[138:141], v[154:157], v[62:65]
	v_mfma_f32_16x16x32_bf16 v[58:61], v[146:149], v[154:157], v[58:61]
	v_mfma_f32_16x16x32_bf16 v[54:57], v[138:141], v[162:165], v[54:57]
	v_mfma_f32_16x16x32_bf16 v[50:53], v[146:149], v[162:165], v[50:53]
	v_mfma_f32_16x16x32_bf16 v[46:49], v[138:141], v[170:173], v[46:49]
	v_mfma_f32_16x16x32_bf16 v[42:45], v[146:149], v[170:173], v[42:45]
	v_mfma_f32_16x16x32_bf16 v[38:41], v[138:141], v[178:181], v[38:41]
	v_mfma_f32_16x16x32_bf16 v[34:37], v[146:149], v[178:181], v[34:37]
	v_mfma_f32_16x16x32_bf16 v[62:65], v[142:145], v[158:161], v[62:65]
	v_mfma_f32_16x16x32_bf16 v[58:61], v[150:153], v[158:161], v[58:61]
	v_mfma_f32_16x16x32_bf16 v[54:57], v[142:145], v[166:169], v[54:57]
	v_mfma_f32_16x16x32_bf16 v[50:53], v[150:153], v[166:169], v[50:53]
	v_mfma_f32_16x16x32_bf16 v[46:49], v[142:145], v[174:177], v[46:49]
	v_mfma_f32_16x16x32_bf16 v[42:45], v[150:153], v[174:177], v[42:45]
	v_mfma_f32_16x16x32_bf16 v[38:41], v[142:145], v[182:185], v[38:41]
	v_mfma_f32_16x16x32_bf16 v[34:37], v[150:153], v[182:185], v[34:37]
	s_barrier
	s_mov_b32 m0, s48
	s_add_u32 s98, s0, s68
	s_addc_u32 s99, s1, s69
	global_load_lds_dwordx4 v221, s[98:99]
	s_mov_b32 m0, s49
	s_add_u32 s98, s0, s70
	s_addc_u32 s99, s1, s71
	global_load_lds_dwordx4 v221, s[98:99]
	s_waitcnt vmcnt(8)
	s_barrier
; #define LDA(dst, b, h) for (int m = 0; m < 4; ++m) for (int k = 0; k < 2; ++k) \
;     dst[m][k] = *reinterpret_cast<const bf16x8*>((char*)SA(b, h) + a_thr + (m * 2 + k) * 1024)
; #define LDB(dst, b, h) for (int n = 0; n < 2; ++n) for (int k = 0; k < 2; ++k) \
;     dst[n][k] = *reinterpret_cast<const bf16x8*>((char*)SB(b, h) + b_thr + (n * 2 + k) * 1024)
; #define MMA(ai, bj, At, Btf) do { __builtin_amdgcn_s_setprio(1); \
;     for (int m = 0; m < 4; ++m) for (int n = 0; n < 2; ++n) for (int k = 0; k < 2; ++k) \
;       acc[ai][bj][m][n] = __builtin_amdgcn_mfma_f32_16x16x32_bf16(Btf[n][k], At[m][k], acc[ai][bj][m][n], 0, 0, 0); \
;     __builtin_amdgcn_s_setprio(0); } while (0)
; #define WAIT_V(n) asm volatile("s_waitcnt vmcnt(" #n ")" ::: "memory")
; #define WAIT_L(n) asm volatile("s_waitcnt lgkmcnt(" #n ")" ::: "memory")
; #define BAR __builtin_amdgcn_s_barrier()
; #define SCHED __builtin_amdgcn_sched_barrier(0)
; template <bool OVL, bool PANEL = false, class Epi>
; __device__ __forceinline__ void gemm_phase(const bf16_t* __restrict__ A, long lda, const bf16_t* __restrict__ Bt, long ldb, int nM, int nN, int K,
;                                            const Epi& epi, bf16_t* shm, int w0) {
;     ...
;       WAIT_V(6); BAR; MMA(1, 1, At, B1); BAR;
;       LDB(B0, 1, 0); SCHED; LDA(At, 1, 0); STAGE(SA(0, 1), A, lda, aoff, brow + HALF, t + 2);
;       WAIT_L(8); BAR; WAIT_L(0); MMA(0, 0, At, B0); BAR; SCHED;
;       LDB(B1, 1, 1); STAGE(SB(1, 0), Bt, ldb, boff, bcol, t + 3);
;       BAR; WAIT_L(0); MMA(0, 1, At, B1); BAR;
;       LDA(At, 1, 1); STAGE(SA(1, 0), A, lda, aoff, brow, t + 3);
	v_mfma_f32_16x16x32_bf16 v[30:33], v[186:189], v[154:157], v[30:33]
	ds_read_b128 v[138:141], v208
	v_mfma_f32_16x16x32_bf16 v[26:29], v[194:197], v[154:157], v[26:29]
	v_mfma_f32_16x16x32_bf16 v[22:25], v[186:189], v[162:165], v[22:25]
	ds_read_b128 v[142:145], v208 offset:1024
	v_mfma_f32_16x16x32_bf16 v[18:21], v[194:197], v[162:165], v[18:21]
	v_mfma_f32_16x16x32_bf16 v[14:17], v[186:189], v[170:173], v[14:17]
	ds_read_b128 v[146:149], v208 offset:2048
	v_mfma_f32_16x16x32_bf16 v[10:13], v[194:197], v[170:173], v[10:13]
	v_mfma_f32_16x16x32_bf16 v[6:9], v[186:189], v[178:181], v[6:9]
	ds_read_b128 v[150:153], v208 offset:3072
	v_mfma_f32_16x16x32_bf16 v[2:5], v[194:197], v[178:181], v[2:5]
	v_mfma_f32_16x16x32_bf16 v[30:33], v[190:193], v[158:161], v[30:33]
	ds_read_b128 v[154:157], v241 offset:32768
	v_mfma_f32_16x16x32_bf16 v[26:29], v[198:201], v[158:161], v[26:29]
	v_mfma_f32_16x16x32_bf16 v[22:25], v[190:193], v[166:169], v[22:25]
	ds_read_b128 v[162:165], v241 offset:34816
	v_mfma_f32_16x16x32_bf16 v[18:21], v[198:201], v[166:169], v[18:21]
	v_mfma_f32_16x16x32_bf16 v[14:17], v[190:193], v[174:177], v[14:17]
	ds_read_b128 v[170:173], v241 offset:36864
	v_mfma_f32_16x16x32_bf16 v[10:13], v[198:201], v[174:177], v[10:13]
	v_mfma_f32_16x16x32_bf16 v[6:9], v[190:193], v[182:185], v[6:9]
	ds_read_b128 v[178:181], v241 offset:38912
	v_mfma_f32_16x16x32_bf16 v[2:5], v[198:201], v[182:185], v[2:5]
	s_barrier
	ds_read_b128 v[158:161], v241 offset:33792
	ds_read_b128 v[166:169], v241 offset:35840
	ds_read_b128 v[174:177], v241 offset:37888
	ds_read_b128 v[182:185], v241 offset:39936
	s_mov_b32 m0, s50
	s_add_u32 s98, vcc_lo, s68
	s_addc_u32 s99, vcc_hi, s69
	global_load_lds_dwordx4 v221, s[98:99]
	s_mov_b32 m0, s51
	s_add_u32 s98, vcc_lo, s70
	s_addc_u32 s99, vcc_hi, s71
	global_load_lds_dwordx4 v221, s[98:99]
	s_waitcnt lgkmcnt(8)
	s_waitcnt vmcnt(8)
	s_barrier
	s_waitcnt lgkmcnt(0)
	s_waitcnt lgkmcnt(0)
	v_mfma_f32_16x16x32_bf16 v[126:129], v[138:141], v[154:157], v[126:129]
	ds_read_b128 v[186:189], v209
	v_mfma_f32_16x16x32_bf16 v[122:125], v[146:149], v[154:157], v[122:125]
	v_mfma_f32_16x16x32_bf16 v[118:121], v[138:141], v[162:165], v[118:121]
	ds_read_b128 v[190:193], v209 offset:1024
	v_mfma_f32_16x16x32_bf16 v[114:117], v[146:149], v[162:165], v[114:117]
	v_mfma_f32_16x16x32_bf16 v[110:113], v[138:141], v[170:173], v[110:113]
	ds_read_b128 v[194:197], v209 offset:2048
	v_mfma_f32_16x16x32_bf16 v[106:109], v[146:149], v[170:173], v[106:109]
	v_mfma_f32_16x16x32_bf16 v[102:105], v[138:141], v[178:181], v[102:105]
	ds_read_b128 v[198:201], v209 offset:3072
	v_mfma_f32_16x16x32_bf16 v[98:101], v[146:149], v[178:181], v[98:101]
	v_mfma_f32_16x16x32_bf16 v[126:129], v[142:145], v[158:161], v[126:129]
	v_mfma_f32_16x16x32_bf16 v[122:125], v[150:153], v[158:161], v[122:125]
	v_mfma_f32_16x16x32_bf16 v[118:121], v[142:145], v[166:169], v[118:121]
	v_mfma_f32_16x16x32_bf16 v[114:117], v[150:153], v[166:169], v[114:117]
	v_mfma_f32_16x16x32_bf16 v[110:113], v[142:145], v[174:177], v[110:113]
	v_mfma_f32_16x16x32_bf16 v[106:109], v[150:153], v[174:177], v[106:109]
	v_mfma_f32_16x16x32_bf16 v[102:105], v[142:145], v[182:185], v[102:105]
	v_mfma_f32_16x16x32_bf16 v[98:101], v[150:153], v[182:185], v[98:101]
	s_barrier
	s_mov_b32 m0, s52
	s_add_u32 s98, s0, s94
	s_addc_u32 s99, s1, s95
	global_load_lds_dwordx4 v221, s[98:99]
	s_mov_b32 m0, s53
	s_add_u32 s98, s0, s72
	s_addc_u32 s99, s1, s73
	global_load_lds_dwordx4 v221, s[98:99]
	s_barrier
	s_waitcnt lgkmcnt(0)
	s_waitcnt lgkmcnt(0)
	v_mfma_f32_16x16x32_bf16 v[94:97], v[186:189], v[154:157], v[94:97]
	v_mfma_f32_16x16x32_bf16 v[90:93], v[194:197], v[154:157], v[90:93]
	v_mfma_f32_16x16x32_bf16 v[86:89], v[186:189], v[162:165], v[86:89]
	v_mfma_f32_16x16x32_bf16 v[82:85], v[194:197], v[162:165], v[82:85]
	v_mfma_f32_16x16x32_bf16 v[78:81], v[186:189], v[170:173], v[78:81]
	v_mfma_f32_16x16x32_bf16 v[74:77], v[194:197], v[170:173], v[74:77]
	v_mfma_f32_16x16x32_bf16 v[70:73], v[186:189], v[178:181], v[70:73]
	v_mfma_f32_16x16x32_bf16 v[66:69], v[194:197], v[178:181], v[66:69]
	v_mfma_f32_16x16x32_bf16 v[94:97], v[190:193], v[158:161], v[94:97]
	ds_read_b128 v[154:157], v241 offset:49152
	v_mfma_f32_16x16x32_bf16 v[90:93], v[198:201], v[158:161], v[90:93]
	v_mfma_f32_16x16x32_bf16 v[86:89], v[190:193], v[166:169], v[86:89]
	ds_read_b128 v[162:165], v241 offset:51200
	v_mfma_f32_16x16x32_bf16 v[82:85], v[198:201], v[166:169], v[82:85]
	v_mfma_f32_16x16x32_bf16 v[78:81], v[190:193], v[174:177], v[78:81]
	ds_read_b128 v[170:173], v241 offset:53248
	v_mfma_f32_16x16x32_bf16 v[74:77], v[198:201], v[174:177], v[74:77]
	v_mfma_f32_16x16x32_bf16 v[70:73], v[190:193], v[182:185], v[70:73]
	ds_read_b128 v[178:181], v241 offset:55296
	v_mfma_f32_16x16x32_bf16 v[66:69], v[198:201], v[182:185], v[66:69]
	s_barrier
; #define LDA(dst, b, h) for (int m = 0; m < 4; ++m) for (int k = 0; k < 2; ++k) \
;     dst[m][k] = *reinterpret_cast<const bf16x8*>((char*)SA(b, h) + a_thr + (m * 2 + k) * 1024)
; #define LDB(dst, b, h) for (int n = 0; n < 2; ++n) for (int k = 0; k < 2; ++k) \
;     dst[n][k] = *reinterpret_cast<const bf16x8*>((char*)SB(b, h) + b_thr + (n * 2 + k) * 1024)
; #define MMA(ai, bj, At, Btf) do { __builtin_amdgcn_s_setprio(1); \
;     for (int m = 0; m < 4; ++m) for (int n = 0; n < 2; ++n) for (int k = 0; k < 2; ++k) \
;       acc[ai][bj][m][n] = __builtin_amdgcn_mfma_f32_16x16x32_bf16(Btf[n][k], At[m][k], acc[ai][bj][m][n], 0, 0, 0); \
;     __builtin_amdgcn_s_setprio(0); } while (0)
; #define WAIT_V(n) asm volatile("s_waitcnt vmcnt(" #n ")" ::: "memory")
; #define WAIT_L(n) asm volatile("s_waitcnt lgkmcnt(" #n ")" ::: "memory")
; #define BAR __builtin_amdgcn_s_barrier()
; #define SCHED __builtin_amdgcn_sched_barrier(0)
; template <bool OVL, bool PANEL = false, class Epi>
; __device__ __forceinline__ void gemm_phase(const bf16_t* __restrict__ A, long lda, const bf16_t* __restrict__ Bt, long ldb, int nM, int nN, int K,
;                                            const Epi& epi, bf16_t* shm, int w0) {
;     ...
;       LDA(At, 1, 1); STAGE(SA(1, 0), A, lda, aoff, brow, t + 3);
;       BAR; WAIT_L(0); MMA(1, 0, At, B0); BAR; SCHED;
;       STAGE(SB(1, 1), Bt, ldb, boff, bcol + HALF, t + 3);
;       WAIT_V(6); BAR; MMA(1, 1, At, B1); BAR;
;     }
;     { LDB(B0, 0, 0); LDA(At, 0, 0); STAGE(SA(1, 1), A, lda, aoff, brow + HALF, nt - 1);
	ds_read_b128 v[158:161], v241 offset:50176
	ds_read_b128 v[166:169], v241 offset:52224
	ds_read_b128 v[174:177], v241 offset:54272
	ds_read_b128 v[182:185], v241 offset:56320
	s_mov_b32 m0, s54
	s_add_u32 s98, vcc_lo, s94
	s_addc_u32 s99, vcc_hi, s95
	global_load_lds_dwordx4 v221, s[98:99]
	s_mov_b32 m0, s55
	s_add_u32 s98, vcc_lo, s72
	s_addc_u32 s99, vcc_hi, s73
	global_load_lds_dwordx4 v221, s[98:99]
	s_waitcnt vmcnt(8)
	s_barrier
	s_waitcnt lgkmcnt(0)
	s_waitcnt lgkmcnt(0)
	v_mfma_f32_16x16x32_bf16 v[62:65], v[138:141], v[154:157], v[62:65]
	v_mfma_f32_16x16x32_bf16 v[58:61], v[146:149], v[154:157], v[58:61]
	v_mfma_f32_16x16x32_bf16 v[54:57], v[138:141], v[162:165], v[54:57]
	v_mfma_f32_16x16x32_bf16 v[50:53], v[146:149], v[162:165], v[50:53]
	v_mfma_f32_16x16x32_bf16 v[46:49], v[138:141], v[170:173], v[46:49]
	v_mfma_f32_16x16x32_bf16 v[42:45], v[146:149], v[170:173], v[42:45]
	v_mfma_f32_16x16x32_bf16 v[38:41], v[138:141], v[178:181], v[38:41]
	v_mfma_f32_16x16x32_bf16 v[34:37], v[146:149], v[178:181], v[34:37]
	v_mfma_f32_16x16x32_bf16 v[62:65], v[142:145], v[158:161], v[62:65]
	v_mfma_f32_16x16x32_bf16 v[58:61], v[150:153], v[158:161], v[58:61]
	v_mfma_f32_16x16x32_bf16 v[54:57], v[142:145], v[166:169], v[54:57]
	v_mfma_f32_16x16x32_bf16 v[50:53], v[150:153], v[166:169], v[50:53]
	v_mfma_f32_16x16x32_bf16 v[46:49], v[142:145], v[174:177], v[46:49]
	v_mfma_f32_16x16x32_bf16 v[42:45], v[150:153], v[174:177], v[42:45]
	v_mfma_f32_16x16x32_bf16 v[38:41], v[142:145], v[182:185], v[38:41]
	v_mfma_f32_16x16x32_bf16 v[34:37], v[150:153], v[182:185], v[34:37]
	s_barrier
	s_mov_b32 m0, s56
	s_add_u32 s98, s0, s14
	s_addc_u32 s99, s1, s15
	global_load_lds_dwordx4 v221, s[98:99]
	s_mov_b32 m0, s57
	s_add_u32 s98, s0, s18
	s_addc_u32 s99, s1, s19
	global_load_lds_dwordx4 v221, s[98:99]
	s_waitcnt vmcnt(8)
	s_barrier
	v_mfma_f32_16x16x32_bf16 v[30:33], v[186:189], v[154:157], v[30:33]
	ds_read_b128 v[138:141], v206
	v_mfma_f32_16x16x32_bf16 v[26:29], v[194:197], v[154:157], v[26:29]
	v_mfma_f32_16x16x32_bf16 v[22:25], v[186:189], v[162:165], v[22:25]
	ds_read_b128 v[142:145], v206 offset:1024
	v_mfma_f32_16x16x32_bf16 v[18:21], v[194:197], v[162:165], v[18:21]
	v_mfma_f32_16x16x32_bf16 v[14:17], v[186:189], v[170:173], v[14:17]
	ds_read_b128 v[146:149], v206 offset:2048
	v_mfma_f32_16x16x32_bf16 v[10:13], v[194:197], v[170:173], v[10:13]
	v_mfma_f32_16x16x32_bf16 v[6:9], v[186:189], v[178:181], v[6:9]
	ds_read_b128 v[150:153], v206 offset:3072
	v_mfma_f32_16x16x32_bf16 v[2:5], v[194:197], v[178:181], v[2:5]
	v_mfma_f32_16x16x32_bf16 v[30:33], v[190:193], v[158:161], v[30:33]
	ds_read_b128 v[154:157], v241
	v_mfma_f32_16x16x32_bf16 v[26:29], v[198:201], v[158:161], v[26:29]
	v_mfma_f32_16x16x32_bf16 v[22:25], v[190:193], v[166:169], v[22:25]
	ds_read_b128 v[162:165], v241 offset:2048
	v_mfma_f32_16x16x32_bf16 v[18:21], v[198:201], v[166:169], v[18:21]
	v_mfma_f32_16x16x32_bf16 v[14:17], v[190:193], v[174:177], v[14:17]
	ds_read_b128 v[170:173], v241 offset:4096
	v_mfma_f32_16x16x32_bf16 v[10:13], v[198:201], v[174:177], v[10:13]
	v_mfma_f32_16x16x32_bf16 v[6:9], v[190:193], v[182:185], v[6:9]
	ds_read_b128 v[178:181], v241 offset:6144
	v_mfma_f32_16x16x32_bf16 v[2:5], v[198:201], v[182:185], v[2:5]
	s_add_i32 s2, s2, 2
	s_add_u32 s80, s80, 0x100
	s_addc_u32 s81, s81, 0
	s_cmp_gt_u32 s2, 11
	s_barrier
	s_cbranch_scc0 .LBB0_472
	s_waitcnt vmcnt(6)
	s_or_b32 s0, s82, 0x80
	s_ashr_i32 s1, s0, 31
	v_readlane_b32 s44, v252, 20
	s_lshl_b64 s[0:1], s[0:1], 11
	v_readlane_b32 s50, v252, 26
	v_add_u32_e32 v206, 16, v240
	v_readlane_b32 s51, v252, 27
	s_add_u32 s0, s50, s0
	v_add_u32_e32 v0, 0x10000, v206
	s_addc_u32 s1, s51, s1
	ds_read_b128 v[130:133], v0
	ds_read_b128 v[138:141], v0 offset:1024
	ds_read_b128 v[142:145], v0 offset:2048
	ds_read_b128 v[146:149], v0 offset:3072
	ds_read_b128 v[150:153], v241
	ds_read_b128 v[154:157], v241 offset:1024
	ds_read_b128 v[158:161], v241 offset:2048
	ds_read_b128 v[162:165], v241 offset:3072
	ds_read_b128 v[166:169], v241 offset:4096
	ds_read_b128 v[170:173], v241 offset:5120
	ds_read_b128 v[174:177], v241 offset:6144
	ds_read_b128 v[178:181], v241 offset:7168
	v_mov_b32_e32 v0, v221
	v_readlane_b32 s45, v252, 21
	v_lshl_add_u64 v[134:135], s[0:1], 0, v[0:1]
	s_mov_b64 s[0:1], 0x780
	v_lshl_add_u64 v[182:183], v[134:135], 0, s[0:1]
	v_readfirstlane_b32 s0, v136
	s_mov_b32 m0, s0
	s_mov_b64 s[0:1], 0x20780
	v_lshl_add_u64 v[134:135], v[134:135], 0, s[0:1]
	v_readfirstlane_b32 s0, v137
	global_load_lds_dwordx4 v[182:183], off
	s_mov_b32 m0, s0
	v_readlane_b32 s46, v252, 22
	global_load_lds_dwordx4 v[134:135], off
	s_barrier
	s_waitcnt lgkmcnt(0)
	v_readlane_b32 s47, v252, 23
	v_readlane_b32 s48, v252, 24
	v_readlane_b32 s49, v252, 25
	v_readlane_b32 s52, v252, 28
	v_readlane_b32 s53, v252, 29
	v_readlane_b32 s54, v252, 30
	v_readlane_b32 s55, v252, 31
	v_readlane_b32 s56, v252, 32
	v_readlane_b32 s57, v252, 33
	v_readlane_b32 s58, v252, 34
	v_readlane_b32 s59, v252, 35

; #define LDA(dst, b, h) for (int m = 0; m < 4; ++m) for (int k = 0; k < 2; ++k) \
;     dst[m][k] = *reinterpret_cast<const bf16x8*>((char*)SA(b, h) + a_thr + (m * 2 + k) * 1024)
; #define LDB(dst, b, h) for (int n = 0; n < 2; ++n) for (int k = 0; k < 2; ++k) \
;     dst[n][k] = *reinterpret_cast<const bf16x8*>((char*)SB(b, h) + b_thr + (n * 2 + k) * 1024)
; #define MMA(ai, bj, At, Btf) do { __builtin_amdgcn_s_setprio(1); \
;     for (int m = 0; m < 4; ++m) for (int n = 0; n < 2; ++n) for (int k = 0; k < 2; ++k) \
;       acc[ai][bj][m][n] = __builtin_amdgcn_mfma_f32_16x16x32_bf16(Btf[n][k], At[m][k], acc[ai][bj][m][n], 0, 0, 0); \
;     __builtin_amdgcn_s_setprio(0); } while (0)
; #define WAIT_L(n) asm volatile("s_waitcnt lgkmcnt(" #n ")" ::: "memory")
; #define BAR __builtin_amdgcn_s_barrier()
; template <bool OVL, bool PANEL = false, class Epi>
; __device__ __forceinline__ void gemm_phase(const bf16_t* __restrict__ A, long lda, const bf16_t* __restrict__ Bt, long ldb, int nM, int nN, int K,
;                                            const Epi& epi, bf16_t* shm, int w0) {
;     ...
;     { LDB(B0, 0, 0); LDA(At, 0, 0); STAGE(SA(1, 1), A, lda, aoff, brow + HALF, nt - 1);
;       BAR; WAIT_L(0); MMA(0, 0, At, B0); BAR;
	s_waitcnt lgkmcnt(0)
	v_mfma_f32_16x16x32_bf16 v[126:129], v[130:133], v[150:153], v[126:129]
	v_mfma_f32_16x16x32_bf16 v[122:125], v[142:145], v[150:153], v[122:125]
	v_mfma_f32_16x16x32_bf16 v[118:121], v[130:133], v[158:161], v[118:121]
	v_mfma_f32_16x16x32_bf16 v[114:117], v[142:145], v[158:161], v[114:117]
	v_mfma_f32_16x16x32_bf16 v[106:109], v[142:145], v[166:169], v[106:109]
	v_mfma_f32_16x16x32_bf16 v[102:105], v[130:133], v[174:177], v[102:105]
	v_mfma_f32_16x16x32_bf16 v[98:101], v[142:145], v[174:177], v[98:101]
	v_mfma_f32_16x16x32_bf16 v[126:129], v[138:141], v[154:157], v[126:129]
	v_mfma_f32_16x16x32_bf16 v[122:125], v[146:149], v[154:157], v[122:125]
	v_mfma_f32_16x16x32_bf16 v[118:121], v[138:141], v[162:165], v[118:121]
	v_mfma_f32_16x16x32_bf16 v[114:117], v[146:149], v[162:165], v[114:117]
	v_mfma_f32_16x16x32_bf16 v[110:113], v[130:133], v[166:169], v[110:113]
	v_mfma_f32_16x16x32_bf16 v[106:109], v[146:149], v[170:173], v[106:109]
	v_mfma_f32_16x16x32_bf16 v[102:105], v[138:141], v[178:181], v[102:105]
	v_mfma_f32_16x16x32_bf16 v[98:101], v[146:149], v[178:181], v[98:101]
	v_mfma_f32_16x16x32_bf16 v[134:137], v[138:141], v[170:173], v[110:113]

; #define LDB(dst, b, h) for (int n = 0; n < 2; ++n) for (int k = 0; k < 2; ++k) \
;     dst[n][k] = *reinterpret_cast<const bf16x8*>((char*)SB(b, h) + b_thr + (n * 2 + k) * 1024)
; #define MMA(ai, bj, At, Btf) do { __builtin_amdgcn_s_setprio(1); \
;     for (int m = 0; m < 4; ++m) for (int n = 0; n < 2; ++n) for (int k = 0; k < 2; ++k) \
;       acc[ai][bj][m][n] = __builtin_amdgcn_mfma_f32_16x16x32_bf16(Btf[n][k], At[m][k], acc[ai][bj][m][n], 0, 0, 0); \
;     __builtin_amdgcn_s_setprio(0); } while (0)
; #define WAIT_L(n) asm volatile("s_waitcnt lgkmcnt(" #n ")" ::: "memory")
; #define BAR __builtin_amdgcn_s_barrier()
; template <bool OVL, bool PANEL = false, class Epi>
; __device__ __forceinline__ void gemm_phase(const bf16_t* __restrict__ A, long lda, const bf16_t* __restrict__ Bt, long ldb, int nM, int nN, int K,
;                                            const Epi& epi, bf16_t* shm, int w0) {
;     ...
;       LDB(B1, 0, 1); BAR; WAIT_L(0); MMA(0, 1, At, B1); BAR;
	v_add_u32_e32 v0, 0x14000, v206
	s_barrier
	s_nop 0
	ds_read_b128 v[110:113], v0
	ds_read_b128 v[182:185], v0 offset:1024
	ds_read_b128 v[186:189], v0 offset:2048
	ds_read_b128 v[190:193], v0 offset:3072
	s_barrier
	s_waitcnt lgkmcnt(0)

; #define LDB(dst, b, h) for (int n = 0; n < 2; ++n) for (int k = 0; k < 2; ++k) \
;     dst[n][k] = *reinterpret_cast<const bf16x8*>((char*)SB(b, h) + b_thr + (n * 2 + k) * 1024)
; #define MMA(ai, bj, At, Btf) do { __builtin_amdgcn_s_setprio(1); \
;     for (int m = 0; m < 4; ++m) for (int n = 0; n < 2; ++n) for (int k = 0; k < 2; ++k) \
;       acc[ai][bj][m][n] = __builtin_amdgcn_mfma_f32_16x16x32_bf16(Btf[n][k], At[m][k], acc[ai][bj][m][n], 0, 0, 0); \
;     __builtin_amdgcn_s_setprio(0); } while (0)
; #define WAIT_L(n) asm volatile("s_waitcnt lgkmcnt(" #n ")" ::: "memory")
; #define BAR __builtin_amdgcn_s_barrier()
; template <bool OVL, bool PANEL = false, class Epi>
; __device__ __forceinline__ void gemm_phase(const bf16_t* __restrict__ A, long lda, const bf16_t* __restrict__ Bt, long ldb, int nM, int nN, int K,
;                                            const Epi& epi, bf16_t* shm, int w0) {
;     ...
;       LDB(B1, 0, 1); BAR; WAIT_L(0); MMA(0, 1, At, B1); BAR;
	s_waitcnt lgkmcnt(0)
	v_mfma_f32_16x16x32_bf16 v[90:93], v[186:189], v[150:153], v[90:93]
	v_mfma_f32_16x16x32_bf16 v[74:77], v[186:189], v[166:169], v[74:77]
	v_mfma_f32_16x16x32_bf16 v[70:73], v[110:113], v[174:177], v[70:73]
	v_mfma_f32_16x16x32_bf16 v[66:69], v[186:189], v[174:177], v[66:69]
	v_mfma_f32_16x16x32_bf16 v[94:97], v[110:113], v[150:153], v[94:97]
	v_mfma_f32_16x16x32_bf16 v[90:93], v[190:193], v[154:157], v[90:93]
	v_mfma_f32_16x16x32_bf16 v[86:89], v[110:113], v[158:161], v[86:89]
	v_mfma_f32_16x16x32_bf16 v[82:85], v[186:189], v[158:161], v[82:85]
	v_mfma_f32_16x16x32_bf16 v[78:81], v[110:113], v[166:169], v[78:81]
	v_mfma_f32_16x16x32_bf16 v[74:77], v[190:193], v[170:173], v[74:77]
	v_mfma_f32_16x16x32_bf16 v[70:73], v[182:185], v[178:181], v[70:73]
	v_mfma_f32_16x16x32_bf16 v[66:69], v[190:193], v[178:181], v[66:69]
	v_mfma_f32_16x16x32_bf16 v[194:197], v[182:185], v[154:157], v[94:97]
	v_mfma_f32_16x16x32_bf16 v[150:153], v[182:185], v[162:165], v[86:89]
	v_mfma_f32_16x16x32_bf16 v[154:157], v[190:193], v[162:165], v[82:85]
	v_mfma_f32_16x16x32_bf16 v[158:161], v[182:185], v[170:173], v[78:81]

; #define LDA(dst, b, h) for (int m = 0; m < 4; ++m) for (int k = 0; k < 2; ++k) \
;     dst[m][k] = *reinterpret_cast<const bf16x8*>((char*)SA(b, h) + a_thr + (m * 2 + k) * 1024)
; #define MMA(ai, bj, At, Btf) do { __builtin_amdgcn_s_setprio(1); \
;     for (int m = 0; m < 4; ++m) for (int n = 0; n < 2; ++n) for (int k = 0; k < 2; ++k) \
;       acc[ai][bj][m][n] = __builtin_amdgcn_mfma_f32_16x16x32_bf16(Btf[n][k], At[m][k], acc[ai][bj][m][n], 0, 0, 0); \
;     __builtin_amdgcn_s_setprio(0); } while (0)
; #define WAIT_V(n) asm volatile("s_waitcnt vmcnt(" #n ")" ::: "memory")
; #define WAIT_L(n) asm volatile("s_waitcnt lgkmcnt(" #n ")" ::: "memory")
; #define BAR __builtin_amdgcn_s_barrier()
; template <bool OVL, bool PANEL = false, class Epi>
; __device__ __forceinline__ void gemm_phase(const bf16_t* __restrict__ A, long lda, const bf16_t* __restrict__ Bt, long ldb, int nM, int nN, int K,
;                                            const Epi& epi, bf16_t* shm, int w0) {
;     ...
;       LDA(At, 0, 1); WAIT_V(4); BAR; WAIT_L(0); MMA(1, 0, At, B0); MMA(1, 1, At, B1); BAR; }
	s_barrier
	s_nop 0
	ds_read_b128 v[78:81], v241 offset:16384
	ds_read_b128 v[82:85], v241 offset:17408
	ds_read_b128 v[86:89], v241 offset:18432
	ds_read_b128 v[94:97], v241 offset:19456
	ds_read_b128 v[162:165], v241 offset:20480
	ds_read_b128 v[166:169], v241 offset:21504
	ds_read_b128 v[170:173], v241 offset:22528
	ds_read_b128 v[174:177], v241 offset:23552
	s_waitcnt vmcnt(4)
	s_barrier
	s_waitcnt lgkmcnt(0)

; #define LDA(dst, b, h) for (int m = 0; m < 4; ++m) for (int k = 0; k < 2; ++k) \
;     dst[m][k] = *reinterpret_cast<const bf16x8*>((char*)SA(b, h) + a_thr + (m * 2 + k) * 1024)
; #define MMA(ai, bj, At, Btf) do { __builtin_amdgcn_s_setprio(1); \
;     for (int m = 0; m < 4; ++m) for (int n = 0; n < 2; ++n) for (int k = 0; k < 2; ++k) \
;       acc[ai][bj][m][n] = __builtin_amdgcn_mfma_f32_16x16x32_bf16(Btf[n][k], At[m][k], acc[ai][bj][m][n], 0, 0, 0); \
;     __builtin_amdgcn_s_setprio(0); } while (0)
; #define WAIT_V(n) asm volatile("s_waitcnt vmcnt(" #n ")" ::: "memory")
; #define WAIT_L(n) asm volatile("s_waitcnt lgkmcnt(" #n ")" ::: "memory")
; #define BAR __builtin_amdgcn_s_barrier()
; template <bool OVL, bool PANEL = false, class Epi>
; __device__ __forceinline__ void gemm_phase(const bf16_t* __restrict__ A, long lda, const bf16_t* __restrict__ Bt, long ldb, int nM, int nN, int K,
;                                            const Epi& epi, bf16_t* shm, int w0) {
;     ...
;       LDA(At, 0, 1); WAIT_V(4); BAR; WAIT_L(0); MMA(1, 0, At, B0); MMA(1, 1, At, B1); BAR; }
	s_waitcnt lgkmcnt(0)
	v_mfma_f32_16x16x32_bf16 v[62:65], v[130:133], v[78:81], v[62:65]
	v_mfma_f32_16x16x32_bf16 v[58:61], v[142:145], v[78:81], v[58:61]
	v_mfma_f32_16x16x32_bf16 v[54:57], v[130:133], v[86:89], v[54:57]
	v_mfma_f32_16x16x32_bf16 v[50:53], v[142:145], v[86:89], v[50:53]
	v_mfma_f32_16x16x32_bf16 v[46:49], v[130:133], v[162:165], v[46:49]
	v_mfma_f32_16x16x32_bf16 v[42:45], v[142:145], v[162:165], v[42:45]
	v_mfma_f32_16x16x32_bf16 v[34:37], v[142:145], v[170:173], v[34:37]
	v_mfma_f32_16x16x32_bf16 v[62:65], v[138:141], v[82:85], v[62:65]
	v_mfma_f32_16x16x32_bf16 v[58:61], v[146:149], v[82:85], v[58:61]
	v_mfma_f32_16x16x32_bf16 v[54:57], v[138:141], v[94:97], v[54:57]
	v_mfma_f32_16x16x32_bf16 v[50:53], v[146:149], v[94:97], v[50:53]
	v_mfma_f32_16x16x32_bf16 v[46:49], v[138:141], v[166:169], v[46:49]
	v_mfma_f32_16x16x32_bf16 v[42:45], v[146:149], v[166:169], v[42:45]
	v_mfma_f32_16x16x32_bf16 v[38:41], v[130:133], v[170:173], v[38:41]
	v_mfma_f32_16x16x32_bf16 v[34:37], v[146:149], v[174:177], v[34:37]
	v_mfma_f32_16x16x32_bf16 v[130:133], v[138:141], v[174:177], v[38:41]


; #define LDA(dst, b, h) for (int m = 0; m < 4; ++m) for (int k = 0; k < 2; ++k) \
;     dst[m][k] = *reinterpret_cast<const bf16x8*>((char*)SA(b, h) + a_thr + (m * 2 + k) * 1024)
; #define MMA(ai, bj, At, Btf) do { __builtin_amdgcn_s_setprio(1); \
;     for (int m = 0; m < 4; ++m) for (int n = 0; n < 2; ++n) for (int k = 0; k < 2; ++k) \
;       acc[ai][bj][m][n] = __builtin_amdgcn_mfma_f32_16x16x32_bf16(Btf[n][k], At[m][k], acc[ai][bj][m][n], 0, 0, 0); \
;     __builtin_amdgcn_s_setprio(0); } while (0)
; #define WAIT_V(n) asm volatile("s_waitcnt vmcnt(" #n ")" ::: "memory")
; #define WAIT_L(n) asm volatile("s_waitcnt lgkmcnt(" #n ")" ::: "memory")
; #define BAR __builtin_amdgcn_s_barrier()
; template <bool OVL, bool PANEL = false, class Epi>
; __device__ __forceinline__ void gemm_phase(const bf16_t* __restrict__ A, long lda, const bf16_t* __restrict__ Bt, long ldb, int nM, int nN, int K,
;                                            const Epi& epi, bf16_t* shm, int w0) {
;     ...
;       LDA(At, 0, 1); WAIT_V(4); BAR; WAIT_L(0); MMA(1, 0, At, B0); MMA(1, 1, At, B1); BAR; }
	v_mfma_f32_16x16x32_bf16 v[30:33], v[110:113], v[78:81], v[30:33]
	v_mfma_f32_16x16x32_bf16 v[26:29], v[186:189], v[78:81], v[26:29]
	v_mfma_f32_16x16x32_bf16 v[22:25], v[110:113], v[86:89], v[22:25]
	v_mfma_f32_16x16x32_bf16 v[18:21], v[186:189], v[86:89], v[18:21]
	v_mfma_f32_16x16x32_bf16 v[14:17], v[110:113], v[162:165], v[14:17]
	v_mfma_f32_16x16x32_bf16 v[10:13], v[186:189], v[162:165], v[10:13]
	v_mfma_f32_16x16x32_bf16 v[6:9], v[110:113], v[170:173], v[6:9]
	v_mfma_f32_16x16x32_bf16 v[2:5], v[186:189], v[170:173], v[2:5]
	v_mfma_f32_16x16x32_bf16 v[138:141], v[182:185], v[82:85], v[30:33]
	v_mfma_f32_16x16x32_bf16 v[142:145], v[190:193], v[82:85], v[26:29]
	v_mfma_f32_16x16x32_bf16 v[146:149], v[182:185], v[94:97], v[22:25]
	v_mfma_f32_16x16x32_bf16 v[178:181], v[190:193], v[94:97], v[18:21]
	v_mfma_f32_16x16x32_bf16 v[198:201], v[182:185], v[166:169], v[14:17]
	v_mfma_f32_16x16x32_bf16 v[162:165], v[190:193], v[166:169], v[10:13]
	v_mfma_f32_16x16x32_bf16 v[166:169], v[182:185], v[174:177], v[6:9]
	v_mfma_f32_16x16x32_bf16 v[170:173], v[190:193], v[174:177], v[2:5]

; #define LDA(dst, b, h) for (int m = 0; m < 4; ++m) for (int k = 0; k < 2; ++k) \
;     dst[m][k] = *reinterpret_cast<const bf16x8*>((char*)SA(b, h) + a_thr + (m * 2 + k) * 1024)
; #define LDB(dst, b, h) for (int n = 0; n < 2; ++n) for (int k = 0; k < 2; ++k) \
;     dst[n][k] = *reinterpret_cast<const bf16x8*>((char*)SB(b, h) + b_thr + (n * 2 + k) * 1024)
; #define MMA(ai, bj, At, Btf) do { __builtin_amdgcn_s_setprio(1); \
;     for (int m = 0; m < 4; ++m) for (int n = 0; n < 2; ++n) for (int k = 0; k < 2; ++k) \
;       acc[ai][bj][m][n] = __builtin_amdgcn_mfma_f32_16x16x32_bf16(Btf[n][k], At[m][k], acc[ai][bj][m][n], 0, 0, 0); \
;     __builtin_amdgcn_s_setprio(0); } while (0)
; #define WAIT_V(n) asm volatile("s_waitcnt vmcnt(" #n ")" ::: "memory")
; #define WAIT_L(n) asm volatile("s_waitcnt lgkmcnt(" #n ")" ::: "memory")
; #define BAR __builtin_amdgcn_s_barrier()
; template <bool OVL, bool PANEL = false, class Epi>
; __device__ __forceinline__ void gemm_phase(const bf16_t* __restrict__ A, long lda, const bf16_t* __restrict__ Bt, long ldb, int nM, int nN, int K,
;                                            const Epi& epi, bf16_t* shm, int w0) {
;     ...
;     { LDB(B0, 1, 0); LDA(At, 1, 0); WAIT_V(2); BAR; WAIT_L(0); MMA(0, 0, At, B0); BAR;
	v_add_u32_e32 v0, 0x18000, v206
	s_barrier
	ds_read_b128 v[174:177], v0
	ds_read_b128 v[182:185], v0 offset:1024
	ds_read_b128 v[186:189], v0 offset:2048
	ds_read_b128 v[190:193], v0 offset:3072
	ds_read_b128 v[6:9], v241 offset:32768
	ds_read_b128 v[14:17], v241 offset:33792
	ds_read_b128 v[18:21], v241 offset:34816
	ds_read_b128 v[22:25], v241 offset:35840
	ds_read_b128 v[26:29], v241 offset:36864
	ds_read_b128 v[30:33], v241 offset:37888
	ds_read_b128 v[38:41], v241 offset:38912
	ds_read_b128 v[202:205], v241 offset:39936
	s_waitcnt vmcnt(2)
	s_barrier
	s_waitcnt lgkmcnt(0)

; #define LDA(dst, b, h) for (int m = 0; m < 4; ++m) for (int k = 0; k < 2; ++k) \
;     dst[m][k] = *reinterpret_cast<const bf16x8*>((char*)SA(b, h) + a_thr + (m * 2 + k) * 1024)
; #define LDB(dst, b, h) for (int n = 0; n < 2; ++n) for (int k = 0; k < 2; ++k) \
;     dst[n][k] = *reinterpret_cast<const bf16x8*>((char*)SB(b, h) + b_thr + (n * 2 + k) * 1024)
; #define MMA(ai, bj, At, Btf) do { __builtin_amdgcn_s_setprio(1); \
;     for (int m = 0; m < 4; ++m) for (int n = 0; n < 2; ++n) for (int k = 0; k < 2; ++k) \
;       acc[ai][bj][m][n] = __builtin_amdgcn_mfma_f32_16x16x32_bf16(Btf[n][k], At[m][k], acc[ai][bj][m][n], 0, 0, 0); \
;     __builtin_amdgcn_s_setprio(0); } while (0)
; #define WAIT_V(n) asm volatile("s_waitcnt vmcnt(" #n ")" ::: "memory")
; #define WAIT_L(n) asm volatile("s_waitcnt lgkmcnt(" #n ")" ::: "memory")
; #define BAR __builtin_amdgcn_s_barrier()
; template <bool OVL, bool PANEL = false, class Epi>
; __device__ __forceinline__ void gemm_phase(const bf16_t* __restrict__ A, long lda, const bf16_t* __restrict__ Bt, long ldb, int nM, int nN, int K,
;                                            const Epi& epi, bf16_t* shm, int w0) {
;     ...
;     { LDB(B0, 1, 0); LDA(At, 1, 0); WAIT_V(2); BAR; WAIT_L(0); MMA(0, 0, At, B0); BAR;
	s_waitcnt lgkmcnt(0)
	v_mfma_f32_16x16x32_bf16 v[2:5], v[174:177], v[6:9], v[126:129]
	v_mfma_f32_16x16x32_bf16 v[126:129], v[182:185], v[14:17], v[2:5]
	v_mfma_f32_16x16x32_bf16 v[2:5], v[186:189], v[6:9], v[122:125]
	v_mfma_f32_16x16x32_bf16 v[82:85], v[190:193], v[14:17], v[2:5]
	v_mfma_f32_16x16x32_bf16 v[2:5], v[174:177], v[18:21], v[118:121]
	v_mfma_f32_16x16x32_bf16 v[110:113], v[182:185], v[22:25], v[2:5]
	v_mfma_f32_16x16x32_bf16 v[2:5], v[186:189], v[18:21], v[114:117]
	v_mfma_f32_16x16x32_bf16 v[86:89], v[190:193], v[22:25], v[2:5]
	v_mfma_f32_16x16x32_bf16 v[2:5], v[174:177], v[26:29], v[134:137]
	v_mfma_f32_16x16x32_bf16 v[94:97], v[182:185], v[30:33], v[2:5]
	v_mfma_f32_16x16x32_bf16 v[2:5], v[186:189], v[26:29], v[106:109]
	v_mfma_f32_16x16x32_bf16 v[78:81], v[190:193], v[30:33], v[2:5]
	v_mfma_f32_16x16x32_bf16 v[2:5], v[174:177], v[38:41], v[102:105]
	v_mfma_f32_16x16x32_bf16 v[10:13], v[186:189], v[38:41], v[98:101]
	v_mfma_f32_16x16x32_bf16 v[2:5], v[182:185], v[202:205], v[2:5]
	v_mfma_f32_16x16x32_bf16 v[10:13], v[190:193], v[202:205], v[10:13]

; #define LDB(dst, b, h) for (int n = 0; n < 2; ++n) for (int k = 0; k < 2; ++k) \
;     dst[n][k] = *reinterpret_cast<const bf16x8*>((char*)SB(b, h) + b_thr + (n * 2 + k) * 1024)
; #define MMA(ai, bj, At, Btf) do { __builtin_amdgcn_s_setprio(1); \
;     for (int m = 0; m < 4; ++m) for (int n = 0; n < 2; ++n) for (int k = 0; k < 2; ++k) \
;       acc[ai][bj][m][n] = __builtin_amdgcn_mfma_f32_16x16x32_bf16(Btf[n][k], At[m][k], acc[ai][bj][m][n], 0, 0, 0); \
;     __builtin_amdgcn_s_setprio(0); } while (0)
; #define WAIT_V(n) asm volatile("s_waitcnt vmcnt(" #n ")" ::: "memory")
; #define WAIT_L(n) asm volatile("s_waitcnt lgkmcnt(" #n ")" ::: "memory")
; #define BAR __builtin_amdgcn_s_barrier()
; template <bool OVL, bool PANEL = false, class Epi>
; __device__ __forceinline__ void gemm_phase(const bf16_t* __restrict__ A, long lda, const bf16_t* __restrict__ Bt, long ldb, int nM, int nN, int K,
;                                            const Epi& epi, bf16_t* shm, int w0) {
;     ...
;       LDB(B1, 1, 1); WAIT_V(0); BAR; WAIT_L(0); MMA(0, 1, At, B1); BAR;
	v_add_u32_e32 v0, 0x1c000, v206
	s_barrier
	ds_read_b128 v[122:125], v0
	ds_read_b128 v[134:137], v0 offset:1024
	ds_read_b128 v[206:209], v0 offset:2048
	ds_read_b128 v[210:213], v0 offset:3072
	s_waitcnt vmcnt(0)
	s_barrier
	s_waitcnt lgkmcnt(0)

; #define LDB(dst, b, h) for (int n = 0; n < 2; ++n) for (int k = 0; k < 2; ++k) \
;     dst[n][k] = *reinterpret_cast<const bf16x8*>((char*)SB(b, h) + b_thr + (n * 2 + k) * 1024)
; #define MMA(ai, bj, At, Btf) do { __builtin_amdgcn_s_setprio(1); \
;     for (int m = 0; m < 4; ++m) for (int n = 0; n < 2; ++n) for (int k = 0; k < 2; ++k) \
;       acc[ai][bj][m][n] = __builtin_amdgcn_mfma_f32_16x16x32_bf16(Btf[n][k], At[m][k], acc[ai][bj][m][n], 0, 0, 0); \
;     __builtin_amdgcn_s_setprio(0); } while (0)
; #define WAIT_V(n) asm volatile("s_waitcnt vmcnt(" #n ")" ::: "memory")
; #define WAIT_L(n) asm volatile("s_waitcnt lgkmcnt(" #n ")" ::: "memory")
; #define BAR __builtin_amdgcn_s_barrier()
; template <bool OVL, bool PANEL = false, class Epi>
; __device__ __forceinline__ void gemm_phase(const bf16_t* __restrict__ A, long lda, const bf16_t* __restrict__ Bt, long ldb, int nM, int nN, int K,
;                                            const Epi& epi, bf16_t* shm, int w0) {
;     ...
;       LDB(B1, 1, 1); WAIT_V(0); BAR; WAIT_L(0); MMA(0, 1, At, B1); BAR;
	s_waitcnt lgkmcnt(0)
	v_mfma_f32_16x16x32_bf16 v[98:101], v[122:125], v[6:9], v[194:197]
	v_mfma_f32_16x16x32_bf16 v[6:9], v[206:209], v[6:9], v[90:93]
	v_mfma_f32_16x16x32_bf16 v[114:117], v[210:213], v[14:17], v[6:9]
	v_mfma_f32_16x16x32_bf16 v[6:9], v[122:125], v[18:21], v[150:153]
	v_mfma_f32_16x16x32_bf16 v[102:105], v[134:137], v[22:25], v[6:9]
	v_mfma_f32_16x16x32_bf16 v[6:9], v[206:209], v[18:21], v[154:157]
	v_mfma_f32_16x16x32_bf16 v[118:121], v[210:213], v[22:25], v[6:9]
	v_mfma_f32_16x16x32_bf16 v[6:9], v[122:125], v[26:29], v[158:161]
	v_mfma_f32_16x16x32_bf16 v[90:93], v[134:137], v[30:33], v[6:9]
	v_mfma_f32_16x16x32_bf16 v[6:9], v[206:209], v[26:29], v[74:77]
	v_mfma_f32_16x16x32_bf16 v[106:109], v[210:213], v[30:33], v[6:9]
	v_mfma_f32_16x16x32_bf16 v[6:9], v[122:125], v[38:41], v[70:73]
	v_mfma_f32_16x16x32_bf16 v[22:25], v[134:137], v[202:205], v[6:9]
	v_mfma_f32_16x16x32_bf16 v[6:9], v[206:209], v[38:41], v[66:69]
	v_mfma_f32_16x16x32_bf16 v[98:101], v[134:137], v[14:17], v[98:101]
	v_mfma_f32_16x16x32_bf16 v[38:41], v[210:213], v[202:205], v[6:9]

; #define LDA(dst, b, h) for (int m = 0; m < 4; ++m) for (int k = 0; k < 2; ++k) \
;     dst[m][k] = *reinterpret_cast<const bf16x8*>((char*)SA(b, h) + a_thr + (m * 2 + k) * 1024)
; #define MMA(ai, bj, At, Btf) do { __builtin_amdgcn_s_setprio(1); \
;     for (int m = 0; m < 4; ++m) for (int n = 0; n < 2; ++n) for (int k = 0; k < 2; ++k) \
;       acc[ai][bj][m][n] = __builtin_amdgcn_mfma_f32_16x16x32_bf16(Btf[n][k], At[m][k], acc[ai][bj][m][n], 0, 0, 0); \
;     __builtin_amdgcn_s_setprio(0); } while (0)
; #define WAIT_L(n) asm volatile("s_waitcnt lgkmcnt(" #n ")" ::: "memory")
; #define BAR __builtin_amdgcn_s_barrier()
; template <bool OVL, bool PANEL = false, class Epi>
; __device__ __forceinline__ void gemm_phase(const bf16_t* __restrict__ A, long lda, const bf16_t* __restrict__ Bt, long ldb, int nM, int nN, int K,
;                                            const Epi& epi, bf16_t* shm, int w0) {
;     ...
;       LDA(At, 1, 1); BAR; WAIT_L(0); MMA(1, 0, At, B0); MMA(1, 1, At, B1); BAR; }
	s_barrier
	ds_read_b128 v[70:73], v241 offset:49152
	ds_read_b128 v[74:77], v241 offset:50176
	ds_read_b128 v[150:153], v241 offset:51200
	ds_read_b128 v[154:157], v241 offset:52224
	ds_read_b128 v[158:161], v241 offset:53248
	ds_read_b128 v[194:197], v241 offset:54272
	ds_read_b128 v[202:205], v241 offset:55296
	ds_read_b128 v[214:217], v241 offset:56320
	s_barrier
	s_waitcnt lgkmcnt(0)

; #define LDA(dst, b, h) for (int m = 0; m < 4; ++m) for (int k = 0; k < 2; ++k) \
;     dst[m][k] = *reinterpret_cast<const bf16x8*>((char*)SA(b, h) + a_thr + (m * 2 + k) * 1024)
; #define MMA(ai, bj, At, Btf) do { __builtin_amdgcn_s_setprio(1); \
;     for (int m = 0; m < 4; ++m) for (int n = 0; n < 2; ++n) for (int k = 0; k < 2; ++k) \
;       acc[ai][bj][m][n] = __builtin_amdgcn_mfma_f32_16x16x32_bf16(Btf[n][k], At[m][k], acc[ai][bj][m][n], 0, 0, 0); \
;     __builtin_amdgcn_s_setprio(0); } while (0)
; #define WAIT_L(n) asm volatile("s_waitcnt lgkmcnt(" #n ")" ::: "memory")
; #define BAR __builtin_amdgcn_s_barrier()
; template <bool OVL, bool PANEL = false, class Epi>
; __device__ __forceinline__ void gemm_phase(const bf16_t* __restrict__ A, long lda, const bf16_t* __restrict__ Bt, long ldb, int nM, int nN, int K,
;                                            const Epi& epi, bf16_t* shm, int w0) {
;     ...
;       LDA(At, 1, 1); BAR; WAIT_L(0); MMA(1, 0, At, B0); MMA(1, 1, At, B1); BAR; }
	s_waitcnt lgkmcnt(0)
	v_mfma_f32_16x16x32_bf16 v[14:17], v[186:189], v[70:73], v[58:61]
	v_mfma_f32_16x16x32_bf16 v[42:45], v[186:189], v[158:161], v[42:45]
	v_mfma_f32_16x16x32_bf16 v[6:9], v[174:177], v[70:73], v[62:65]
	v_mfma_f32_16x16x32_bf16 v[18:21], v[190:193], v[74:77], v[14:17]
	v_mfma_f32_16x16x32_bf16 v[14:17], v[174:177], v[150:153], v[54:57]
	v_mfma_f32_16x16x32_bf16 v[26:29], v[186:189], v[150:153], v[50:53]
	v_mfma_f32_16x16x32_bf16 v[30:33], v[174:177], v[158:161], v[46:49]
	v_mfma_f32_16x16x32_bf16 v[46:49], v[190:193], v[194:197], v[42:45]
	v_mfma_f32_16x16x32_bf16 v[42:45], v[174:177], v[202:205], v[130:133]
	v_mfma_f32_16x16x32_bf16 v[34:37], v[186:189], v[202:205], v[34:37]
	v_mfma_f32_16x16x32_bf16 v[6:9], v[182:185], v[74:77], v[6:9]
	v_mfma_f32_16x16x32_bf16 v[14:17], v[182:185], v[154:157], v[14:17]
	v_mfma_f32_16x16x32_bf16 v[26:29], v[190:193], v[154:157], v[26:29]
	v_mfma_f32_16x16x32_bf16 v[30:33], v[182:185], v[194:197], v[30:33]
	v_mfma_f32_16x16x32_bf16 v[54:57], v[182:185], v[214:217], v[42:45]
	v_mfma_f32_16x16x32_bf16 v[66:69], v[190:193], v[214:217], v[34:37]


; #define LDA(dst, b, h) for (int m = 0; m < 4; ++m) for (int k = 0; k < 2; ++k) \
;     dst[m][k] = *reinterpret_cast<const bf16x8*>((char*)SA(b, h) + a_thr + (m * 2 + k) * 1024)
; #define MMA(ai, bj, At, Btf) do { __builtin_amdgcn_s_setprio(1); \
;     for (int m = 0; m < 4; ++m) for (int n = 0; n < 2; ++n) for (int k = 0; k < 2; ++k) \
;       acc[ai][bj][m][n] = __builtin_amdgcn_mfma_f32_16x16x32_bf16(Btf[n][k], At[m][k], acc[ai][bj][m][n], 0, 0, 0); \
;     __builtin_amdgcn_s_setprio(0); } while (0)
; #define WAIT_L(n) asm volatile("s_waitcnt lgkmcnt(" #n ")" ::: "memory")
; #define BAR __builtin_amdgcn_s_barrier()
; template <bool OVL, bool PANEL = false, class Epi>
; __device__ __forceinline__ void gemm_phase(const bf16_t* __restrict__ A, long lda, const bf16_t* __restrict__ Bt, long ldb, int nM, int nN, int K,
;                                            const Epi& epi, bf16_t* shm, int w0) {
;     ...
;       LDA(At, 1, 1); BAR; WAIT_L(0); MMA(1, 0, At, B0); MMA(1, 1, At, B1); BAR; }
	v_mfma_f32_16x16x32_bf16 v[34:37], v[122:125], v[70:73], v[138:141]
	v_mfma_f32_16x16x32_bf16 v[42:45], v[206:209], v[70:73], v[142:145]
	v_mfma_f32_16x16x32_bf16 v[34:37], v[134:137], v[74:77], v[34:37]
	v_mfma_f32_16x16x32_bf16 v[50:53], v[210:213], v[74:77], v[42:45]
	v_mfma_f32_16x16x32_bf16 v[42:45], v[122:125], v[150:153], v[146:149]
	v_mfma_f32_16x16x32_bf16 v[58:61], v[206:209], v[150:153], v[178:181]
	v_mfma_f32_16x16x32_bf16 v[62:65], v[122:125], v[158:161], v[198:201]
	v_mfma_f32_16x16x32_bf16 v[70:73], v[206:209], v[158:161], v[162:165]
	v_mfma_f32_16x16x32_bf16 v[74:77], v[122:125], v[202:205], v[166:169]
	v_mfma_f32_16x16x32_bf16 v[122:125], v[206:209], v[202:205], v[170:173]
	v_mfma_f32_16x16x32_bf16 v[42:45], v[134:137], v[154:157], v[42:45]
	v_mfma_f32_16x16x32_bf16 v[58:61], v[210:213], v[154:157], v[58:61]
	v_mfma_f32_16x16x32_bf16 v[62:65], v[134:137], v[194:197], v[62:65]
	v_mfma_f32_16x16x32_bf16 v[70:73], v[210:213], v[194:197], v[70:73]
	v_mfma_f32_16x16x32_bf16 v[74:77], v[134:137], v[214:217], v[74:77]
	v_mfma_f32_16x16x32_bf16 v[122:125], v[210:213], v[214:217], v[122:125]

; #define LDA(dst, b, h) for (int m = 0; m < 4; ++m) for (int k = 0; k < 2; ++k) \
;     dst[m][k] = *reinterpret_cast<const bf16x8*>((char*)SA(b, h) + a_thr + (m * 2 + k) * 1024)
; #define MMA(ai, bj, At, Btf) do { __builtin_amdgcn_s_setprio(1); \
;     for (int m = 0; m < 4; ++m) for (int n = 0; n < 2; ++n) for (int k = 0; k < 2; ++k) \
;       acc[ai][bj][m][n] = __builtin_amdgcn_mfma_f32_16x16x32_bf16(Btf[n][k], At[m][k], acc[ai][bj][m][n], 0, 0, 0); \
;     __builtin_amdgcn_s_setprio(0); } while (0)
; #define WAIT_L(n) asm volatile("s_waitcnt lgkmcnt(" #n ")" ::: "memory")
; #define BAR __builtin_amdgcn_s_barrier()
; template <bool OVL, bool PANEL = false, class Epi>
; __device__ __forceinline__ void gemm_phase(const bf16_t* __restrict__ A, long lda, const bf16_t* __restrict__ Bt, long ldb, int nM, int nN, int K,
;                                            const Epi& epi, bf16_t* shm, int w0) {
;     ...
;       LDA(At, 1, 1); BAR; WAIT_L(0); MMA(1, 0, At, B0); MMA(1, 1, At, B1); BAR; }
;     if (wr == 0) BAR;
	s_barrier
	s_and_saveexec_b64 s[0:1], s[90:91]
	s_cbranch_execz .LBB0_475
	s_barrier

; #define LDA(dst, b, h) for (int m = 0; m < 4; ++m) for (int k = 0; k < 2; ++k) \
;     dst[m][k] = *reinterpret_cast<const bf16x8*>((char*)SA(b, h) + a_thr + (m * 2 + k) * 1024)
; #define LDB(dst, b, h) for (int n = 0; n < 2; ++n) for (int k = 0; k < 2; ++k) \
;     dst[n][k] = *reinterpret_cast<const bf16x8*>((char*)SB(b, h) + b_thr + (n * 2 + k) * 1024)
; #define WAIT_V(n) asm volatile("s_waitcnt vmcnt(" #n ")" ::: "memory")
; #define BAR __builtin_amdgcn_s_barrier()
; #define SCHED __builtin_amdgcn_sched_barrier(0)
; template <bool OVL, bool PANEL = false, class Epi>
; __device__ __forceinline__ void gemm_phase(const bf16_t* __restrict__ A, long lda, const bf16_t* __restrict__ Bt, long ldb, int nM, int nN, int K,
;                                            const Epi& epi, bf16_t* shm, int w0) {
;     ...
;   for (int it = 0; have; ++it) {
;     const int brow = pm * BM, bcol = pn * BM;
;     f32x4 acc[2][2][4][2];
; #pragma unroll
;     for (int a0 = 0; a0 < 2; ++a0)
; #pragma unroll
;       for (int a1 = 0; a1 < 2; ++a1)
; #pragma unroll
;         for (int a2 = 0; a2 < 4; ++a2)
; #pragma unroll
;           for (int a3 = 0; a3 < 2; ++a3) acc[a0][a1][a2][a3] = (f32x4){0.f, 0.f, 0.f, 0.f};
;     bf16x8 At[4][2], B0[2][2], B1[2][2];
;     if (wr == 1) BAR;
;     WAIT_V(4); BAR;
;     STAGE(SB(1, 0), Bt, ldb, boff, bcol, 1); STAGE(SA(1, 0), A, lda, aoff, brow, 1); STAGE(SB(1, 1), Bt, ldb, boff, bcol + HALF, 1);
;     WAIT_V(6); BAR;
;     for (int t = 0; t < nt - 2; t += 2) {
;       LDB(B0, 0, 0); SCHED; LDA(At, 0, 0); STAGE(SA(1, 1), A, lda, aoff, brow + HALF, t + 1);
.LBB0_1052:
	s_or_b64 exec, exec, s[0:1]
	s_lshl_b32 s12, s57, 8
	s_ashr_i32 s13, s12, 31
	v_readlane_b32 s16, v252, 3
	s_lshl_b32 s0, s58, 8
	s_lshl_b64 s[8:9], s[12:13], 11
	v_readlane_b32 s22, v252, 9
	v_readlane_b32 s23, v252, 10
	s_add_u32 s8, s22, s8
	v_readlane_b32 s17, v252, 4
	s_addc_u32 s9, s23, s9
	v_mov_b32_e32 v0, v135
	v_add_u32_e32 v130, s96, v134
	s_waitcnt vmcnt(4)
	s_barrier
	s_mov_b64 s[16:17], 0x80
	v_lshl_add_u64 v[2:3], s[8:9], 0, v[0:1]
	v_readfirstlane_b32 s1, v130
	v_add_u32_e32 v131, 0x2000, v130
	v_lshl_add_u64 v[4:5], v[2:3], 0, s[16:17]
	s_mov_b32 m0, s1
	v_readfirstlane_b32 s1, v131
	global_load_lds_dwordx4 v[4:5], off
	s_mov_b32 m0, s1
	s_ashr_i32 s1, s0, 31
	v_readlane_b32 s40, v252, 20
	s_lshl_b64 s[10:11], s[0:1], 11
	v_readlane_b32 s46, v252, 26
	v_readlane_b32 s18, v252, 5
	v_readlane_b32 s19, v252, 6
	v_readlane_b32 s47, v252, 27
	s_add_u32 s10, s46, s10
	s_mov_b64 s[18:19], 0x20080
	s_addc_u32 s11, s47, s11
	s_or_b32 s14, s12, 0x80
	v_lshl_add_u64 v[2:3], v[2:3], 0, s[18:19]
	v_mov_b32_e32 v0, v135
	v_add_u32_e32 v132, 0x8000, v138
	s_ashr_i32 s15, s14, 31
	global_load_lds_dwordx4 v[2:3], off
	v_readfirstlane_b32 s1, v132
	v_lshl_add_u64 v[2:3], s[10:11], 0, v[0:1]
	v_add_u32_e32 v133, 0xa000, v138
	s_lshl_b64 s[14:15], s[14:15], 11
	v_lshl_add_u64 v[4:5], v[2:3], 0, s[16:17]
	s_mov_b32 m0, s1
	v_readfirstlane_b32 s1, v133
	s_add_u32 s14, s22, s14
	global_load_lds_dwordx4 v[4:5], off
	v_lshl_add_u64 v[2:3], v[2:3], 0, s[18:19]
	s_mov_b32 m0, s1
	s_addc_u32 s15, s23, s15
	v_mov_b32_e32 v0, v135
	v_add_u32_e32 v148, s75, v134
	global_load_lds_dwordx4 v[2:3], off
	v_readfirstlane_b32 s1, v148
	v_lshl_add_u64 v[2:3], s[14:15], 0, v[0:1]
	v_add_u32_e32 v149, 0x2000, v148
	v_lshl_add_u64 v[4:5], v[2:3], 0, s[16:17]
	s_mov_b32 m0, s1
	v_readfirstlane_b32 s1, v149
	global_load_lds_dwordx4 v[4:5], off
	v_lshl_add_u64 v[2:3], v[2:3], 0, s[18:19]
	s_mov_b32 m0, s1
	v_readlane_b32 s20, v252, 7
	global_load_lds_dwordx4 v[2:3], off
	s_waitcnt vmcnt(6)
	v_readlane_b32 s21, v252, 8
	v_mov_b32_e32 v2, 0
	s_mov_b32 s1, -2
	s_mov_b64 s[14:15], 0
	v_mov_b32_e32 v3, v2
	v_mov_b32_e32 v4, v2
	v_mov_b32_e32 v5, v2
	v_mov_b32_e32 v6, v2
	v_mov_b32_e32 v7, v2
	v_mov_b32_e32 v8, v2
	v_mov_b32_e32 v9, v2
	v_mov_b32_e32 v10, v2
	v_mov_b32_e32 v11, v2
	v_mov_b32_e32 v12, v2
	v_mov_b32_e32 v13, v2
	s_waitcnt lgkmcnt(0)
	v_mov_b32_e32 v14, v2
	v_mov_b32_e32 v15, v2
	v_mov_b32_e32 v16, v2
	v_mov_b32_e32 v17, v2
	v_mov_b32_e32 v18, v2
	v_mov_b32_e32 v19, v2
	v_mov_b32_e32 v20, v2
	v_mov_b32_e32 v21, v2
	v_mov_b32_e32 v22, v2
	v_mov_b32_e32 v23, v2
	v_mov_b32_e32 v24, v2
	v_mov_b32_e32 v25, v2
	v_mov_b32_e32 v26, v2
	v_mov_b32_e32 v27, v2
	v_mov_b32_e32 v28, v2
	v_mov_b32_e32 v29, v2
	v_mov_b32_e32 v30, v2
	v_mov_b32_e32 v31, v2
	v_mov_b32_e32 v32, v2
	v_mov_b32_e32 v33, v2
	v_mov_b32_e32 v34, v2
	v_mov_b32_e32 v35, v2
	v_mov_b32_e32 v36, v2
	v_mov_b32_e32 v37, v2
	v_mov_b32_e32 v38, v2
	v_mov_b32_e32 v39, v2
	v_mov_b32_e32 v40, v2
	v_mov_b32_e32 v41, v2
	v_mov_b32_e32 v42, v2
	v_mov_b32_e32 v43, v2
	v_mov_b32_e32 v44, v2
	v_mov_b32_e32 v45, v2
	v_mov_b32_e32 v46, v2
	v_mov_b32_e32 v47, v2
	v_mov_b32_e32 v48, v2
	v_mov_b32_e32 v49, v2
	v_mov_b32_e32 v50, v2
	v_mov_b32_e32 v51, v2
	v_mov_b32_e32 v52, v2
	v_mov_b32_e32 v53, v2
	v_mov_b32_e32 v54, v2
	v_mov_b32_e32 v55, v2
	v_mov_b32_e32 v56, v2
	v_mov_b32_e32 v57, v2
	v_mov_b32_e32 v58, v2
	v_mov_b32_e32 v59, v2
	v_mov_b32_e32 v60, v2
	v_mov_b32_e32 v61, v2
	v_mov_b32_e32 v62, v2
	v_mov_b32_e32 v63, v2
	v_mov_b32_e32 v64, v2
	v_mov_b32_e32 v65, v2
	v_mov_b32_e32 v66, v2
	v_mov_b32_e32 v67, v2
	v_mov_b32_e32 v68, v2
	v_mov_b32_e32 v69, v2
	v_mov_b32_e32 v70, v2
	v_mov_b32_e32 v71, v2
	v_mov_b32_e32 v72, v2
	v_mov_b32_e32 v73, v2
	v_mov_b32_e32 v74, v2
	v_mov_b32_e32 v75, v2
	v_mov_b32_e32 v76, v2
	v_mov_b32_e32 v77, v2
	v_mov_b32_e32 v78, v2
	v_mov_b32_e32 v79, v2
	v_mov_b32_e32 v80, v2
	v_mov_b32_e32 v81, v2
	v_mov_b32_e32 v82, v2
	v_mov_b32_e32 v83, v2
	v_mov_b32_e32 v84, v2
	v_mov_b32_e32 v85, v2
	v_mov_b32_e32 v86, v2
	v_mov_b32_e32 v87, v2
	v_mov_b32_e32 v88, v2
	v_mov_b32_e32 v89, v2
	v_mov_b32_e32 v90, v2
	v_mov_b32_e32 v91, v2
	v_mov_b32_e32 v92, v2
	v_mov_b32_e32 v93, v2
	v_mov_b32_e32 v94, v2
	v_mov_b32_e32 v95, v2
	v_mov_b32_e32 v96, v2
	v_mov_b32_e32 v97, v2
	v_mov_b32_e32 v98, v2
	v_mov_b32_e32 v99, v2
	v_mov_b32_e32 v100, v2
	v_mov_b32_e32 v101, v2
	v_mov_b32_e32 v102, v2
	v_mov_b32_e32 v103, v2
	v_mov_b32_e32 v104, v2
	v_mov_b32_e32 v105, v2
	v_mov_b32_e32 v106, v2
	v_mov_b32_e32 v107, v2
	v_mov_b32_e32 v108, v2
	v_mov_b32_e32 v109, v2
	v_mov_b32_e32 v110, v2
	v_mov_b32_e32 v111, v2
	v_mov_b32_e32 v112, v2
	v_mov_b32_e32 v113, v2
	v_mov_b32_e32 v114, v2
	v_mov_b32_e32 v115, v2
	v_mov_b32_e32 v116, v2
	v_mov_b32_e32 v117, v2
	v_mov_b32_e32 v118, v2
	v_mov_b32_e32 v119, v2
	v_mov_b32_e32 v120, v2
	v_mov_b32_e32 v121, v2
	v_mov_b32_e32 v122, v2
	v_mov_b32_e32 v123, v2
	v_mov_b32_e32 v124, v2
	v_mov_b32_e32 v125, v2
	v_mov_b32_e32 v126, v2
	v_mov_b32_e32 v127, v2
	v_mov_b32_e32 v128, v2
	v_mov_b32_e32 v129, v2
	s_mov_b64 s[16:17], 0x40080
	s_mov_b64 s[18:19], 0x40180
	s_mov_b64 s[20:21], 0x60180
	v_readlane_b32 s24, v252, 11
	v_readlane_b32 s25, v252, 12
	v_readlane_b32 s26, v252, 13
	v_readlane_b32 s27, v252, 14
	v_readlane_b32 s28, v252, 15
	v_readlane_b32 s29, v252, 16
	v_readlane_b32 s30, v252, 17
	v_readlane_b32 s31, v252, 18
	v_readlane_b32 s41, v252, 21
	v_readlane_b32 s42, v252, 22
	v_readlane_b32 s43, v252, 23
	v_readlane_b32 s44, v252, 24
	v_readlane_b32 s45, v252, 25
	v_readlane_b32 s48, v252, 28
	v_readlane_b32 s49, v252, 29
	v_readlane_b32 s50, v252, 30
	v_readlane_b32 s51, v252, 31
	v_readlane_b32 s52, v252, 32
	v_readlane_b32 s53, v252, 33
	v_readlane_b32 s54, v252, 34
	v_readlane_b32 s55, v252, 35
	s_barrier
	v_add_u32_e32 v184, s2, v144
	v_readfirstlane_b32 s22, v138
	s_add_u32 s22, s22, 0xc000
	v_readfirstlane_b32 s23, v138
	s_add_u32 s23, s23, 0xe000
	v_add_u32_e32 v185, s33, v144
	v_readfirstlane_b32 s24, v136
	v_readfirstlane_b32 s25, v137
	v_readfirstlane_b32 s26, v138
	v_readfirstlane_b32 s27, v139
	v_readfirstlane_b32 s28, v140
	v_readfirstlane_b32 s29, v141
	v_add_u32_e32 v186, s96, v144
	v_readfirstlane_b32 s30, v142
	v_readfirstlane_b32 s31, v143
	v_add_u32_e32 v187, s75, v144
	v_readfirstlane_b32 s32, v130
	v_readfirstlane_b32 s44, v131
	v_readfirstlane_b32 s45, v132
	v_readfirstlane_b32 s46, v133
	v_readfirstlane_b32 s47, v148
	v_readfirstlane_b32 s48, v149
	v_add_u32_e32 v150, 0xc000, v138
	v_add_u32_e32 v151, 0xe000, v138
	ds_read_b128 v[152:155], v184
	ds_read_b128 v[156:159], v184 offset:1024
	ds_read_b128 v[160:163], v184 offset:2048
	ds_read_b128 v[164:167], v184 offset:3072
	ds_read_b128 v[168:171], v147
	ds_read_b128 v[176:179], v147 offset:2048
	ds_read_b128 v[198:201], v147 offset:4096
	ds_read_b128 v[206:209], v147 offset:6144
; #define LDA(dst, b, h) for (int m = 0; m < 4; ++m) for (int k = 0; k < 2; ++k) \
;     dst[m][k] = *reinterpret_cast<const bf16x8*>((char*)SA(b, h) + a_thr + (m * 2 + k) * 1024)
; #define LDB(dst, b, h) for (int n = 0; n < 2; ++n) for (int k = 0; k < 2; ++k) \
;     dst[n][k] = *reinterpret_cast<const bf16x8*>((char*)SB(b, h) + b_thr + (n * 2 + k) * 1024)
; #define MMA(ai, bj, At, Btf) do { __builtin_amdgcn_s_setprio(1); \
;     for (int m = 0; m < 4; ++m) for (int n = 0; n < 2; ++n) for (int k = 0; k < 2; ++k) \
;       acc[ai][bj][m][n] = __builtin_amdgcn_mfma_f32_16x16x32_bf16(Btf[n][k], At[m][k], acc[ai][bj][m][n], 0, 0, 0); \
;     __builtin_amdgcn_s_setprio(0); } while (0)
; #define WAIT_V(n) asm volatile("s_waitcnt vmcnt(" #n ")" ::: "memory")
; #define WAIT_L(n) asm volatile("s_waitcnt lgkmcnt(" #n ")" ::: "memory")
; #define BAR __builtin_amdgcn_s_barrier()
; #define SCHED __builtin_amdgcn_sched_barrier(0)
; template <bool OVL, bool PANEL = false, class Epi>
; __device__ __forceinline__ void gemm_phase(const bf16_t* __restrict__ A, long lda, const bf16_t* __restrict__ Bt, long ldb, int nM, int nN, int K,
;                                            const Epi& epi, bf16_t* shm, int w0) {
;     ...
;       LDB(B0, 0, 0); SCHED; LDA(At, 0, 0); STAGE(SA(1, 1), A, lda, aoff, brow + HALF, t + 1);
;       WAIT_L(8); BAR; WAIT_L(0); MMA(0, 0, At, B0); BAR; SCHED;
;       LDB(B1, 0, 1); STAGE(SB(0, 0), Bt, ldb, boff, bcol, t + 2);
;       BAR; WAIT_L(0); MMA(0, 1, At, B1); BAR;
;       LDA(At, 0, 1); STAGE(SA(0, 0), A, lda, aoff, brow, t + 2);
;       BAR; WAIT_L(0); MMA(1, 0, At, B0); BAR; SCHED;
;       STAGE(SB(0, 1), Bt, ldb, boff, bcol + HALF, t + 2);
;       WAIT_V(6); BAR; MMA(1, 1, At, B1); BAR;
;       LDB(B0, 1, 0); SCHED; LDA(At, 1, 0); STAGE(SA(0, 1), A, lda, aoff, brow + HALF, t + 2);
.LBB0_1053:
	s_add_u32 s40, s10, s14
	s_addc_u32 s41, s11, s15
	ds_read_b128 v[172:175], v147 offset:1024
	ds_read_b128 v[194:197], v147 offset:3072
	ds_read_b128 v[202:205], v147 offset:5120
	ds_read_b128 v[210:213], v147 offset:7168
	s_mov_b32 m0, s22
	s_add_u32 s98, s40, s16
	s_addc_u32 s99, s41, s17
	global_load_lds_dwordx4 v135, s[98:99]
	s_mov_b32 m0, s23
	s_add_u32 s98, s40, s36
	s_addc_u32 s99, s41, s37
	global_load_lds_dwordx4 v135, s[98:99]
	s_waitcnt lgkmcnt(8)
	s_waitcnt vmcnt(8)
	s_barrier
	s_waitcnt lgkmcnt(0)
	s_waitcnt lgkmcnt(0)
	v_mfma_f32_16x16x32_bf16 v[126:129], v[152:155], v[168:171], v[126:129]
	ds_read_b128 v[214:217], v185
	v_mfma_f32_16x16x32_bf16 v[122:125], v[160:163], v[168:171], v[122:125]
	v_mfma_f32_16x16x32_bf16 v[118:121], v[152:155], v[176:179], v[118:121]
	ds_read_b128 v[218:221], v185 offset:1024
	v_mfma_f32_16x16x32_bf16 v[114:117], v[160:163], v[176:179], v[114:117]
	v_mfma_f32_16x16x32_bf16 v[110:113], v[152:155], v[198:201], v[110:113]
	ds_read_b128 v[234:237], v185 offset:2048
	v_mfma_f32_16x16x32_bf16 v[106:109], v[160:163], v[198:201], v[106:109]
	v_mfma_f32_16x16x32_bf16 v[102:105], v[152:155], v[206:209], v[102:105]
	ds_read_b128 v[238:241], v185 offset:3072
	v_mfma_f32_16x16x32_bf16 v[98:101], v[160:163], v[206:209], v[98:101]
	v_mfma_f32_16x16x32_bf16 v[126:129], v[156:159], v[172:175], v[126:129]
	v_mfma_f32_16x16x32_bf16 v[122:125], v[164:167], v[172:175], v[122:125]
	v_mfma_f32_16x16x32_bf16 v[118:121], v[156:159], v[194:197], v[118:121]
	v_mfma_f32_16x16x32_bf16 v[114:117], v[164:167], v[194:197], v[114:117]
	v_mfma_f32_16x16x32_bf16 v[110:113], v[156:159], v[202:205], v[110:113]
	v_mfma_f32_16x16x32_bf16 v[106:109], v[164:167], v[202:205], v[106:109]
	v_mfma_f32_16x16x32_bf16 v[102:105], v[156:159], v[210:213], v[102:105]
	v_mfma_f32_16x16x32_bf16 v[98:101], v[164:167], v[210:213], v[98:101]
	s_barrier
	s_add_u32 s42, s8, s14
	s_addc_u32 s43, s9, s15
	s_mov_b32 m0, s24
	s_add_u32 s98, s42, s34
	s_addc_u32 s99, s43, s35
	global_load_lds_dwordx4 v135, s[98:99]
	s_mov_b32 m0, s25
	s_add_u32 s98, s42, s64
	s_addc_u32 s99, s43, s65
	global_load_lds_dwordx4 v135, s[98:99]
	s_barrier
	s_waitcnt lgkmcnt(0)
	s_waitcnt lgkmcnt(0)
	v_mfma_f32_16x16x32_bf16 v[94:97], v[214:217], v[168:171], v[94:97]
	v_mfma_f32_16x16x32_bf16 v[90:93], v[234:237], v[168:171], v[90:93]
	v_mfma_f32_16x16x32_bf16 v[86:89], v[214:217], v[176:179], v[86:89]
	v_mfma_f32_16x16x32_bf16 v[82:85], v[234:237], v[176:179], v[82:85]
	v_mfma_f32_16x16x32_bf16 v[78:81], v[214:217], v[198:201], v[78:81]
	v_mfma_f32_16x16x32_bf16 v[74:77], v[234:237], v[198:201], v[74:77]
	v_mfma_f32_16x16x32_bf16 v[70:73], v[214:217], v[206:209], v[70:73]
	v_mfma_f32_16x16x32_bf16 v[66:69], v[234:237], v[206:209], v[66:69]
	v_mfma_f32_16x16x32_bf16 v[94:97], v[218:221], v[172:175], v[94:97]
	ds_read_b128 v[168:171], v147 offset:16384
	v_mfma_f32_16x16x32_bf16 v[90:93], v[238:241], v[172:175], v[90:93]
	v_mfma_f32_16x16x32_bf16 v[86:89], v[218:221], v[194:197], v[86:89]
	ds_read_b128 v[176:179], v147 offset:18432
	v_mfma_f32_16x16x32_bf16 v[82:85], v[238:241], v[194:197], v[82:85]
	v_mfma_f32_16x16x32_bf16 v[78:81], v[218:221], v[202:205], v[78:81]
	ds_read_b128 v[198:201], v147 offset:20480
	v_mfma_f32_16x16x32_bf16 v[74:77], v[238:241], v[202:205], v[74:77]
	v_mfma_f32_16x16x32_bf16 v[70:73], v[218:221], v[210:213], v[70:73]
	ds_read_b128 v[206:209], v147 offset:22528
	v_mfma_f32_16x16x32_bf16 v[66:69], v[238:241], v[210:213], v[66:69]
	s_barrier
	ds_read_b128 v[172:175], v147 offset:17408
	ds_read_b128 v[194:197], v147 offset:19456
	ds_read_b128 v[202:205], v147 offset:21504
	ds_read_b128 v[210:213], v147 offset:23552
	s_mov_b32 m0, s26
	s_add_u32 s98, s40, s34
	s_addc_u32 s99, s41, s35
	global_load_lds_dwordx4 v135, s[98:99]
	s_mov_b32 m0, s27
	s_add_u32 s98, s40, s64
	s_addc_u32 s99, s41, s65
	global_load_lds_dwordx4 v135, s[98:99]
	s_waitcnt vmcnt(8)
	s_barrier
	s_waitcnt lgkmcnt(0)
	s_waitcnt lgkmcnt(0)
	v_mfma_f32_16x16x32_bf16 v[62:65], v[152:155], v[168:171], v[62:65]
	v_mfma_f32_16x16x32_bf16 v[58:61], v[160:163], v[168:171], v[58:61]
	v_mfma_f32_16x16x32_bf16 v[54:57], v[152:155], v[176:179], v[54:57]
	v_mfma_f32_16x16x32_bf16 v[50:53], v[160:163], v[176:179], v[50:53]
	v_mfma_f32_16x16x32_bf16 v[46:49], v[152:155], v[198:201], v[46:49]
	v_mfma_f32_16x16x32_bf16 v[42:45], v[160:163], v[198:201], v[42:45]
	v_mfma_f32_16x16x32_bf16 v[38:41], v[152:155], v[206:209], v[38:41]
	v_mfma_f32_16x16x32_bf16 v[34:37], v[160:163], v[206:209], v[34:37]
	v_mfma_f32_16x16x32_bf16 v[62:65], v[156:159], v[172:175], v[62:65]
	v_mfma_f32_16x16x32_bf16 v[58:61], v[164:167], v[172:175], v[58:61]
	v_mfma_f32_16x16x32_bf16 v[54:57], v[156:159], v[194:197], v[54:57]
	v_mfma_f32_16x16x32_bf16 v[50:53], v[164:167], v[194:197], v[50:53]
	v_mfma_f32_16x16x32_bf16 v[46:49], v[156:159], v[202:205], v[46:49]
	v_mfma_f32_16x16x32_bf16 v[42:45], v[164:167], v[202:205], v[42:45]
	v_mfma_f32_16x16x32_bf16 v[38:41], v[156:159], v[210:213], v[38:41]
	v_mfma_f32_16x16x32_bf16 v[34:37], v[164:167], v[210:213], v[34:37]
	s_barrier
	s_mov_b32 m0, s28
	s_add_u32 s98, s42, s68
	s_addc_u32 s99, s43, s69
	global_load_lds_dwordx4 v135, s[98:99]
	s_mov_b32 m0, s29
	s_add_u32 s98, s42, s70
	s_addc_u32 s99, s43, s71
	global_load_lds_dwordx4 v135, s[98:99]
	s_waitcnt vmcnt(8)
	s_barrier
; #define LDA(dst, b, h) for (int m = 0; m < 4; ++m) for (int k = 0; k < 2; ++k) \
;     dst[m][k] = *reinterpret_cast<const bf16x8*>((char*)SA(b, h) + a_thr + (m * 2 + k) * 1024)
; #define LDB(dst, b, h) for (int n = 0; n < 2; ++n) for (int k = 0; k < 2; ++k) \
;     dst[n][k] = *reinterpret_cast<const bf16x8*>((char*)SB(b, h) + b_thr + (n * 2 + k) * 1024)
; #define MMA(ai, bj, At, Btf) do { __builtin_amdgcn_s_setprio(1); \
;     for (int m = 0; m < 4; ++m) for (int n = 0; n < 2; ++n) for (int k = 0; k < 2; ++k) \
;       acc[ai][bj][m][n] = __builtin_amdgcn_mfma_f32_16x16x32_bf16(Btf[n][k], At[m][k], acc[ai][bj][m][n], 0, 0, 0); \
;     __builtin_amdgcn_s_setprio(0); } while (0)
; #define WAIT_V(n) asm volatile("s_waitcnt vmcnt(" #n ")" ::: "memory")
; #define WAIT_L(n) asm volatile("s_waitcnt lgkmcnt(" #n ")" ::: "memory")
; #define BAR __builtin_amdgcn_s_barrier()
; #define SCHED __builtin_amdgcn_sched_barrier(0)
; template <bool OVL, bool PANEL = false, class Epi>
; __device__ __forceinline__ void gemm_phase(const bf16_t* __restrict__ A, long lda, const bf16_t* __restrict__ Bt, long ldb, int nM, int nN, int K,
;                                            const Epi& epi, bf16_t* shm, int w0) {
;     ...
;       WAIT_V(6); BAR; MMA(1, 1, At, B1); BAR;
;       LDB(B0, 1, 0); SCHED; LDA(At, 1, 0); STAGE(SA(0, 1), A, lda, aoff, brow + HALF, t + 2);
;       WAIT_L(8); BAR; WAIT_L(0); MMA(0, 0, At, B0); BAR; SCHED;
;       LDB(B1, 1, 1); STAGE(SB(1, 0), Bt, ldb, boff, bcol, t + 3);
;       BAR; WAIT_L(0); MMA(0, 1, At, B1); BAR;
;       LDA(At, 1, 1); STAGE(SA(1, 0), A, lda, aoff, brow, t + 3);
	v_mfma_f32_16x16x32_bf16 v[30:33], v[214:217], v[168:171], v[30:33]
	ds_read_b128 v[152:155], v186
	v_mfma_f32_16x16x32_bf16 v[26:29], v[234:237], v[168:171], v[26:29]
	v_mfma_f32_16x16x32_bf16 v[22:25], v[214:217], v[176:179], v[22:25]
	ds_read_b128 v[156:159], v186 offset:1024
	v_mfma_f32_16x16x32_bf16 v[18:21], v[234:237], v[176:179], v[18:21]
	v_mfma_f32_16x16x32_bf16 v[14:17], v[214:217], v[198:201], v[14:17]
	ds_read_b128 v[160:163], v186 offset:2048
	v_mfma_f32_16x16x32_bf16 v[10:13], v[234:237], v[198:201], v[10:13]
	v_mfma_f32_16x16x32_bf16 v[6:9], v[214:217], v[206:209], v[6:9]
	ds_read_b128 v[164:167], v186 offset:3072
	v_mfma_f32_16x16x32_bf16 v[2:5], v[234:237], v[206:209], v[2:5]
	v_mfma_f32_16x16x32_bf16 v[30:33], v[218:221], v[172:175], v[30:33]
	ds_read_b128 v[168:171], v147 offset:32768
	v_mfma_f32_16x16x32_bf16 v[26:29], v[238:241], v[172:175], v[26:29]
	v_mfma_f32_16x16x32_bf16 v[22:25], v[218:221], v[194:197], v[22:25]
	ds_read_b128 v[176:179], v147 offset:34816
	v_mfma_f32_16x16x32_bf16 v[18:21], v[238:241], v[194:197], v[18:21]
	v_mfma_f32_16x16x32_bf16 v[14:17], v[218:221], v[202:205], v[14:17]
	ds_read_b128 v[198:201], v147 offset:36864
	v_mfma_f32_16x16x32_bf16 v[10:13], v[238:241], v[202:205], v[10:13]
	v_mfma_f32_16x16x32_bf16 v[6:9], v[218:221], v[210:213], v[6:9]
	ds_read_b128 v[206:209], v147 offset:38912
	v_mfma_f32_16x16x32_bf16 v[2:5], v[238:241], v[210:213], v[2:5]
	s_barrier
	ds_read_b128 v[172:175], v147 offset:33792
	ds_read_b128 v[194:197], v147 offset:35840
	ds_read_b128 v[202:205], v147 offset:37888
	ds_read_b128 v[210:213], v147 offset:39936
	s_mov_b32 m0, s30
	s_add_u32 s98, s40, s68
	s_addc_u32 s99, s41, s69
	global_load_lds_dwordx4 v135, s[98:99]
	s_mov_b32 m0, s31
	s_add_u32 s98, s40, s70
	s_addc_u32 s99, s41, s71
	global_load_lds_dwordx4 v135, s[98:99]
	s_waitcnt lgkmcnt(8)
	s_waitcnt vmcnt(8)
	s_barrier
	s_waitcnt lgkmcnt(0)
	s_waitcnt lgkmcnt(0)
	v_mfma_f32_16x16x32_bf16 v[126:129], v[152:155], v[168:171], v[126:129]
	ds_read_b128 v[214:217], v187
	v_mfma_f32_16x16x32_bf16 v[122:125], v[160:163], v[168:171], v[122:125]
	v_mfma_f32_16x16x32_bf16 v[118:121], v[152:155], v[176:179], v[118:121]
	ds_read_b128 v[218:221], v187 offset:1024
	v_mfma_f32_16x16x32_bf16 v[114:117], v[160:163], v[176:179], v[114:117]
	v_mfma_f32_16x16x32_bf16 v[110:113], v[152:155], v[198:201], v[110:113]
	ds_read_b128 v[234:237], v187 offset:2048
	v_mfma_f32_16x16x32_bf16 v[106:109], v[160:163], v[198:201], v[106:109]
	v_mfma_f32_16x16x32_bf16 v[102:105], v[152:155], v[206:209], v[102:105]
	ds_read_b128 v[238:241], v187 offset:3072
	v_mfma_f32_16x16x32_bf16 v[98:101], v[160:163], v[206:209], v[98:101]
	v_mfma_f32_16x16x32_bf16 v[126:129], v[156:159], v[172:175], v[126:129]
	v_mfma_f32_16x16x32_bf16 v[122:125], v[164:167], v[172:175], v[122:125]
	v_mfma_f32_16x16x32_bf16 v[118:121], v[156:159], v[194:197], v[118:121]
	v_mfma_f32_16x16x32_bf16 v[114:117], v[164:167], v[194:197], v[114:117]
	v_mfma_f32_16x16x32_bf16 v[110:113], v[156:159], v[202:205], v[110:113]
	v_mfma_f32_16x16x32_bf16 v[106:109], v[164:167], v[202:205], v[106:109]
	v_mfma_f32_16x16x32_bf16 v[102:105], v[156:159], v[210:213], v[102:105]
	v_mfma_f32_16x16x32_bf16 v[98:101], v[164:167], v[210:213], v[98:101]
	s_barrier
	s_mov_b32 m0, s32
	s_add_u32 s98, s42, s94
	s_addc_u32 s99, s43, s95
	global_load_lds_dwordx4 v135, s[98:99]
	s_mov_b32 m0, s44
	s_add_u32 s98, s42, s72
	s_addc_u32 s99, s43, s73
	global_load_lds_dwordx4 v135, s[98:99]
	s_barrier
	s_waitcnt lgkmcnt(0)
	s_waitcnt lgkmcnt(0)
	v_mfma_f32_16x16x32_bf16 v[94:97], v[214:217], v[168:171], v[94:97]
	v_mfma_f32_16x16x32_bf16 v[90:93], v[234:237], v[168:171], v[90:93]
	v_mfma_f32_16x16x32_bf16 v[86:89], v[214:217], v[176:179], v[86:89]
	v_mfma_f32_16x16x32_bf16 v[82:85], v[234:237], v[176:179], v[82:85]
	v_mfma_f32_16x16x32_bf16 v[78:81], v[214:217], v[198:201], v[78:81]
	v_mfma_f32_16x16x32_bf16 v[74:77], v[234:237], v[198:201], v[74:77]
	v_mfma_f32_16x16x32_bf16 v[70:73], v[214:217], v[206:209], v[70:73]
	v_mfma_f32_16x16x32_bf16 v[66:69], v[234:237], v[206:209], v[66:69]
	v_mfma_f32_16x16x32_bf16 v[94:97], v[218:221], v[172:175], v[94:97]
	ds_read_b128 v[168:171], v147 offset:49152
	v_mfma_f32_16x16x32_bf16 v[90:93], v[238:241], v[172:175], v[90:93]
	v_mfma_f32_16x16x32_bf16 v[86:89], v[218:221], v[194:197], v[86:89]
	ds_read_b128 v[176:179], v147 offset:51200
	v_mfma_f32_16x16x32_bf16 v[82:85], v[238:241], v[194:197], v[82:85]
	v_mfma_f32_16x16x32_bf16 v[78:81], v[218:221], v[202:205], v[78:81]
	ds_read_b128 v[198:201], v147 offset:53248
	v_mfma_f32_16x16x32_bf16 v[74:77], v[238:241], v[202:205], v[74:77]
	v_mfma_f32_16x16x32_bf16 v[70:73], v[218:221], v[210:213], v[70:73]
	ds_read_b128 v[206:209], v147 offset:55296
	v_mfma_f32_16x16x32_bf16 v[66:69], v[238:241], v[210:213], v[66:69]
	s_barrier
; #define LDA(dst, b, h) for (int m = 0; m < 4; ++m) for (int k = 0; k < 2; ++k) \
;     dst[m][k] = *reinterpret_cast<const bf16x8*>((char*)SA(b, h) + a_thr + (m * 2 + k) * 1024)
; #define LDB(dst, b, h) for (int n = 0; n < 2; ++n) for (int k = 0; k < 2; ++k) \
;     dst[n][k] = *reinterpret_cast<const bf16x8*>((char*)SB(b, h) + b_thr + (n * 2 + k) * 1024)
; #define MMA(ai, bj, At, Btf) do { __builtin_amdgcn_s_setprio(1); \
;     for (int m = 0; m < 4; ++m) for (int n = 0; n < 2; ++n) for (int k = 0; k < 2; ++k) \
;       acc[ai][bj][m][n] = __builtin_amdgcn_mfma_f32_16x16x32_bf16(Btf[n][k], At[m][k], acc[ai][bj][m][n], 0, 0, 0); \
;     __builtin_amdgcn_s_setprio(0); } while (0)
; #define WAIT_V(n) asm volatile("s_waitcnt vmcnt(" #n ")" ::: "memory")
; #define WAIT_L(n) asm volatile("s_waitcnt lgkmcnt(" #n ")" ::: "memory")
; #define BAR __builtin_amdgcn_s_barrier()
; #define SCHED __builtin_amdgcn_sched_barrier(0)
; template <bool OVL, bool PANEL = false, class Epi>
; __device__ __forceinline__ void gemm_phase(const bf16_t* __restrict__ A, long lda, const bf16_t* __restrict__ Bt, long ldb, int nM, int nN, int K,
;                                            const Epi& epi, bf16_t* shm, int w0) {
;     ...
;       LDA(At, 1, 1); STAGE(SA(1, 0), A, lda, aoff, brow, t + 3);
;       BAR; WAIT_L(0); MMA(1, 0, At, B0); BAR; SCHED;
;       STAGE(SB(1, 1), Bt, ldb, boff, bcol + HALF, t + 3);
;       WAIT_V(6); BAR; MMA(1, 1, At, B1); BAR;
;     }
;     { LDB(B0, 0, 0); LDA(At, 0, 0); STAGE(SA(1, 1), A, lda, aoff, brow + HALF, nt - 1);
	ds_read_b128 v[172:175], v147 offset:50176
	ds_read_b128 v[194:197], v147 offset:52224
	ds_read_b128 v[202:205], v147 offset:54272
	ds_read_b128 v[210:213], v147 offset:56320
	s_mov_b32 m0, s45
	s_add_u32 s98, s40, s94
	s_addc_u32 s99, s41, s95
	global_load_lds_dwordx4 v135, s[98:99]
	s_mov_b32 m0, s46
	s_add_u32 s98, s40, s72
	s_addc_u32 s99, s41, s73
	global_load_lds_dwordx4 v135, s[98:99]
	s_waitcnt vmcnt(8)
	s_barrier
	s_waitcnt lgkmcnt(0)
	s_waitcnt lgkmcnt(0)
	v_mfma_f32_16x16x32_bf16 v[62:65], v[152:155], v[168:171], v[62:65]
	v_mfma_f32_16x16x32_bf16 v[58:61], v[160:163], v[168:171], v[58:61]
	v_mfma_f32_16x16x32_bf16 v[54:57], v[152:155], v[176:179], v[54:57]
	v_mfma_f32_16x16x32_bf16 v[50:53], v[160:163], v[176:179], v[50:53]
	v_mfma_f32_16x16x32_bf16 v[46:49], v[152:155], v[198:201], v[46:49]
	v_mfma_f32_16x16x32_bf16 v[42:45], v[160:163], v[198:201], v[42:45]
	v_mfma_f32_16x16x32_bf16 v[38:41], v[152:155], v[206:209], v[38:41]
	v_mfma_f32_16x16x32_bf16 v[34:37], v[160:163], v[206:209], v[34:37]
	v_mfma_f32_16x16x32_bf16 v[62:65], v[156:159], v[172:175], v[62:65]
	v_mfma_f32_16x16x32_bf16 v[58:61], v[164:167], v[172:175], v[58:61]
	v_mfma_f32_16x16x32_bf16 v[54:57], v[156:159], v[194:197], v[54:57]
	v_mfma_f32_16x16x32_bf16 v[50:53], v[164:167], v[194:197], v[50:53]
	v_mfma_f32_16x16x32_bf16 v[46:49], v[156:159], v[202:205], v[46:49]
	v_mfma_f32_16x16x32_bf16 v[42:45], v[164:167], v[202:205], v[42:45]
	v_mfma_f32_16x16x32_bf16 v[38:41], v[156:159], v[210:213], v[38:41]
	v_mfma_f32_16x16x32_bf16 v[34:37], v[164:167], v[210:213], v[34:37]
	s_barrier
	s_mov_b32 m0, s47
	s_add_u32 s98, s42, s18
	s_addc_u32 s99, s43, s19
	global_load_lds_dwordx4 v135, s[98:99]
	s_mov_b32 m0, s48
	s_add_u32 s98, s42, s20
	s_addc_u32 s99, s43, s21
	global_load_lds_dwordx4 v135, s[98:99]
	s_waitcnt vmcnt(8)
	s_barrier
	v_mfma_f32_16x16x32_bf16 v[30:33], v[214:217], v[168:171], v[30:33]
	ds_read_b128 v[152:155], v184
	v_mfma_f32_16x16x32_bf16 v[26:29], v[234:237], v[168:171], v[26:29]
	v_mfma_f32_16x16x32_bf16 v[22:25], v[214:217], v[176:179], v[22:25]
	ds_read_b128 v[156:159], v184 offset:1024
	v_mfma_f32_16x16x32_bf16 v[18:21], v[234:237], v[176:179], v[18:21]
	v_mfma_f32_16x16x32_bf16 v[14:17], v[214:217], v[198:201], v[14:17]
	ds_read_b128 v[160:163], v184 offset:2048
	v_mfma_f32_16x16x32_bf16 v[10:13], v[234:237], v[198:201], v[10:13]
	v_mfma_f32_16x16x32_bf16 v[6:9], v[214:217], v[206:209], v[6:9]
	ds_read_b128 v[164:167], v184 offset:3072
	v_mfma_f32_16x16x32_bf16 v[2:5], v[234:237], v[206:209], v[2:5]
	v_mfma_f32_16x16x32_bf16 v[30:33], v[218:221], v[172:175], v[30:33]
	ds_read_b128 v[168:171], v147
	v_mfma_f32_16x16x32_bf16 v[26:29], v[238:241], v[172:175], v[26:29]
	v_mfma_f32_16x16x32_bf16 v[22:25], v[218:221], v[194:197], v[22:25]
	ds_read_b128 v[176:179], v147 offset:2048
	v_mfma_f32_16x16x32_bf16 v[18:21], v[238:241], v[194:197], v[18:21]
	v_mfma_f32_16x16x32_bf16 v[14:17], v[218:221], v[202:205], v[14:17]
	ds_read_b128 v[198:201], v147 offset:4096
	v_mfma_f32_16x16x32_bf16 v[10:13], v[238:241], v[202:205], v[10:13]
	v_mfma_f32_16x16x32_bf16 v[6:9], v[218:221], v[210:213], v[6:9]
	ds_read_b128 v[206:209], v147 offset:6144
	v_mfma_f32_16x16x32_bf16 v[2:5], v[238:241], v[210:213], v[2:5]
	s_add_i32 s1, s1, 2
	s_add_u32 s14, s14, 0x100
	s_addc_u32 s15, s15, 0
	s_cmp_lt_u32 s1, 12
	s_barrier
	s_cbranch_scc1 .LBB0_1053
	s_waitcnt vmcnt(6)
	s_or_b32 s8, s0, 0x80
	s_ashr_i32 s9, s8, 31
	v_readlane_b32 s40, v252, 20
	s_lshl_b64 s[8:9], s[8:9], 11
	v_readlane_b32 s46, v252, 26
	v_add_u32_e32 v182, 16, v144
	v_readlane_b32 s47, v252, 27
	s_add_u32 s8, s46, s8
	v_add_u32_e32 v0, 0x10000, v182
	s_addc_u32 s9, s47, s9
	ds_read_b128 v[130:133], v0
	ds_read_b128 v[152:155], v0 offset:1024
	ds_read_b128 v[156:159], v0 offset:2048
	ds_read_b128 v[160:163], v0 offset:3072
	ds_read_b128 v[164:167], v147
	ds_read_b128 v[168:171], v147 offset:1024
	ds_read_b128 v[172:175], v147 offset:2048
	ds_read_b128 v[176:179], v147 offset:3072
	ds_read_b128 v[194:197], v147 offset:4096
	ds_read_b128 v[198:201], v147 offset:5120
	ds_read_b128 v[202:205], v147 offset:6144
	ds_read_b128 v[206:209], v147 offset:7168
	v_mov_b32_e32 v0, v135
	v_readfirstlane_b32 s1, v150
	v_lshl_add_u64 v[148:149], s[8:9], 0, v[0:1]
	s_mov_b64 s[8:9], 0x780
	v_lshl_add_u64 v[180:181], v[148:149], 0, s[8:9]
	s_mov_b32 m0, s1
	s_mov_b64 s[8:9], 0x20780
	v_readfirstlane_b32 s1, v151
	global_load_lds_dwordx4 v[180:181], off
	v_lshl_add_u64 v[148:149], v[148:149], 0, s[8:9]
	s_mov_b32 m0, s1
	v_readlane_b32 s41, v252, 21
	global_load_lds_dwordx4 v[148:149], off
	s_barrier
	s_waitcnt lgkmcnt(0)
	v_readlane_b32 s42, v252, 22
	v_readlane_b32 s43, v252, 23
	v_readlane_b32 s44, v252, 24
	v_readlane_b32 s45, v252, 25
	v_readlane_b32 s48, v252, 28
	v_readlane_b32 s49, v252, 29
	v_readlane_b32 s50, v252, 30
	v_readlane_b32 s51, v252, 31
	v_readlane_b32 s52, v252, 32
	v_readlane_b32 s53, v252, 33
	v_readlane_b32 s54, v252, 34
	v_readlane_b32 s55, v252, 35

; #define LDA(dst, b, h) for (int m = 0; m < 4; ++m) for (int k = 0; k < 2; ++k) \
;     dst[m][k] = *reinterpret_cast<const bf16x8*>((char*)SA(b, h) + a_thr + (m * 2 + k) * 1024)
; #define LDB(dst, b, h) for (int n = 0; n < 2; ++n) for (int k = 0; k < 2; ++k) \
;     dst[n][k] = *reinterpret_cast<const bf16x8*>((char*)SB(b, h) + b_thr + (n * 2 + k) * 1024)
; #define MMA(ai, bj, At, Btf) do { __builtin_amdgcn_s_setprio(1); \
;     for (int m = 0; m < 4; ++m) for (int n = 0; n < 2; ++n) for (int k = 0; k < 2; ++k) \
;       acc[ai][bj][m][n] = __builtin_amdgcn_mfma_f32_16x16x32_bf16(Btf[n][k], At[m][k], acc[ai][bj][m][n], 0, 0, 0); \
;     __builtin_amdgcn_s_setprio(0); } while (0)
; #define WAIT_L(n) asm volatile("s_waitcnt lgkmcnt(" #n ")" ::: "memory")
; #define BAR __builtin_amdgcn_s_barrier()
; template <bool OVL, bool PANEL = false, class Epi>
; __device__ __forceinline__ void gemm_phase(const bf16_t* __restrict__ A, long lda, const bf16_t* __restrict__ Bt, long ldb, int nM, int nN, int K,
;                                            const Epi& epi, bf16_t* shm, int w0) {
;     ...
;     { LDB(B0, 0, 0); LDA(At, 0, 0); STAGE(SA(1, 1), A, lda, aoff, brow + HALF, nt - 1);
;       BAR; WAIT_L(0); MMA(0, 0, At, B0); BAR;
	s_waitcnt lgkmcnt(0)
	v_mfma_f32_16x16x32_bf16 v[126:129], v[130:133], v[164:167], v[126:129]
	v_mfma_f32_16x16x32_bf16 v[122:125], v[156:159], v[164:167], v[122:125]
	v_mfma_f32_16x16x32_bf16 v[118:121], v[130:133], v[172:175], v[118:121]
	v_mfma_f32_16x16x32_bf16 v[114:117], v[156:159], v[172:175], v[114:117]
	v_mfma_f32_16x16x32_bf16 v[110:113], v[130:133], v[194:197], v[110:113]
	v_mfma_f32_16x16x32_bf16 v[106:109], v[156:159], v[194:197], v[106:109]
	v_mfma_f32_16x16x32_bf16 v[102:105], v[130:133], v[202:205], v[102:105]
	v_mfma_f32_16x16x32_bf16 v[98:101], v[156:159], v[202:205], v[98:101]
	v_mfma_f32_16x16x32_bf16 v[126:129], v[152:155], v[168:171], v[126:129]
	v_mfma_f32_16x16x32_bf16 v[122:125], v[160:163], v[168:171], v[122:125]
	v_mfma_f32_16x16x32_bf16 v[118:121], v[152:155], v[176:179], v[118:121]
	v_mfma_f32_16x16x32_bf16 v[114:117], v[160:163], v[176:179], v[114:117]
	v_mfma_f32_16x16x32_bf16 v[110:113], v[152:155], v[198:201], v[110:113]
	v_mfma_f32_16x16x32_bf16 v[106:109], v[160:163], v[198:201], v[106:109]
	v_mfma_f32_16x16x32_bf16 v[102:105], v[152:155], v[206:209], v[102:105]
	v_mfma_f32_16x16x32_bf16 v[98:101], v[160:163], v[206:209], v[98:101]

; #define LDB(dst, b, h) for (int n = 0; n < 2; ++n) for (int k = 0; k < 2; ++k) \
;     dst[n][k] = *reinterpret_cast<const bf16x8*>((char*)SB(b, h) + b_thr + (n * 2 + k) * 1024)
; #define MMA(ai, bj, At, Btf) do { __builtin_amdgcn_s_setprio(1); \
;     for (int m = 0; m < 4; ++m) for (int n = 0; n < 2; ++n) for (int k = 0; k < 2; ++k) \
;       acc[ai][bj][m][n] = __builtin_amdgcn_mfma_f32_16x16x32_bf16(Btf[n][k], At[m][k], acc[ai][bj][m][n], 0, 0, 0); \
;     __builtin_amdgcn_s_setprio(0); } while (0)
; #define WAIT_L(n) asm volatile("s_waitcnt lgkmcnt(" #n ")" ::: "memory")
; #define BAR __builtin_amdgcn_s_barrier()
; template <bool OVL, bool PANEL = false, class Epi>
; __device__ __forceinline__ void gemm_phase(const bf16_t* __restrict__ A, long lda, const bf16_t* __restrict__ Bt, long ldb, int nM, int nN, int K,
;                                            const Epi& epi, bf16_t* shm, int w0) {
;     ...
;       LDB(B1, 0, 1); BAR; WAIT_L(0); MMA(0, 1, At, B1); BAR;
	v_add_u32_e32 v0, 0x14000, v182
	s_barrier
	ds_read_b128 v[148:151], v0
	ds_read_b128 v[210:213], v0 offset:1024
	ds_read_b128 v[214:217], v0 offset:2048
	ds_read_b128 v[218:221], v0 offset:3072
	s_barrier
	s_waitcnt lgkmcnt(0)

; #define LDB(dst, b, h) for (int n = 0; n < 2; ++n) for (int k = 0; k < 2; ++k) \
;     dst[n][k] = *reinterpret_cast<const bf16x8*>((char*)SB(b, h) + b_thr + (n * 2 + k) * 1024)
; #define MMA(ai, bj, At, Btf) do { __builtin_amdgcn_s_setprio(1); \
;     for (int m = 0; m < 4; ++m) for (int n = 0; n < 2; ++n) for (int k = 0; k < 2; ++k) \
;       acc[ai][bj][m][n] = __builtin_amdgcn_mfma_f32_16x16x32_bf16(Btf[n][k], At[m][k], acc[ai][bj][m][n], 0, 0, 0); \
;     __builtin_amdgcn_s_setprio(0); } while (0)
; #define WAIT_L(n) asm volatile("s_waitcnt lgkmcnt(" #n ")" ::: "memory")
; #define BAR __builtin_amdgcn_s_barrier()
; template <bool OVL, bool PANEL = false, class Epi>
; __device__ __forceinline__ void gemm_phase(const bf16_t* __restrict__ A, long lda, const bf16_t* __restrict__ Bt, long ldb, int nM, int nN, int K,
;                                            const Epi& epi, bf16_t* shm, int w0) {
;     ...
;       LDB(B1, 0, 1); BAR; WAIT_L(0); MMA(0, 1, At, B1); BAR;
	s_waitcnt lgkmcnt(0)
	v_mfma_f32_16x16x32_bf16 v[94:97], v[148:151], v[164:167], v[94:97]
	v_mfma_f32_16x16x32_bf16 v[90:93], v[214:217], v[164:167], v[90:93]
	v_mfma_f32_16x16x32_bf16 v[86:89], v[148:151], v[172:175], v[86:89]
	v_mfma_f32_16x16x32_bf16 v[82:85], v[214:217], v[172:175], v[82:85]
	v_mfma_f32_16x16x32_bf16 v[78:81], v[148:151], v[194:197], v[78:81]
	v_mfma_f32_16x16x32_bf16 v[74:77], v[214:217], v[194:197], v[74:77]
	v_mfma_f32_16x16x32_bf16 v[70:73], v[148:151], v[202:205], v[70:73]
	v_mfma_f32_16x16x32_bf16 v[66:69], v[214:217], v[202:205], v[66:69]
	v_mfma_f32_16x16x32_bf16 v[94:97], v[210:213], v[168:171], v[94:97]
	v_mfma_f32_16x16x32_bf16 v[90:93], v[218:221], v[168:171], v[90:93]
	v_mfma_f32_16x16x32_bf16 v[86:89], v[210:213], v[176:179], v[86:89]
	v_mfma_f32_16x16x32_bf16 v[82:85], v[218:221], v[176:179], v[82:85]
	v_mfma_f32_16x16x32_bf16 v[78:81], v[210:213], v[198:201], v[78:81]
	v_mfma_f32_16x16x32_bf16 v[74:77], v[218:221], v[198:201], v[74:77]
	v_mfma_f32_16x16x32_bf16 v[70:73], v[210:213], v[206:209], v[70:73]
	v_mfma_f32_16x16x32_bf16 v[66:69], v[218:221], v[206:209], v[66:69]

; #define LDA(dst, b, h) for (int m = 0; m < 4; ++m) for (int k = 0; k < 2; ++k) \
;     dst[m][k] = *reinterpret_cast<const bf16x8*>((char*)SA(b, h) + a_thr + (m * 2 + k) * 1024)
; #define MMA(ai, bj, At, Btf) do { __builtin_amdgcn_s_setprio(1); \
;     for (int m = 0; m < 4; ++m) for (int n = 0; n < 2; ++n) for (int k = 0; k < 2; ++k) \
;       acc[ai][bj][m][n] = __builtin_amdgcn_mfma_f32_16x16x32_bf16(Btf[n][k], At[m][k], acc[ai][bj][m][n], 0, 0, 0); \
;     __builtin_amdgcn_s_setprio(0); } while (0)
; #define WAIT_V(n) asm volatile("s_waitcnt vmcnt(" #n ")" ::: "memory")
; #define WAIT_L(n) asm volatile("s_waitcnt lgkmcnt(" #n ")" ::: "memory")
; #define BAR __builtin_amdgcn_s_barrier()
; template <bool OVL, bool PANEL = false, class Epi>
; __device__ __forceinline__ void gemm_phase(const bf16_t* __restrict__ A, long lda, const bf16_t* __restrict__ Bt, long ldb, int nM, int nN, int K,
;                                            const Epi& epi, bf16_t* shm, int w0) {
;     ...
;       LDA(At, 0, 1); WAIT_V(4); BAR; WAIT_L(0); MMA(1, 0, At, B0); MMA(1, 1, At, B1); BAR; }
	s_barrier
	ds_read_b128 v[164:167], v147 offset:16384
	ds_read_b128 v[168:171], v147 offset:17408
	ds_read_b128 v[172:175], v147 offset:18432
	ds_read_b128 v[176:179], v147 offset:19456
	ds_read_b128 v[194:197], v147 offset:20480
	ds_read_b128 v[198:201], v147 offset:21504
	ds_read_b128 v[202:205], v147 offset:22528
	ds_read_b128 v[206:209], v147 offset:23552
	s_waitcnt vmcnt(4)
	s_barrier
	s_waitcnt lgkmcnt(0)

; #define LDA(dst, b, h) for (int m = 0; m < 4; ++m) for (int k = 0; k < 2; ++k) \
;     dst[m][k] = *reinterpret_cast<const bf16x8*>((char*)SA(b, h) + a_thr + (m * 2 + k) * 1024)
; #define MMA(ai, bj, At, Btf) do { __builtin_amdgcn_s_setprio(1); \
;     for (int m = 0; m < 4; ++m) for (int n = 0; n < 2; ++n) for (int k = 0; k < 2; ++k) \
;       acc[ai][bj][m][n] = __builtin_amdgcn_mfma_f32_16x16x32_bf16(Btf[n][k], At[m][k], acc[ai][bj][m][n], 0, 0, 0); \
;     __builtin_amdgcn_s_setprio(0); } while (0)
; #define WAIT_V(n) asm volatile("s_waitcnt vmcnt(" #n ")" ::: "memory")
; #define WAIT_L(n) asm volatile("s_waitcnt lgkmcnt(" #n ")" ::: "memory")
; #define BAR __builtin_amdgcn_s_barrier()
; template <bool OVL, bool PANEL = false, class Epi>
; __device__ __forceinline__ void gemm_phase(const bf16_t* __restrict__ A, long lda, const bf16_t* __restrict__ Bt, long ldb, int nM, int nN, int K,
;                                            const Epi& epi, bf16_t* shm, int w0) {
;     ...
;       LDA(At, 0, 1); WAIT_V(4); BAR; WAIT_L(0); MMA(1, 0, At, B0); MMA(1, 1, At, B1); BAR; }
	s_waitcnt lgkmcnt(0)
	v_mfma_f32_16x16x32_bf16 v[62:65], v[130:133], v[164:167], v[62:65]
	v_mfma_f32_16x16x32_bf16 v[58:61], v[156:159], v[164:167], v[58:61]
	v_mfma_f32_16x16x32_bf16 v[54:57], v[130:133], v[172:175], v[54:57]
	v_mfma_f32_16x16x32_bf16 v[50:53], v[156:159], v[172:175], v[50:53]
	v_mfma_f32_16x16x32_bf16 v[46:49], v[130:133], v[194:197], v[46:49]
	v_mfma_f32_16x16x32_bf16 v[42:45], v[156:159], v[194:197], v[42:45]
	v_mfma_f32_16x16x32_bf16 v[38:41], v[130:133], v[202:205], v[38:41]
	v_mfma_f32_16x16x32_bf16 v[34:37], v[156:159], v[202:205], v[34:37]
	v_mfma_f32_16x16x32_bf16 v[62:65], v[152:155], v[168:171], v[62:65]
	v_mfma_f32_16x16x32_bf16 v[58:61], v[160:163], v[168:171], v[58:61]
	v_mfma_f32_16x16x32_bf16 v[54:57], v[152:155], v[176:179], v[54:57]
	v_mfma_f32_16x16x32_bf16 v[50:53], v[160:163], v[176:179], v[50:53]
	v_mfma_f32_16x16x32_bf16 v[46:49], v[152:155], v[198:201], v[46:49]
	v_mfma_f32_16x16x32_bf16 v[42:45], v[160:163], v[198:201], v[42:45]
	v_mfma_f32_16x16x32_bf16 v[38:41], v[152:155], v[206:209], v[38:41]
	v_mfma_f32_16x16x32_bf16 v[34:37], v[160:163], v[206:209], v[34:37]


; #define LDA(dst, b, h) for (int m = 0; m < 4; ++m) for (int k = 0; k < 2; ++k) \
;     dst[m][k] = *reinterpret_cast<const bf16x8*>((char*)SA(b, h) + a_thr + (m * 2 + k) * 1024)
; #define MMA(ai, bj, At, Btf) do { __builtin_amdgcn_s_setprio(1); \
;     for (int m = 0; m < 4; ++m) for (int n = 0; n < 2; ++n) for (int k = 0; k < 2; ++k) \
;       acc[ai][bj][m][n] = __builtin_amdgcn_mfma_f32_16x16x32_bf16(Btf[n][k], At[m][k], acc[ai][bj][m][n], 0, 0, 0); \
;     __builtin_amdgcn_s_setprio(0); } while (0)
; #define WAIT_V(n) asm volatile("s_waitcnt vmcnt(" #n ")" ::: "memory")
; #define WAIT_L(n) asm volatile("s_waitcnt lgkmcnt(" #n ")" ::: "memory")
; #define BAR __builtin_amdgcn_s_barrier()
; template <bool OVL, bool PANEL = false, class Epi>
; __device__ __forceinline__ void gemm_phase(const bf16_t* __restrict__ A, long lda, const bf16_t* __restrict__ Bt, long ldb, int nM, int nN, int K,
;                                            const Epi& epi, bf16_t* shm, int w0) {
;     ...
;       LDA(At, 0, 1); WAIT_V(4); BAR; WAIT_L(0); MMA(1, 0, At, B0); MMA(1, 1, At, B1); BAR; }
	v_mfma_f32_16x16x32_bf16 v[30:33], v[148:151], v[164:167], v[30:33]
	v_mfma_f32_16x16x32_bf16 v[26:29], v[214:217], v[164:167], v[26:29]
	v_mfma_f32_16x16x32_bf16 v[22:25], v[148:151], v[172:175], v[22:25]
	v_mfma_f32_16x16x32_bf16 v[18:21], v[214:217], v[172:175], v[18:21]
	v_mfma_f32_16x16x32_bf16 v[14:17], v[148:151], v[194:197], v[14:17]
	v_mfma_f32_16x16x32_bf16 v[10:13], v[214:217], v[194:197], v[10:13]
	v_mfma_f32_16x16x32_bf16 v[6:9], v[148:151], v[202:205], v[6:9]
	v_mfma_f32_16x16x32_bf16 v[2:5], v[214:217], v[202:205], v[2:5]
	v_mfma_f32_16x16x32_bf16 v[30:33], v[210:213], v[168:171], v[30:33]
	v_mfma_f32_16x16x32_bf16 v[26:29], v[218:221], v[168:171], v[26:29]
	v_mfma_f32_16x16x32_bf16 v[22:25], v[210:213], v[176:179], v[22:25]
	v_mfma_f32_16x16x32_bf16 v[18:21], v[218:221], v[176:179], v[18:21]
	v_mfma_f32_16x16x32_bf16 v[14:17], v[210:213], v[198:201], v[14:17]
	v_mfma_f32_16x16x32_bf16 v[10:13], v[218:221], v[198:201], v[10:13]
	v_mfma_f32_16x16x32_bf16 v[6:9], v[210:213], v[206:209], v[6:9]
	v_mfma_f32_16x16x32_bf16 v[2:5], v[218:221], v[206:209], v[2:5]

; #define LDA(dst, b, h) for (int m = 0; m < 4; ++m) for (int k = 0; k < 2; ++k) \
;     dst[m][k] = *reinterpret_cast<const bf16x8*>((char*)SA(b, h) + a_thr + (m * 2 + k) * 1024)
; #define LDB(dst, b, h) for (int n = 0; n < 2; ++n) for (int k = 0; k < 2; ++k) \
;     dst[n][k] = *reinterpret_cast<const bf16x8*>((char*)SB(b, h) + b_thr + (n * 2 + k) * 1024)
; #define MMA(ai, bj, At, Btf) do { __builtin_amdgcn_s_setprio(1); \
;     for (int m = 0; m < 4; ++m) for (int n = 0; n < 2; ++n) for (int k = 0; k < 2; ++k) \
;       acc[ai][bj][m][n] = __builtin_amdgcn_mfma_f32_16x16x32_bf16(Btf[n][k], At[m][k], acc[ai][bj][m][n], 0, 0, 0); \
;     __builtin_amdgcn_s_setprio(0); } while (0)
; #define WAIT_V(n) asm volatile("s_waitcnt vmcnt(" #n ")" ::: "memory")
; #define WAIT_L(n) asm volatile("s_waitcnt lgkmcnt(" #n ")" ::: "memory")
; #define BAR __builtin_amdgcn_s_barrier()
; template <bool OVL, bool PANEL = false, class Epi>
; __device__ __forceinline__ void gemm_phase(const bf16_t* __restrict__ A, long lda, const bf16_t* __restrict__ Bt, long ldb, int nM, int nN, int K,
;                                            const Epi& epi, bf16_t* shm, int w0) {
;     ...
;     { LDB(B0, 1, 0); LDA(At, 1, 0); WAIT_V(2); BAR; WAIT_L(0); MMA(0, 0, At, B0); BAR;
	v_add_u32_e32 v0, 0x18000, v182
	s_barrier
	ds_read_b128 v[130:133], v0
	ds_read_b128 v[148:151], v0 offset:1024
	ds_read_b128 v[152:155], v0 offset:2048
	ds_read_b128 v[156:159], v0 offset:3072
	ds_read_b128 v[160:163], v147 offset:32768
	ds_read_b128 v[164:167], v147 offset:33792
	ds_read_b128 v[168:171], v147 offset:34816
	ds_read_b128 v[172:175], v147 offset:35840
	ds_read_b128 v[176:179], v147 offset:36864
	ds_read_b128 v[194:197], v147 offset:37888
	ds_read_b128 v[198:201], v147 offset:38912
	ds_read_b128 v[202:205], v147 offset:39936
	s_waitcnt vmcnt(2)
	s_barrier
	s_waitcnt lgkmcnt(0)

; #define LDA(dst, b, h) for (int m = 0; m < 4; ++m) for (int k = 0; k < 2; ++k) \
;     dst[m][k] = *reinterpret_cast<const bf16x8*>((char*)SA(b, h) + a_thr + (m * 2 + k) * 1024)
; #define LDB(dst, b, h) for (int n = 0; n < 2; ++n) for (int k = 0; k < 2; ++k) \
;     dst[n][k] = *reinterpret_cast<const bf16x8*>((char*)SB(b, h) + b_thr + (n * 2 + k) * 1024)
; #define MMA(ai, bj, At, Btf) do { __builtin_amdgcn_s_setprio(1); \
;     for (int m = 0; m < 4; ++m) for (int n = 0; n < 2; ++n) for (int k = 0; k < 2; ++k) \
;       acc[ai][bj][m][n] = __builtin_amdgcn_mfma_f32_16x16x32_bf16(Btf[n][k], At[m][k], acc[ai][bj][m][n], 0, 0, 0); \
;     __builtin_amdgcn_s_setprio(0); } while (0)
; #define WAIT_V(n) asm volatile("s_waitcnt vmcnt(" #n ")" ::: "memory")
; #define WAIT_L(n) asm volatile("s_waitcnt lgkmcnt(" #n ")" ::: "memory")
; #define BAR __builtin_amdgcn_s_barrier()
; template <bool OVL, bool PANEL = false, class Epi>
; __device__ __forceinline__ void gemm_phase(const bf16_t* __restrict__ A, long lda, const bf16_t* __restrict__ Bt, long ldb, int nM, int nN, int K,
;                                            const Epi& epi, bf16_t* shm, int w0) {
;     ...
;     { LDB(B0, 1, 0); LDA(At, 1, 0); WAIT_V(2); BAR; WAIT_L(0); MMA(0, 0, At, B0); BAR;
	s_waitcnt lgkmcnt(0)
	v_mfma_f32_16x16x32_bf16 v[126:129], v[130:133], v[160:163], v[126:129]
	v_mfma_f32_16x16x32_bf16 v[122:125], v[152:155], v[160:163], v[122:125]
	v_mfma_f32_16x16x32_bf16 v[118:121], v[130:133], v[168:171], v[118:121]
	v_mfma_f32_16x16x32_bf16 v[114:117], v[152:155], v[168:171], v[114:117]
	v_mfma_f32_16x16x32_bf16 v[110:113], v[130:133], v[176:179], v[110:113]
	v_mfma_f32_16x16x32_bf16 v[106:109], v[152:155], v[176:179], v[106:109]
	v_mfma_f32_16x16x32_bf16 v[102:105], v[130:133], v[198:201], v[102:105]
	v_mfma_f32_16x16x32_bf16 v[98:101], v[152:155], v[198:201], v[98:101]
	v_mfma_f32_16x16x32_bf16 v[126:129], v[148:151], v[164:167], v[126:129]
	v_mfma_f32_16x16x32_bf16 v[122:125], v[156:159], v[164:167], v[122:125]
	v_mfma_f32_16x16x32_bf16 v[118:121], v[148:151], v[172:175], v[118:121]
	v_mfma_f32_16x16x32_bf16 v[114:117], v[156:159], v[172:175], v[114:117]
	v_mfma_f32_16x16x32_bf16 v[110:113], v[148:151], v[194:197], v[110:113]
	v_mfma_f32_16x16x32_bf16 v[106:109], v[156:159], v[194:197], v[106:109]
	v_mfma_f32_16x16x32_bf16 v[102:105], v[148:151], v[202:205], v[102:105]
	v_mfma_f32_16x16x32_bf16 v[98:101], v[156:159], v[202:205], v[98:101]

; #define LDB(dst, b, h) for (int n = 0; n < 2; ++n) for (int k = 0; k < 2; ++k) \
;     dst[n][k] = *reinterpret_cast<const bf16x8*>((char*)SB(b, h) + b_thr + (n * 2 + k) * 1024)
; #define MMA(ai, bj, At, Btf) do { __builtin_amdgcn_s_setprio(1); \
;     for (int m = 0; m < 4; ++m) for (int n = 0; n < 2; ++n) for (int k = 0; k < 2; ++k) \
;       acc[ai][bj][m][n] = __builtin_amdgcn_mfma_f32_16x16x32_bf16(Btf[n][k], At[m][k], acc[ai][bj][m][n], 0, 0, 0); \
;     __builtin_amdgcn_s_setprio(0); } while (0)
; #define WAIT_V(n) asm volatile("s_waitcnt vmcnt(" #n ")" ::: "memory")
; #define WAIT_L(n) asm volatile("s_waitcnt lgkmcnt(" #n ")" ::: "memory")
; #define BAR __builtin_amdgcn_s_barrier()
; template <bool OVL, bool PANEL = false, class Epi>
; __device__ __forceinline__ void gemm_phase(const bf16_t* __restrict__ A, long lda, const bf16_t* __restrict__ Bt, long ldb, int nM, int nN, int K,
;                                            const Epi& epi, bf16_t* shm, int w0) {
;     ...
;       LDB(B1, 1, 1); WAIT_V(0); BAR; WAIT_L(0); MMA(0, 1, At, B1); BAR;
	v_add_u32_e32 v0, 0x1c000, v182
	s_barrier
	ds_read_b128 v[206:209], v0
	ds_read_b128 v[210:213], v0 offset:1024
	ds_read_b128 v[214:217], v0 offset:2048
	ds_read_b128 v[218:221], v0 offset:3072
	s_waitcnt vmcnt(0)
	s_barrier
	s_waitcnt lgkmcnt(0)

; #define LDB(dst, b, h) for (int n = 0; n < 2; ++n) for (int k = 0; k < 2; ++k) \
;     dst[n][k] = *reinterpret_cast<const bf16x8*>((char*)SB(b, h) + b_thr + (n * 2 + k) * 1024)
; #define MMA(ai, bj, At, Btf) do { __builtin_amdgcn_s_setprio(1); \
;     for (int m = 0; m < 4; ++m) for (int n = 0; n < 2; ++n) for (int k = 0; k < 2; ++k) \
;       acc[ai][bj][m][n] = __builtin_amdgcn_mfma_f32_16x16x32_bf16(Btf[n][k], At[m][k], acc[ai][bj][m][n], 0, 0, 0); \
;     __builtin_amdgcn_s_setprio(0); } while (0)
; #define WAIT_V(n) asm volatile("s_waitcnt vmcnt(" #n ")" ::: "memory")
; #define WAIT_L(n) asm volatile("s_waitcnt lgkmcnt(" #n ")" ::: "memory")
; #define BAR __builtin_amdgcn_s_barrier()
; template <bool OVL, bool PANEL = false, class Epi>
; __device__ __forceinline__ void gemm_phase(const bf16_t* __restrict__ A, long lda, const bf16_t* __restrict__ Bt, long ldb, int nM, int nN, int K,
;                                            const Epi& epi, bf16_t* shm, int w0) {
;     ...
;       LDB(B1, 1, 1); WAIT_V(0); BAR; WAIT_L(0); MMA(0, 1, At, B1); BAR;
	s_waitcnt lgkmcnt(0)
	v_mfma_f32_16x16x32_bf16 v[94:97], v[206:209], v[160:163], v[94:97]
	v_mfma_f32_16x16x32_bf16 v[90:93], v[214:217], v[160:163], v[90:93]
	v_mfma_f32_16x16x32_bf16 v[86:89], v[206:209], v[168:171], v[86:89]
	v_mfma_f32_16x16x32_bf16 v[82:85], v[214:217], v[168:171], v[82:85]
	v_mfma_f32_16x16x32_bf16 v[78:81], v[206:209], v[176:179], v[78:81]
	v_mfma_f32_16x16x32_bf16 v[74:77], v[214:217], v[176:179], v[74:77]
	v_mfma_f32_16x16x32_bf16 v[70:73], v[206:209], v[198:201], v[70:73]
	v_mfma_f32_16x16x32_bf16 v[66:69], v[214:217], v[198:201], v[66:69]
	v_mfma_f32_16x16x32_bf16 v[94:97], v[210:213], v[164:167], v[94:97]
	v_mfma_f32_16x16x32_bf16 v[90:93], v[218:221], v[164:167], v[90:93]
	v_mfma_f32_16x16x32_bf16 v[86:89], v[210:213], v[172:175], v[86:89]
	v_mfma_f32_16x16x32_bf16 v[82:85], v[218:221], v[172:175], v[82:85]
	v_mfma_f32_16x16x32_bf16 v[78:81], v[210:213], v[194:197], v[78:81]
	v_mfma_f32_16x16x32_bf16 v[74:77], v[218:221], v[194:197], v[74:77]
	v_mfma_f32_16x16x32_bf16 v[70:73], v[210:213], v[202:205], v[70:73]
	v_mfma_f32_16x16x32_bf16 v[66:69], v[218:221], v[202:205], v[66:69]

; #define LDA(dst, b, h) for (int m = 0; m < 4; ++m) for (int k = 0; k < 2; ++k) \
;     dst[m][k] = *reinterpret_cast<const bf16x8*>((char*)SA(b, h) + a_thr + (m * 2 + k) * 1024)
; #define MMA(ai, bj, At, Btf) do { __builtin_amdgcn_s_setprio(1); \
;     for (int m = 0; m < 4; ++m) for (int n = 0; n < 2; ++n) for (int k = 0; k < 2; ++k) \
;       acc[ai][bj][m][n] = __builtin_amdgcn_mfma_f32_16x16x32_bf16(Btf[n][k], At[m][k], acc[ai][bj][m][n], 0, 0, 0); \
;     __builtin_amdgcn_s_setprio(0); } while (0)
; #define WAIT_L(n) asm volatile("s_waitcnt lgkmcnt(" #n ")" ::: "memory")
; #define BAR __builtin_amdgcn_s_barrier()
; template <bool OVL, bool PANEL = false, class Epi>
; __device__ __forceinline__ void gemm_phase(const bf16_t* __restrict__ A, long lda, const bf16_t* __restrict__ Bt, long ldb, int nM, int nN, int K,
;                                            const Epi& epi, bf16_t* shm, int w0) {
;     ...
;       LDA(At, 1, 1); BAR; WAIT_L(0); MMA(1, 0, At, B0); MMA(1, 1, At, B1); BAR; }
	s_barrier
	ds_read_b128 v[160:163], v147 offset:49152
	ds_read_b128 v[164:167], v147 offset:50176
	ds_read_b128 v[168:171], v147 offset:51200
	ds_read_b128 v[172:175], v147 offset:52224
	ds_read_b128 v[176:179], v147 offset:53248
	ds_read_b128 v[194:197], v147 offset:54272
	ds_read_b128 v[198:201], v147 offset:55296
	ds_read_b128 v[202:205], v147 offset:56320
	s_barrier
	s_waitcnt lgkmcnt(0)

; #define LDA(dst, b, h) for (int m = 0; m < 4; ++m) for (int k = 0; k < 2; ++k) \
;     dst[m][k] = *reinterpret_cast<const bf16x8*>((char*)SA(b, h) + a_thr + (m * 2 + k) * 1024)
; #define MMA(ai, bj, At, Btf) do { __builtin_amdgcn_s_setprio(1); \
;     for (int m = 0; m < 4; ++m) for (int n = 0; n < 2; ++n) for (int k = 0; k < 2; ++k) \
;       acc[ai][bj][m][n] = __builtin_amdgcn_mfma_f32_16x16x32_bf16(Btf[n][k], At[m][k], acc[ai][bj][m][n], 0, 0, 0); \
;     __builtin_amdgcn_s_setprio(0); } while (0)
; #define WAIT_L(n) asm volatile("s_waitcnt lgkmcnt(" #n ")" ::: "memory")
; #define BAR __builtin_amdgcn_s_barrier()
; template <bool OVL, bool PANEL = false, class Epi>
; __device__ __forceinline__ void gemm_phase(const bf16_t* __restrict__ A, long lda, const bf16_t* __restrict__ Bt, long ldb, int nM, int nN, int K,
;                                            const Epi& epi, bf16_t* shm, int w0) {
;     ...
;       LDA(At, 1, 1); BAR; WAIT_L(0); MMA(1, 0, At, B0); MMA(1, 1, At, B1); BAR; }
	s_waitcnt lgkmcnt(0)
	v_mfma_f32_16x16x32_bf16 v[62:65], v[130:133], v[160:163], v[62:65]
	v_mfma_f32_16x16x32_bf16 v[58:61], v[152:155], v[160:163], v[58:61]
	v_mfma_f32_16x16x32_bf16 v[54:57], v[130:133], v[168:171], v[54:57]
	v_mfma_f32_16x16x32_bf16 v[50:53], v[152:155], v[168:171], v[50:53]
	v_mfma_f32_16x16x32_bf16 v[46:49], v[130:133], v[176:179], v[46:49]
	v_mfma_f32_16x16x32_bf16 v[42:45], v[152:155], v[176:179], v[42:45]
	v_mfma_f32_16x16x32_bf16 v[38:41], v[130:133], v[198:201], v[38:41]
	v_mfma_f32_16x16x32_bf16 v[34:37], v[152:155], v[198:201], v[34:37]
	v_mfma_f32_16x16x32_bf16 v[62:65], v[148:151], v[164:167], v[62:65]
	v_mfma_f32_16x16x32_bf16 v[58:61], v[156:159], v[164:167], v[58:61]
	v_mfma_f32_16x16x32_bf16 v[54:57], v[148:151], v[172:175], v[54:57]
	v_mfma_f32_16x16x32_bf16 v[50:53], v[156:159], v[172:175], v[50:53]
	v_mfma_f32_16x16x32_bf16 v[46:49], v[148:151], v[194:197], v[46:49]
	v_mfma_f32_16x16x32_bf16 v[42:45], v[156:159], v[194:197], v[42:45]
	v_mfma_f32_16x16x32_bf16 v[38:41], v[148:151], v[202:205], v[38:41]
	v_mfma_f32_16x16x32_bf16 v[34:37], v[156:159], v[202:205], v[34:37]


; #define LDA(dst, b, h) for (int m = 0; m < 4; ++m) for (int k = 0; k < 2; ++k) \
;     dst[m][k] = *reinterpret_cast<const bf16x8*>((char*)SA(b, h) + a_thr + (m * 2 + k) * 1024)
; #define MMA(ai, bj, At, Btf) do { __builtin_amdgcn_s_setprio(1); \
;     for (int m = 0; m < 4; ++m) for (int n = 0; n < 2; ++n) for (int k = 0; k < 2; ++k) \
;       acc[ai][bj][m][n] = __builtin_amdgcn_mfma_f32_16x16x32_bf16(Btf[n][k], At[m][k], acc[ai][bj][m][n], 0, 0, 0); \
;     __builtin_amdgcn_s_setprio(0); } while (0)
; #define WAIT_L(n) asm volatile("s_waitcnt lgkmcnt(" #n ")" ::: "memory")
; #define BAR __builtin_amdgcn_s_barrier()
; template <bool OVL, bool PANEL = false, class Epi>
; __device__ __forceinline__ void gemm_phase(const bf16_t* __restrict__ A, long lda, const bf16_t* __restrict__ Bt, long ldb, int nM, int nN, int K,
;                                            const Epi& epi, bf16_t* shm, int w0) {
;     ...
;       LDA(At, 1, 1); BAR; WAIT_L(0); MMA(1, 0, At, B0); MMA(1, 1, At, B1); BAR; }
	v_mfma_f32_16x16x32_bf16 v[30:33], v[206:209], v[160:163], v[30:33]
	v_mfma_f32_16x16x32_bf16 v[26:29], v[214:217], v[160:163], v[26:29]
	v_mfma_f32_16x16x32_bf16 v[22:25], v[206:209], v[168:171], v[22:25]
	v_mfma_f32_16x16x32_bf16 v[18:21], v[214:217], v[168:171], v[18:21]
	v_mfma_f32_16x16x32_bf16 v[14:17], v[206:209], v[176:179], v[14:17]
	v_mfma_f32_16x16x32_bf16 v[10:13], v[214:217], v[176:179], v[10:13]
	v_mfma_f32_16x16x32_bf16 v[6:9], v[206:209], v[198:201], v[6:9]
	v_mfma_f32_16x16x32_bf16 v[2:5], v[214:217], v[198:201], v[2:5]
	v_mfma_f32_16x16x32_bf16 v[30:33], v[210:213], v[164:167], v[30:33]
	v_mfma_f32_16x16x32_bf16 v[26:29], v[218:221], v[164:167], v[26:29]
	v_mfma_f32_16x16x32_bf16 v[22:25], v[210:213], v[172:175], v[22:25]
	v_mfma_f32_16x16x32_bf16 v[18:21], v[218:221], v[172:175], v[18:21]
	v_mfma_f32_16x16x32_bf16 v[14:17], v[210:213], v[194:197], v[14:17]
	v_mfma_f32_16x16x32_bf16 v[10:13], v[218:221], v[194:197], v[10:13]
	v_mfma_f32_16x16x32_bf16 v[6:9], v[210:213], v[202:205], v[6:9]
	v_mfma_f32_16x16x32_bf16 v[2:5], v[218:221], v[202:205], v[2:5]

; #define LDA(dst, b, h) for (int m = 0; m < 4; ++m) for (int k = 0; k < 2; ++k) \
;     dst[m][k] = *reinterpret_cast<const bf16x8*>((char*)SA(b, h) + a_thr + (m * 2 + k) * 1024)
; #define MMA(ai, bj, At, Btf) do { __builtin_amdgcn_s_setprio(1); \
;     for (int m = 0; m < 4; ++m) for (int n = 0; n < 2; ++n) for (int k = 0; k < 2; ++k) \
;       acc[ai][bj][m][n] = __builtin_amdgcn_mfma_f32_16x16x32_bf16(Btf[n][k], At[m][k], acc[ai][bj][m][n], 0, 0, 0); \
;     __builtin_amdgcn_s_setprio(0); } while (0)
; #define WAIT_L(n) asm volatile("s_waitcnt lgkmcnt(" #n ")" ::: "memory")
; #define BAR __builtin_amdgcn_s_barrier()
; template <bool OVL, bool PANEL = false, class Epi>
; __device__ __forceinline__ void gemm_phase(const bf16_t* __restrict__ A, long lda, const bf16_t* __restrict__ Bt, long ldb, int nM, int nN, int K,
;                                            const Epi& epi, bf16_t* shm, int w0) {
;     ...
;       LDA(At, 1, 1); BAR; WAIT_L(0); MMA(1, 0, At, B0); MMA(1, 1, At, B1); BAR; }
;     if (wr == 0) BAR;
	s_barrier
	s_and_saveexec_b64 s[8:9], s[6:7]
	s_cbranch_execz .LBB0_1056
	s_barrier
